# GEMM phases: one static s_setprio 1 for waves 4-7 at phase entry, all per-MFMA-block setprio flips in the 14 K-loops deleted
# baseline (speedup 1.0000x reference)
;     __host__ __device__ bool next(int i, Unit& u) const {
;         const long L = (long)i * G + c; if (L >= nwg) return false;
;         int wgid = (int)L; { const int q = nwg / NXCD, r = nwg % NXCD, xcd = wgid % NXCD, off = wgid / NXCD; wgid = (xcd < r ? xcd * (q + 1) : r * (q + 1) + (xcd - r) * q) + off; }
;         const int nig = WGM * nN, gid = wgid / nig, fm = gid * WGM, gsz = (nM - fm) < WGM ? (nM - fm) : WGM;
;         u.pm = fm + ((wgid % nig) % gsz); u.pn = (wgid % nig) / gsz; return true;
; template <class Epi, class Sched, bool ALIGN_EPI = false, bool SP2 = false>
; __device__ __forceinline__ void gemm_phase(PG8_LAS unsigned char* lds, const Gemm g, const Sched& S, const Epi& E, const int wave_in) {
;     const int wid = __builtin_amdgcn_readfirstlane(wave_in), lane = mk_lane(), tid = wid * 64 + lane, wr = wid >> 2, wc = wid & 3, fr = lane & 15, fq = lane >> 4;
;     const int K = g.K, nt = K / BK;
;     unsigned voffA[2], voffB[2];
; #pragma unroll
;     for (int i = 0; i < 2; ++i) { int R, C; stage_rc(tid * 16 + i * 8192, R, C); const int Rb = Epi::PERM ? ((R & ~31) + perm32(R & 31)) : R;
;         voffA[i] = (unsigned)(R * g.lda + C) * 2u; voffB[i] = (unsigned)(Rb * K + C) * 2u; }
;     const size_t kstep = (size_t)(BK * 2);
;     const size_t hstep = (size_t)HALF * K * 2, hstepA = (size_t)HALF * g.lda * 2;
;     const size_t tstep = 2 * hstep, tstepA = 2 * hstepA;
;     const unsigned ldsw = (unsigned)wid * 1024u;
;     const int aoff = lds_byte(wr * 64 + fr, fq * 8), boff = lds_byte(wc * 32 + fr, fq * 8);
;     ...
;     Unit cur, nxt; int ui = 0;
;     if (!S.next(0, cur)) return;
;     f32x4 acc[2][2][4][2];
; #pragma unroll
;     for (int a = 0; a < 2; ++a)
; #pragma unroll
;         for (int b = 0; b < 2; ++b)
; #pragma unroll
;             for (int m = 0; m < 4; ++m)
; #pragma unroll
;                 for (int n = 0; n < 2; ++n) acc[a][b][m][n] = (f32x4){0.f, 0.f, 0.f, 0.f};
;     bf16x8 At[4][2], B0[2][2], B1[2][2];
;     const char* cA = (const char*)g.A + (size_t)cur.pm * tstepA; const char* cB = (const char*)g.Bt + (size_t)cur.pn * tstep;
;     S.a_ready(cur);
;     if constexpr (SP2) {
;         PG8_STAGE(PG8_SB(0, 0), cB, voffB); PG8_STAGE(PG8_SB(0, 1), cB + hstep, voffB); PG8_STAGE(PG8_SA(0, 0), cA, voffA); PG8_STAGE(PG8_SA(0, 1), cA + hstepA, voffA);
;         if (wr == 1) PG8_BAR;
;         PG8_WAIT_V(2); PG8_BAR;
.LBB0_488:
	s_or_b64 exec, exec, s[0:1]
	s_add_u32 s46, s30, 0x8f00000
	s_addc_u32 s47, s31, 0
	s_add_u32 s44, s30, 0x10f00000
	s_addc_u32 s45, s31, 0
	v_readlane_b32 s2, v255, 0
	v_readlane_b32 s3, v255, 1
	s_cmp_lt_i32 s2, 2
	s_cselect_b64 s[0:1], -1, 0
	s_cmp_gt_i32 s3, 1
	s_cselect_b64 s[2:3], -1, 0
	s_and_b64 s[0:1], s[0:1], s[2:3]
	s_andn2_b64 vcc, exec, s[0:1]
	s_barrier
	s_cbranch_vccnz .LBB0_505
	s_setprio 0
	s_cmp_lt_u32 s89, 4
	s_cbranch_scc1 .Lgprio_0
	s_setprio 1
.Lgprio_0:
	s_cmpk_gt_i32 s88, 0x15ff
	v_mbcnt_lo_u32_b32 v10, -1, 0
	v_mbcnt_hi_u32_b32 v10, -1, v10
	s_cbranch_scc1 .LBB0_505
	s_lshl_b32 s11, s89, 10
	v_lshl_add_u32 v0, v10, 4, s11
	v_add_u32_e32 v1, 0x2000, v0
	v_ashrrev_i32_e32 v2, 31, v1
	v_lshrrev_b32_e32 v2, 22, v2
	v_add_u32_e32 v2, v1, v2
	v_ashrrev_i32_e32 v8, 10, v2
	v_mul_i32_i24_e32 v2, 0x400, v8
	v_sub_u32_e32 v1, v1, v2
	v_lshrrev_b32_e32 v2, 4, v1
	v_bitop3_b32 v1, v2, v1, 32 bitop3:0x6c
	v_ashrrev_i32_e32 v2, 31, v1
	v_lshrrev_b32_e32 v2, 26, v2
	v_add_u32_e32 v2, v1, v2
	v_ashrrev_i32_e32 v9, 6, v2
	v_lshlrev_b32_e32 v3, 3, v8
	v_and_b32_e32 v2, 0xffc0, v2
	v_and_b32_e32 v3, -16, v3
	v_sub_u32_e32 v1, v1, v2
	v_add_u32_e32 v3, v9, v3
	v_lshrrev_b16_e32 v2, 7, v1
	v_and_b32_e32 v4, 3, v9
	s_mov_b32 s0, 0xfffe0
	v_lshrrev_b32_e32 v5, 2, v3
	v_lshlrev_b32_e32 v6, 1, v3
	v_and_b32_e32 v2, 1, v2
	v_and_or_b32 v4, v3, s0, v4
	v_and_b32_e32 v5, 4, v5
	v_and_b32_e32 v6, 24, v6
	v_add_u16_e32 v1, v1, v2
	v_mov_b32_e32 v2, 1
	v_or3_b32 v4, v4, v5, v6
	v_lshlrev_b32_e32 v5, 5, v8
	v_ashrrev_i16_sdwa v1, v2, sext(v1) dst_sel:DWORD dst_unused:UNUSED_PAD src0_sel:DWORD src1_sel:BYTE_0
	v_and_b32_e32 v5, 32, v5
	v_bfe_i32 v11, v1, 0, 16
	v_add_lshl_u32 v1, v5, v11, 1
	v_lshl_add_u32 v128, v4, 12, v1
	v_lshl_add_u32 v130, v3, 12, v1
	v_ashrrev_i32_e32 v1, 31, v0
	v_lshrrev_b32_e32 v1, 22, v1
	v_add_u32_e32 v1, v0, v1
	v_ashrrev_i32_e32 v12, 10, v1
	v_mul_i32_i24_e32 v1, 0x400, v12
	v_sub_u32_e32 v0, v0, v1
	v_lshrrev_b32_e32 v1, 4, v0
	v_bitop3_b32 v0, v1, v0, 32 bitop3:0x6c
	v_ashrrev_i32_e32 v1, 31, v0
	v_lshrrev_b32_e32 v1, 26, v1
	v_add_u32_e32 v1, v0, v1
	v_lshlrev_b32_e32 v3, 3, v12
	v_ashrrev_i32_e32 v13, 6, v1
	v_and_b32_e32 v3, -16, v3
	v_add_u32_e32 v3, v13, v3
	v_and_b32_e32 v4, 3, v13
	s_ashr_i32 s33, s88, 31
	v_and_or_b32 v4, v3, s0, v4
	s_lshr_b32 s0, s33, 29
	s_add_i32 s0, s88, s0
	s_ashr_i32 s2, s0, 3
	s_and_b32 s0, s0, -8
	s_ashr_i32 s1, s89, 2
	s_sub_i32 s0, s88, s0
	s_cmp_lt_i32 s0, 0
	s_movk_i32 s35, 0x2c1
	s_cselect_b32 s3, s35, 0x2c0
	s_mul_i32 s0, s0, s3
	s_add_i32 s0, s0, s2
	s_mul_hi_i32 s2, s0, 0x2e8ba2e9
	s_lshr_b32 s3, s2, 31
	s_ashr_i32 s2, s2, 6
	s_add_i32 s2, s2, s3
	s_lshl_b32 s3, s2, 3
	s_mulk_i32 s2, 0x160
	s_sub_i32 s2, s0, s2
	s_sext_i32_i16 s0, s2
	s_bfe_u32 s0, s0, 0x3001c
	s_add_i32 s4, s2, s0
	s_sext_i32_i16 s0, s4
	s_and_b32 s4, s4, 0xfff8
	s_sub_i32 s2, s2, s4
	s_sext_i32_i16 s2, s2
	v_lshrrev_b32_e32 v5, 2, v3
	v_lshlrev_b32_e32 v6, 1, v3
	v_and_b32_e32 v1, 0xc0, v1
	s_lshr_b32 s0, s0, 3
	s_add_i32 s18, s3, s2
	v_and_b32_e32 v5, 4, v5
	v_and_b32_e32 v6, 24, v6
	v_sub_u32_e32 v0, v0, v1
	s_ashr_i32 s19, s18, 31
	s_bfe_i64 s[4:5], s[0:1], 0x100000
	v_or3_b32 v4, v4, v5, v6
	v_lshlrev_b32_e32 v5, 5, v12
	v_ashrrev_i16_sdwa v0, v2, sext(v0) dst_sel:DWORD dst_unused:UNUSED_PAD src0_sel:DWORD src1_sel:BYTE_0
	s_lshl_b64 s[2:3], s[18:19], 20
	s_lshl_b64 s[4:5], s[4:5], 20
	v_readlane_b32 s6, v255, 46
	v_and_b32_e32 v5, 32, v5
	v_bfe_i32 v14, v0, 0, 16
	v_readlane_b32 s7, v255, 47
	s_add_u32 s4, s6, s4
	v_add_lshl_u32 v0, v5, v14, 1
	s_addc_u32 s5, s7, s5
	s_add_i32 s19, s11, 0
	v_lshl_add_u32 v132, v4, 12, v0
	s_add_i32 m0, s19, 0x10000
	v_lshl_add_u32 v134, v3, 12, v0
	global_load_lds_dwordx4 v132, s[4:5]
	s_add_i32 m0, s19, 0x12000
	s_add_u32 s6, s4, 0x80000
	global_load_lds_dwordx4 v128, s[4:5]
	s_addc_u32 s7, s5, 0
	s_add_i32 m0, s19, 0x14000
	v_mov_b32_e32 v133, 0
	global_load_lds_dwordx4 v132, s[6:7]
	s_add_i32 m0, s19, 0x16000
	s_add_u32 s68, s46, s2
	s_addc_u32 s69, s47, s3
	s_add_i32 s38, s19, 0x2000
	global_load_lds_dwordx4 v128, s[6:7]
	s_mov_b32 m0, s19
	s_add_u32 s2, s68, 0x80000
	global_load_lds_dwordx4 v134, s[68:69]
	s_mov_b32 m0, s38
	s_addc_u32 s3, s69, 0
	s_add_i32 s39, s19, 0x4000
	global_load_lds_dwordx4 v130, s[68:69]
	s_mov_b32 m0, s39
	s_add_i32 s40, s19, 0x6000
	global_load_lds_dwordx4 v134, s[2:3]
	s_mov_b32 m0, s40
	v_mov_b32_e32 v129, v133
	global_load_lds_dwordx4 v130, s[2:3]
	v_mov_b32_e32 v135, v133
	v_mov_b32_e32 v131, v133
	s_cmp_eq_u32 s1, 1
	s_mov_b32 s41, 0
	v_lshl_add_u64 v[6:7], s[4:5], 0, v[132:133]
	v_lshl_add_u64 v[4:5], s[4:5], 0, v[128:129]
	v_lshl_add_u64 v[0:1], s[68:69], 0, v[134:135]
	s_cselect_b64 s[2:3], -1, 0
	s_cmp_lg_u32 s1, 1
	v_lshl_add_u64 v[2:3], s[68:69], 0, v[130:131]
	s_cbranch_scc1 .LBB0_492
	s_barrier

; #define PG8_STAGE(bufoff, gbase, voff) do { _Pragma("unroll") for (int _i = 0; _i < 2; ++_i) \
;         __builtin_amdgcn_global_load_lds((const unsigned*)((const char*)(gbase) + (voff)[_i]), (PG8_LAS unsigned*)(lds + (bufoff) + ldsw + _i * 8192), 16, 0, 0); } while (0)
; #define PG8_LDA(dst, b, h) do { _Pragma("unroll") for (int m = 0; m < 4; ++m) _Pragma("unroll") for (int k = 0; k < 2; ++k) dst[m][k] = *(const PG8_LAS bf16x8*)(lds + PG8_SA(b, h) + aoff + m * 2048 + k * 1024); } while (0)
; #define PG8_LDB(dst, b, h) do { _Pragma("unroll") for (int n = 0; n < 2; ++n) _Pragma("unroll") for (int k = 0; k < 2; ++k) dst[n][k] = *(const PG8_LAS bf16x8*)(lds + PG8_SB(b, h) + boff + n * 2048 + k * 1024); } while (0)
; #define PG8_MMA(ai, bj, At, Bt) do { __builtin_amdgcn_s_setprio(1); _Pragma("unroll") for (int m = 0; m < 4; ++m) _Pragma("unroll") for (int n = 0; n < 2; ++n) _Pragma("unroll") for (int k = 0; k < 2; ++k) \
;         acc[ai][bj][m][n] = __builtin_amdgcn_mfma_f32_16x16x32_bf16(Bt[n][k], At[m][k], acc[ai][bj][m][n], 0, 0, 0); __builtin_amdgcn_s_setprio(0); } while (0)
; #define PG8_WAIT_V(n) asm volatile("s_waitcnt vmcnt(" #n ")" ::: "memory")
; #define PG8_WAIT_L(n) asm volatile("s_waitcnt lgkmcnt(" #n ")" ::: "memory")
; template <class Epi, class Sched, bool ALIGN_EPI = false, bool SP2 = false>
; __device__ __forceinline__ void gemm_phase(PG8_LAS unsigned char* lds, const Gemm g, const Sched& S, const Epi& E, const int wave_in) {
;     ...
;             const bool last = (t == nt - 2);
;             const char* a1 = cA + (size_t)(t + 1) * kstep;
;             const char* a2 = last ? nA : cA + (size_t)(t + 2) * kstep; const char* b2 = last ? nB : cB + (size_t)(t + 2) * kstep;
;             const char* a3 = a2 + kstep; const char* b3 = b2 + kstep;
;             if (last && has_next) S.a_ready(nxt);
;             if constexpr (SP2) {
;             PG8_LDB(B0, 0, 0); PG8_LDB(B1, 0, 1); PG8_SCHED; PG8_LDA(At, 0, 0); PG8_STAGE(PG8_SA(1, 1), a1 + hstepA, voffA);
;             PG8_WAIT_V(8); PG8_WAIT_L(0); PG8_BAR; PG8_MMA(0, 0, At, B0); PG8_MMA(0, 1, At, B1); PG8_BAR; PG8_SCHED;
;             PG8_LDA(At, 0, 1); PG8_STAGE(PG8_SB(0, 0), b2, voffB); PG8_STAGE(PG8_SB(0, 1), b2 + hstep, voffB); PG8_STAGE(PG8_SA(0, 0), a2, voffA);
;             PG8_WAIT_V(8); PG8_WAIT_L(0); PG8_BAR; PG8_MMA(1, 0, At, B0); PG8_MMA(1, 1, At, B1); PG8_BAR; PG8_SCHED;
.LBB0_498:
	ds_read_b128 v[144:147], v153
	ds_read_b128 v[158:161], v153 offset:1024
	ds_read_b128 v[162:165], v153 offset:2048
	ds_read_b128 v[166:169], v153 offset:3072
	ds_read_b128 v[170:173], v154
	ds_read_b128 v[174:177], v154 offset:1024
	ds_read_b128 v[178:181], v154 offset:2048
	ds_read_b128 v[182:185], v154 offset:3072
	s_add_u32 s4, s68, 0xfff80080
	s_addc_u32 s5, s69, -1
	s_cmp_eq_u32 s78, 28
	s_cselect_b32 s71, s36, s5
	s_cselect_b32 s70, s37, s4
	s_cselect_b32 s5, s61, s73
	s_cselect_b32 s4, s63, s72
	v_lshl_add_u64 v[148:149], s[68:69], 0, v[136:137]
	s_add_i32 m0, s19, 0xc000
	ds_read_b128 v[186:189], v155
	ds_read_b128 v[190:193], v155 offset:1024
	ds_read_b128 v[194:197], v155 offset:2048
	ds_read_b128 v[198:201], v155 offset:3072
	ds_read_b128 v[202:205], v155 offset:4096
	ds_read_b128 v[206:209], v155 offset:5120
	ds_read_b128 v[210:213], v155 offset:6144
	ds_read_b128 v[214:217], v155 offset:7168
	global_load_lds_dwordx4 v[148:149], off
	v_lshl_add_u64 v[148:149], s[68:69], 0, v[138:139]
	s_add_i32 m0, s19, 0xe000
	s_nop 0
	global_load_lds_dwordx4 v[148:149], off
	s_waitcnt vmcnt(8)
	s_waitcnt lgkmcnt(0)
	s_barrier
	s_waitcnt lgkmcnt(0)
	v_mfma_f32_16x16x32_bf16 v[120:123], v[144:147], v[186:189], v[120:123]
	v_mfma_f32_16x16x32_bf16 v[116:119], v[162:165], v[186:189], v[116:119]
	v_mfma_f32_16x16x32_bf16 v[104:107], v[144:147], v[194:197], v[104:107]
	v_mfma_f32_16x16x32_bf16 v[100:103], v[162:165], v[194:197], v[100:103]
	v_mfma_f32_16x16x32_bf16 v[88:91], v[144:147], v[202:205], v[88:91]
	v_mfma_f32_16x16x32_bf16 v[84:87], v[162:165], v[202:205], v[84:87]
	v_mfma_f32_16x16x32_bf16 v[72:75], v[144:147], v[210:213], v[72:75]
	v_mfma_f32_16x16x32_bf16 v[68:71], v[162:165], v[210:213], v[68:71]
	v_mfma_f32_16x16x32_bf16 v[120:123], v[158:161], v[190:193], v[120:123]
	v_mfma_f32_16x16x32_bf16 v[116:119], v[166:169], v[190:193], v[116:119]
	v_mfma_f32_16x16x32_bf16 v[104:107], v[158:161], v[198:201], v[104:107]
	v_mfma_f32_16x16x32_bf16 v[100:103], v[166:169], v[198:201], v[100:103]
	v_mfma_f32_16x16x32_bf16 v[88:91], v[158:161], v[206:209], v[88:91]
	v_mfma_f32_16x16x32_bf16 v[84:87], v[166:169], v[206:209], v[84:87]
	v_mfma_f32_16x16x32_bf16 v[72:75], v[158:161], v[214:217], v[72:75]
	v_mfma_f32_16x16x32_bf16 v[68:71], v[166:169], v[214:217], v[68:71]
	v_mfma_f32_16x16x32_bf16 v[124:127], v[170:173], v[186:189], v[124:127]
	v_mfma_f32_16x16x32_bf16 v[112:115], v[178:181], v[186:189], v[112:115]
	v_mfma_f32_16x16x32_bf16 v[108:111], v[170:173], v[194:197], v[108:111]
	v_mfma_f32_16x16x32_bf16 v[96:99], v[178:181], v[194:197], v[96:99]
	v_mfma_f32_16x16x32_bf16 v[92:95], v[170:173], v[202:205], v[92:95]
	v_mfma_f32_16x16x32_bf16 v[80:83], v[178:181], v[202:205], v[80:83]
	v_mfma_f32_16x16x32_bf16 v[76:79], v[170:173], v[210:213], v[76:79]
	v_mfma_f32_16x16x32_bf16 v[64:67], v[178:181], v[210:213], v[64:67]
	v_mfma_f32_16x16x32_bf16 v[124:127], v[174:177], v[190:193], v[124:127]
	v_mfma_f32_16x16x32_bf16 v[112:115], v[182:185], v[190:193], v[112:115]
	v_mfma_f32_16x16x32_bf16 v[108:111], v[174:177], v[198:201], v[108:111]
	v_mfma_f32_16x16x32_bf16 v[96:99], v[182:185], v[198:201], v[96:99]
	v_mfma_f32_16x16x32_bf16 v[92:95], v[174:177], v[206:209], v[92:95]
	v_mfma_f32_16x16x32_bf16 v[80:83], v[182:185], v[206:209], v[80:83]
	v_mfma_f32_16x16x32_bf16 v[76:79], v[174:177], v[214:217], v[76:79]
	v_mfma_f32_16x16x32_bf16 v[64:67], v[182:185], v[214:217], v[64:67]
	s_barrier
	s_add_i32 s79, s48, s11
	v_lshl_add_u64 v[148:149], s[4:5], 0, v[132:133]
	s_mov_b32 m0, s79
	ds_read_b128 v[186:189], v155 offset:16384
	ds_read_b128 v[190:193], v155 offset:17408
	ds_read_b128 v[194:197], v155 offset:18432
	ds_read_b128 v[198:201], v155 offset:19456
	ds_read_b128 v[202:205], v155 offset:20480
	ds_read_b128 v[206:209], v155 offset:21504
	ds_read_b128 v[210:213], v155 offset:22528
	ds_read_b128 v[214:217], v155 offset:23552
	global_load_lds_dwordx4 v[148:149], off
	s_add_i32 m0, s79, 0x2000
	s_add_u32 s84, s4, 0x80000
	v_lshl_add_u64 v[218:219], s[4:5], 0, v[128:129]
	s_addc_u32 s85, s5, 0
	s_add_i32 s79, s49, s11
	global_load_lds_dwordx4 v[218:219], off
	v_lshl_add_u64 v[220:221], s[84:85], 0, v[132:133]
	s_mov_b32 m0, s79
	v_lshl_add_u64 v[222:223], s[70:71], 0, v[130:131]
	global_load_lds_dwordx4 v[220:221], off
	v_lshl_add_u64 v[220:221], s[84:85], 0, v[128:129]
	s_add_i32 m0, s79, 0x2000
	s_nop 0
	global_load_lds_dwordx4 v[220:221], off
	v_lshl_add_u64 v[220:221], s[70:71], 0, v[134:135]
	s_mov_b32 m0, s19
	s_nop 0
	global_load_lds_dwordx4 v[220:221], off
	s_mov_b32 m0, s38
	s_nop 0
	global_load_lds_dwordx4 v[222:223], off
	s_waitcnt vmcnt(8)
	s_waitcnt lgkmcnt(0)
	s_barrier
; #define PG8_STAGE(bufoff, gbase, voff) do { _Pragma("unroll") for (int _i = 0; _i < 2; ++_i) \
;         __builtin_amdgcn_global_load_lds((const unsigned*)((const char*)(gbase) + (voff)[_i]), (PG8_LAS unsigned*)(lds + (bufoff) + ldsw + _i * 8192), 16, 0, 0); } while (0)
; #define PG8_LDA(dst, b, h) do { _Pragma("unroll") for (int m = 0; m < 4; ++m) _Pragma("unroll") for (int k = 0; k < 2; ++k) dst[m][k] = *(const PG8_LAS bf16x8*)(lds + PG8_SA(b, h) + aoff + m * 2048 + k * 1024); } while (0)
; #define PG8_LDB(dst, b, h) do { _Pragma("unroll") for (int n = 0; n < 2; ++n) _Pragma("unroll") for (int k = 0; k < 2; ++k) dst[n][k] = *(const PG8_LAS bf16x8*)(lds + PG8_SB(b, h) + boff + n * 2048 + k * 1024); } while (0)
; #define PG8_MMA(ai, bj, At, Bt) do { __builtin_amdgcn_s_setprio(1); _Pragma("unroll") for (int m = 0; m < 4; ++m) _Pragma("unroll") for (int n = 0; n < 2; ++n) _Pragma("unroll") for (int k = 0; k < 2; ++k) \
;         acc[ai][bj][m][n] = __builtin_amdgcn_mfma_f32_16x16x32_bf16(Bt[n][k], At[m][k], acc[ai][bj][m][n], 0, 0, 0); __builtin_amdgcn_s_setprio(0); } while (0)
; #define PG8_WAIT_V(n) asm volatile("s_waitcnt vmcnt(" #n ")" ::: "memory")
; #define PG8_WAIT_L(n) asm volatile("s_waitcnt lgkmcnt(" #n ")" ::: "memory")
; #define PG8_BAR __builtin_amdgcn_s_barrier()
; #define PG8_SCHED __builtin_amdgcn_sched_barrier(0)
; template <class Epi, class Sched, bool ALIGN_EPI = false, bool SP2 = false>
; __device__ __forceinline__ void gemm_phase(PG8_LAS unsigned char* lds, const Gemm g, const Sched& S, const Epi& E, const int wave_in) {
;     ...
;             PG8_WAIT_V(8); PG8_WAIT_L(0); PG8_BAR; PG8_MMA(1, 0, At, B0); PG8_MMA(1, 1, At, B1); PG8_BAR; PG8_SCHED;
;             PG8_LDB(B0, 1, 0); PG8_LDB(B1, 1, 1); PG8_SCHED; PG8_LDA(At, 1, 0); PG8_STAGE(PG8_SA(0, 1), a2 + hstepA, voffA);
;             PG8_WAIT_V(8); PG8_WAIT_L(0); PG8_BAR; PG8_MMA(0, 0, At, B0); PG8_MMA(0, 1, At, B1); PG8_BAR; PG8_SCHED;
	s_waitcnt lgkmcnt(0)
	v_mfma_f32_16x16x32_bf16 v[56:59], v[144:147], v[186:189], v[56:59]
	v_mfma_f32_16x16x32_bf16 v[52:55], v[162:165], v[186:189], v[52:55]
	v_mfma_f32_16x16x32_bf16 v[40:43], v[144:147], v[194:197], v[40:43]
	v_mfma_f32_16x16x32_bf16 v[36:39], v[162:165], v[194:197], v[36:39]
	v_mfma_f32_16x16x32_bf16 v[24:27], v[144:147], v[202:205], v[24:27]
	v_mfma_f32_16x16x32_bf16 v[20:23], v[162:165], v[202:205], v[20:23]
	v_mfma_f32_16x16x32_bf16 v[8:11], v[144:147], v[210:213], v[8:11]
	v_mfma_f32_16x16x32_bf16 v[4:7], v[162:165], v[210:213], v[4:7]
	v_mfma_f32_16x16x32_bf16 v[56:59], v[158:161], v[190:193], v[56:59]
	v_mfma_f32_16x16x32_bf16 v[52:55], v[166:169], v[190:193], v[52:55]
	v_mfma_f32_16x16x32_bf16 v[40:43], v[158:161], v[198:201], v[40:43]
	v_mfma_f32_16x16x32_bf16 v[36:39], v[166:169], v[198:201], v[36:39]
	v_mfma_f32_16x16x32_bf16 v[24:27], v[158:161], v[206:209], v[24:27]
	v_mfma_f32_16x16x32_bf16 v[20:23], v[166:169], v[206:209], v[20:23]
	v_mfma_f32_16x16x32_bf16 v[8:11], v[158:161], v[214:217], v[8:11]
	v_mfma_f32_16x16x32_bf16 v[4:7], v[166:169], v[214:217], v[4:7]
	v_mfma_f32_16x16x32_bf16 v[60:63], v[170:173], v[186:189], v[60:63]
	v_mfma_f32_16x16x32_bf16 v[48:51], v[178:181], v[186:189], v[48:51]
	v_mfma_f32_16x16x32_bf16 v[44:47], v[170:173], v[194:197], v[44:47]
	v_mfma_f32_16x16x32_bf16 v[32:35], v[178:181], v[194:197], v[32:35]
	v_mfma_f32_16x16x32_bf16 v[28:31], v[170:173], v[202:205], v[28:31]
	v_mfma_f32_16x16x32_bf16 v[16:19], v[178:181], v[202:205], v[16:19]
	v_mfma_f32_16x16x32_bf16 v[12:15], v[170:173], v[210:213], v[12:15]
	v_mfma_f32_16x16x32_bf16 v[0:3], v[178:181], v[210:213], v[0:3]
	v_mfma_f32_16x16x32_bf16 v[60:63], v[174:177], v[190:193], v[60:63]
	v_mfma_f32_16x16x32_bf16 v[48:51], v[182:185], v[190:193], v[48:51]
	v_mfma_f32_16x16x32_bf16 v[44:47], v[174:177], v[198:201], v[44:47]
	v_mfma_f32_16x16x32_bf16 v[32:35], v[182:185], v[198:201], v[32:35]
	v_mfma_f32_16x16x32_bf16 v[28:31], v[174:177], v[206:209], v[28:31]
	v_mfma_f32_16x16x32_bf16 v[16:19], v[182:185], v[206:209], v[16:19]
	v_mfma_f32_16x16x32_bf16 v[12:15], v[174:177], v[214:217], v[12:15]
	v_mfma_f32_16x16x32_bf16 v[0:3], v[182:185], v[214:217], v[0:3]
	s_barrier
	s_add_i32 s79, 0, 0x18000
	v_add_u32_e32 v157, s79, v151
	s_add_i32 s84, 0, 0x1c000
	ds_read_b128 v[144:147], v157
	ds_read_b128 v[158:161], v157 offset:1024
	ds_read_b128 v[162:165], v157 offset:2048
	ds_read_b128 v[166:169], v157 offset:3072
	v_add_u32_e32 v157, s84, v151
	ds_read_b128 v[170:173], v157
	ds_read_b128 v[174:177], v157 offset:1024
	ds_read_b128 v[178:181], v157 offset:2048
	ds_read_b128 v[182:185], v157 offset:3072
	s_add_u32 s70, s70, 0x80000
	s_addc_u32 s71, s71, 0
	s_mov_b32 m0, s39
	v_lshl_add_u64 v[224:225], s[70:71], 0, v[134:135]
	ds_read_b128 v[186:189], v155 offset:32768
	ds_read_b128 v[190:193], v155 offset:33792
	ds_read_b128 v[194:197], v155 offset:34816
	ds_read_b128 v[198:201], v155 offset:35840
	ds_read_b128 v[202:205], v155 offset:36864
	ds_read_b128 v[206:209], v155 offset:37888
	ds_read_b128 v[210:213], v155 offset:38912
	ds_read_b128 v[214:217], v155 offset:39936
	global_load_lds_dwordx4 v[224:225], off
	v_lshl_add_u64 v[224:225], s[70:71], 0, v[130:131]
	s_mov_b32 m0, s40
	s_nop 0
	global_load_lds_dwordx4 v[224:225], off
	s_waitcnt vmcnt(8)
	s_waitcnt lgkmcnt(0)
	s_barrier
	s_waitcnt lgkmcnt(0)
	v_mfma_f32_16x16x32_bf16 v[120:123], v[144:147], v[186:189], v[120:123]
	v_mfma_f32_16x16x32_bf16 v[116:119], v[162:165], v[186:189], v[116:119]
	v_mfma_f32_16x16x32_bf16 v[104:107], v[144:147], v[194:197], v[104:107]
	v_mfma_f32_16x16x32_bf16 v[100:103], v[162:165], v[194:197], v[100:103]
	v_mfma_f32_16x16x32_bf16 v[88:91], v[144:147], v[202:205], v[88:91]
	v_mfma_f32_16x16x32_bf16 v[84:87], v[162:165], v[202:205], v[84:87]
	v_mfma_f32_16x16x32_bf16 v[72:75], v[144:147], v[210:213], v[72:75]
	v_mfma_f32_16x16x32_bf16 v[68:71], v[162:165], v[210:213], v[68:71]
	v_mfma_f32_16x16x32_bf16 v[120:123], v[158:161], v[190:193], v[120:123]
	v_mfma_f32_16x16x32_bf16 v[116:119], v[166:169], v[190:193], v[116:119]
	v_mfma_f32_16x16x32_bf16 v[104:107], v[158:161], v[198:201], v[104:107]
	v_mfma_f32_16x16x32_bf16 v[100:103], v[166:169], v[198:201], v[100:103]
	v_mfma_f32_16x16x32_bf16 v[88:91], v[158:161], v[206:209], v[88:91]
	v_mfma_f32_16x16x32_bf16 v[84:87], v[166:169], v[206:209], v[84:87]
	v_mfma_f32_16x16x32_bf16 v[72:75], v[158:161], v[214:217], v[72:75]
	v_mfma_f32_16x16x32_bf16 v[68:71], v[166:169], v[214:217], v[68:71]
	v_mfma_f32_16x16x32_bf16 v[124:127], v[170:173], v[186:189], v[124:127]
	v_mfma_f32_16x16x32_bf16 v[112:115], v[178:181], v[186:189], v[112:115]
	v_mfma_f32_16x16x32_bf16 v[108:111], v[170:173], v[194:197], v[108:111]
	v_mfma_f32_16x16x32_bf16 v[96:99], v[178:181], v[194:197], v[96:99]
	v_mfma_f32_16x16x32_bf16 v[92:95], v[170:173], v[202:205], v[92:95]
	v_mfma_f32_16x16x32_bf16 v[80:83], v[178:181], v[202:205], v[80:83]
	v_mfma_f32_16x16x32_bf16 v[76:79], v[170:173], v[210:213], v[76:79]
	v_mfma_f32_16x16x32_bf16 v[64:67], v[178:181], v[210:213], v[64:67]
	v_mfma_f32_16x16x32_bf16 v[124:127], v[174:177], v[190:193], v[124:127]
	v_mfma_f32_16x16x32_bf16 v[112:115], v[182:185], v[190:193], v[112:115]
	v_mfma_f32_16x16x32_bf16 v[108:111], v[174:177], v[198:201], v[108:111]
	v_mfma_f32_16x16x32_bf16 v[96:99], v[182:185], v[198:201], v[96:99]
	v_mfma_f32_16x16x32_bf16 v[92:95], v[174:177], v[206:209], v[92:95]
	v_mfma_f32_16x16x32_bf16 v[80:83], v[182:185], v[206:209], v[80:83]
	v_mfma_f32_16x16x32_bf16 v[76:79], v[174:177], v[214:217], v[76:79]
	v_mfma_f32_16x16x32_bf16 v[64:67], v[182:185], v[214:217], v[64:67]
	s_barrier
; #define PG8_STAGE(bufoff, gbase, voff) do { _Pragma("unroll") for (int _i = 0; _i < 2; ++_i) \
;         __builtin_amdgcn_global_load_lds((const unsigned*)((const char*)(gbase) + (voff)[_i]), (PG8_LAS unsigned*)(lds + (bufoff) + ldsw + _i * 8192), 16, 0, 0); } while (0)
; #define PG8_LDA(dst, b, h) do { _Pragma("unroll") for (int m = 0; m < 4; ++m) _Pragma("unroll") for (int k = 0; k < 2; ++k) dst[m][k] = *(const PG8_LAS bf16x8*)(lds + PG8_SA(b, h) + aoff + m * 2048 + k * 1024); } while (0)
; #define PG8_MMA(ai, bj, At, Bt) do { __builtin_amdgcn_s_setprio(1); _Pragma("unroll") for (int m = 0; m < 4; ++m) _Pragma("unroll") for (int n = 0; n < 2; ++n) _Pragma("unroll") for (int k = 0; k < 2; ++k) \
;         acc[ai][bj][m][n] = __builtin_amdgcn_mfma_f32_16x16x32_bf16(Bt[n][k], At[m][k], acc[ai][bj][m][n], 0, 0, 0); __builtin_amdgcn_s_setprio(0); } while (0)
; #define PG8_WAIT_V(n) asm volatile("s_waitcnt vmcnt(" #n ")" ::: "memory")
; #define PG8_WAIT_L(n) asm volatile("s_waitcnt lgkmcnt(" #n ")" ::: "memory")
; #define PG8_BAR __builtin_amdgcn_s_barrier()
; #define PG8_SCHED __builtin_amdgcn_sched_barrier(0)
; template <class Epi, class Sched, bool ALIGN_EPI = false, bool SP2 = false>
; __device__ __forceinline__ void gemm_phase(PG8_LAS unsigned char* lds, const Gemm g, const Sched& S, const Epi& E, const int wave_in) {
;     ...
;             PG8_LDA(At, 1, 1); PG8_STAGE(PG8_SB(1, 0), b3, voffB); PG8_STAGE(PG8_SB(1, 1), b3 + hstep, voffB); PG8_STAGE(PG8_SA(1, 0), a3, voffA);
;             PG8_WAIT_V(8); PG8_WAIT_L(0); PG8_BAR; PG8_MMA(1, 0, At, B0); PG8_MMA(1, 1, At, B1); PG8_BAR; PG8_SCHED;
	s_add_i32 s70, s79, s11
	v_lshl_add_u64 v[148:149], v[148:149], 0, s[56:57]
	s_mov_b32 m0, s70
	ds_read_b128 v[186:189], v155 offset:49152
	ds_read_b128 v[190:193], v155 offset:50176
	ds_read_b128 v[194:197], v155 offset:51200
	ds_read_b128 v[198:201], v155 offset:52224
	ds_read_b128 v[202:205], v155 offset:53248
	ds_read_b128 v[206:209], v155 offset:54272
	ds_read_b128 v[210:213], v155 offset:55296
	ds_read_b128 v[214:217], v155 offset:56320
	global_load_lds_dwordx4 v[148:149], off
	s_add_i32 m0, s70, 0x2000
	s_add_u32 s4, s4, 0x80080
	v_lshl_add_u64 v[148:149], v[218:219], 0, s[56:57]
	s_addc_u32 s5, s5, 0
	s_add_i32 s70, s84, s11
	global_load_lds_dwordx4 v[148:149], off
	v_lshl_add_u64 v[148:149], s[4:5], 0, v[132:133]
	s_mov_b32 m0, s70
	s_nop 0
	global_load_lds_dwordx4 v[148:149], off
	v_lshl_add_u64 v[148:149], s[4:5], 0, v[128:129]
	s_add_i32 m0, s70, 0x2000
	s_nop 0
	global_load_lds_dwordx4 v[148:149], off
	v_lshl_add_u64 v[148:149], v[220:221], 0, s[56:57]
	s_mov_b32 m0, s42
	s_nop 0
	global_load_lds_dwordx4 v[148:149], off
	v_lshl_add_u64 v[148:149], v[222:223], 0, s[56:57]
	s_mov_b32 m0, s43
	s_nop 0
	global_load_lds_dwordx4 v[148:149], off
	s_waitcnt vmcnt(8)
	s_waitcnt lgkmcnt(0)
	s_barrier
	s_waitcnt lgkmcnt(0)
	v_mfma_f32_16x16x32_bf16 v[56:59], v[144:147], v[186:189], v[56:59]
	v_mfma_f32_16x16x32_bf16 v[52:55], v[162:165], v[186:189], v[52:55]
	v_mfma_f32_16x16x32_bf16 v[40:43], v[144:147], v[194:197], v[40:43]
	v_mfma_f32_16x16x32_bf16 v[36:39], v[162:165], v[194:197], v[36:39]
	v_mfma_f32_16x16x32_bf16 v[24:27], v[144:147], v[202:205], v[24:27]
	v_mfma_f32_16x16x32_bf16 v[20:23], v[162:165], v[202:205], v[20:23]
	v_mfma_f32_16x16x32_bf16 v[8:11], v[144:147], v[210:213], v[8:11]
	v_mfma_f32_16x16x32_bf16 v[4:7], v[162:165], v[210:213], v[4:7]
	v_mfma_f32_16x16x32_bf16 v[56:59], v[158:161], v[190:193], v[56:59]
	v_mfma_f32_16x16x32_bf16 v[52:55], v[166:169], v[190:193], v[52:55]
	v_mfma_f32_16x16x32_bf16 v[40:43], v[158:161], v[198:201], v[40:43]
	v_mfma_f32_16x16x32_bf16 v[36:39], v[166:169], v[198:201], v[36:39]
	v_mfma_f32_16x16x32_bf16 v[24:27], v[158:161], v[206:209], v[24:27]
	v_mfma_f32_16x16x32_bf16 v[20:23], v[166:169], v[206:209], v[20:23]
	v_mfma_f32_16x16x32_bf16 v[8:11], v[158:161], v[214:217], v[8:11]
	v_mfma_f32_16x16x32_bf16 v[4:7], v[166:169], v[214:217], v[4:7]
	v_mfma_f32_16x16x32_bf16 v[60:63], v[170:173], v[186:189], v[60:63]
	v_mfma_f32_16x16x32_bf16 v[48:51], v[178:181], v[186:189], v[48:51]
	v_mfma_f32_16x16x32_bf16 v[44:47], v[170:173], v[194:197], v[44:47]
	v_mfma_f32_16x16x32_bf16 v[32:35], v[178:181], v[194:197], v[32:35]
	v_mfma_f32_16x16x32_bf16 v[28:31], v[170:173], v[202:205], v[28:31]
	v_mfma_f32_16x16x32_bf16 v[16:19], v[178:181], v[202:205], v[16:19]
	v_mfma_f32_16x16x32_bf16 v[12:15], v[170:173], v[210:213], v[12:15]
	v_mfma_f32_16x16x32_bf16 v[0:3], v[178:181], v[210:213], v[0:3]
	v_mfma_f32_16x16x32_bf16 v[60:63], v[174:177], v[190:193], v[60:63]
	v_mfma_f32_16x16x32_bf16 v[48:51], v[182:185], v[190:193], v[48:51]
	v_mfma_f32_16x16x32_bf16 v[44:47], v[174:177], v[198:201], v[44:47]
	v_mfma_f32_16x16x32_bf16 v[32:35], v[182:185], v[198:201], v[32:35]
	v_mfma_f32_16x16x32_bf16 v[28:31], v[174:177], v[206:209], v[28:31]
	v_mfma_f32_16x16x32_bf16 v[16:19], v[182:185], v[206:209], v[16:19]
	v_mfma_f32_16x16x32_bf16 v[12:15], v[174:177], v[214:217], v[12:15]
	v_mfma_f32_16x16x32_bf16 v[0:3], v[182:185], v[214:217], v[0:3]
	s_barrier
	s_add_i32 s78, s78, 2
	s_add_u32 s68, s68, 0x100
	s_addc_u32 s69, s69, 0
	s_add_u32 s72, s72, 0x100
	s_addc_u32 s73, s73, 0
	s_cmp_gt_u32 s78, 29
	s_cbranch_scc0 .LBB0_498
	s_and_b64 vcc, exec, s[58:59]
	s_cbranch_vccz .LBB0_501
	s_barrier

; #define GEMM_RESID(Aop, Kdim, WT, XIN, ssi, ALPHA) do { pg8::Gemm g_{Aop, WT, T, DM, Kdim, Kdim}; pg8::StaticOrder S_; S_.init(T, DM, G, bx); pg8::EpiResid E_{XIN, p.out, XB, SS + (size_t)(ssi) * T, ALPHA}; \
;         pg8::gemm_phase<pg8::EpiResid, pg8::StaticOrder, true, true>(ldsl, g_, S_, E_, wave); } while (0)
;     __host__ __device__ bool next(int i, Unit& u) const {
;         const long L = (long)i * G + c; if (L >= nwg) return false;
;         int wgid = (int)L; { const int q = nwg / NXCD, r = nwg % NXCD, xcd = wgid % NXCD, off = wgid / NXCD; wgid = (xcd < r ? xcd * (q + 1) : r * (q + 1) + (xcd - r) * q) + off; }
; __global__ void __launch_bounds__(512, 2) fwd_kernel(Params p) {
;     ...
;     if (IN(2)) GEMM_RESID(Hh, FF, W_DN1, p.in[0], 1, 0.5f);
.LBB0_559:
	v_readlane_b32 s2, v255, 0
	v_readlane_b32 s3, v255, 1
	s_cmp_lt_i32 s2, 3
	s_cselect_b64 s[0:1], -1, 0
	s_cmp_gt_i32 s3, 2
	s_cselect_b64 s[2:3], -1, 0
	s_and_b64 s[0:1], s[0:1], s[2:3]
	s_andn2_b64 vcc, exec, s[0:1]
	s_waitcnt lgkmcnt(0)
	s_barrier
	s_cbranch_vccnz .LBB0_606
	s_setprio 0
	s_cmp_lt_u32 s89, 4
	s_cbranch_scc1 .Lgprio_1
	s_setprio 1
.Lgprio_1:
	s_cmpk_lt_i32 s88, 0x400
	s_cselect_b64 s[0:1], -1, 0
	s_cmpk_gt_i32 s88, 0x3ff
	v_mbcnt_lo_u32_b32 v8, -1, 0
	v_mbcnt_hi_u32_b32 v8, -1, v8
	s_cbranch_scc1 .LBB0_566
	s_ashr_i32 s2, s88, 31
	s_lshr_b32 s2, s2, 29
	s_add_i32 s4, s88, s2
	s_and_b32 s2, s4, -8
	s_sub_i32 s5, s88, s2
	s_cmp_gt_i32 s5, -1
	s_cbranch_scc0 .LBB0_563
	s_lshl_b32 s6, s5, 7
	s_cbranch_execz .LBB0_564
	s_branch .LBB0_565

; #define PG8_STAGE(bufoff, gbase, voff) do { _Pragma("unroll") for (int _i = 0; _i < 2; ++_i) \
;         __builtin_amdgcn_global_load_lds((const unsigned*)((const char*)(gbase) + (voff)[_i]), (PG8_LAS unsigned*)(lds + (bufoff) + ldsw + _i * 8192), 16, 0, 0); } while (0)
; #define PG8_LDA(dst, b, h) do { _Pragma("unroll") for (int m = 0; m < 4; ++m) _Pragma("unroll") for (int k = 0; k < 2; ++k) dst[m][k] = *(const PG8_LAS bf16x8*)(lds + PG8_SA(b, h) + aoff + m * 2048 + k * 1024); } while (0)
; #define PG8_LDB(dst, b, h) do { _Pragma("unroll") for (int n = 0; n < 2; ++n) _Pragma("unroll") for (int k = 0; k < 2; ++k) dst[n][k] = *(const PG8_LAS bf16x8*)(lds + PG8_SB(b, h) + boff + n * 2048 + k * 1024); } while (0)
; #define PG8_MMA(ai, bj, At, Bt) do { __builtin_amdgcn_s_setprio(1); _Pragma("unroll") for (int m = 0; m < 4; ++m) _Pragma("unroll") for (int n = 0; n < 2; ++n) _Pragma("unroll") for (int k = 0; k < 2; ++k) \
;         acc[ai][bj][m][n] = __builtin_amdgcn_mfma_f32_16x16x32_bf16(Bt[n][k], At[m][k], acc[ai][bj][m][n], 0, 0, 0); __builtin_amdgcn_s_setprio(0); } while (0)
; #define PG8_WAIT_V(n) asm volatile("s_waitcnt vmcnt(" #n ")" ::: "memory")
; #define PG8_WAIT_L(n) asm volatile("s_waitcnt lgkmcnt(" #n ")" ::: "memory")
; template <class Epi, class Sched, bool ALIGN_EPI = false, bool SP2 = false>
; __device__ __forceinline__ void gemm_phase(PG8_LAS unsigned char* lds, const Gemm g, const Sched& S, const Epi& E, const int wave_in) {
;     ...
;             const bool last = (t == nt - 2);
;             const char* a1 = cA + (size_t)(t + 1) * kstep;
;             const char* a2 = last ? nA : cA + (size_t)(t + 2) * kstep; const char* b2 = last ? nB : cB + (size_t)(t + 2) * kstep;
;             const char* a3 = a2 + kstep; const char* b3 = b2 + kstep;
;             if (last && has_next) S.a_ready(nxt);
;             if constexpr (SP2) {
;             PG8_LDB(B0, 0, 0); PG8_LDB(B1, 0, 1); PG8_SCHED; PG8_LDA(At, 0, 0); PG8_STAGE(PG8_SA(1, 1), a1 + hstepA, voffA);
;             PG8_WAIT_V(8); PG8_WAIT_L(0); PG8_BAR; PG8_MMA(0, 0, At, B0); PG8_MMA(0, 1, At, B1); PG8_BAR; PG8_SCHED;
;             PG8_LDA(At, 0, 1); PG8_STAGE(PG8_SB(0, 0), b2, voffB); PG8_STAGE(PG8_SB(0, 1), b2 + hstep, voffB); PG8_STAGE(PG8_SA(0, 0), a2, voffA);
;             PG8_WAIT_V(8); PG8_WAIT_L(0); PG8_BAR; PG8_MMA(1, 0, At, B0); PG8_MMA(1, 1, At, B1); PG8_BAR; PG8_SCHED;
.LBB0_583:
	ds_read_b128 v[144:147], v151
	ds_read_b128 v[156:159], v151 offset:1024
	ds_read_b128 v[160:163], v151 offset:2048
	ds_read_b128 v[164:167], v151 offset:3072
	ds_read_b128 v[168:171], v152
	ds_read_b128 v[172:175], v152 offset:1024
	ds_read_b128 v[176:179], v152 offset:2048
	ds_read_b128 v[180:183], v152 offset:3072
	s_add_u32 s64, s62, 0x100
	s_addc_u32 s65, s63, 0
	s_cmpk_eq_i32 s72, 0x54
	s_cselect_b32 s69, s7, s65
	s_cselect_b32 s68, s6, s64
	s_cselect_b32 s67, s61, s71
	s_cselect_b32 s66, s60, s70
	v_lshl_add_u64 v[216:217], s[62:63], 0, v[136:137]
	s_add_i32 m0, s33, 0xc000
	ds_read_b128 v[184:187], v153
	ds_read_b128 v[188:191], v153 offset:1024
	ds_read_b128 v[192:195], v153 offset:2048
	ds_read_b128 v[196:199], v153 offset:3072
	ds_read_b128 v[200:203], v153 offset:4096
	ds_read_b128 v[204:207], v153 offset:5120
	ds_read_b128 v[208:211], v153 offset:6144
	ds_read_b128 v[212:215], v153 offset:7168
	global_load_lds_dwordx4 v[216:217], off
	v_lshl_add_u64 v[216:217], s[62:63], 0, v[138:139]
	s_add_i32 m0, s33, 0xe000
	s_nop 0
	global_load_lds_dwordx4 v[216:217], off
	s_waitcnt vmcnt(8)
	s_waitcnt lgkmcnt(0)
	s_barrier
	s_waitcnt lgkmcnt(0)
	v_mfma_f32_16x16x32_bf16 v[124:127], v[144:147], v[184:187], v[124:127]
	v_mfma_f32_16x16x32_bf16 v[120:123], v[160:163], v[184:187], v[120:123]
	v_mfma_f32_16x16x32_bf16 v[108:111], v[144:147], v[192:195], v[108:111]
	v_mfma_f32_16x16x32_bf16 v[104:107], v[160:163], v[192:195], v[104:107]
	v_mfma_f32_16x16x32_bf16 v[92:95], v[144:147], v[200:203], v[92:95]
	v_mfma_f32_16x16x32_bf16 v[88:91], v[160:163], v[200:203], v[88:91]
	v_mfma_f32_16x16x32_bf16 v[76:79], v[144:147], v[208:211], v[76:79]
	v_mfma_f32_16x16x32_bf16 v[72:75], v[160:163], v[208:211], v[72:75]
	v_mfma_f32_16x16x32_bf16 v[124:127], v[156:159], v[188:191], v[124:127]
	v_mfma_f32_16x16x32_bf16 v[120:123], v[164:167], v[188:191], v[120:123]
	v_mfma_f32_16x16x32_bf16 v[108:111], v[156:159], v[196:199], v[108:111]
	v_mfma_f32_16x16x32_bf16 v[104:107], v[164:167], v[196:199], v[104:107]
	v_mfma_f32_16x16x32_bf16 v[92:95], v[156:159], v[204:207], v[92:95]
	v_mfma_f32_16x16x32_bf16 v[88:91], v[164:167], v[204:207], v[88:91]
	v_mfma_f32_16x16x32_bf16 v[76:79], v[156:159], v[212:215], v[76:79]
	v_mfma_f32_16x16x32_bf16 v[72:75], v[164:167], v[212:215], v[72:75]
	v_mfma_f32_16x16x32_bf16 v[116:119], v[168:171], v[184:187], v[116:119]
	v_mfma_f32_16x16x32_bf16 v[112:115], v[176:179], v[184:187], v[112:115]
	v_mfma_f32_16x16x32_bf16 v[100:103], v[168:171], v[192:195], v[100:103]
	v_mfma_f32_16x16x32_bf16 v[96:99], v[176:179], v[192:195], v[96:99]
	v_mfma_f32_16x16x32_bf16 v[84:87], v[168:171], v[200:203], v[84:87]
	v_mfma_f32_16x16x32_bf16 v[80:83], v[176:179], v[200:203], v[80:83]
	v_mfma_f32_16x16x32_bf16 v[68:71], v[168:171], v[208:211], v[68:71]
	v_mfma_f32_16x16x32_bf16 v[64:67], v[176:179], v[208:211], v[64:67]
	v_mfma_f32_16x16x32_bf16 v[116:119], v[172:175], v[188:191], v[116:119]
	v_mfma_f32_16x16x32_bf16 v[112:115], v[180:183], v[188:191], v[112:115]
	v_mfma_f32_16x16x32_bf16 v[100:103], v[172:175], v[196:199], v[100:103]
	v_mfma_f32_16x16x32_bf16 v[96:99], v[180:183], v[196:199], v[96:99]
	v_mfma_f32_16x16x32_bf16 v[84:87], v[172:175], v[204:207], v[84:87]
	v_mfma_f32_16x16x32_bf16 v[80:83], v[180:183], v[204:207], v[80:83]
	v_mfma_f32_16x16x32_bf16 v[68:71], v[172:175], v[212:215], v[68:71]
	v_mfma_f32_16x16x32_bf16 v[64:67], v[180:183], v[212:215], v[64:67]
	s_barrier
	s_add_i32 s62, s48, s11
	v_lshl_add_u64 v[216:217], s[66:67], 0, v[130:131]
	s_mov_b32 m0, s62
	ds_read_b128 v[184:187], v153 offset:16384
	ds_read_b128 v[188:191], v153 offset:17408
	ds_read_b128 v[192:195], v153 offset:18432
	ds_read_b128 v[196:199], v153 offset:19456
	ds_read_b128 v[200:203], v153 offset:20480
	ds_read_b128 v[204:207], v153 offset:21504
	ds_read_b128 v[208:211], v153 offset:22528
	ds_read_b128 v[212:215], v153 offset:23552
	global_load_lds_dwordx4 v[216:217], off
	s_add_i32 m0, s62, 0x2000
	s_add_u32 s62, s66, 0x160000
	v_lshl_add_u64 v[218:219], s[66:67], 0, v[134:135]
	s_addc_u32 s63, s67, 0
	s_add_i32 s73, s49, s11
	global_load_lds_dwordx4 v[218:219], off
	v_lshl_add_u64 v[220:221], s[62:63], 0, v[130:131]
	s_mov_b32 m0, s73
	v_lshl_add_u64 v[222:223], s[68:69], 0, v[132:133]
	global_load_lds_dwordx4 v[220:221], off
	v_lshl_add_u64 v[220:221], s[62:63], 0, v[134:135]
	s_add_i32 m0, s73, 0x2000
	s_nop 0
	global_load_lds_dwordx4 v[220:221], off
	v_lshl_add_u64 v[220:221], s[68:69], 0, v[128:129]
	s_mov_b32 m0, s33
	s_nop 0
	global_load_lds_dwordx4 v[220:221], off
	s_mov_b32 m0, s35
	s_nop 0
	global_load_lds_dwordx4 v[222:223], off
	s_waitcnt vmcnt(8)
	s_waitcnt lgkmcnt(0)
	s_barrier
; #define PG8_STAGE(bufoff, gbase, voff) do { _Pragma("unroll") for (int _i = 0; _i < 2; ++_i) \
;         __builtin_amdgcn_global_load_lds((const unsigned*)((const char*)(gbase) + (voff)[_i]), (PG8_LAS unsigned*)(lds + (bufoff) + ldsw + _i * 8192), 16, 0, 0); } while (0)
; #define PG8_LDA(dst, b, h) do { _Pragma("unroll") for (int m = 0; m < 4; ++m) _Pragma("unroll") for (int k = 0; k < 2; ++k) dst[m][k] = *(const PG8_LAS bf16x8*)(lds + PG8_SA(b, h) + aoff + m * 2048 + k * 1024); } while (0)
; #define PG8_LDB(dst, b, h) do { _Pragma("unroll") for (int n = 0; n < 2; ++n) _Pragma("unroll") for (int k = 0; k < 2; ++k) dst[n][k] = *(const PG8_LAS bf16x8*)(lds + PG8_SB(b, h) + boff + n * 2048 + k * 1024); } while (0)
; #define PG8_MMA(ai, bj, At, Bt) do { __builtin_amdgcn_s_setprio(1); _Pragma("unroll") for (int m = 0; m < 4; ++m) _Pragma("unroll") for (int n = 0; n < 2; ++n) _Pragma("unroll") for (int k = 0; k < 2; ++k) \
;         acc[ai][bj][m][n] = __builtin_amdgcn_mfma_f32_16x16x32_bf16(Bt[n][k], At[m][k], acc[ai][bj][m][n], 0, 0, 0); __builtin_amdgcn_s_setprio(0); } while (0)
; #define PG8_WAIT_V(n) asm volatile("s_waitcnt vmcnt(" #n ")" ::: "memory")
; #define PG8_WAIT_L(n) asm volatile("s_waitcnt lgkmcnt(" #n ")" ::: "memory")
; #define PG8_BAR __builtin_amdgcn_s_barrier()
; #define PG8_SCHED __builtin_amdgcn_sched_barrier(0)
; template <class Epi, class Sched, bool ALIGN_EPI = false, bool SP2 = false>
; __device__ __forceinline__ void gemm_phase(PG8_LAS unsigned char* lds, const Gemm g, const Sched& S, const Epi& E, const int wave_in) {
;     ...
;             PG8_WAIT_V(8); PG8_WAIT_L(0); PG8_BAR; PG8_MMA(1, 0, At, B0); PG8_MMA(1, 1, At, B1); PG8_BAR; PG8_SCHED;
;             PG8_LDB(B0, 1, 0); PG8_LDB(B1, 1, 1); PG8_SCHED; PG8_LDA(At, 1, 0); PG8_STAGE(PG8_SA(0, 1), a2 + hstepA, voffA);
;             PG8_WAIT_V(8); PG8_WAIT_L(0); PG8_BAR; PG8_MMA(0, 0, At, B0); PG8_MMA(0, 1, At, B1); PG8_BAR; PG8_SCHED;
	s_waitcnt lgkmcnt(0)
	v_mfma_f32_16x16x32_bf16 v[60:63], v[144:147], v[184:187], v[60:63]
	v_mfma_f32_16x16x32_bf16 v[56:59], v[160:163], v[184:187], v[56:59]
	v_mfma_f32_16x16x32_bf16 v[44:47], v[144:147], v[192:195], v[44:47]
	v_mfma_f32_16x16x32_bf16 v[40:43], v[160:163], v[192:195], v[40:43]
	v_mfma_f32_16x16x32_bf16 v[28:31], v[144:147], v[200:203], v[28:31]
	v_mfma_f32_16x16x32_bf16 v[24:27], v[160:163], v[200:203], v[24:27]
	v_mfma_f32_16x16x32_bf16 v[12:15], v[144:147], v[208:211], v[12:15]
	v_mfma_f32_16x16x32_bf16 v[8:11], v[160:163], v[208:211], v[8:11]
	v_mfma_f32_16x16x32_bf16 v[60:63], v[156:159], v[188:191], v[60:63]
	v_mfma_f32_16x16x32_bf16 v[56:59], v[164:167], v[188:191], v[56:59]
	v_mfma_f32_16x16x32_bf16 v[44:47], v[156:159], v[196:199], v[44:47]
	v_mfma_f32_16x16x32_bf16 v[40:43], v[164:167], v[196:199], v[40:43]
	v_mfma_f32_16x16x32_bf16 v[28:31], v[156:159], v[204:207], v[28:31]
	v_mfma_f32_16x16x32_bf16 v[24:27], v[164:167], v[204:207], v[24:27]
	v_mfma_f32_16x16x32_bf16 v[12:15], v[156:159], v[212:215], v[12:15]
	v_mfma_f32_16x16x32_bf16 v[8:11], v[164:167], v[212:215], v[8:11]
	v_mfma_f32_16x16x32_bf16 v[52:55], v[168:171], v[184:187], v[52:55]
	v_mfma_f32_16x16x32_bf16 v[48:51], v[176:179], v[184:187], v[48:51]
	v_mfma_f32_16x16x32_bf16 v[36:39], v[168:171], v[192:195], v[36:39]
	v_mfma_f32_16x16x32_bf16 v[32:35], v[176:179], v[192:195], v[32:35]
	v_mfma_f32_16x16x32_bf16 v[20:23], v[168:171], v[200:203], v[20:23]
	v_mfma_f32_16x16x32_bf16 v[16:19], v[176:179], v[200:203], v[16:19]
	v_mfma_f32_16x16x32_bf16 v[4:7], v[168:171], v[208:211], v[4:7]
	v_mfma_f32_16x16x32_bf16 v[0:3], v[176:179], v[208:211], v[0:3]
	v_mfma_f32_16x16x32_bf16 v[52:55], v[172:175], v[188:191], v[52:55]
	v_mfma_f32_16x16x32_bf16 v[48:51], v[180:183], v[188:191], v[48:51]
	v_mfma_f32_16x16x32_bf16 v[36:39], v[172:175], v[196:199], v[36:39]
	v_mfma_f32_16x16x32_bf16 v[32:35], v[180:183], v[196:199], v[32:35]
	v_mfma_f32_16x16x32_bf16 v[20:23], v[172:175], v[204:207], v[20:23]
	v_mfma_f32_16x16x32_bf16 v[16:19], v[180:183], v[204:207], v[16:19]
	v_mfma_f32_16x16x32_bf16 v[4:7], v[172:175], v[212:215], v[4:7]
	v_mfma_f32_16x16x32_bf16 v[0:3], v[180:183], v[212:215], v[0:3]
	s_barrier
	s_add_i32 s73, 0, 0x18000
	v_add_u32_e32 v155, s73, v149
	s_add_i32 s78, 0, 0x1c000
	ds_read_b128 v[144:147], v155
	ds_read_b128 v[156:159], v155 offset:1024
	ds_read_b128 v[160:163], v155 offset:2048
	ds_read_b128 v[164:167], v155 offset:3072
	v_add_u32_e32 v155, s78, v149
	ds_read_b128 v[168:171], v155
	ds_read_b128 v[172:175], v155 offset:1024
	ds_read_b128 v[176:179], v155 offset:2048
	ds_read_b128 v[180:183], v155 offset:3072
	s_add_u32 s62, s68, 0x160000
	s_addc_u32 s63, s69, 0
	s_mov_b32 m0, s38
	v_lshl_add_u64 v[224:225], s[62:63], 0, v[128:129]
	ds_read_b128 v[184:187], v153 offset:32768
	ds_read_b128 v[188:191], v153 offset:33792
	ds_read_b128 v[192:195], v153 offset:34816
	ds_read_b128 v[196:199], v153 offset:35840
	ds_read_b128 v[200:203], v153 offset:36864
	ds_read_b128 v[204:207], v153 offset:37888
	ds_read_b128 v[208:211], v153 offset:38912
	ds_read_b128 v[212:215], v153 offset:39936
	global_load_lds_dwordx4 v[224:225], off
	v_lshl_add_u64 v[224:225], s[62:63], 0, v[132:133]
	s_mov_b32 m0, s39
	s_nop 0
	global_load_lds_dwordx4 v[224:225], off
	s_waitcnt vmcnt(8)
	s_waitcnt lgkmcnt(0)
	s_barrier
	s_waitcnt lgkmcnt(0)
	v_mfma_f32_16x16x32_bf16 v[124:127], v[144:147], v[184:187], v[124:127]
	v_mfma_f32_16x16x32_bf16 v[120:123], v[160:163], v[184:187], v[120:123]
	v_mfma_f32_16x16x32_bf16 v[108:111], v[144:147], v[192:195], v[108:111]
	v_mfma_f32_16x16x32_bf16 v[104:107], v[160:163], v[192:195], v[104:107]
	v_mfma_f32_16x16x32_bf16 v[92:95], v[144:147], v[200:203], v[92:95]
	v_mfma_f32_16x16x32_bf16 v[88:91], v[160:163], v[200:203], v[88:91]
	v_mfma_f32_16x16x32_bf16 v[76:79], v[144:147], v[208:211], v[76:79]
	v_mfma_f32_16x16x32_bf16 v[72:75], v[160:163], v[208:211], v[72:75]
	v_mfma_f32_16x16x32_bf16 v[124:127], v[156:159], v[188:191], v[124:127]
	v_mfma_f32_16x16x32_bf16 v[120:123], v[164:167], v[188:191], v[120:123]
	v_mfma_f32_16x16x32_bf16 v[108:111], v[156:159], v[196:199], v[108:111]
	v_mfma_f32_16x16x32_bf16 v[104:107], v[164:167], v[196:199], v[104:107]
	v_mfma_f32_16x16x32_bf16 v[92:95], v[156:159], v[204:207], v[92:95]
	v_mfma_f32_16x16x32_bf16 v[88:91], v[164:167], v[204:207], v[88:91]
	v_mfma_f32_16x16x32_bf16 v[76:79], v[156:159], v[212:215], v[76:79]
	v_mfma_f32_16x16x32_bf16 v[72:75], v[164:167], v[212:215], v[72:75]
	v_mfma_f32_16x16x32_bf16 v[116:119], v[168:171], v[184:187], v[116:119]
	v_mfma_f32_16x16x32_bf16 v[112:115], v[176:179], v[184:187], v[112:115]
	v_mfma_f32_16x16x32_bf16 v[100:103], v[168:171], v[192:195], v[100:103]
	v_mfma_f32_16x16x32_bf16 v[96:99], v[176:179], v[192:195], v[96:99]
	v_mfma_f32_16x16x32_bf16 v[84:87], v[168:171], v[200:203], v[84:87]
	v_mfma_f32_16x16x32_bf16 v[80:83], v[176:179], v[200:203], v[80:83]
	v_mfma_f32_16x16x32_bf16 v[68:71], v[168:171], v[208:211], v[68:71]
	v_mfma_f32_16x16x32_bf16 v[64:67], v[176:179], v[208:211], v[64:67]
	v_mfma_f32_16x16x32_bf16 v[116:119], v[172:175], v[188:191], v[116:119]
	v_mfma_f32_16x16x32_bf16 v[112:115], v[180:183], v[188:191], v[112:115]
	v_mfma_f32_16x16x32_bf16 v[100:103], v[172:175], v[196:199], v[100:103]
	v_mfma_f32_16x16x32_bf16 v[96:99], v[180:183], v[196:199], v[96:99]
	v_mfma_f32_16x16x32_bf16 v[84:87], v[172:175], v[204:207], v[84:87]
	v_mfma_f32_16x16x32_bf16 v[80:83], v[180:183], v[204:207], v[80:83]
	v_mfma_f32_16x16x32_bf16 v[68:71], v[172:175], v[212:215], v[68:71]
	v_mfma_f32_16x16x32_bf16 v[64:67], v[180:183], v[212:215], v[64:67]
	s_barrier
; #define PG8_STAGE(bufoff, gbase, voff) do { _Pragma("unroll") for (int _i = 0; _i < 2; ++_i) \
;         __builtin_amdgcn_global_load_lds((const unsigned*)((const char*)(gbase) + (voff)[_i]), (PG8_LAS unsigned*)(lds + (bufoff) + ldsw + _i * 8192), 16, 0, 0); } while (0)
; #define PG8_LDA(dst, b, h) do { _Pragma("unroll") for (int m = 0; m < 4; ++m) _Pragma("unroll") for (int k = 0; k < 2; ++k) dst[m][k] = *(const PG8_LAS bf16x8*)(lds + PG8_SA(b, h) + aoff + m * 2048 + k * 1024); } while (0)
; #define PG8_MMA(ai, bj, At, Bt) do { __builtin_amdgcn_s_setprio(1); _Pragma("unroll") for (int m = 0; m < 4; ++m) _Pragma("unroll") for (int n = 0; n < 2; ++n) _Pragma("unroll") for (int k = 0; k < 2; ++k) \
;         acc[ai][bj][m][n] = __builtin_amdgcn_mfma_f32_16x16x32_bf16(Bt[n][k], At[m][k], acc[ai][bj][m][n], 0, 0, 0); __builtin_amdgcn_s_setprio(0); } while (0)
; #define PG8_WAIT_V(n) asm volatile("s_waitcnt vmcnt(" #n ")" ::: "memory")
; #define PG8_WAIT_L(n) asm volatile("s_waitcnt lgkmcnt(" #n ")" ::: "memory")
; #define PG8_BAR __builtin_amdgcn_s_barrier()
; #define PG8_SCHED __builtin_amdgcn_sched_barrier(0)
; template <class Epi, class Sched, bool ALIGN_EPI = false, bool SP2 = false>
; __device__ __forceinline__ void gemm_phase(PG8_LAS unsigned char* lds, const Gemm g, const Sched& S, const Epi& E, const int wave_in) {
;     ...
;             PG8_LDA(At, 1, 1); PG8_STAGE(PG8_SB(1, 0), b3, voffB); PG8_STAGE(PG8_SB(1, 1), b3 + hstep, voffB); PG8_STAGE(PG8_SA(1, 0), a3, voffA);
;             PG8_WAIT_V(8); PG8_WAIT_L(0); PG8_BAR; PG8_MMA(1, 0, At, B0); PG8_MMA(1, 1, At, B1); PG8_BAR; PG8_SCHED;
	s_add_i32 s62, s73, s11
	v_lshl_add_u64 v[216:217], v[216:217], 0, s[56:57]
	s_mov_b32 m0, s62
	ds_read_b128 v[184:187], v153 offset:49152
	ds_read_b128 v[188:191], v153 offset:50176
	ds_read_b128 v[192:195], v153 offset:51200
	ds_read_b128 v[196:199], v153 offset:52224
	ds_read_b128 v[200:203], v153 offset:53248
	ds_read_b128 v[204:207], v153 offset:54272
	ds_read_b128 v[208:211], v153 offset:55296
	ds_read_b128 v[212:215], v153 offset:56320
	global_load_lds_dwordx4 v[216:217], off
	s_add_i32 m0, s62, 0x2000
	s_add_u32 s62, s66, 0x160080
	v_lshl_add_u64 v[216:217], v[218:219], 0, s[56:57]
	s_addc_u32 s63, s67, 0
	s_add_i32 s66, s78, s11
	global_load_lds_dwordx4 v[216:217], off
	v_lshl_add_u64 v[216:217], s[62:63], 0, v[130:131]
	s_mov_b32 m0, s66
	s_nop 0
	global_load_lds_dwordx4 v[216:217], off
	v_lshl_add_u64 v[216:217], s[62:63], 0, v[134:135]
	s_add_i32 m0, s66, 0x2000
	s_nop 0
	global_load_lds_dwordx4 v[216:217], off
	v_lshl_add_u64 v[216:217], v[220:221], 0, s[56:57]
	s_mov_b32 m0, s41
	s_nop 0
	global_load_lds_dwordx4 v[216:217], off
	v_lshl_add_u64 v[216:217], v[222:223], 0, s[56:57]
	s_mov_b32 m0, s42
	s_nop 0
	global_load_lds_dwordx4 v[216:217], off
	s_waitcnt vmcnt(8)
	s_waitcnt lgkmcnt(0)
	s_barrier
	s_waitcnt lgkmcnt(0)
	v_mfma_f32_16x16x32_bf16 v[60:63], v[144:147], v[184:187], v[60:63]
	v_mfma_f32_16x16x32_bf16 v[56:59], v[160:163], v[184:187], v[56:59]
	v_mfma_f32_16x16x32_bf16 v[44:47], v[144:147], v[192:195], v[44:47]
	v_mfma_f32_16x16x32_bf16 v[40:43], v[160:163], v[192:195], v[40:43]
	v_mfma_f32_16x16x32_bf16 v[28:31], v[144:147], v[200:203], v[28:31]
	v_mfma_f32_16x16x32_bf16 v[24:27], v[160:163], v[200:203], v[24:27]
	v_mfma_f32_16x16x32_bf16 v[12:15], v[144:147], v[208:211], v[12:15]
	v_mfma_f32_16x16x32_bf16 v[8:11], v[160:163], v[208:211], v[8:11]
	v_mfma_f32_16x16x32_bf16 v[60:63], v[156:159], v[188:191], v[60:63]
	v_mfma_f32_16x16x32_bf16 v[56:59], v[164:167], v[188:191], v[56:59]
	v_mfma_f32_16x16x32_bf16 v[44:47], v[156:159], v[196:199], v[44:47]
	v_mfma_f32_16x16x32_bf16 v[40:43], v[164:167], v[196:199], v[40:43]
	v_mfma_f32_16x16x32_bf16 v[28:31], v[156:159], v[204:207], v[28:31]
	v_mfma_f32_16x16x32_bf16 v[24:27], v[164:167], v[204:207], v[24:27]
	v_mfma_f32_16x16x32_bf16 v[12:15], v[156:159], v[212:215], v[12:15]
	v_mfma_f32_16x16x32_bf16 v[8:11], v[164:167], v[212:215], v[8:11]
	v_mfma_f32_16x16x32_bf16 v[52:55], v[168:171], v[184:187], v[52:55]
	v_mfma_f32_16x16x32_bf16 v[48:51], v[176:179], v[184:187], v[48:51]
	v_mfma_f32_16x16x32_bf16 v[36:39], v[168:171], v[192:195], v[36:39]
	v_mfma_f32_16x16x32_bf16 v[32:35], v[176:179], v[192:195], v[32:35]
	v_mfma_f32_16x16x32_bf16 v[20:23], v[168:171], v[200:203], v[20:23]
	v_mfma_f32_16x16x32_bf16 v[16:19], v[176:179], v[200:203], v[16:19]
	v_mfma_f32_16x16x32_bf16 v[4:7], v[168:171], v[208:211], v[4:7]
	v_mfma_f32_16x16x32_bf16 v[0:3], v[176:179], v[208:211], v[0:3]
	v_mfma_f32_16x16x32_bf16 v[52:55], v[172:175], v[188:191], v[52:55]
	v_mfma_f32_16x16x32_bf16 v[48:51], v[180:183], v[188:191], v[48:51]
	v_mfma_f32_16x16x32_bf16 v[36:39], v[172:175], v[196:199], v[36:39]
	v_mfma_f32_16x16x32_bf16 v[32:35], v[180:183], v[196:199], v[32:35]
	v_mfma_f32_16x16x32_bf16 v[20:23], v[172:175], v[204:207], v[20:23]
	v_mfma_f32_16x16x32_bf16 v[16:19], v[180:183], v[204:207], v[16:19]
	v_mfma_f32_16x16x32_bf16 v[4:7], v[172:175], v[212:215], v[4:7]
	v_mfma_f32_16x16x32_bf16 v[0:3], v[180:183], v[212:215], v[0:3]
	s_barrier
	s_add_i32 s72, s72, 2
	s_add_u32 s70, s70, 0x100
	s_addc_u32 s71, s71, 0
	s_cmpk_gt_u32 s72, 0x55
	s_mov_b64 s[62:63], s[64:65]
	s_cbranch_scc0 .LBB0_583
	s_and_b64 vcc, exec, s[58:59]
	s_cbranch_vccz .LBB0_586
	s_barrier

;     __host__ __device__ bool next(int i, Unit& u) const {
;         const long L = (long)i * G + c; if (L >= nwg) return false;
;         int wgid = (int)L; { const int q = nwg / NXCD, r = nwg % NXCD, xcd = wgid % NXCD, off = wgid / NXCD; wgid = (xcd < r ? xcd * (q + 1) : r * (q + 1) + (xcd - r) * q) + off; }
;         const int nig = WGM * nN, gid = wgid / nig, fm = gid * WGM, gsz = (nM - fm) < WGM ? (nM - fm) : WGM;
;         u.pm = fm + ((wgid % nig) % gsz); u.pn = (wgid % nig) / gsz; return true;
; __global__ void __launch_bounds__(512, 2) fwd_kernel(Params p) {
;     ...
;     if (IN(3)) { pg8::Gemm g_{XB, W_IN0, T, 4352, DM, DM}; pg8::StaticOrder S_; S_.init(T, 4352, G, bx);
;         pg8::EpiIn0 E_{Z0, KF, MG, SS + (size_t)1 * T, SS + (size_t)7 * T, SS + (size_t)8 * T, CS, p.in[11]};
;         pg8::gemm_phase<pg8::EpiIn0, pg8::StaticOrder, true, true>(ldsl, g_, S_, E_, wave); }
.LBB0_660:
	s_add_u32 s80, s30, 0xa00000
	s_addc_u32 s81, s31, 0
	s_add_u32 s52, s30, 0x28f00000
	s_addc_u32 s53, s31, 0
	v_readlane_b32 s2, v255, 0
	v_readlane_b32 s3, v255, 1
	s_cmp_lt_i32 s2, 4
	s_cselect_b64 s[0:1], -1, 0
	s_cmp_gt_i32 s3, 3
	s_cselect_b64 s[2:3], -1, 0
	s_and_b64 s[0:1], s[0:1], s[2:3]
	s_andn2_b64 vcc, exec, s[0:1]
	s_waitcnt lgkmcnt(0)
	s_barrier
	s_cbranch_vccnz .LBB0_720
	s_setprio 0
	s_cmp_lt_u32 s89, 4
	s_cbranch_scc1 .Lgprio_2
	s_setprio 1
.Lgprio_2:
	s_cmpk_lt_i32 s88, 0x880
	s_cselect_b64 s[2:3], -1, 0
	s_cmpk_gt_i32 s88, 0x87f
	v_mbcnt_lo_u32_b32 v8, -1, 0
	v_mbcnt_hi_u32_b32 v8, -1, v8
	s_cbranch_scc1 .LBB0_663
	s_ashr_i32 s0, s88, 31
	s_lshr_b32 s0, s0, 29
	s_add_i32 s0, s88, s0
	s_ashr_i32 s1, s0, 3
	s_and_b32 s0, s0, -8
	s_sub_i32 s0, s88, s0
	s_cmp_lt_i32 s0, 0
	s_movk_i32 s4, 0x111
	s_cselect_b32 s4, s4, 0x110
	s_mul_i32 s0, s0, s4
	s_add_i32 s0, s0, s1
	s_mul_hi_i32 s1, s0, 0x78787879
	s_lshr_b32 s4, s1, 31
	s_ashr_i32 s1, s1, 6
	s_add_i32 s1, s1, s4
	s_lshl_b32 s4, s1, 3
	s_mulk_i32 s1, 0x88
	s_sub_i32 s0, s0, s1
	s_sext_i32_i16 s1, s0
	s_bfe_u32 s1, s1, 0x3001c
	s_add_i32 s1, s0, s1
	s_sext_i32_i16 s5, s1
	s_and_b32 s1, s1, 0xfff8
	s_sub_i32 s0, s0, s1
	s_sext_i32_i16 s0, s0
	s_add_i32 s0, s4, s0
	s_ashr_i32 s6, s5, 3

; #define PG8_STAGE(bufoff, gbase, voff) do { _Pragma("unroll") for (int _i = 0; _i < 2; ++_i) \
;         __builtin_amdgcn_global_load_lds((const unsigned*)((const char*)(gbase) + (voff)[_i]), (PG8_LAS unsigned*)(lds + (bufoff) + ldsw + _i * 8192), 16, 0, 0); } while (0)
; #define PG8_LDA(dst, b, h) do { _Pragma("unroll") for (int m = 0; m < 4; ++m) _Pragma("unroll") for (int k = 0; k < 2; ++k) dst[m][k] = *(const PG8_LAS bf16x8*)(lds + PG8_SA(b, h) + aoff + m * 2048 + k * 1024); } while (0)
; #define PG8_LDB(dst, b, h) do { _Pragma("unroll") for (int n = 0; n < 2; ++n) _Pragma("unroll") for (int k = 0; k < 2; ++k) dst[n][k] = *(const PG8_LAS bf16x8*)(lds + PG8_SB(b, h) + boff + n * 2048 + k * 1024); } while (0)
; #define PG8_MMA(ai, bj, At, Bt) do { __builtin_amdgcn_s_setprio(1); _Pragma("unroll") for (int m = 0; m < 4; ++m) _Pragma("unroll") for (int n = 0; n < 2; ++n) _Pragma("unroll") for (int k = 0; k < 2; ++k) \
;         acc[ai][bj][m][n] = __builtin_amdgcn_mfma_f32_16x16x32_bf16(Bt[n][k], At[m][k], acc[ai][bj][m][n], 0, 0, 0); __builtin_amdgcn_s_setprio(0); } while (0)
; #define PG8_WAIT_V(n) asm volatile("s_waitcnt vmcnt(" #n ")" ::: "memory")
; #define PG8_WAIT_L(n) asm volatile("s_waitcnt lgkmcnt(" #n ")" ::: "memory")
; #define PG8_BAR __builtin_amdgcn_s_barrier()
; #define PG8_SCHED __builtin_amdgcn_sched_barrier(0)
; template <class Epi, class Sched, bool ALIGN_EPI = false, bool SP2 = false>
; __device__ __forceinline__ void gemm_phase(PG8_LAS unsigned char* lds, const Gemm g, const Sched& S, const Epi& E, const int wave_in) {
;     ...
;             PG8_LDB(B0, 0, 0); PG8_LDB(B1, 0, 1); PG8_SCHED; PG8_LDA(At, 0, 0); PG8_STAGE(PG8_SA(1, 1), a1 + hstepA, voffA);
;             PG8_WAIT_V(8); PG8_WAIT_L(0); PG8_BAR; PG8_MMA(0, 0, At, B0); PG8_MMA(0, 1, At, B1); PG8_BAR; PG8_SCHED;
;             PG8_LDA(At, 0, 1); PG8_STAGE(PG8_SB(0, 0), b2, voffB); PG8_STAGE(PG8_SB(0, 1), b2 + hstep, voffB); PG8_STAGE(PG8_SA(0, 0), a2, voffA);
.LBB0_672:
	ds_read_b128 v[128:131], v169
	ds_read_b128 v[132:135], v169 offset:1024
	ds_read_b128 v[160:163], v169 offset:2048
	ds_read_b128 v[174:177], v169 offset:3072
	ds_read_b128 v[178:181], v170
	ds_read_b128 v[182:185], v170 offset:1024
	ds_read_b128 v[186:189], v170 offset:2048
	ds_read_b128 v[190:193], v170 offset:3072
	s_add_u32 s73, s18, 0xfff80080
	s_addc_u32 s78, s19, -1
	s_cmp_eq_u32 s71, 28
	s_cselect_b32 s85, s1, s78
	s_cselect_b32 s84, s7, s73
	s_cselect_b32 s79, s36, s57
	s_cselect_b32 s78, s37, s56
	v_lshl_add_u64 v[164:165], s[18:19], 0, v[152:153]
	s_add_i32 m0, s33, 0xc000
	ds_read_b128 v[194:197], v171
	ds_read_b128 v[198:201], v171 offset:1024
	ds_read_b128 v[202:205], v171 offset:2048
	ds_read_b128 v[206:209], v171 offset:3072
	ds_read_b128 v[210:213], v171 offset:4096
	ds_read_b128 v[214:217], v171 offset:5120
	ds_read_b128 v[218:221], v171 offset:6144
	ds_read_b128 v[222:225], v171 offset:7168
	global_load_lds_dwordx4 v[164:165], off
	v_lshl_add_u64 v[164:165], s[18:19], 0, v[154:155]
	s_add_i32 m0, s33, 0xe000
	s_nop 0
	global_load_lds_dwordx4 v[164:165], off
	s_waitcnt vmcnt(8)
	s_waitcnt lgkmcnt(0)
	s_barrier
	s_waitcnt lgkmcnt(0)
	v_mfma_f32_16x16x32_bf16 v[124:127], v[128:131], v[194:197], v[124:127]
	v_mfma_f32_16x16x32_bf16 v[120:123], v[160:163], v[194:197], v[120:123]
	v_mfma_f32_16x16x32_bf16 v[108:111], v[128:131], v[202:205], v[108:111]
	v_mfma_f32_16x16x32_bf16 v[104:107], v[160:163], v[202:205], v[104:107]
	v_mfma_f32_16x16x32_bf16 v[92:95], v[128:131], v[210:213], v[92:95]
	v_mfma_f32_16x16x32_bf16 v[88:91], v[160:163], v[210:213], v[88:91]
	v_mfma_f32_16x16x32_bf16 v[76:79], v[128:131], v[218:221], v[76:79]
	v_mfma_f32_16x16x32_bf16 v[72:75], v[160:163], v[218:221], v[72:75]
	v_mfma_f32_16x16x32_bf16 v[124:127], v[132:135], v[198:201], v[124:127]
	v_mfma_f32_16x16x32_bf16 v[120:123], v[174:177], v[198:201], v[120:123]
	v_mfma_f32_16x16x32_bf16 v[108:111], v[132:135], v[206:209], v[108:111]
	v_mfma_f32_16x16x32_bf16 v[104:107], v[174:177], v[206:209], v[104:107]
	v_mfma_f32_16x16x32_bf16 v[92:95], v[132:135], v[214:217], v[92:95]
	v_mfma_f32_16x16x32_bf16 v[88:91], v[174:177], v[214:217], v[88:91]
	v_mfma_f32_16x16x32_bf16 v[76:79], v[132:135], v[222:225], v[76:79]
	v_mfma_f32_16x16x32_bf16 v[72:75], v[174:177], v[222:225], v[72:75]
	v_mfma_f32_16x16x32_bf16 v[116:119], v[178:181], v[194:197], v[116:119]
	v_mfma_f32_16x16x32_bf16 v[112:115], v[186:189], v[194:197], v[112:115]
	v_mfma_f32_16x16x32_bf16 v[100:103], v[178:181], v[202:205], v[100:103]
	v_mfma_f32_16x16x32_bf16 v[96:99], v[186:189], v[202:205], v[96:99]
	v_mfma_f32_16x16x32_bf16 v[84:87], v[178:181], v[210:213], v[84:87]
	v_mfma_f32_16x16x32_bf16 v[80:83], v[186:189], v[210:213], v[80:83]
	v_mfma_f32_16x16x32_bf16 v[68:71], v[178:181], v[218:221], v[68:71]
	v_mfma_f32_16x16x32_bf16 v[64:67], v[186:189], v[218:221], v[64:67]
	v_mfma_f32_16x16x32_bf16 v[116:119], v[182:185], v[198:201], v[116:119]
	v_mfma_f32_16x16x32_bf16 v[112:115], v[190:193], v[198:201], v[112:115]
	v_mfma_f32_16x16x32_bf16 v[100:103], v[182:185], v[206:209], v[100:103]
	v_mfma_f32_16x16x32_bf16 v[96:99], v[190:193], v[206:209], v[96:99]
	v_mfma_f32_16x16x32_bf16 v[84:87], v[182:185], v[214:217], v[84:87]
	v_mfma_f32_16x16x32_bf16 v[80:83], v[190:193], v[214:217], v[80:83]
	v_mfma_f32_16x16x32_bf16 v[68:71], v[182:185], v[222:225], v[68:71]
	v_mfma_f32_16x16x32_bf16 v[64:67], v[190:193], v[222:225], v[64:67]
	s_barrier
	s_add_i32 s73, s92, s11
	v_lshl_add_u64 v[164:165], s[78:79], 0, v[138:139]
	s_mov_b32 m0, s73
	ds_read_b128 v[194:197], v171 offset:16384
	ds_read_b128 v[198:201], v171 offset:17408
	ds_read_b128 v[202:205], v171 offset:18432
	ds_read_b128 v[206:209], v171 offset:19456
	ds_read_b128 v[210:213], v171 offset:20480
	ds_read_b128 v[214:217], v171 offset:21504
	ds_read_b128 v[218:221], v171 offset:22528
	ds_read_b128 v[222:225], v171 offset:23552
	global_load_lds_dwordx4 v[164:165], off
	s_add_i32 m0, s73, 0x2000
	s_add_u32 vcc_lo, s78, 0x80000
	v_lshl_add_u64 v[226:227], s[78:79], 0, v[142:143]
	s_addc_u32 vcc_hi, s79, 0
	s_add_i32 s73, s93, s11
	global_load_lds_dwordx4 v[226:227], off
	v_lshl_add_u64 v[228:229], vcc, 0, v[138:139]
	s_mov_b32 m0, s73
	v_lshl_add_u64 v[230:231], s[84:85], 0, v[140:141]
	global_load_lds_dwordx4 v[228:229], off
	v_lshl_add_u64 v[228:229], vcc, 0, v[142:143]
	s_add_i32 m0, s73, 0x2000
	s_nop 0
	global_load_lds_dwordx4 v[228:229], off
	v_lshl_add_u64 v[228:229], s[84:85], 0, v[136:137]
	s_mov_b32 m0, s33
	s_nop 0
	global_load_lds_dwordx4 v[228:229], off
	s_mov_b32 m0, s35
	s_nop 0
	global_load_lds_dwordx4 v[230:231], off
	s_waitcnt vmcnt(8)
	s_waitcnt lgkmcnt(0)
	s_barrier
; #define PG8_STAGE(bufoff, gbase, voff) do { _Pragma("unroll") for (int _i = 0; _i < 2; ++_i) \
;         __builtin_amdgcn_global_load_lds((const unsigned*)((const char*)(gbase) + (voff)[_i]), (PG8_LAS unsigned*)(lds + (bufoff) + ldsw + _i * 8192), 16, 0, 0); } while (0)
; #define PG8_LDA(dst, b, h) do { _Pragma("unroll") for (int m = 0; m < 4; ++m) _Pragma("unroll") for (int k = 0; k < 2; ++k) dst[m][k] = *(const PG8_LAS bf16x8*)(lds + PG8_SA(b, h) + aoff + m * 2048 + k * 1024); } while (0)
; #define PG8_LDB(dst, b, h) do { _Pragma("unroll") for (int n = 0; n < 2; ++n) _Pragma("unroll") for (int k = 0; k < 2; ++k) dst[n][k] = *(const PG8_LAS bf16x8*)(lds + PG8_SB(b, h) + boff + n * 2048 + k * 1024); } while (0)
; #define PG8_MMA(ai, bj, At, Bt) do { __builtin_amdgcn_s_setprio(1); _Pragma("unroll") for (int m = 0; m < 4; ++m) _Pragma("unroll") for (int n = 0; n < 2; ++n) _Pragma("unroll") for (int k = 0; k < 2; ++k) \
;         acc[ai][bj][m][n] = __builtin_amdgcn_mfma_f32_16x16x32_bf16(Bt[n][k], At[m][k], acc[ai][bj][m][n], 0, 0, 0); __builtin_amdgcn_s_setprio(0); } while (0)
; #define PG8_WAIT_V(n) asm volatile("s_waitcnt vmcnt(" #n ")" ::: "memory")
; #define PG8_WAIT_L(n) asm volatile("s_waitcnt lgkmcnt(" #n ")" ::: "memory")
; #define PG8_BAR __builtin_amdgcn_s_barrier()
; #define PG8_SCHED __builtin_amdgcn_sched_barrier(0)
; template <class Epi, class Sched, bool ALIGN_EPI = false, bool SP2 = false>
; __device__ __forceinline__ void gemm_phase(PG8_LAS unsigned char* lds, const Gemm g, const Sched& S, const Epi& E, const int wave_in) {
;     ...
;             PG8_WAIT_V(8); PG8_WAIT_L(0); PG8_BAR; PG8_MMA(1, 0, At, B0); PG8_MMA(1, 1, At, B1); PG8_BAR; PG8_SCHED;
;             PG8_LDB(B0, 1, 0); PG8_LDB(B1, 1, 1); PG8_SCHED; PG8_LDA(At, 1, 0); PG8_STAGE(PG8_SA(0, 1), a2 + hstepA, voffA);
;             PG8_WAIT_V(8); PG8_WAIT_L(0); PG8_BAR; PG8_MMA(0, 0, At, B0); PG8_MMA(0, 1, At, B1); PG8_BAR; PG8_SCHED;
	s_waitcnt lgkmcnt(0)
	v_mfma_f32_16x16x32_bf16 v[60:63], v[128:131], v[194:197], v[60:63]
	v_mfma_f32_16x16x32_bf16 v[56:59], v[160:163], v[194:197], v[56:59]
	v_mfma_f32_16x16x32_bf16 v[44:47], v[128:131], v[202:205], v[44:47]
	v_mfma_f32_16x16x32_bf16 v[40:43], v[160:163], v[202:205], v[40:43]
	v_mfma_f32_16x16x32_bf16 v[28:31], v[128:131], v[210:213], v[28:31]
	v_mfma_f32_16x16x32_bf16 v[24:27], v[160:163], v[210:213], v[24:27]
	v_mfma_f32_16x16x32_bf16 v[12:15], v[128:131], v[218:221], v[12:15]
	v_mfma_f32_16x16x32_bf16 v[8:11], v[160:163], v[218:221], v[8:11]
	v_mfma_f32_16x16x32_bf16 v[60:63], v[132:135], v[198:201], v[60:63]
	v_mfma_f32_16x16x32_bf16 v[56:59], v[174:177], v[198:201], v[56:59]
	v_mfma_f32_16x16x32_bf16 v[44:47], v[132:135], v[206:209], v[44:47]
	v_mfma_f32_16x16x32_bf16 v[40:43], v[174:177], v[206:209], v[40:43]
	v_mfma_f32_16x16x32_bf16 v[28:31], v[132:135], v[214:217], v[28:31]
	v_mfma_f32_16x16x32_bf16 v[24:27], v[174:177], v[214:217], v[24:27]
	v_mfma_f32_16x16x32_bf16 v[12:15], v[132:135], v[222:225], v[12:15]
	v_mfma_f32_16x16x32_bf16 v[8:11], v[174:177], v[222:225], v[8:11]
	v_mfma_f32_16x16x32_bf16 v[52:55], v[178:181], v[194:197], v[52:55]
	v_mfma_f32_16x16x32_bf16 v[48:51], v[186:189], v[194:197], v[48:51]
	v_mfma_f32_16x16x32_bf16 v[36:39], v[178:181], v[202:205], v[36:39]
	v_mfma_f32_16x16x32_bf16 v[32:35], v[186:189], v[202:205], v[32:35]
	v_mfma_f32_16x16x32_bf16 v[20:23], v[178:181], v[210:213], v[20:23]
	v_mfma_f32_16x16x32_bf16 v[16:19], v[186:189], v[210:213], v[16:19]
	v_mfma_f32_16x16x32_bf16 v[4:7], v[178:181], v[218:221], v[4:7]
	v_mfma_f32_16x16x32_bf16 v[0:3], v[186:189], v[218:221], v[0:3]
	v_mfma_f32_16x16x32_bf16 v[52:55], v[182:185], v[198:201], v[52:55]
	v_mfma_f32_16x16x32_bf16 v[48:51], v[190:193], v[198:201], v[48:51]
	v_mfma_f32_16x16x32_bf16 v[36:39], v[182:185], v[206:209], v[36:39]
	v_mfma_f32_16x16x32_bf16 v[32:35], v[190:193], v[206:209], v[32:35]
	v_mfma_f32_16x16x32_bf16 v[20:23], v[182:185], v[214:217], v[20:23]
	v_mfma_f32_16x16x32_bf16 v[16:19], v[190:193], v[214:217], v[16:19]
	v_mfma_f32_16x16x32_bf16 v[4:7], v[182:185], v[222:225], v[4:7]
	v_mfma_f32_16x16x32_bf16 v[0:3], v[190:193], v[222:225], v[0:3]
	s_barrier
	s_add_i32 s73, 0, 0x18000
	s_add_i32 vcc_lo, 0, 0x1c000
	v_add_u32_e32 v174, s73, v167
	v_add_u32_e32 v190, vcc_lo, v167
	ds_read_b128 v[128:131], v174
	ds_read_b128 v[132:135], v174 offset:1024
	ds_read_b128 v[160:163], v174 offset:2048
	ds_read_b128 v[174:177], v174 offset:3072
	ds_read_b128 v[178:181], v190
	ds_read_b128 v[182:185], v190 offset:1024
	ds_read_b128 v[186:189], v190 offset:2048
	ds_read_b128 v[190:193], v190 offset:3072
	s_add_u32 s84, s84, 0x80000
	s_addc_u32 s85, s85, 0
	s_mov_b32 m0, s38
	v_lshl_add_u64 v[232:233], s[84:85], 0, v[136:137]
	ds_read_b128 v[194:197], v171 offset:32768
	ds_read_b128 v[198:201], v171 offset:33792
	ds_read_b128 v[202:205], v171 offset:34816
	ds_read_b128 v[206:209], v171 offset:35840
	ds_read_b128 v[210:213], v171 offset:36864
	ds_read_b128 v[214:217], v171 offset:37888
	ds_read_b128 v[218:221], v171 offset:38912
	ds_read_b128 v[222:225], v171 offset:39936
	global_load_lds_dwordx4 v[232:233], off
	v_lshl_add_u64 v[232:233], s[84:85], 0, v[140:141]
	s_mov_b32 m0, s39
	s_nop 0
	global_load_lds_dwordx4 v[232:233], off
	s_waitcnt vmcnt(8)
	s_waitcnt lgkmcnt(0)
	s_barrier
	s_waitcnt lgkmcnt(0)
	v_mfma_f32_16x16x32_bf16 v[124:127], v[128:131], v[194:197], v[124:127]
	v_mfma_f32_16x16x32_bf16 v[120:123], v[160:163], v[194:197], v[120:123]
	v_mfma_f32_16x16x32_bf16 v[108:111], v[128:131], v[202:205], v[108:111]
	v_mfma_f32_16x16x32_bf16 v[104:107], v[160:163], v[202:205], v[104:107]
	v_mfma_f32_16x16x32_bf16 v[92:95], v[128:131], v[210:213], v[92:95]
	v_mfma_f32_16x16x32_bf16 v[88:91], v[160:163], v[210:213], v[88:91]
	v_mfma_f32_16x16x32_bf16 v[76:79], v[128:131], v[218:221], v[76:79]
	v_mfma_f32_16x16x32_bf16 v[72:75], v[160:163], v[218:221], v[72:75]
	v_mfma_f32_16x16x32_bf16 v[124:127], v[132:135], v[198:201], v[124:127]
	v_mfma_f32_16x16x32_bf16 v[120:123], v[174:177], v[198:201], v[120:123]
	v_mfma_f32_16x16x32_bf16 v[108:111], v[132:135], v[206:209], v[108:111]
	v_mfma_f32_16x16x32_bf16 v[104:107], v[174:177], v[206:209], v[104:107]
	v_mfma_f32_16x16x32_bf16 v[92:95], v[132:135], v[214:217], v[92:95]
	v_mfma_f32_16x16x32_bf16 v[88:91], v[174:177], v[214:217], v[88:91]
	v_mfma_f32_16x16x32_bf16 v[76:79], v[132:135], v[222:225], v[76:79]
	v_mfma_f32_16x16x32_bf16 v[72:75], v[174:177], v[222:225], v[72:75]
	v_mfma_f32_16x16x32_bf16 v[116:119], v[178:181], v[194:197], v[116:119]
	v_mfma_f32_16x16x32_bf16 v[112:115], v[186:189], v[194:197], v[112:115]
	v_mfma_f32_16x16x32_bf16 v[100:103], v[178:181], v[202:205], v[100:103]
	v_mfma_f32_16x16x32_bf16 v[96:99], v[186:189], v[202:205], v[96:99]
	v_mfma_f32_16x16x32_bf16 v[84:87], v[178:181], v[210:213], v[84:87]
	v_mfma_f32_16x16x32_bf16 v[80:83], v[186:189], v[210:213], v[80:83]
	v_mfma_f32_16x16x32_bf16 v[68:71], v[178:181], v[218:221], v[68:71]
	v_mfma_f32_16x16x32_bf16 v[64:67], v[186:189], v[218:221], v[64:67]
	v_mfma_f32_16x16x32_bf16 v[116:119], v[182:185], v[198:201], v[116:119]
	v_mfma_f32_16x16x32_bf16 v[112:115], v[190:193], v[198:201], v[112:115]
	v_mfma_f32_16x16x32_bf16 v[100:103], v[182:185], v[206:209], v[100:103]
	v_mfma_f32_16x16x32_bf16 v[96:99], v[190:193], v[206:209], v[96:99]
	v_mfma_f32_16x16x32_bf16 v[84:87], v[182:185], v[214:217], v[84:87]
	v_mfma_f32_16x16x32_bf16 v[80:83], v[190:193], v[214:217], v[80:83]
	v_mfma_f32_16x16x32_bf16 v[68:71], v[182:185], v[222:225], v[68:71]
	v_mfma_f32_16x16x32_bf16 v[64:67], v[190:193], v[222:225], v[64:67]
	s_barrier
; #define PG8_STAGE(bufoff, gbase, voff) do { _Pragma("unroll") for (int _i = 0; _i < 2; ++_i) \
;         __builtin_amdgcn_global_load_lds((const unsigned*)((const char*)(gbase) + (voff)[_i]), (PG8_LAS unsigned*)(lds + (bufoff) + ldsw + _i * 8192), 16, 0, 0); } while (0)
; #define PG8_LDA(dst, b, h) do { _Pragma("unroll") for (int m = 0; m < 4; ++m) _Pragma("unroll") for (int k = 0; k < 2; ++k) dst[m][k] = *(const PG8_LAS bf16x8*)(lds + PG8_SA(b, h) + aoff + m * 2048 + k * 1024); } while (0)
; #define PG8_MMA(ai, bj, At, Bt) do { __builtin_amdgcn_s_setprio(1); _Pragma("unroll") for (int m = 0; m < 4; ++m) _Pragma("unroll") for (int n = 0; n < 2; ++n) _Pragma("unroll") for (int k = 0; k < 2; ++k) \
;         acc[ai][bj][m][n] = __builtin_amdgcn_mfma_f32_16x16x32_bf16(Bt[n][k], At[m][k], acc[ai][bj][m][n], 0, 0, 0); __builtin_amdgcn_s_setprio(0); } while (0)
; #define PG8_WAIT_V(n) asm volatile("s_waitcnt vmcnt(" #n ")" ::: "memory")
; #define PG8_WAIT_L(n) asm volatile("s_waitcnt lgkmcnt(" #n ")" ::: "memory")
; #define PG8_BAR __builtin_amdgcn_s_barrier()
; #define PG8_SCHED __builtin_amdgcn_sched_barrier(0)
; template <class Epi, class Sched, bool ALIGN_EPI = false, bool SP2 = false>
; __device__ __forceinline__ void gemm_phase(PG8_LAS unsigned char* lds, const Gemm g, const Sched& S, const Epi& E, const int wave_in) {
;     ...
;             PG8_LDA(At, 1, 1); PG8_STAGE(PG8_SB(1, 0), b3, voffB); PG8_STAGE(PG8_SB(1, 1), b3 + hstep, voffB); PG8_STAGE(PG8_SA(1, 0), a3, voffA);
;             PG8_WAIT_V(8); PG8_WAIT_L(0); PG8_BAR; PG8_MMA(1, 0, At, B0); PG8_MMA(1, 1, At, B1); PG8_BAR; PG8_SCHED;
	s_add_i32 s73, s73, s11
	v_lshl_add_u64 v[164:165], v[164:165], 0, s[62:63]
	s_mov_b32 m0, s73
	ds_read_b128 v[194:197], v171 offset:49152
	ds_read_b128 v[198:201], v171 offset:50176
	ds_read_b128 v[202:205], v171 offset:51200
	ds_read_b128 v[206:209], v171 offset:52224
	ds_read_b128 v[210:213], v171 offset:53248
	ds_read_b128 v[214:217], v171 offset:54272
	ds_read_b128 v[218:221], v171 offset:55296
	ds_read_b128 v[222:225], v171 offset:56320
	global_load_lds_dwordx4 v[164:165], off
	s_add_i32 m0, s73, 0x2000
	s_add_u32 s78, s78, 0x80080
	v_lshl_add_u64 v[164:165], v[226:227], 0, s[62:63]
	s_addc_u32 s79, s79, 0
	s_add_i32 s73, vcc_lo, s11
	global_load_lds_dwordx4 v[164:165], off
	v_lshl_add_u64 v[164:165], s[78:79], 0, v[138:139]
	s_mov_b32 m0, s73
	s_nop 0
	global_load_lds_dwordx4 v[164:165], off
	v_lshl_add_u64 v[164:165], s[78:79], 0, v[142:143]
	s_add_i32 m0, s73, 0x2000
	s_nop 0
	global_load_lds_dwordx4 v[164:165], off
	v_lshl_add_u64 v[164:165], v[228:229], 0, s[62:63]
	s_mov_b32 m0, s49
	s_nop 0
	global_load_lds_dwordx4 v[164:165], off
	v_lshl_add_u64 v[164:165], v[230:231], 0, s[62:63]
	s_mov_b32 m0, s50
	s_nop 0
	global_load_lds_dwordx4 v[164:165], off
	s_waitcnt vmcnt(8)
	s_waitcnt lgkmcnt(0)
	s_barrier
	s_waitcnt lgkmcnt(0)
	v_mfma_f32_16x16x32_bf16 v[60:63], v[128:131], v[194:197], v[60:63]
	v_mfma_f32_16x16x32_bf16 v[56:59], v[160:163], v[194:197], v[56:59]
	v_mfma_f32_16x16x32_bf16 v[44:47], v[128:131], v[202:205], v[44:47]
	v_mfma_f32_16x16x32_bf16 v[40:43], v[160:163], v[202:205], v[40:43]
	v_mfma_f32_16x16x32_bf16 v[28:31], v[128:131], v[210:213], v[28:31]
	v_mfma_f32_16x16x32_bf16 v[24:27], v[160:163], v[210:213], v[24:27]
	v_mfma_f32_16x16x32_bf16 v[12:15], v[128:131], v[218:221], v[12:15]
	v_mfma_f32_16x16x32_bf16 v[8:11], v[160:163], v[218:221], v[8:11]
	v_mfma_f32_16x16x32_bf16 v[60:63], v[132:135], v[198:201], v[60:63]
	v_mfma_f32_16x16x32_bf16 v[56:59], v[174:177], v[198:201], v[56:59]
	v_mfma_f32_16x16x32_bf16 v[44:47], v[132:135], v[206:209], v[44:47]
	v_mfma_f32_16x16x32_bf16 v[40:43], v[174:177], v[206:209], v[40:43]
	v_mfma_f32_16x16x32_bf16 v[28:31], v[132:135], v[214:217], v[28:31]
	v_mfma_f32_16x16x32_bf16 v[24:27], v[174:177], v[214:217], v[24:27]
	v_mfma_f32_16x16x32_bf16 v[12:15], v[132:135], v[222:225], v[12:15]
	v_mfma_f32_16x16x32_bf16 v[8:11], v[174:177], v[222:225], v[8:11]
	v_mfma_f32_16x16x32_bf16 v[52:55], v[178:181], v[194:197], v[52:55]
	v_mfma_f32_16x16x32_bf16 v[48:51], v[186:189], v[194:197], v[48:51]
	v_mfma_f32_16x16x32_bf16 v[36:39], v[178:181], v[202:205], v[36:39]
	v_mfma_f32_16x16x32_bf16 v[32:35], v[186:189], v[202:205], v[32:35]
	v_mfma_f32_16x16x32_bf16 v[20:23], v[178:181], v[210:213], v[20:23]
	v_mfma_f32_16x16x32_bf16 v[16:19], v[186:189], v[210:213], v[16:19]
	v_mfma_f32_16x16x32_bf16 v[4:7], v[178:181], v[218:221], v[4:7]
	v_mfma_f32_16x16x32_bf16 v[0:3], v[186:189], v[218:221], v[0:3]
	v_mfma_f32_16x16x32_bf16 v[52:55], v[182:185], v[198:201], v[52:55]
	v_mfma_f32_16x16x32_bf16 v[48:51], v[190:193], v[198:201], v[48:51]
	v_mfma_f32_16x16x32_bf16 v[36:39], v[182:185], v[206:209], v[36:39]
	v_mfma_f32_16x16x32_bf16 v[32:35], v[190:193], v[206:209], v[32:35]
	v_mfma_f32_16x16x32_bf16 v[20:23], v[182:185], v[214:217], v[20:23]
	v_mfma_f32_16x16x32_bf16 v[16:19], v[190:193], v[214:217], v[16:19]
	v_mfma_f32_16x16x32_bf16 v[4:7], v[182:185], v[222:225], v[4:7]
	v_mfma_f32_16x16x32_bf16 v[0:3], v[190:193], v[222:225], v[0:3]
	s_barrier
	s_add_i32 s71, s71, 2
	s_add_u32 s18, s18, 0x100
	s_addc_u32 s19, s19, 0
	s_add_u32 s56, s56, 0x100
	s_addc_u32 s57, s57, 0
	s_cmp_gt_u32 s71, 29
	s_cbranch_scc0 .LBB0_672
	s_and_b64 vcc, exec, s[64:65]
	s_cbranch_vccnz .LBB0_676
	v_lshl_add_u32 v160, s0, 8, v166
	s_cmp_gt_i32 s6, 15
	s_mov_b64 s[0:1], -1
	s_cbranch_scc1 .LBB0_677

; #define PG8_STAGE(bufoff, gbase, voff) do { _Pragma("unroll") for (int _i = 0; _i < 2; ++_i) \
;         __builtin_amdgcn_global_load_lds((const unsigned*)((const char*)(gbase) + (voff)[_i]), (PG8_LAS unsigned*)(lds + (bufoff) + ldsw + _i * 8192), 16, 0, 0); } while (0)
; #define PG8_LDA(dst, b, h) do { _Pragma("unroll") for (int m = 0; m < 4; ++m) _Pragma("unroll") for (int k = 0; k < 2; ++k) dst[m][k] = *(const PG8_LAS bf16x8*)(lds + PG8_SA(b, h) + aoff + m * 2048 + k * 1024); } while (0)
; #define PG8_LDB(dst, b, h) do { _Pragma("unroll") for (int n = 0; n < 2; ++n) _Pragma("unroll") for (int k = 0; k < 2; ++k) dst[n][k] = *(const PG8_LAS bf16x8*)(lds + PG8_SB(b, h) + boff + n * 2048 + k * 1024); } while (0)
; #define PG8_MMA(ai, bj, At, Bt) do { __builtin_amdgcn_s_setprio(1); _Pragma("unroll") for (int m = 0; m < 4; ++m) _Pragma("unroll") for (int n = 0; n < 2; ++n) _Pragma("unroll") for (int k = 0; k < 2; ++k) \
;         acc[ai][bj][m][n] = __builtin_amdgcn_mfma_f32_16x16x32_bf16(Bt[n][k], At[m][k], acc[ai][bj][m][n], 0, 0, 0); __builtin_amdgcn_s_setprio(0); } while (0)
; #define PG8_WAIT_V(n) asm volatile("s_waitcnt vmcnt(" #n ")" ::: "memory")
; #define PG8_WAIT_L(n) asm volatile("s_waitcnt lgkmcnt(" #n ")" ::: "memory")
; #define PG8_BAR __builtin_amdgcn_s_barrier()
; #define PG8_SCHED __builtin_amdgcn_sched_barrier(0)
; template <class Epi, class Sched, bool ALIGN_EPI = false, bool SP2 = false>
; __device__ __forceinline__ void gemm_phase(PG8_LAS unsigned char* lds, const Gemm g, const Sched& S, const Epi& E, const int wave_in) {
;     ...
;             PG8_LDB(B0, 0, 0); PG8_LDB(B1, 0, 1); PG8_SCHED; PG8_LDA(At, 0, 0); PG8_STAGE(PG8_SA(1, 1), a1 + hstepA, voffA);
;             PG8_WAIT_V(8); PG8_WAIT_L(0); PG8_BAR; PG8_MMA(0, 0, At, B0); PG8_MMA(0, 1, At, B1); PG8_BAR; PG8_SCHED;
;             PG8_LDA(At, 0, 1); PG8_STAGE(PG8_SB(0, 0), b2, voffB); PG8_STAGE(PG8_SB(0, 1), b2 + hstep, voffB); PG8_STAGE(PG8_SA(0, 0), a2, voffA);
.LBB0_786:
	ds_read_b128 v[128:131], v160
	ds_read_b128 v[152:155], v160 offset:1024
	ds_read_b128 v[164:167], v160 offset:2048
	ds_read_b128 v[168:171], v160 offset:3072
	ds_read_b128 v[172:175], v161
	ds_read_b128 v[176:179], v161 offset:1024
	ds_read_b128 v[180:183], v161 offset:2048
	ds_read_b128 v[184:187], v161 offset:3072
	s_add_u32 s60, s18, 0xfff00080
	s_addc_u32 s61, s19, -1
	s_cmp_eq_u32 s75, 4
	s_cselect_b32 s85, s1, s61
	s_cselect_b32 s84, s5, s60
	s_cselect_b32 s61, s36, s73
	s_cselect_b32 s60, s37, s62
	v_lshl_add_u64 v[156:157], s[18:19], 0, v[144:145]
	s_add_i32 m0, s42, 0xc000
	ds_read_b128 v[188:191], v162
	ds_read_b128 v[192:195], v162 offset:1024
	ds_read_b128 v[196:199], v162 offset:2048
	ds_read_b128 v[200:203], v162 offset:3072
	ds_read_b128 v[204:207], v162 offset:4096
	ds_read_b128 v[208:211], v162 offset:5120
	ds_read_b128 v[212:215], v162 offset:6144
	ds_read_b128 v[216:219], v162 offset:7168
	global_load_lds_dwordx4 v[156:157], off
	v_lshl_add_u64 v[156:157], s[18:19], 0, v[146:147]
	s_add_i32 m0, s42, 0xe000
	s_nop 0
	global_load_lds_dwordx4 v[156:157], off
	s_waitcnt vmcnt(8)
	s_waitcnt lgkmcnt(0)
	s_barrier
	s_waitcnt lgkmcnt(0)
	v_mfma_f32_16x16x32_bf16 v[124:127], v[128:131], v[188:191], v[124:127]
	v_mfma_f32_16x16x32_bf16 v[120:123], v[164:167], v[188:191], v[120:123]
	v_mfma_f32_16x16x32_bf16 v[108:111], v[128:131], v[196:199], v[108:111]
	v_mfma_f32_16x16x32_bf16 v[104:107], v[164:167], v[196:199], v[104:107]
	v_mfma_f32_16x16x32_bf16 v[92:95], v[128:131], v[204:207], v[92:95]
	v_mfma_f32_16x16x32_bf16 v[88:91], v[164:167], v[204:207], v[88:91]
	v_mfma_f32_16x16x32_bf16 v[76:79], v[128:131], v[212:215], v[76:79]
	v_mfma_f32_16x16x32_bf16 v[72:75], v[164:167], v[212:215], v[72:75]
	v_mfma_f32_16x16x32_bf16 v[124:127], v[152:155], v[192:195], v[124:127]
	v_mfma_f32_16x16x32_bf16 v[120:123], v[168:171], v[192:195], v[120:123]
	v_mfma_f32_16x16x32_bf16 v[108:111], v[152:155], v[200:203], v[108:111]
	v_mfma_f32_16x16x32_bf16 v[104:107], v[168:171], v[200:203], v[104:107]
	v_mfma_f32_16x16x32_bf16 v[92:95], v[152:155], v[208:211], v[92:95]
	v_mfma_f32_16x16x32_bf16 v[88:91], v[168:171], v[208:211], v[88:91]
	v_mfma_f32_16x16x32_bf16 v[76:79], v[152:155], v[216:219], v[76:79]
	v_mfma_f32_16x16x32_bf16 v[72:75], v[168:171], v[216:219], v[72:75]
	v_mfma_f32_16x16x32_bf16 v[116:119], v[172:175], v[188:191], v[116:119]
	v_mfma_f32_16x16x32_bf16 v[112:115], v[180:183], v[188:191], v[112:115]
	v_mfma_f32_16x16x32_bf16 v[100:103], v[172:175], v[196:199], v[100:103]
	v_mfma_f32_16x16x32_bf16 v[96:99], v[180:183], v[196:199], v[96:99]
	v_mfma_f32_16x16x32_bf16 v[84:87], v[172:175], v[204:207], v[84:87]
	v_mfma_f32_16x16x32_bf16 v[80:83], v[180:183], v[204:207], v[80:83]
	v_mfma_f32_16x16x32_bf16 v[68:71], v[172:175], v[212:215], v[68:71]
	v_mfma_f32_16x16x32_bf16 v[64:67], v[180:183], v[212:215], v[64:67]
	v_mfma_f32_16x16x32_bf16 v[116:119], v[176:179], v[192:195], v[116:119]
	v_mfma_f32_16x16x32_bf16 v[112:115], v[184:187], v[192:195], v[112:115]
	v_mfma_f32_16x16x32_bf16 v[100:103], v[176:179], v[200:203], v[100:103]
	v_mfma_f32_16x16x32_bf16 v[96:99], v[184:187], v[200:203], v[96:99]
	v_mfma_f32_16x16x32_bf16 v[84:87], v[176:179], v[208:211], v[84:87]
	v_mfma_f32_16x16x32_bf16 v[80:83], v[184:187], v[208:211], v[80:83]
	v_mfma_f32_16x16x32_bf16 v[68:71], v[176:179], v[216:219], v[68:71]
	v_mfma_f32_16x16x32_bf16 v[64:67], v[184:187], v[216:219], v[64:67]
	s_barrier
	s_add_i32 vcc_lo, s93, s41
	v_lshl_add_u64 v[156:157], s[60:61], 0, v[134:135]
	s_mov_b32 m0, vcc_lo
	ds_read_b128 v[188:191], v162 offset:16384
	ds_read_b128 v[192:195], v162 offset:17408
	ds_read_b128 v[196:199], v162 offset:18432
	ds_read_b128 v[200:203], v162 offset:19456
	ds_read_b128 v[204:207], v162 offset:20480
	ds_read_b128 v[208:211], v162 offset:21504
	ds_read_b128 v[212:215], v162 offset:22528
	ds_read_b128 v[216:219], v162 offset:23552
	global_load_lds_dwordx4 v[156:157], off
	s_add_i32 m0, vcc_lo, 0x2000
	s_add_u32 vcc_lo, s60, 0x20000
	v_lshl_add_u64 v[220:221], s[60:61], 0, v[138:139]
	s_addc_u32 vcc_hi, s61, 0
	s_add_i32 s11, s40, s41
	global_load_lds_dwordx4 v[220:221], off
	v_lshl_add_u64 v[222:223], vcc, 0, v[134:135]
	s_mov_b32 m0, s11
	v_lshl_add_u64 v[224:225], s[84:85], 0, v[136:137]
	global_load_lds_dwordx4 v[222:223], off
	v_lshl_add_u64 v[222:223], vcc, 0, v[138:139]
	s_add_i32 m0, s11, 0x2000
	s_nop 0
	global_load_lds_dwordx4 v[222:223], off
	v_lshl_add_u64 v[222:223], s[84:85], 0, v[132:133]
	s_mov_b32 m0, s42
	s_nop 0
	global_load_lds_dwordx4 v[222:223], off
	s_mov_b32 m0, s43
	s_nop 0
	global_load_lds_dwordx4 v[224:225], off
	s_waitcnt vmcnt(8)
	s_waitcnt lgkmcnt(0)
	s_barrier
; #define PG8_STAGE(bufoff, gbase, voff) do { _Pragma("unroll") for (int _i = 0; _i < 2; ++_i) \
;         __builtin_amdgcn_global_load_lds((const unsigned*)((const char*)(gbase) + (voff)[_i]), (PG8_LAS unsigned*)(lds + (bufoff) + ldsw + _i * 8192), 16, 0, 0); } while (0)
; #define PG8_LDA(dst, b, h) do { _Pragma("unroll") for (int m = 0; m < 4; ++m) _Pragma("unroll") for (int k = 0; k < 2; ++k) dst[m][k] = *(const PG8_LAS bf16x8*)(lds + PG8_SA(b, h) + aoff + m * 2048 + k * 1024); } while (0)
; #define PG8_LDB(dst, b, h) do { _Pragma("unroll") for (int n = 0; n < 2; ++n) _Pragma("unroll") for (int k = 0; k < 2; ++k) dst[n][k] = *(const PG8_LAS bf16x8*)(lds + PG8_SB(b, h) + boff + n * 2048 + k * 1024); } while (0)
; #define PG8_MMA(ai, bj, At, Bt) do { __builtin_amdgcn_s_setprio(1); _Pragma("unroll") for (int m = 0; m < 4; ++m) _Pragma("unroll") for (int n = 0; n < 2; ++n) _Pragma("unroll") for (int k = 0; k < 2; ++k) \
;         acc[ai][bj][m][n] = __builtin_amdgcn_mfma_f32_16x16x32_bf16(Bt[n][k], At[m][k], acc[ai][bj][m][n], 0, 0, 0); __builtin_amdgcn_s_setprio(0); } while (0)
; #define PG8_WAIT_V(n) asm volatile("s_waitcnt vmcnt(" #n ")" ::: "memory")
; #define PG8_WAIT_L(n) asm volatile("s_waitcnt lgkmcnt(" #n ")" ::: "memory")
; #define PG8_BAR __builtin_amdgcn_s_barrier()
; #define PG8_SCHED __builtin_amdgcn_sched_barrier(0)
; template <class Epi, class Sched, bool ALIGN_EPI = false, bool SP2 = false>
; __device__ __forceinline__ void gemm_phase(PG8_LAS unsigned char* lds, const Gemm g, const Sched& S, const Epi& E, const int wave_in) {
;     ...
;             PG8_WAIT_V(8); PG8_WAIT_L(0); PG8_BAR; PG8_MMA(1, 0, At, B0); PG8_MMA(1, 1, At, B1); PG8_BAR; PG8_SCHED;
;             PG8_LDB(B0, 1, 0); PG8_LDB(B1, 1, 1); PG8_SCHED; PG8_LDA(At, 1, 0); PG8_STAGE(PG8_SA(0, 1), a2 + hstepA, voffA);
;             PG8_WAIT_V(8); PG8_WAIT_L(0); PG8_BAR; PG8_MMA(0, 0, At, B0); PG8_MMA(0, 1, At, B1); PG8_BAR; PG8_SCHED;
	s_waitcnt lgkmcnt(0)
	v_mfma_f32_16x16x32_bf16 v[60:63], v[128:131], v[188:191], v[60:63]
	v_mfma_f32_16x16x32_bf16 v[56:59], v[164:167], v[188:191], v[56:59]
	v_mfma_f32_16x16x32_bf16 v[44:47], v[128:131], v[196:199], v[44:47]
	v_mfma_f32_16x16x32_bf16 v[40:43], v[164:167], v[196:199], v[40:43]
	v_mfma_f32_16x16x32_bf16 v[28:31], v[128:131], v[204:207], v[28:31]
	v_mfma_f32_16x16x32_bf16 v[24:27], v[164:167], v[204:207], v[24:27]
	v_mfma_f32_16x16x32_bf16 v[12:15], v[128:131], v[212:215], v[12:15]
	v_mfma_f32_16x16x32_bf16 v[8:11], v[164:167], v[212:215], v[8:11]
	v_mfma_f32_16x16x32_bf16 v[60:63], v[152:155], v[192:195], v[60:63]
	v_mfma_f32_16x16x32_bf16 v[56:59], v[168:171], v[192:195], v[56:59]
	v_mfma_f32_16x16x32_bf16 v[44:47], v[152:155], v[200:203], v[44:47]
	v_mfma_f32_16x16x32_bf16 v[40:43], v[168:171], v[200:203], v[40:43]
	v_mfma_f32_16x16x32_bf16 v[28:31], v[152:155], v[208:211], v[28:31]
	v_mfma_f32_16x16x32_bf16 v[24:27], v[168:171], v[208:211], v[24:27]
	v_mfma_f32_16x16x32_bf16 v[12:15], v[152:155], v[216:219], v[12:15]
	v_mfma_f32_16x16x32_bf16 v[8:11], v[168:171], v[216:219], v[8:11]
	v_mfma_f32_16x16x32_bf16 v[52:55], v[172:175], v[188:191], v[52:55]
	v_mfma_f32_16x16x32_bf16 v[48:51], v[180:183], v[188:191], v[48:51]
	v_mfma_f32_16x16x32_bf16 v[36:39], v[172:175], v[196:199], v[36:39]
	v_mfma_f32_16x16x32_bf16 v[32:35], v[180:183], v[196:199], v[32:35]
	v_mfma_f32_16x16x32_bf16 v[20:23], v[172:175], v[204:207], v[20:23]
	v_mfma_f32_16x16x32_bf16 v[16:19], v[180:183], v[204:207], v[16:19]
	v_mfma_f32_16x16x32_bf16 v[4:7], v[172:175], v[212:215], v[4:7]
	v_mfma_f32_16x16x32_bf16 v[0:3], v[180:183], v[212:215], v[0:3]
	v_mfma_f32_16x16x32_bf16 v[52:55], v[176:179], v[192:195], v[52:55]
	v_mfma_f32_16x16x32_bf16 v[48:51], v[184:187], v[192:195], v[48:51]
	v_mfma_f32_16x16x32_bf16 v[36:39], v[176:179], v[200:203], v[36:39]
	v_mfma_f32_16x16x32_bf16 v[32:35], v[184:187], v[200:203], v[32:35]
	v_mfma_f32_16x16x32_bf16 v[20:23], v[176:179], v[208:211], v[20:23]
	v_mfma_f32_16x16x32_bf16 v[16:19], v[184:187], v[208:211], v[16:19]
	v_mfma_f32_16x16x32_bf16 v[4:7], v[176:179], v[216:219], v[4:7]
	v_mfma_f32_16x16x32_bf16 v[0:3], v[184:187], v[216:219], v[0:3]
	s_barrier
	s_add_i32 s11, 0, 0x18000
	s_add_i32 vcc_lo, 0, 0x1c000
	v_add_u32_e32 v168, s11, v159
	v_add_u32_e32 v184, vcc_lo, v159
	ds_read_b128 v[128:131], v168
	ds_read_b128 v[152:155], v168 offset:1024
	ds_read_b128 v[164:167], v168 offset:2048
	ds_read_b128 v[168:171], v168 offset:3072
	ds_read_b128 v[172:175], v184
	ds_read_b128 v[176:179], v184 offset:1024
	ds_read_b128 v[180:183], v184 offset:2048
	ds_read_b128 v[184:187], v184 offset:3072
	s_add_u32 s84, s84, 0x100000
	s_addc_u32 s85, s85, 0
	s_mov_b32 m0, s48
	v_lshl_add_u64 v[226:227], s[84:85], 0, v[132:133]
	ds_read_b128 v[188:191], v162 offset:32768
	ds_read_b128 v[192:195], v162 offset:33792
	ds_read_b128 v[196:199], v162 offset:34816
	ds_read_b128 v[200:203], v162 offset:35840
	ds_read_b128 v[204:207], v162 offset:36864
	ds_read_b128 v[208:211], v162 offset:37888
	ds_read_b128 v[212:215], v162 offset:38912
	ds_read_b128 v[216:219], v162 offset:39936
	global_load_lds_dwordx4 v[226:227], off
	v_lshl_add_u64 v[226:227], s[84:85], 0, v[136:137]
	s_mov_b32 m0, s49
	s_nop 0
	global_load_lds_dwordx4 v[226:227], off
	s_waitcnt vmcnt(8)
	s_waitcnt lgkmcnt(0)
	s_barrier
	s_waitcnt lgkmcnt(0)
	v_mfma_f32_16x16x32_bf16 v[124:127], v[128:131], v[188:191], v[124:127]
	v_mfma_f32_16x16x32_bf16 v[120:123], v[164:167], v[188:191], v[120:123]
	v_mfma_f32_16x16x32_bf16 v[108:111], v[128:131], v[196:199], v[108:111]
	v_mfma_f32_16x16x32_bf16 v[104:107], v[164:167], v[196:199], v[104:107]
	v_mfma_f32_16x16x32_bf16 v[92:95], v[128:131], v[204:207], v[92:95]
	v_mfma_f32_16x16x32_bf16 v[88:91], v[164:167], v[204:207], v[88:91]
	v_mfma_f32_16x16x32_bf16 v[76:79], v[128:131], v[212:215], v[76:79]
	v_mfma_f32_16x16x32_bf16 v[72:75], v[164:167], v[212:215], v[72:75]
	v_mfma_f32_16x16x32_bf16 v[124:127], v[152:155], v[192:195], v[124:127]
	v_mfma_f32_16x16x32_bf16 v[120:123], v[168:171], v[192:195], v[120:123]
	v_mfma_f32_16x16x32_bf16 v[108:111], v[152:155], v[200:203], v[108:111]
	v_mfma_f32_16x16x32_bf16 v[104:107], v[168:171], v[200:203], v[104:107]
	v_mfma_f32_16x16x32_bf16 v[92:95], v[152:155], v[208:211], v[92:95]
	v_mfma_f32_16x16x32_bf16 v[88:91], v[168:171], v[208:211], v[88:91]
	v_mfma_f32_16x16x32_bf16 v[76:79], v[152:155], v[216:219], v[76:79]
	v_mfma_f32_16x16x32_bf16 v[72:75], v[168:171], v[216:219], v[72:75]
	v_mfma_f32_16x16x32_bf16 v[116:119], v[172:175], v[188:191], v[116:119]
	v_mfma_f32_16x16x32_bf16 v[112:115], v[180:183], v[188:191], v[112:115]
	v_mfma_f32_16x16x32_bf16 v[100:103], v[172:175], v[196:199], v[100:103]
	v_mfma_f32_16x16x32_bf16 v[96:99], v[180:183], v[196:199], v[96:99]
	v_mfma_f32_16x16x32_bf16 v[84:87], v[172:175], v[204:207], v[84:87]
	v_mfma_f32_16x16x32_bf16 v[80:83], v[180:183], v[204:207], v[80:83]
	v_mfma_f32_16x16x32_bf16 v[68:71], v[172:175], v[212:215], v[68:71]
	v_mfma_f32_16x16x32_bf16 v[64:67], v[180:183], v[212:215], v[64:67]
	v_mfma_f32_16x16x32_bf16 v[116:119], v[176:179], v[192:195], v[116:119]
	v_mfma_f32_16x16x32_bf16 v[112:115], v[184:187], v[192:195], v[112:115]
	v_mfma_f32_16x16x32_bf16 v[100:103], v[176:179], v[200:203], v[100:103]
	v_mfma_f32_16x16x32_bf16 v[96:99], v[184:187], v[200:203], v[96:99]
	v_mfma_f32_16x16x32_bf16 v[84:87], v[176:179], v[208:211], v[84:87]
	v_mfma_f32_16x16x32_bf16 v[80:83], v[184:187], v[208:211], v[80:83]
	v_mfma_f32_16x16x32_bf16 v[68:71], v[176:179], v[216:219], v[68:71]
	v_mfma_f32_16x16x32_bf16 v[64:67], v[184:187], v[216:219], v[64:67]
	s_barrier
; #define PG8_STAGE(bufoff, gbase, voff) do { _Pragma("unroll") for (int _i = 0; _i < 2; ++_i) \
;         __builtin_amdgcn_global_load_lds((const unsigned*)((const char*)(gbase) + (voff)[_i]), (PG8_LAS unsigned*)(lds + (bufoff) + ldsw + _i * 8192), 16, 0, 0); } while (0)
; #define PG8_LDA(dst, b, h) do { _Pragma("unroll") for (int m = 0; m < 4; ++m) _Pragma("unroll") for (int k = 0; k < 2; ++k) dst[m][k] = *(const PG8_LAS bf16x8*)(lds + PG8_SA(b, h) + aoff + m * 2048 + k * 1024); } while (0)
; #define PG8_MMA(ai, bj, At, Bt) do { __builtin_amdgcn_s_setprio(1); _Pragma("unroll") for (int m = 0; m < 4; ++m) _Pragma("unroll") for (int n = 0; n < 2; ++n) _Pragma("unroll") for (int k = 0; k < 2; ++k) \
;         acc[ai][bj][m][n] = __builtin_amdgcn_mfma_f32_16x16x32_bf16(Bt[n][k], At[m][k], acc[ai][bj][m][n], 0, 0, 0); __builtin_amdgcn_s_setprio(0); } while (0)
; #define PG8_WAIT_V(n) asm volatile("s_waitcnt vmcnt(" #n ")" ::: "memory")
; #define PG8_WAIT_L(n) asm volatile("s_waitcnt lgkmcnt(" #n ")" ::: "memory")
; #define PG8_BAR __builtin_amdgcn_s_barrier()
; #define PG8_SCHED __builtin_amdgcn_sched_barrier(0)
; template <class Epi, class Sched, bool ALIGN_EPI = false, bool SP2 = false>
; __device__ __forceinline__ void gemm_phase(PG8_LAS unsigned char* lds, const Gemm g, const Sched& S, const Epi& E, const int wave_in) {
;     ...
;             PG8_LDA(At, 1, 1); PG8_STAGE(PG8_SB(1, 0), b3, voffB); PG8_STAGE(PG8_SB(1, 1), b3 + hstep, voffB); PG8_STAGE(PG8_SA(1, 0), a3, voffA);
;             PG8_WAIT_V(8); PG8_WAIT_L(0); PG8_BAR; PG8_MMA(1, 0, At, B0); PG8_MMA(1, 1, At, B1); PG8_BAR; PG8_SCHED;
	s_add_i32 s11, s11, s41
	v_lshl_add_u64 v[156:157], v[156:157], 0, s[68:69]
	s_mov_b32 m0, s11
	ds_read_b128 v[188:191], v162 offset:49152
	ds_read_b128 v[192:195], v162 offset:50176
	ds_read_b128 v[196:199], v162 offset:51200
	ds_read_b128 v[200:203], v162 offset:52224
	ds_read_b128 v[204:207], v162 offset:53248
	ds_read_b128 v[208:211], v162 offset:54272
	ds_read_b128 v[212:215], v162 offset:55296
	ds_read_b128 v[216:219], v162 offset:56320
	global_load_lds_dwordx4 v[156:157], off
	s_add_i32 m0, s11, 0x2000
	s_add_u32 s60, s60, 0x20080
	v_lshl_add_u64 v[156:157], v[220:221], 0, s[68:69]
	s_addc_u32 s61, s61, 0
	s_add_i32 s11, vcc_lo, s41
	global_load_lds_dwordx4 v[156:157], off
	v_lshl_add_u64 v[156:157], s[60:61], 0, v[134:135]
	s_mov_b32 m0, s11
	s_nop 0
	global_load_lds_dwordx4 v[156:157], off
	v_lshl_add_u64 v[156:157], s[60:61], 0, v[138:139]
	s_add_i32 m0, s11, 0x2000
	s_nop 0
	global_load_lds_dwordx4 v[156:157], off
	v_lshl_add_u64 v[156:157], v[222:223], 0, s[68:69]
	s_mov_b32 m0, s51
	s_nop 0
	global_load_lds_dwordx4 v[156:157], off
	v_lshl_add_u64 v[156:157], v[224:225], 0, s[68:69]
	s_mov_b32 m0, s39
	s_nop 0
	global_load_lds_dwordx4 v[156:157], off
	s_waitcnt vmcnt(8)
	s_waitcnt lgkmcnt(0)
	s_barrier
	s_waitcnt lgkmcnt(0)
	v_mfma_f32_16x16x32_bf16 v[60:63], v[128:131], v[188:191], v[60:63]
	v_mfma_f32_16x16x32_bf16 v[56:59], v[164:167], v[188:191], v[56:59]
	v_mfma_f32_16x16x32_bf16 v[44:47], v[128:131], v[196:199], v[44:47]
	v_mfma_f32_16x16x32_bf16 v[40:43], v[164:167], v[196:199], v[40:43]
	v_mfma_f32_16x16x32_bf16 v[28:31], v[128:131], v[204:207], v[28:31]
	v_mfma_f32_16x16x32_bf16 v[24:27], v[164:167], v[204:207], v[24:27]
	v_mfma_f32_16x16x32_bf16 v[12:15], v[128:131], v[212:215], v[12:15]
	v_mfma_f32_16x16x32_bf16 v[8:11], v[164:167], v[212:215], v[8:11]
	v_mfma_f32_16x16x32_bf16 v[60:63], v[152:155], v[192:195], v[60:63]
	v_mfma_f32_16x16x32_bf16 v[56:59], v[168:171], v[192:195], v[56:59]
	v_mfma_f32_16x16x32_bf16 v[44:47], v[152:155], v[200:203], v[44:47]
	v_mfma_f32_16x16x32_bf16 v[40:43], v[168:171], v[200:203], v[40:43]
	v_mfma_f32_16x16x32_bf16 v[28:31], v[152:155], v[208:211], v[28:31]
	v_mfma_f32_16x16x32_bf16 v[24:27], v[168:171], v[208:211], v[24:27]
	v_mfma_f32_16x16x32_bf16 v[12:15], v[152:155], v[216:219], v[12:15]
	v_mfma_f32_16x16x32_bf16 v[8:11], v[168:171], v[216:219], v[8:11]
	v_mfma_f32_16x16x32_bf16 v[52:55], v[172:175], v[188:191], v[52:55]
	v_mfma_f32_16x16x32_bf16 v[48:51], v[180:183], v[188:191], v[48:51]
	v_mfma_f32_16x16x32_bf16 v[36:39], v[172:175], v[196:199], v[36:39]
	v_mfma_f32_16x16x32_bf16 v[32:35], v[180:183], v[196:199], v[32:35]
	v_mfma_f32_16x16x32_bf16 v[20:23], v[172:175], v[204:207], v[20:23]
	v_mfma_f32_16x16x32_bf16 v[16:19], v[180:183], v[204:207], v[16:19]
	v_mfma_f32_16x16x32_bf16 v[4:7], v[172:175], v[212:215], v[4:7]
	v_mfma_f32_16x16x32_bf16 v[0:3], v[180:183], v[212:215], v[0:3]
	v_mfma_f32_16x16x32_bf16 v[52:55], v[176:179], v[192:195], v[52:55]
	v_mfma_f32_16x16x32_bf16 v[48:51], v[184:187], v[192:195], v[48:51]
	v_mfma_f32_16x16x32_bf16 v[36:39], v[176:179], v[200:203], v[36:39]
	v_mfma_f32_16x16x32_bf16 v[32:35], v[184:187], v[200:203], v[32:35]
	v_mfma_f32_16x16x32_bf16 v[20:23], v[176:179], v[208:211], v[20:23]
	v_mfma_f32_16x16x32_bf16 v[16:19], v[184:187], v[208:211], v[16:19]
	v_mfma_f32_16x16x32_bf16 v[4:7], v[176:179], v[216:219], v[4:7]
	v_mfma_f32_16x16x32_bf16 v[0:3], v[184:187], v[216:219], v[0:3]
	s_barrier
	s_add_i32 s75, s75, 2
	s_add_u32 s18, s18, 0x100
	s_addc_u32 s19, s19, 0
	s_add_u32 s62, s62, 0x100
	s_addc_u32 s73, s73, 0
	s_cmp_gt_u32 s75, 5
	s_cbranch_scc0 .LBB0_786
	s_and_b64 vcc, exec, s[70:71]
	s_cbranch_vccz .LBB0_789
	s_barrier

; #define PG8_STAGE(bufoff, gbase, voff) do { _Pragma("unroll") for (int _i = 0; _i < 2; ++_i) \
;         __builtin_amdgcn_global_load_lds((const unsigned*)((const char*)(gbase) + (voff)[_i]), (PG8_LAS unsigned*)(lds + (bufoff) + ldsw + _i * 8192), 16, 0, 0); } while (0)
; #define PG8_LDA(dst, b, h) do { _Pragma("unroll") for (int m = 0; m < 4; ++m) _Pragma("unroll") for (int k = 0; k < 2; ++k) dst[m][k] = *(const PG8_LAS bf16x8*)(lds + PG8_SA(b, h) + aoff + m * 2048 + k * 1024); } while (0)
; #define PG8_LDB(dst, b, h) do { _Pragma("unroll") for (int n = 0; n < 2; ++n) _Pragma("unroll") for (int k = 0; k < 2; ++k) dst[n][k] = *(const PG8_LAS bf16x8*)(lds + PG8_SB(b, h) + boff + n * 2048 + k * 1024); } while (0)
; #define PG8_MMA(ai, bj, At, Bt) do { __builtin_amdgcn_s_setprio(1); _Pragma("unroll") for (int m = 0; m < 4; ++m) _Pragma("unroll") for (int n = 0; n < 2; ++n) _Pragma("unroll") for (int k = 0; k < 2; ++k) \
;         acc[ai][bj][m][n] = __builtin_amdgcn_mfma_f32_16x16x32_bf16(Bt[n][k], At[m][k], acc[ai][bj][m][n], 0, 0, 0); __builtin_amdgcn_s_setprio(0); } while (0)
; #define PG8_WAIT_V(n) asm volatile("s_waitcnt vmcnt(" #n ")" ::: "memory")
; #define PG8_WAIT_L(n) asm volatile("s_waitcnt lgkmcnt(" #n ")" ::: "memory")
; #define PG8_BAR __builtin_amdgcn_s_barrier()
; #define PG8_SCHED __builtin_amdgcn_sched_barrier(0)
; template <class Epi, class Sched, bool ALIGN_EPI = false, bool SP2 = false>
; __device__ __forceinline__ void gemm_phase(PG8_LAS unsigned char* lds, const Gemm g, const Sched& S, const Epi& E, const int wave_in) {
;     ...
;             PG8_LDB(B0, 0, 0); PG8_LDB(B1, 0, 1); PG8_SCHED; PG8_LDA(At, 0, 0); PG8_STAGE(PG8_SA(1, 1), a1 + hstepA, voffA);
;             PG8_WAIT_V(8); PG8_WAIT_L(0); PG8_BAR; PG8_MMA(0, 0, At, B0); PG8_MMA(0, 1, At, B1); PG8_BAR; PG8_SCHED;
;             PG8_LDA(At, 0, 1); PG8_STAGE(PG8_SB(0, 0), b2, voffB); PG8_STAGE(PG8_SB(0, 1), b2 + hstep, voffB); PG8_STAGE(PG8_SA(0, 0), a2, voffA);
.LBB0_838:
	ds_read_b128 v[146:149], v152
	ds_read_b128 v[156:159], v152 offset:1024
	ds_read_b128 v[160:163], v152 offset:2048
	ds_read_b128 v[164:167], v152 offset:3072
	ds_read_b128 v[168:171], v153
	ds_read_b128 v[172:175], v153 offset:1024
	ds_read_b128 v[176:179], v153 offset:2048
	ds_read_b128 v[180:183], v153 offset:3072
	s_add_u32 s11, s18, 0xfff00080
	s_addc_u32 s78, s19, -1
	s_cmp_eq_u32 s94, 4
	s_cselect_b32 s85, s1, s78
	s_cselect_b32 s84, s36, s11
	s_cselect_b32 s79, s37, s93
	s_cselect_b32 s78, s69, s71
	v_lshl_add_u64 v[216:217], s[18:19], 0, v[136:137]
	s_add_i32 m0, s42, 0xc000
	ds_read_b128 v[184:187], v154
	ds_read_b128 v[188:191], v154 offset:1024
	ds_read_b128 v[192:195], v154 offset:2048
	ds_read_b128 v[196:199], v154 offset:3072
	ds_read_b128 v[200:203], v154 offset:4096
	ds_read_b128 v[204:207], v154 offset:5120
	ds_read_b128 v[208:211], v154 offset:6144
	ds_read_b128 v[212:215], v154 offset:7168
	global_load_lds_dwordx4 v[216:217], off
	v_lshl_add_u64 v[216:217], s[18:19], 0, v[138:139]
	s_add_i32 m0, s42, 0xe000
	s_nop 0
	global_load_lds_dwordx4 v[216:217], off
	s_waitcnt vmcnt(8)
	s_waitcnt lgkmcnt(0)
	s_barrier
	s_waitcnt lgkmcnt(0)
	v_mfma_f32_16x16x32_bf16 v[124:127], v[146:149], v[184:187], v[124:127]
	v_mfma_f32_16x16x32_bf16 v[120:123], v[160:163], v[184:187], v[120:123]
	v_mfma_f32_16x16x32_bf16 v[108:111], v[146:149], v[192:195], v[108:111]
	v_mfma_f32_16x16x32_bf16 v[104:107], v[160:163], v[192:195], v[104:107]
	v_mfma_f32_16x16x32_bf16 v[92:95], v[146:149], v[200:203], v[92:95]
	v_mfma_f32_16x16x32_bf16 v[88:91], v[160:163], v[200:203], v[88:91]
	v_mfma_f32_16x16x32_bf16 v[76:79], v[146:149], v[208:211], v[76:79]
	v_mfma_f32_16x16x32_bf16 v[72:75], v[160:163], v[208:211], v[72:75]
	v_mfma_f32_16x16x32_bf16 v[124:127], v[156:159], v[188:191], v[124:127]
	v_mfma_f32_16x16x32_bf16 v[120:123], v[164:167], v[188:191], v[120:123]
	v_mfma_f32_16x16x32_bf16 v[108:111], v[156:159], v[196:199], v[108:111]
	v_mfma_f32_16x16x32_bf16 v[104:107], v[164:167], v[196:199], v[104:107]
	v_mfma_f32_16x16x32_bf16 v[92:95], v[156:159], v[204:207], v[92:95]
	v_mfma_f32_16x16x32_bf16 v[88:91], v[164:167], v[204:207], v[88:91]
	v_mfma_f32_16x16x32_bf16 v[76:79], v[156:159], v[212:215], v[76:79]
	v_mfma_f32_16x16x32_bf16 v[72:75], v[164:167], v[212:215], v[72:75]
	v_mfma_f32_16x16x32_bf16 v[116:119], v[168:171], v[184:187], v[116:119]
	v_mfma_f32_16x16x32_bf16 v[112:115], v[176:179], v[184:187], v[112:115]
	v_mfma_f32_16x16x32_bf16 v[100:103], v[168:171], v[192:195], v[100:103]
	v_mfma_f32_16x16x32_bf16 v[96:99], v[176:179], v[192:195], v[96:99]
	v_mfma_f32_16x16x32_bf16 v[84:87], v[168:171], v[200:203], v[84:87]
	v_mfma_f32_16x16x32_bf16 v[80:83], v[176:179], v[200:203], v[80:83]
	v_mfma_f32_16x16x32_bf16 v[68:71], v[168:171], v[208:211], v[68:71]
	v_mfma_f32_16x16x32_bf16 v[64:67], v[176:179], v[208:211], v[64:67]
	v_mfma_f32_16x16x32_bf16 v[116:119], v[172:175], v[188:191], v[116:119]
	v_mfma_f32_16x16x32_bf16 v[112:115], v[180:183], v[188:191], v[112:115]
	v_mfma_f32_16x16x32_bf16 v[100:103], v[172:175], v[196:199], v[100:103]
	v_mfma_f32_16x16x32_bf16 v[96:99], v[180:183], v[196:199], v[96:99]
	v_mfma_f32_16x16x32_bf16 v[84:87], v[172:175], v[204:207], v[84:87]
	v_mfma_f32_16x16x32_bf16 v[80:83], v[180:183], v[204:207], v[80:83]
	v_mfma_f32_16x16x32_bf16 v[68:71], v[172:175], v[212:215], v[68:71]
	v_mfma_f32_16x16x32_bf16 v[64:67], v[180:183], v[212:215], v[64:67]
	s_barrier
	s_add_i32 s11, s56, s39
	v_lshl_add_u64 v[216:217], s[78:79], 0, v[132:133]
	s_mov_b32 m0, s11
	ds_read_b128 v[184:187], v154 offset:16384
	ds_read_b128 v[188:191], v154 offset:17408
	ds_read_b128 v[192:195], v154 offset:18432
	ds_read_b128 v[196:199], v154 offset:19456
	ds_read_b128 v[200:203], v154 offset:20480
	ds_read_b128 v[204:207], v154 offset:21504
	ds_read_b128 v[208:211], v154 offset:22528
	ds_read_b128 v[212:215], v154 offset:23552
	global_load_lds_dwordx4 v[216:217], off
	s_add_i32 m0, s11, 0x2000
	s_add_u32 vcc_lo, s78, 0x20000
	v_lshl_add_u64 v[218:219], s[78:79], 0, v[128:129]
	s_addc_u32 vcc_hi, s79, 0
	s_add_i32 s11, s57, s39
	global_load_lds_dwordx4 v[218:219], off
	v_lshl_add_u64 v[220:221], vcc, 0, v[132:133]
	s_mov_b32 m0, s11
	v_lshl_add_u64 v[222:223], s[84:85], 0, v[130:131]
	global_load_lds_dwordx4 v[220:221], off
	v_lshl_add_u64 v[220:221], vcc, 0, v[128:129]
	s_add_i32 m0, s11, 0x2000
	s_nop 0
	global_load_lds_dwordx4 v[220:221], off
	v_lshl_add_u64 v[220:221], s[84:85], 0, v[134:135]
	s_mov_b32 m0, s42
	s_nop 0
	global_load_lds_dwordx4 v[220:221], off
	s_mov_b32 m0, s43
	s_nop 0
	global_load_lds_dwordx4 v[222:223], off
	s_waitcnt vmcnt(8)
	s_waitcnt lgkmcnt(0)
	s_barrier
; #define PG8_STAGE(bufoff, gbase, voff) do { _Pragma("unroll") for (int _i = 0; _i < 2; ++_i) \
;         __builtin_amdgcn_global_load_lds((const unsigned*)((const char*)(gbase) + (voff)[_i]), (PG8_LAS unsigned*)(lds + (bufoff) + ldsw + _i * 8192), 16, 0, 0); } while (0)
; #define PG8_LDA(dst, b, h) do { _Pragma("unroll") for (int m = 0; m < 4; ++m) _Pragma("unroll") for (int k = 0; k < 2; ++k) dst[m][k] = *(const PG8_LAS bf16x8*)(lds + PG8_SA(b, h) + aoff + m * 2048 + k * 1024); } while (0)
; #define PG8_LDB(dst, b, h) do { _Pragma("unroll") for (int n = 0; n < 2; ++n) _Pragma("unroll") for (int k = 0; k < 2; ++k) dst[n][k] = *(const PG8_LAS bf16x8*)(lds + PG8_SB(b, h) + boff + n * 2048 + k * 1024); } while (0)
; #define PG8_MMA(ai, bj, At, Bt) do { __builtin_amdgcn_s_setprio(1); _Pragma("unroll") for (int m = 0; m < 4; ++m) _Pragma("unroll") for (int n = 0; n < 2; ++n) _Pragma("unroll") for (int k = 0; k < 2; ++k) \
;         acc[ai][bj][m][n] = __builtin_amdgcn_mfma_f32_16x16x32_bf16(Bt[n][k], At[m][k], acc[ai][bj][m][n], 0, 0, 0); __builtin_amdgcn_s_setprio(0); } while (0)
; #define PG8_WAIT_V(n) asm volatile("s_waitcnt vmcnt(" #n ")" ::: "memory")
; #define PG8_WAIT_L(n) asm volatile("s_waitcnt lgkmcnt(" #n ")" ::: "memory")
; #define PG8_BAR __builtin_amdgcn_s_barrier()
; #define PG8_SCHED __builtin_amdgcn_sched_barrier(0)
; template <class Epi, class Sched, bool ALIGN_EPI = false, bool SP2 = false>
; __device__ __forceinline__ void gemm_phase(PG8_LAS unsigned char* lds, const Gemm g, const Sched& S, const Epi& E, const int wave_in) {
;     ...
;             PG8_WAIT_V(8); PG8_WAIT_L(0); PG8_BAR; PG8_MMA(1, 0, At, B0); PG8_MMA(1, 1, At, B1); PG8_BAR; PG8_SCHED;
;             PG8_LDB(B0, 1, 0); PG8_LDB(B1, 1, 1); PG8_SCHED; PG8_LDA(At, 1, 0); PG8_STAGE(PG8_SA(0, 1), a2 + hstepA, voffA);
;             PG8_WAIT_V(8); PG8_WAIT_L(0); PG8_BAR; PG8_MMA(0, 0, At, B0); PG8_MMA(0, 1, At, B1); PG8_BAR; PG8_SCHED;
	s_waitcnt lgkmcnt(0)
	v_mfma_f32_16x16x32_bf16 v[60:63], v[146:149], v[184:187], v[60:63]
	v_mfma_f32_16x16x32_bf16 v[56:59], v[160:163], v[184:187], v[56:59]
	v_mfma_f32_16x16x32_bf16 v[44:47], v[146:149], v[192:195], v[44:47]
	v_mfma_f32_16x16x32_bf16 v[40:43], v[160:163], v[192:195], v[40:43]
	v_mfma_f32_16x16x32_bf16 v[28:31], v[146:149], v[200:203], v[28:31]
	v_mfma_f32_16x16x32_bf16 v[24:27], v[160:163], v[200:203], v[24:27]
	v_mfma_f32_16x16x32_bf16 v[12:15], v[146:149], v[208:211], v[12:15]
	v_mfma_f32_16x16x32_bf16 v[8:11], v[160:163], v[208:211], v[8:11]
	v_mfma_f32_16x16x32_bf16 v[60:63], v[156:159], v[188:191], v[60:63]
	v_mfma_f32_16x16x32_bf16 v[56:59], v[164:167], v[188:191], v[56:59]
	v_mfma_f32_16x16x32_bf16 v[44:47], v[156:159], v[196:199], v[44:47]
	v_mfma_f32_16x16x32_bf16 v[40:43], v[164:167], v[196:199], v[40:43]
	v_mfma_f32_16x16x32_bf16 v[28:31], v[156:159], v[204:207], v[28:31]
	v_mfma_f32_16x16x32_bf16 v[24:27], v[164:167], v[204:207], v[24:27]
	v_mfma_f32_16x16x32_bf16 v[12:15], v[156:159], v[212:215], v[12:15]
	v_mfma_f32_16x16x32_bf16 v[8:11], v[164:167], v[212:215], v[8:11]
	v_mfma_f32_16x16x32_bf16 v[52:55], v[168:171], v[184:187], v[52:55]
	v_mfma_f32_16x16x32_bf16 v[48:51], v[176:179], v[184:187], v[48:51]
	v_mfma_f32_16x16x32_bf16 v[36:39], v[168:171], v[192:195], v[36:39]
	v_mfma_f32_16x16x32_bf16 v[32:35], v[176:179], v[192:195], v[32:35]
	v_mfma_f32_16x16x32_bf16 v[20:23], v[168:171], v[200:203], v[20:23]
	v_mfma_f32_16x16x32_bf16 v[16:19], v[176:179], v[200:203], v[16:19]
	v_mfma_f32_16x16x32_bf16 v[4:7], v[168:171], v[208:211], v[4:7]
	v_mfma_f32_16x16x32_bf16 v[0:3], v[176:179], v[208:211], v[0:3]
	v_mfma_f32_16x16x32_bf16 v[52:55], v[172:175], v[188:191], v[52:55]
	v_mfma_f32_16x16x32_bf16 v[48:51], v[180:183], v[188:191], v[48:51]
	v_mfma_f32_16x16x32_bf16 v[36:39], v[172:175], v[196:199], v[36:39]
	v_mfma_f32_16x16x32_bf16 v[32:35], v[180:183], v[196:199], v[32:35]
	v_mfma_f32_16x16x32_bf16 v[20:23], v[172:175], v[204:207], v[20:23]
	v_mfma_f32_16x16x32_bf16 v[16:19], v[180:183], v[204:207], v[16:19]
	v_mfma_f32_16x16x32_bf16 v[4:7], v[172:175], v[212:215], v[4:7]
	v_mfma_f32_16x16x32_bf16 v[0:3], v[180:183], v[212:215], v[0:3]
	s_barrier
	s_add_i32 s11, 0, 0x18000
	s_add_i32 s95, 0, 0x1c000
	v_add_u32_e32 v164, s11, v151
	v_add_u32_e32 v180, s95, v151
	ds_read_b128 v[146:149], v164
	ds_read_b128 v[156:159], v164 offset:1024
	ds_read_b128 v[160:163], v164 offset:2048
	ds_read_b128 v[164:167], v164 offset:3072
	ds_read_b128 v[168:171], v180
	ds_read_b128 v[172:175], v180 offset:1024
	ds_read_b128 v[176:179], v180 offset:2048
	ds_read_b128 v[180:183], v180 offset:3072
	s_add_u32 s84, s84, 0x100000
	s_addc_u32 s85, s85, 0
	s_mov_b32 m0, s48
	v_lshl_add_u64 v[224:225], s[84:85], 0, v[134:135]
	ds_read_b128 v[184:187], v154 offset:32768
	ds_read_b128 v[188:191], v154 offset:33792
	ds_read_b128 v[192:195], v154 offset:34816
	ds_read_b128 v[196:199], v154 offset:35840
	ds_read_b128 v[200:203], v154 offset:36864
	ds_read_b128 v[204:207], v154 offset:37888
	ds_read_b128 v[208:211], v154 offset:38912
	ds_read_b128 v[212:215], v154 offset:39936
	global_load_lds_dwordx4 v[224:225], off
	v_lshl_add_u64 v[224:225], s[84:85], 0, v[130:131]
	s_mov_b32 m0, s49
	s_nop 0
	global_load_lds_dwordx4 v[224:225], off
	s_waitcnt vmcnt(8)
	s_waitcnt lgkmcnt(0)
	s_barrier
	s_waitcnt lgkmcnt(0)
	v_mfma_f32_16x16x32_bf16 v[124:127], v[146:149], v[184:187], v[124:127]
	v_mfma_f32_16x16x32_bf16 v[120:123], v[160:163], v[184:187], v[120:123]
	v_mfma_f32_16x16x32_bf16 v[108:111], v[146:149], v[192:195], v[108:111]
	v_mfma_f32_16x16x32_bf16 v[104:107], v[160:163], v[192:195], v[104:107]
	v_mfma_f32_16x16x32_bf16 v[92:95], v[146:149], v[200:203], v[92:95]
	v_mfma_f32_16x16x32_bf16 v[88:91], v[160:163], v[200:203], v[88:91]
	v_mfma_f32_16x16x32_bf16 v[76:79], v[146:149], v[208:211], v[76:79]
	v_mfma_f32_16x16x32_bf16 v[72:75], v[160:163], v[208:211], v[72:75]
	v_mfma_f32_16x16x32_bf16 v[124:127], v[156:159], v[188:191], v[124:127]
	v_mfma_f32_16x16x32_bf16 v[120:123], v[164:167], v[188:191], v[120:123]
	v_mfma_f32_16x16x32_bf16 v[108:111], v[156:159], v[196:199], v[108:111]
	v_mfma_f32_16x16x32_bf16 v[104:107], v[164:167], v[196:199], v[104:107]
	v_mfma_f32_16x16x32_bf16 v[92:95], v[156:159], v[204:207], v[92:95]
	v_mfma_f32_16x16x32_bf16 v[88:91], v[164:167], v[204:207], v[88:91]
	v_mfma_f32_16x16x32_bf16 v[76:79], v[156:159], v[212:215], v[76:79]
	v_mfma_f32_16x16x32_bf16 v[72:75], v[164:167], v[212:215], v[72:75]
	v_mfma_f32_16x16x32_bf16 v[116:119], v[168:171], v[184:187], v[116:119]
	v_mfma_f32_16x16x32_bf16 v[112:115], v[176:179], v[184:187], v[112:115]
	v_mfma_f32_16x16x32_bf16 v[100:103], v[168:171], v[192:195], v[100:103]
	v_mfma_f32_16x16x32_bf16 v[96:99], v[176:179], v[192:195], v[96:99]
	v_mfma_f32_16x16x32_bf16 v[84:87], v[168:171], v[200:203], v[84:87]
	v_mfma_f32_16x16x32_bf16 v[80:83], v[176:179], v[200:203], v[80:83]
	v_mfma_f32_16x16x32_bf16 v[68:71], v[168:171], v[208:211], v[68:71]
	v_mfma_f32_16x16x32_bf16 v[64:67], v[176:179], v[208:211], v[64:67]
	v_mfma_f32_16x16x32_bf16 v[116:119], v[172:175], v[188:191], v[116:119]
	v_mfma_f32_16x16x32_bf16 v[112:115], v[180:183], v[188:191], v[112:115]
	v_mfma_f32_16x16x32_bf16 v[100:103], v[172:175], v[196:199], v[100:103]
	v_mfma_f32_16x16x32_bf16 v[96:99], v[180:183], v[196:199], v[96:99]
	v_mfma_f32_16x16x32_bf16 v[84:87], v[172:175], v[204:207], v[84:87]
	v_mfma_f32_16x16x32_bf16 v[80:83], v[180:183], v[204:207], v[80:83]
	v_mfma_f32_16x16x32_bf16 v[68:71], v[172:175], v[212:215], v[68:71]
	v_mfma_f32_16x16x32_bf16 v[64:67], v[180:183], v[212:215], v[64:67]
	s_barrier
; #define PG8_STAGE(bufoff, gbase, voff) do { _Pragma("unroll") for (int _i = 0; _i < 2; ++_i) \
;         __builtin_amdgcn_global_load_lds((const unsigned*)((const char*)(gbase) + (voff)[_i]), (PG8_LAS unsigned*)(lds + (bufoff) + ldsw + _i * 8192), 16, 0, 0); } while (0)
; #define PG8_LDA(dst, b, h) do { _Pragma("unroll") for (int m = 0; m < 4; ++m) _Pragma("unroll") for (int k = 0; k < 2; ++k) dst[m][k] = *(const PG8_LAS bf16x8*)(lds + PG8_SA(b, h) + aoff + m * 2048 + k * 1024); } while (0)
; #define PG8_MMA(ai, bj, At, Bt) do { __builtin_amdgcn_s_setprio(1); _Pragma("unroll") for (int m = 0; m < 4; ++m) _Pragma("unroll") for (int n = 0; n < 2; ++n) _Pragma("unroll") for (int k = 0; k < 2; ++k) \
;         acc[ai][bj][m][n] = __builtin_amdgcn_mfma_f32_16x16x32_bf16(Bt[n][k], At[m][k], acc[ai][bj][m][n], 0, 0, 0); __builtin_amdgcn_s_setprio(0); } while (0)
; #define PG8_WAIT_V(n) asm volatile("s_waitcnt vmcnt(" #n ")" ::: "memory")
; #define PG8_WAIT_L(n) asm volatile("s_waitcnt lgkmcnt(" #n ")" ::: "memory")
; #define PG8_BAR __builtin_amdgcn_s_barrier()
; #define PG8_SCHED __builtin_amdgcn_sched_barrier(0)
; template <class Epi, class Sched, bool ALIGN_EPI = false, bool SP2 = false>
; __device__ __forceinline__ void gemm_phase(PG8_LAS unsigned char* lds, const Gemm g, const Sched& S, const Epi& E, const int wave_in) {
;     ...
;             PG8_LDA(At, 1, 1); PG8_STAGE(PG8_SB(1, 0), b3, voffB); PG8_STAGE(PG8_SB(1, 1), b3 + hstep, voffB); PG8_STAGE(PG8_SA(1, 0), a3, voffA);
;             PG8_WAIT_V(8); PG8_WAIT_L(0); PG8_BAR; PG8_MMA(1, 0, At, B0); PG8_MMA(1, 1, At, B1); PG8_BAR; PG8_SCHED;
	s_add_i32 s11, s11, s39
	v_lshl_add_u64 v[216:217], v[216:217], 0, s[64:65]
	s_mov_b32 m0, s11
	ds_read_b128 v[184:187], v154 offset:49152
	ds_read_b128 v[188:191], v154 offset:50176
	ds_read_b128 v[192:195], v154 offset:51200
	ds_read_b128 v[196:199], v154 offset:52224
	ds_read_b128 v[200:203], v154 offset:53248
	ds_read_b128 v[204:207], v154 offset:54272
	ds_read_b128 v[208:211], v154 offset:55296
	ds_read_b128 v[212:215], v154 offset:56320
	global_load_lds_dwordx4 v[216:217], off
	s_add_i32 m0, s11, 0x2000
	s_add_u32 s78, s78, 0x20080
	v_lshl_add_u64 v[216:217], v[218:219], 0, s[64:65]
	s_addc_u32 s79, s79, 0
	s_add_i32 s11, s95, s39
	global_load_lds_dwordx4 v[216:217], off
	v_lshl_add_u64 v[216:217], s[78:79], 0, v[132:133]
	s_mov_b32 m0, s11
	s_nop 0
	global_load_lds_dwordx4 v[216:217], off
	v_lshl_add_u64 v[216:217], s[78:79], 0, v[128:129]
	s_add_i32 m0, s11, 0x2000
	s_nop 0
	global_load_lds_dwordx4 v[216:217], off
	v_lshl_add_u64 v[216:217], v[220:221], 0, s[64:65]
	s_mov_b32 m0, s50
	s_nop 0
	global_load_lds_dwordx4 v[216:217], off
	v_lshl_add_u64 v[216:217], v[222:223], 0, s[64:65]
	s_mov_b32 m0, s51
	s_nop 0
	global_load_lds_dwordx4 v[216:217], off
	s_waitcnt vmcnt(8)
	s_waitcnt lgkmcnt(0)
	s_barrier
	s_waitcnt lgkmcnt(0)
	v_mfma_f32_16x16x32_bf16 v[60:63], v[146:149], v[184:187], v[60:63]
	v_mfma_f32_16x16x32_bf16 v[56:59], v[160:163], v[184:187], v[56:59]
	v_mfma_f32_16x16x32_bf16 v[44:47], v[146:149], v[192:195], v[44:47]
	v_mfma_f32_16x16x32_bf16 v[40:43], v[160:163], v[192:195], v[40:43]
	v_mfma_f32_16x16x32_bf16 v[28:31], v[146:149], v[200:203], v[28:31]
	v_mfma_f32_16x16x32_bf16 v[24:27], v[160:163], v[200:203], v[24:27]
	v_mfma_f32_16x16x32_bf16 v[12:15], v[146:149], v[208:211], v[12:15]
	v_mfma_f32_16x16x32_bf16 v[8:11], v[160:163], v[208:211], v[8:11]
	v_mfma_f32_16x16x32_bf16 v[60:63], v[156:159], v[188:191], v[60:63]
	v_mfma_f32_16x16x32_bf16 v[56:59], v[164:167], v[188:191], v[56:59]
	v_mfma_f32_16x16x32_bf16 v[44:47], v[156:159], v[196:199], v[44:47]
	v_mfma_f32_16x16x32_bf16 v[40:43], v[164:167], v[196:199], v[40:43]
	v_mfma_f32_16x16x32_bf16 v[28:31], v[156:159], v[204:207], v[28:31]
	v_mfma_f32_16x16x32_bf16 v[24:27], v[164:167], v[204:207], v[24:27]
	v_mfma_f32_16x16x32_bf16 v[12:15], v[156:159], v[212:215], v[12:15]
	v_mfma_f32_16x16x32_bf16 v[8:11], v[164:167], v[212:215], v[8:11]
	v_mfma_f32_16x16x32_bf16 v[52:55], v[168:171], v[184:187], v[52:55]
	v_mfma_f32_16x16x32_bf16 v[48:51], v[176:179], v[184:187], v[48:51]
	v_mfma_f32_16x16x32_bf16 v[36:39], v[168:171], v[192:195], v[36:39]
	v_mfma_f32_16x16x32_bf16 v[32:35], v[176:179], v[192:195], v[32:35]
	v_mfma_f32_16x16x32_bf16 v[20:23], v[168:171], v[200:203], v[20:23]
	v_mfma_f32_16x16x32_bf16 v[16:19], v[176:179], v[200:203], v[16:19]
	v_mfma_f32_16x16x32_bf16 v[4:7], v[168:171], v[208:211], v[4:7]
	v_mfma_f32_16x16x32_bf16 v[0:3], v[176:179], v[208:211], v[0:3]
	v_mfma_f32_16x16x32_bf16 v[52:55], v[172:175], v[188:191], v[52:55]
	v_mfma_f32_16x16x32_bf16 v[48:51], v[180:183], v[188:191], v[48:51]
	v_mfma_f32_16x16x32_bf16 v[36:39], v[172:175], v[196:199], v[36:39]
	v_mfma_f32_16x16x32_bf16 v[32:35], v[180:183], v[196:199], v[32:35]
	v_mfma_f32_16x16x32_bf16 v[20:23], v[172:175], v[204:207], v[20:23]
	v_mfma_f32_16x16x32_bf16 v[16:19], v[180:183], v[204:207], v[16:19]
	v_mfma_f32_16x16x32_bf16 v[4:7], v[172:175], v[212:215], v[4:7]
	v_mfma_f32_16x16x32_bf16 v[0:3], v[180:183], v[212:215], v[0:3]
	s_barrier
	s_add_i32 s94, s94, 2
	s_add_u32 s18, s18, 0x100
	s_addc_u32 s19, s19, 0
	s_add_u32 s71, s71, 0x100
	s_addc_u32 s93, s93, 0
	s_cmp_gt_u32 s94, 5
	s_cbranch_scc0 .LBB0_838
	s_and_b64 vcc, exec, s[66:67]
	s_cbranch_vccz .LBB0_841
	s_barrier

; __global__ void __launch_bounds__(512, 2) fwd_kernel(Params p) {
;     ...
;         if (P5SEL & 1) for (int it = vcu; it < 1024; it += G) {
;             att::AttnUnit U{};
;             const int qb = it & 15, bh = it >> 4, b = bh >> 3, h = bh & 7; const size_t r0 = (size_t)b * SEQ;
;             U.Q = Qm + (r0 + qb * 256) * 1536 + h * 192; U.K = KF + r0 * 1536 + h * 192; U.V = Vm + r0 * 1024 + h * 128; U.O = AO + (r0 + qb * 256) * 2048 + h * 128;
;             U.ldq = 1536; U.ldk = 1536; U.ldv = 1024; U.ldo = 2048; U.jt0 = 0; U.NT = 64; U.q0 = qb * 256;
;             U.C = 0.07216878364870322f * LOG2E; U.thr = 8.0f / 0.07216878364870322f;
;             U.wid = wave; att::attn_unit_dma<192, 0>(U, (char*)lds);
.LBB0_1015:
	s_add_u32 s80, s30, 0x32f00000
	s_addc_u32 s81, s31, 0
	s_cmp_lt_i32 s92, 6
	s_cselect_b64 s[0:1], -1, 0
	s_cmp_gt_i32 s93, 5
	s_cselect_b64 s[2:3], -1, 0
	s_cmpk_lt_i32 s8, 0x400
	s_cselect_b64 s[4:5], -1, 0
	s_and_b64 s[0:1], s[0:1], s[4:5]
	s_and_b64 s[0:1], s[0:1], s[2:3]
	s_andn2_b64 vcc, exec, s[0:1]
	s_waitcnt lgkmcnt(0)
	s_barrier
	s_cbranch_vccnz .LBB0_1064
	s_setprio 0
	s_add_u32 s40, s30, 0x2ef40000
	s_addc_u32 s41, s31, 0
	s_add_u32 s42, s30, 0x28f60000
	s_addc_u32 s43, s31, 0
	v_mov_b32_e32 v156, s89
	s_movk_i32 s48, 0x600
	s_mov_b32 s49, 0x2aaaaaab
	s_movk_i32 s50, 0xffe8
	s_movk_i32 s51, 0x70
	s_waitcnt vmcnt(0)
	v_mov_b32_e32 v0, 0
	s_mov_b32 s60, s8
	s_branch .LBB0_1018

; #define GEMM_RESID(Aop, Kdim, WT, XIN, ssi, ALPHA) do { pg8::Gemm g_{Aop, WT, T, DM, Kdim, Kdim}; pg8::StaticOrder S_; S_.init(T, DM, G, bx); pg8::EpiResid E_{XIN, p.out, XB, SS + (size_t)(ssi) * T, ALPHA}; \
;         pg8::gemm_phase<pg8::EpiResid, pg8::StaticOrder, true, true>(ldsl, g_, S_, E_, wave); } while (0)
;     __host__ __device__ bool next(int i, Unit& u) const {
;         const long L = (long)i * G + c; if (L >= nwg) return false;
;         int wgid = (int)L; { const int q = nwg / NXCD, r = nwg % NXCD, xcd = wgid % NXCD, off = wgid / NXCD; wgid = (xcd < r ? xcd * (q + 1) : r * (q + 1) + (xcd - r) * q) + off; }
;         const int nig = WGM * nN, gid = wgid / nig, fm = gid * WGM, gsz = (nM - fm) < WGM ? (nM - fm) : WGM;
;         u.pm = fm + ((wgid % nig) % gsz); u.pn = (wgid % nig) / gsz; return true;
; __global__ void __launch_bounds__(512, 2) fwd_kernel(Params p) {
;     ...
;     if (IN(7)) GEMM_RESID(AO, DM, W_O0, p.out, 2, 1.0f);
.LBB0_1283:
	s_cmp_lt_i32 s92, 8
	s_cselect_b64 s[0:1], -1, 0
	s_cmp_gt_i32 s93, 7
	s_cselect_b64 s[2:3], -1, 0
	s_and_b64 s[0:1], s[0:1], s[2:3]
	s_andn2_b64 vcc, exec, s[0:1]
	s_waitcnt lgkmcnt(0)
	s_barrier
	s_cbranch_vccnz .LBB0_1326
	s_setprio 0
	s_cmp_lt_u32 s89, 4
	s_cbranch_scc1 .Lgprio_3
	s_setprio 1
.Lgprio_3:
	s_cmpk_lt_i32 s88, 0x400
	s_cselect_b64 s[0:1], -1, 0
	s_cmpk_gt_i32 s88, 0x3ff
	s_waitcnt vmcnt(0)
	v_mbcnt_lo_u32_b32 v8, -1, 0
	v_mbcnt_hi_u32_b32 v8, -1, v8
	s_cbranch_scc1 .LBB0_1290
	s_ashr_i32 s2, s88, 31
	s_lshr_b32 s2, s2, 29
	s_add_i32 s4, s88, s2
	s_and_b32 s2, s4, -8
	s_sub_i32 s5, s88, s2
	s_cmp_gt_i32 s5, -1
	s_cbranch_scc0 .LBB0_1287
	s_lshl_b32 s6, s5, 7
	s_cbranch_execz .LBB0_1288
	s_branch .LBB0_1289

; #define PG8_STAGE(bufoff, gbase, voff) do { _Pragma("unroll") for (int _i = 0; _i < 2; ++_i) \
;         __builtin_amdgcn_global_load_lds((const unsigned*)((const char*)(gbase) + (voff)[_i]), (PG8_LAS unsigned*)(lds + (bufoff) + ldsw + _i * 8192), 16, 0, 0); } while (0)
; #define PG8_LDA(dst, b, h) do { _Pragma("unroll") for (int m = 0; m < 4; ++m) _Pragma("unroll") for (int k = 0; k < 2; ++k) dst[m][k] = *(const PG8_LAS bf16x8*)(lds + PG8_SA(b, h) + aoff + m * 2048 + k * 1024); } while (0)
; #define PG8_LDB(dst, b, h) do { _Pragma("unroll") for (int n = 0; n < 2; ++n) _Pragma("unroll") for (int k = 0; k < 2; ++k) dst[n][k] = *(const PG8_LAS bf16x8*)(lds + PG8_SB(b, h) + boff + n * 2048 + k * 1024); } while (0)
; #define PG8_MMA(ai, bj, At, Bt) do { __builtin_amdgcn_s_setprio(1); _Pragma("unroll") for (int m = 0; m < 4; ++m) _Pragma("unroll") for (int n = 0; n < 2; ++n) _Pragma("unroll") for (int k = 0; k < 2; ++k) \
;         acc[ai][bj][m][n] = __builtin_amdgcn_mfma_f32_16x16x32_bf16(Bt[n][k], At[m][k], acc[ai][bj][m][n], 0, 0, 0); __builtin_amdgcn_s_setprio(0); } while (0)
; #define PG8_WAIT_V(n) asm volatile("s_waitcnt vmcnt(" #n ")" ::: "memory")
; #define PG8_WAIT_L(n) asm volatile("s_waitcnt lgkmcnt(" #n ")" ::: "memory")
; #define PG8_BAR __builtin_amdgcn_s_barrier()
; #define PG8_SCHED __builtin_amdgcn_sched_barrier(0)
; template <class Epi, class Sched, bool ALIGN_EPI = false, bool SP2 = false>
; __device__ __forceinline__ void gemm_phase(PG8_LAS unsigned char* lds, const Gemm g, const Sched& S, const Epi& E, const int wave_in) {
;     ...
;             PG8_LDB(B0, 0, 0); PG8_LDB(B1, 0, 1); PG8_SCHED; PG8_LDA(At, 0, 0); PG8_STAGE(PG8_SA(1, 1), a1 + hstepA, voffA);
;             PG8_WAIT_V(8); PG8_WAIT_L(0); PG8_BAR; PG8_MMA(0, 0, At, B0); PG8_MMA(0, 1, At, B1); PG8_BAR; PG8_SCHED;
;             PG8_LDA(At, 0, 1); PG8_STAGE(PG8_SB(0, 0), b2, voffB); PG8_STAGE(PG8_SB(0, 1), b2 + hstep, voffB); PG8_STAGE(PG8_SA(0, 0), a2, voffA);
.LBB0_1303:
	ds_read_b128 v[144:147], v151
	ds_read_b128 v[156:159], v151 offset:1024
	ds_read_b128 v[160:163], v151 offset:2048
	ds_read_b128 v[164:167], v151 offset:3072
	ds_read_b128 v[168:171], v152
	ds_read_b128 v[172:175], v152 offset:1024
	ds_read_b128 v[176:179], v152 offset:2048
	ds_read_b128 v[180:183], v152 offset:3072
	s_add_u32 s68, s66, 0xfff80080
	s_addc_u32 s69, s67, -1
	s_cmp_eq_u32 s78, 28
	s_cselect_b32 s71, s43, s69
	s_cselect_b32 s70, s48, s68
	s_cselect_b32 s69, s41, s77
	s_cselect_b32 s68, s49, s76
	v_lshl_add_u64 v[216:217], s[66:67], 0, v[136:137]
	s_add_i32 m0, s33, 0xc000
	ds_read_b128 v[184:187], v153
	ds_read_b128 v[188:191], v153 offset:1024
	ds_read_b128 v[192:195], v153 offset:2048
	ds_read_b128 v[196:199], v153 offset:3072
	ds_read_b128 v[200:203], v153 offset:4096
	ds_read_b128 v[204:207], v153 offset:5120
	ds_read_b128 v[208:211], v153 offset:6144
	ds_read_b128 v[212:215], v153 offset:7168
	global_load_lds_dwordx4 v[216:217], off
	v_lshl_add_u64 v[216:217], s[66:67], 0, v[138:139]
	s_add_i32 m0, s33, 0xe000
	s_nop 0
	global_load_lds_dwordx4 v[216:217], off
	s_waitcnt vmcnt(8)
	s_waitcnt lgkmcnt(0)
	s_barrier
	s_waitcnt lgkmcnt(0)
	v_mfma_f32_16x16x32_bf16 v[124:127], v[144:147], v[184:187], v[124:127]
	v_mfma_f32_16x16x32_bf16 v[120:123], v[160:163], v[184:187], v[120:123]
	v_mfma_f32_16x16x32_bf16 v[108:111], v[144:147], v[192:195], v[108:111]
	v_mfma_f32_16x16x32_bf16 v[104:107], v[160:163], v[192:195], v[104:107]
	v_mfma_f32_16x16x32_bf16 v[92:95], v[144:147], v[200:203], v[92:95]
	v_mfma_f32_16x16x32_bf16 v[88:91], v[160:163], v[200:203], v[88:91]
	v_mfma_f32_16x16x32_bf16 v[76:79], v[144:147], v[208:211], v[76:79]
	v_mfma_f32_16x16x32_bf16 v[72:75], v[160:163], v[208:211], v[72:75]
	v_mfma_f32_16x16x32_bf16 v[124:127], v[156:159], v[188:191], v[124:127]
	v_mfma_f32_16x16x32_bf16 v[120:123], v[164:167], v[188:191], v[120:123]
	v_mfma_f32_16x16x32_bf16 v[108:111], v[156:159], v[196:199], v[108:111]
	v_mfma_f32_16x16x32_bf16 v[104:107], v[164:167], v[196:199], v[104:107]
	v_mfma_f32_16x16x32_bf16 v[92:95], v[156:159], v[204:207], v[92:95]
	v_mfma_f32_16x16x32_bf16 v[88:91], v[164:167], v[204:207], v[88:91]
	v_mfma_f32_16x16x32_bf16 v[76:79], v[156:159], v[212:215], v[76:79]
	v_mfma_f32_16x16x32_bf16 v[72:75], v[164:167], v[212:215], v[72:75]
	v_mfma_f32_16x16x32_bf16 v[116:119], v[168:171], v[184:187], v[116:119]
	v_mfma_f32_16x16x32_bf16 v[112:115], v[176:179], v[184:187], v[112:115]
	v_mfma_f32_16x16x32_bf16 v[100:103], v[168:171], v[192:195], v[100:103]
	v_mfma_f32_16x16x32_bf16 v[96:99], v[176:179], v[192:195], v[96:99]
	v_mfma_f32_16x16x32_bf16 v[84:87], v[168:171], v[200:203], v[84:87]
	v_mfma_f32_16x16x32_bf16 v[80:83], v[176:179], v[200:203], v[80:83]
	v_mfma_f32_16x16x32_bf16 v[68:71], v[168:171], v[208:211], v[68:71]
	v_mfma_f32_16x16x32_bf16 v[64:67], v[176:179], v[208:211], v[64:67]
	v_mfma_f32_16x16x32_bf16 v[116:119], v[172:175], v[188:191], v[116:119]
	v_mfma_f32_16x16x32_bf16 v[112:115], v[180:183], v[188:191], v[112:115]
	v_mfma_f32_16x16x32_bf16 v[100:103], v[172:175], v[196:199], v[100:103]
	v_mfma_f32_16x16x32_bf16 v[96:99], v[180:183], v[196:199], v[96:99]
	v_mfma_f32_16x16x32_bf16 v[84:87], v[172:175], v[204:207], v[84:87]
	v_mfma_f32_16x16x32_bf16 v[80:83], v[180:183], v[204:207], v[80:83]
	v_mfma_f32_16x16x32_bf16 v[68:71], v[172:175], v[212:215], v[68:71]
	v_mfma_f32_16x16x32_bf16 v[64:67], v[180:183], v[212:215], v[64:67]
	s_barrier
	s_add_i32 s79, s74, s11
	v_lshl_add_u64 v[216:217], s[68:69], 0, v[130:131]
	s_mov_b32 m0, s79
	ds_read_b128 v[184:187], v153 offset:16384
	ds_read_b128 v[188:191], v153 offset:17408
	ds_read_b128 v[192:195], v153 offset:18432
	ds_read_b128 v[196:199], v153 offset:19456
	ds_read_b128 v[200:203], v153 offset:20480
	ds_read_b128 v[204:207], v153 offset:21504
	ds_read_b128 v[208:211], v153 offset:22528
	ds_read_b128 v[212:215], v153 offset:23552
	global_load_lds_dwordx4 v[216:217], off
	s_add_i32 m0, s79, 0x2000
	s_add_u32 s82, s68, 0x80000
	v_lshl_add_u64 v[218:219], s[68:69], 0, v[134:135]
	s_addc_u32 s83, s69, 0
	s_add_i32 s79, s75, s11
	global_load_lds_dwordx4 v[218:219], off
	v_lshl_add_u64 v[220:221], s[82:83], 0, v[130:131]
	s_mov_b32 m0, s79
	v_lshl_add_u64 v[222:223], s[70:71], 0, v[132:133]
	global_load_lds_dwordx4 v[220:221], off
	v_lshl_add_u64 v[220:221], s[82:83], 0, v[134:135]
	s_add_i32 m0, s79, 0x2000
	s_nop 0
	global_load_lds_dwordx4 v[220:221], off
	v_lshl_add_u64 v[220:221], s[70:71], 0, v[128:129]
	s_mov_b32 m0, s33
	s_nop 0
	global_load_lds_dwordx4 v[220:221], off
	s_mov_b32 m0, s35
	s_nop 0
	global_load_lds_dwordx4 v[222:223], off
	s_waitcnt vmcnt(8)
	s_waitcnt lgkmcnt(0)
	s_barrier
; #define PG8_STAGE(bufoff, gbase, voff) do { _Pragma("unroll") for (int _i = 0; _i < 2; ++_i) \
;         __builtin_amdgcn_global_load_lds((const unsigned*)((const char*)(gbase) + (voff)[_i]), (PG8_LAS unsigned*)(lds + (bufoff) + ldsw + _i * 8192), 16, 0, 0); } while (0)
; #define PG8_LDA(dst, b, h) do { _Pragma("unroll") for (int m = 0; m < 4; ++m) _Pragma("unroll") for (int k = 0; k < 2; ++k) dst[m][k] = *(const PG8_LAS bf16x8*)(lds + PG8_SA(b, h) + aoff + m * 2048 + k * 1024); } while (0)
; #define PG8_LDB(dst, b, h) do { _Pragma("unroll") for (int n = 0; n < 2; ++n) _Pragma("unroll") for (int k = 0; k < 2; ++k) dst[n][k] = *(const PG8_LAS bf16x8*)(lds + PG8_SB(b, h) + boff + n * 2048 + k * 1024); } while (0)
; #define PG8_MMA(ai, bj, At, Bt) do { __builtin_amdgcn_s_setprio(1); _Pragma("unroll") for (int m = 0; m < 4; ++m) _Pragma("unroll") for (int n = 0; n < 2; ++n) _Pragma("unroll") for (int k = 0; k < 2; ++k) \
;         acc[ai][bj][m][n] = __builtin_amdgcn_mfma_f32_16x16x32_bf16(Bt[n][k], At[m][k], acc[ai][bj][m][n], 0, 0, 0); __builtin_amdgcn_s_setprio(0); } while (0)
; #define PG8_WAIT_V(n) asm volatile("s_waitcnt vmcnt(" #n ")" ::: "memory")
; #define PG8_WAIT_L(n) asm volatile("s_waitcnt lgkmcnt(" #n ")" ::: "memory")
; #define PG8_BAR __builtin_amdgcn_s_barrier()
; #define PG8_SCHED __builtin_amdgcn_sched_barrier(0)
; template <class Epi, class Sched, bool ALIGN_EPI = false, bool SP2 = false>
; __device__ __forceinline__ void gemm_phase(PG8_LAS unsigned char* lds, const Gemm g, const Sched& S, const Epi& E, const int wave_in) {
;     ...
;             PG8_WAIT_V(8); PG8_WAIT_L(0); PG8_BAR; PG8_MMA(1, 0, At, B0); PG8_MMA(1, 1, At, B1); PG8_BAR; PG8_SCHED;
;             PG8_LDB(B0, 1, 0); PG8_LDB(B1, 1, 1); PG8_SCHED; PG8_LDA(At, 1, 0); PG8_STAGE(PG8_SA(0, 1), a2 + hstepA, voffA);
;             PG8_WAIT_V(8); PG8_WAIT_L(0); PG8_BAR; PG8_MMA(0, 0, At, B0); PG8_MMA(0, 1, At, B1); PG8_BAR; PG8_SCHED;
	s_waitcnt lgkmcnt(0)
	v_mfma_f32_16x16x32_bf16 v[60:63], v[144:147], v[184:187], v[60:63]
	v_mfma_f32_16x16x32_bf16 v[56:59], v[160:163], v[184:187], v[56:59]
	v_mfma_f32_16x16x32_bf16 v[44:47], v[144:147], v[192:195], v[44:47]
	v_mfma_f32_16x16x32_bf16 v[40:43], v[160:163], v[192:195], v[40:43]
	v_mfma_f32_16x16x32_bf16 v[28:31], v[144:147], v[200:203], v[28:31]
	v_mfma_f32_16x16x32_bf16 v[24:27], v[160:163], v[200:203], v[24:27]
	v_mfma_f32_16x16x32_bf16 v[12:15], v[144:147], v[208:211], v[12:15]
	v_mfma_f32_16x16x32_bf16 v[8:11], v[160:163], v[208:211], v[8:11]
	v_mfma_f32_16x16x32_bf16 v[60:63], v[156:159], v[188:191], v[60:63]
	v_mfma_f32_16x16x32_bf16 v[56:59], v[164:167], v[188:191], v[56:59]
	v_mfma_f32_16x16x32_bf16 v[44:47], v[156:159], v[196:199], v[44:47]
	v_mfma_f32_16x16x32_bf16 v[40:43], v[164:167], v[196:199], v[40:43]
	v_mfma_f32_16x16x32_bf16 v[28:31], v[156:159], v[204:207], v[28:31]
	v_mfma_f32_16x16x32_bf16 v[24:27], v[164:167], v[204:207], v[24:27]
	v_mfma_f32_16x16x32_bf16 v[12:15], v[156:159], v[212:215], v[12:15]
	v_mfma_f32_16x16x32_bf16 v[8:11], v[164:167], v[212:215], v[8:11]
	v_mfma_f32_16x16x32_bf16 v[52:55], v[168:171], v[184:187], v[52:55]
	v_mfma_f32_16x16x32_bf16 v[48:51], v[176:179], v[184:187], v[48:51]
	v_mfma_f32_16x16x32_bf16 v[36:39], v[168:171], v[192:195], v[36:39]
	v_mfma_f32_16x16x32_bf16 v[32:35], v[176:179], v[192:195], v[32:35]
	v_mfma_f32_16x16x32_bf16 v[20:23], v[168:171], v[200:203], v[20:23]
	v_mfma_f32_16x16x32_bf16 v[16:19], v[176:179], v[200:203], v[16:19]
	v_mfma_f32_16x16x32_bf16 v[4:7], v[168:171], v[208:211], v[4:7]
	v_mfma_f32_16x16x32_bf16 v[0:3], v[176:179], v[208:211], v[0:3]
	v_mfma_f32_16x16x32_bf16 v[52:55], v[172:175], v[188:191], v[52:55]
	v_mfma_f32_16x16x32_bf16 v[48:51], v[180:183], v[188:191], v[48:51]
	v_mfma_f32_16x16x32_bf16 v[36:39], v[172:175], v[196:199], v[36:39]
	v_mfma_f32_16x16x32_bf16 v[32:35], v[180:183], v[196:199], v[32:35]
	v_mfma_f32_16x16x32_bf16 v[20:23], v[172:175], v[204:207], v[20:23]
	v_mfma_f32_16x16x32_bf16 v[16:19], v[180:183], v[204:207], v[16:19]
	v_mfma_f32_16x16x32_bf16 v[4:7], v[172:175], v[212:215], v[4:7]
	v_mfma_f32_16x16x32_bf16 v[0:3], v[180:183], v[212:215], v[0:3]
	s_barrier
	s_add_i32 s79, 0, 0x18000
	v_add_u32_e32 v155, s79, v149
	s_add_i32 s82, 0, 0x1c000
	ds_read_b128 v[144:147], v155
	ds_read_b128 v[156:159], v155 offset:1024
	ds_read_b128 v[160:163], v155 offset:2048
	ds_read_b128 v[164:167], v155 offset:3072
	v_add_u32_e32 v155, s82, v149
	ds_read_b128 v[168:171], v155
	ds_read_b128 v[172:175], v155 offset:1024
	ds_read_b128 v[176:179], v155 offset:2048
	ds_read_b128 v[180:183], v155 offset:3072
	s_add_u32 s70, s70, 0x80000
	s_addc_u32 s71, s71, 0
	s_mov_b32 m0, s50
	v_lshl_add_u64 v[224:225], s[70:71], 0, v[128:129]
	ds_read_b128 v[184:187], v153 offset:32768
	ds_read_b128 v[188:191], v153 offset:33792
	ds_read_b128 v[192:195], v153 offset:34816
	ds_read_b128 v[196:199], v153 offset:35840
	ds_read_b128 v[200:203], v153 offset:36864
	ds_read_b128 v[204:207], v153 offset:37888
	ds_read_b128 v[208:211], v153 offset:38912
	ds_read_b128 v[212:215], v153 offset:39936
	global_load_lds_dwordx4 v[224:225], off
	v_lshl_add_u64 v[224:225], s[70:71], 0, v[132:133]
	s_mov_b32 m0, s51
	s_nop 0
	global_load_lds_dwordx4 v[224:225], off
	s_waitcnt vmcnt(8)
	s_waitcnt lgkmcnt(0)
	s_barrier
	s_waitcnt lgkmcnt(0)
	v_mfma_f32_16x16x32_bf16 v[124:127], v[144:147], v[184:187], v[124:127]
	v_mfma_f32_16x16x32_bf16 v[120:123], v[160:163], v[184:187], v[120:123]
	v_mfma_f32_16x16x32_bf16 v[108:111], v[144:147], v[192:195], v[108:111]
	v_mfma_f32_16x16x32_bf16 v[104:107], v[160:163], v[192:195], v[104:107]
	v_mfma_f32_16x16x32_bf16 v[92:95], v[144:147], v[200:203], v[92:95]
	v_mfma_f32_16x16x32_bf16 v[88:91], v[160:163], v[200:203], v[88:91]
	v_mfma_f32_16x16x32_bf16 v[76:79], v[144:147], v[208:211], v[76:79]
	v_mfma_f32_16x16x32_bf16 v[72:75], v[160:163], v[208:211], v[72:75]
	v_mfma_f32_16x16x32_bf16 v[124:127], v[156:159], v[188:191], v[124:127]
	v_mfma_f32_16x16x32_bf16 v[120:123], v[164:167], v[188:191], v[120:123]
	v_mfma_f32_16x16x32_bf16 v[108:111], v[156:159], v[196:199], v[108:111]
	v_mfma_f32_16x16x32_bf16 v[104:107], v[164:167], v[196:199], v[104:107]
	v_mfma_f32_16x16x32_bf16 v[92:95], v[156:159], v[204:207], v[92:95]
	v_mfma_f32_16x16x32_bf16 v[88:91], v[164:167], v[204:207], v[88:91]
	v_mfma_f32_16x16x32_bf16 v[76:79], v[156:159], v[212:215], v[76:79]
	v_mfma_f32_16x16x32_bf16 v[72:75], v[164:167], v[212:215], v[72:75]
	v_mfma_f32_16x16x32_bf16 v[116:119], v[168:171], v[184:187], v[116:119]
	v_mfma_f32_16x16x32_bf16 v[112:115], v[176:179], v[184:187], v[112:115]
	v_mfma_f32_16x16x32_bf16 v[100:103], v[168:171], v[192:195], v[100:103]
	v_mfma_f32_16x16x32_bf16 v[96:99], v[176:179], v[192:195], v[96:99]
	v_mfma_f32_16x16x32_bf16 v[84:87], v[168:171], v[200:203], v[84:87]
	v_mfma_f32_16x16x32_bf16 v[80:83], v[176:179], v[200:203], v[80:83]
	v_mfma_f32_16x16x32_bf16 v[68:71], v[168:171], v[208:211], v[68:71]
	v_mfma_f32_16x16x32_bf16 v[64:67], v[176:179], v[208:211], v[64:67]
	v_mfma_f32_16x16x32_bf16 v[116:119], v[172:175], v[188:191], v[116:119]
	v_mfma_f32_16x16x32_bf16 v[112:115], v[180:183], v[188:191], v[112:115]
	v_mfma_f32_16x16x32_bf16 v[100:103], v[172:175], v[196:199], v[100:103]
	v_mfma_f32_16x16x32_bf16 v[96:99], v[180:183], v[196:199], v[96:99]
	v_mfma_f32_16x16x32_bf16 v[84:87], v[172:175], v[204:207], v[84:87]
	v_mfma_f32_16x16x32_bf16 v[80:83], v[180:183], v[204:207], v[80:83]
	v_mfma_f32_16x16x32_bf16 v[68:71], v[172:175], v[212:215], v[68:71]
	v_mfma_f32_16x16x32_bf16 v[64:67], v[180:183], v[212:215], v[64:67]
	s_barrier
; #define PG8_STAGE(bufoff, gbase, voff) do { _Pragma("unroll") for (int _i = 0; _i < 2; ++_i) \
;         __builtin_amdgcn_global_load_lds((const unsigned*)((const char*)(gbase) + (voff)[_i]), (PG8_LAS unsigned*)(lds + (bufoff) + ldsw + _i * 8192), 16, 0, 0); } while (0)
; #define PG8_LDA(dst, b, h) do { _Pragma("unroll") for (int m = 0; m < 4; ++m) _Pragma("unroll") for (int k = 0; k < 2; ++k) dst[m][k] = *(const PG8_LAS bf16x8*)(lds + PG8_SA(b, h) + aoff + m * 2048 + k * 1024); } while (0)
; #define PG8_MMA(ai, bj, At, Bt) do { __builtin_amdgcn_s_setprio(1); _Pragma("unroll") for (int m = 0; m < 4; ++m) _Pragma("unroll") for (int n = 0; n < 2; ++n) _Pragma("unroll") for (int k = 0; k < 2; ++k) \
;         acc[ai][bj][m][n] = __builtin_amdgcn_mfma_f32_16x16x32_bf16(Bt[n][k], At[m][k], acc[ai][bj][m][n], 0, 0, 0); __builtin_amdgcn_s_setprio(0); } while (0)
; #define PG8_WAIT_V(n) asm volatile("s_waitcnt vmcnt(" #n ")" ::: "memory")
; #define PG8_WAIT_L(n) asm volatile("s_waitcnt lgkmcnt(" #n ")" ::: "memory")
; #define PG8_BAR __builtin_amdgcn_s_barrier()
; #define PG8_SCHED __builtin_amdgcn_sched_barrier(0)
; template <class Epi, class Sched, bool ALIGN_EPI = false, bool SP2 = false>
; __device__ __forceinline__ void gemm_phase(PG8_LAS unsigned char* lds, const Gemm g, const Sched& S, const Epi& E, const int wave_in) {
;     ...
;             PG8_LDA(At, 1, 1); PG8_STAGE(PG8_SB(1, 0), b3, voffB); PG8_STAGE(PG8_SB(1, 1), b3 + hstep, voffB); PG8_STAGE(PG8_SA(1, 0), a3, voffA);
;             PG8_WAIT_V(8); PG8_WAIT_L(0); PG8_BAR; PG8_MMA(1, 0, At, B0); PG8_MMA(1, 1, At, B1); PG8_BAR; PG8_SCHED;
	s_add_i32 s70, s79, s11
	v_lshl_add_u64 v[216:217], v[216:217], 0, s[18:19]
	s_mov_b32 m0, s70
	ds_read_b128 v[184:187], v153 offset:49152
	ds_read_b128 v[188:191], v153 offset:50176
	ds_read_b128 v[192:195], v153 offset:51200
	ds_read_b128 v[196:199], v153 offset:52224
	ds_read_b128 v[200:203], v153 offset:53248
	ds_read_b128 v[204:207], v153 offset:54272
	ds_read_b128 v[208:211], v153 offset:55296
	ds_read_b128 v[212:215], v153 offset:56320
	global_load_lds_dwordx4 v[216:217], off
	s_add_i32 m0, s70, 0x2000
	s_add_u32 s68, s68, 0x80080
	v_lshl_add_u64 v[216:217], v[218:219], 0, s[18:19]
	s_addc_u32 s69, s69, 0
	s_add_i32 s70, s82, s11
	global_load_lds_dwordx4 v[216:217], off
	v_lshl_add_u64 v[216:217], s[68:69], 0, v[130:131]
	s_mov_b32 m0, s70
	s_nop 0
	global_load_lds_dwordx4 v[216:217], off
	v_lshl_add_u64 v[216:217], s[68:69], 0, v[134:135]
	s_add_i32 m0, s70, 0x2000
	s_nop 0
	global_load_lds_dwordx4 v[216:217], off
	v_lshl_add_u64 v[216:217], v[220:221], 0, s[18:19]
	s_mov_b32 m0, s65
	s_nop 0
	global_load_lds_dwordx4 v[216:217], off
	v_lshl_add_u64 v[216:217], v[222:223], 0, s[18:19]
	s_mov_b32 m0, s72
	s_nop 0
	global_load_lds_dwordx4 v[216:217], off
	s_waitcnt vmcnt(8)
	s_waitcnt lgkmcnt(0)
	s_barrier
	s_waitcnt lgkmcnt(0)
	v_mfma_f32_16x16x32_bf16 v[60:63], v[144:147], v[184:187], v[60:63]
	v_mfma_f32_16x16x32_bf16 v[56:59], v[160:163], v[184:187], v[56:59]
	v_mfma_f32_16x16x32_bf16 v[44:47], v[144:147], v[192:195], v[44:47]
	v_mfma_f32_16x16x32_bf16 v[40:43], v[160:163], v[192:195], v[40:43]
	v_mfma_f32_16x16x32_bf16 v[28:31], v[144:147], v[200:203], v[28:31]
	v_mfma_f32_16x16x32_bf16 v[24:27], v[160:163], v[200:203], v[24:27]
	v_mfma_f32_16x16x32_bf16 v[12:15], v[144:147], v[208:211], v[12:15]
	v_mfma_f32_16x16x32_bf16 v[8:11], v[160:163], v[208:211], v[8:11]
	v_mfma_f32_16x16x32_bf16 v[60:63], v[156:159], v[188:191], v[60:63]
	v_mfma_f32_16x16x32_bf16 v[56:59], v[164:167], v[188:191], v[56:59]
	v_mfma_f32_16x16x32_bf16 v[44:47], v[156:159], v[196:199], v[44:47]
	v_mfma_f32_16x16x32_bf16 v[40:43], v[164:167], v[196:199], v[40:43]
	v_mfma_f32_16x16x32_bf16 v[28:31], v[156:159], v[204:207], v[28:31]
	v_mfma_f32_16x16x32_bf16 v[24:27], v[164:167], v[204:207], v[24:27]
	v_mfma_f32_16x16x32_bf16 v[12:15], v[156:159], v[212:215], v[12:15]
	v_mfma_f32_16x16x32_bf16 v[8:11], v[164:167], v[212:215], v[8:11]
	v_mfma_f32_16x16x32_bf16 v[52:55], v[168:171], v[184:187], v[52:55]
	v_mfma_f32_16x16x32_bf16 v[48:51], v[176:179], v[184:187], v[48:51]
	v_mfma_f32_16x16x32_bf16 v[36:39], v[168:171], v[192:195], v[36:39]
	v_mfma_f32_16x16x32_bf16 v[32:35], v[176:179], v[192:195], v[32:35]
	v_mfma_f32_16x16x32_bf16 v[20:23], v[168:171], v[200:203], v[20:23]
	v_mfma_f32_16x16x32_bf16 v[16:19], v[176:179], v[200:203], v[16:19]
	v_mfma_f32_16x16x32_bf16 v[4:7], v[168:171], v[208:211], v[4:7]
	v_mfma_f32_16x16x32_bf16 v[0:3], v[176:179], v[208:211], v[0:3]
	v_mfma_f32_16x16x32_bf16 v[52:55], v[172:175], v[188:191], v[52:55]
	v_mfma_f32_16x16x32_bf16 v[48:51], v[180:183], v[188:191], v[48:51]
	v_mfma_f32_16x16x32_bf16 v[36:39], v[172:175], v[196:199], v[36:39]
	v_mfma_f32_16x16x32_bf16 v[32:35], v[180:183], v[196:199], v[32:35]
	v_mfma_f32_16x16x32_bf16 v[20:23], v[172:175], v[204:207], v[20:23]
	v_mfma_f32_16x16x32_bf16 v[16:19], v[180:183], v[204:207], v[16:19]
	v_mfma_f32_16x16x32_bf16 v[4:7], v[172:175], v[212:215], v[4:7]
	v_mfma_f32_16x16x32_bf16 v[0:3], v[180:183], v[212:215], v[0:3]
	s_barrier
	s_add_i32 s78, s78, 2
	s_add_u32 s66, s66, 0x100
	s_addc_u32 s67, s67, 0
	s_add_u32 s76, s76, 0x100
	s_addc_u32 s77, s77, 0
	s_cmp_gt_u32 s78, 29
	s_cbranch_scc0 .LBB0_1303
	s_and_b64 vcc, exec, s[38:39]
	s_cbranch_vccz .LBB0_1306
	s_barrier

; __device__ __forceinline__ int mk_lane() { int l; asm volatile("v_mbcnt_lo_u32_b32 %0, -1, 0\n\tv_mbcnt_hi_u32_b32 %0, -1, %0" : "=v"(l)); return l; }
; #define PG8_STAGE(bufoff, gbase, voff) do { _Pragma("unroll") for (int _i = 0; _i < 2; ++_i) \
;         __builtin_amdgcn_global_load_lds((const unsigned*)((const char*)(gbase) + (voff)[_i]), (PG8_LAS unsigned*)(lds + (bufoff) + ldsw + _i * 8192), 16, 0, 0); } while (0)
; #define PG8_WAIT_V(n) asm volatile("s_waitcnt vmcnt(" #n ")" ::: "memory")
; #define lane mk_lane()
; template <class Epi, class Sched, bool ALIGN_EPI = false, bool SP2 = false>
; __device__ __forceinline__ void gemm_phase(PG8_LAS unsigned char* lds, const Gemm g, const Sched& S, const Epi& E, const int wave_in) {
;     const int wid = __builtin_amdgcn_readfirstlane(wave_in), lane = mk_lane(), tid = wid * 64 + lane, wr = wid >> 2, wc = wid & 3, fr = lane & 15, fq = lane >> 4;
;     const int K = g.K, nt = K / BK;
;     unsigned voffA[2], voffB[2];
; #pragma unroll
;     for (int i = 0; i < 2; ++i) { int R, C; stage_rc(tid * 16 + i * 8192, R, C); const int Rb = Epi::PERM ? ((R & ~31) + perm32(R & 31)) : R;
;         voffA[i] = (unsigned)(R * g.lda + C) * 2u; voffB[i] = (unsigned)(Rb * K + C) * 2u; }
;     const size_t kstep = (size_t)(BK * 2);
;     const size_t hstep = (size_t)HALF * K * 2, hstepA = (size_t)HALF * g.lda * 2;
;     const size_t tstep = 2 * hstep, tstepA = 2 * hstepA;
;     const unsigned ldsw = (unsigned)wid * 1024u;
;     const int aoff = lds_byte(wr * 64 + fr, fq * 8), boff = lds_byte(wc * 32 + fr, fq * 8);
;     ...
;     Unit cur, nxt; int ui = 0;
;     if (!S.next(0, cur)) return;
;     f32x4 acc[2][2][4][2];
; #pragma unroll
;     for (int a = 0; a < 2; ++a)
; #pragma unroll
;         for (int b = 0; b < 2; ++b)
; #pragma unroll
;             for (int m = 0; m < 4; ++m)
; #pragma unroll
;                 for (int n = 0; n < 2; ++n) acc[a][b][m][n] = (f32x4){0.f, 0.f, 0.f, 0.f};
;     bf16x8 At[4][2], B0[2][2], B1[2][2];
;     const char* cA = (const char*)g.A + (size_t)cur.pm * tstepA; const char* cB = (const char*)g.Bt + (size_t)cur.pn * tstep;
;     S.a_ready(cur);
;     if constexpr (SP2) {
;         PG8_STAGE(PG8_SB(0, 0), cB, voffB); PG8_STAGE(PG8_SB(0, 1), cB + hstep, voffB); PG8_STAGE(PG8_SA(0, 0), cA, voffA); PG8_STAGE(PG8_SA(0, 1), cA + hstepA, voffA);
;         if (wr == 1) PG8_BAR;
;         PG8_WAIT_V(2); PG8_BAR;
.LBB0_1380:
	s_cmp_lt_i32 s92, 9
	s_cselect_b64 s[0:1], -1, 0
	s_cmp_gt_i32 s93, 8
	s_cselect_b64 s[2:3], -1, 0
	s_and_b64 s[0:1], s[0:1], s[2:3]
	s_andn2_b64 vcc, exec, s[0:1]
	s_waitcnt lgkmcnt(0)
	s_barrier
	s_cbranch_vccnz .LBB0_1397
	s_setprio 0
	s_cmp_lt_u32 s89, 4
	s_cbranch_scc1 .Lgprio_4
	s_setprio 1
.Lgprio_4:
	s_cmpk_gt_i32 s88, 0x15ff
	s_waitcnt vmcnt(0)
	v_mbcnt_lo_u32_b32 v10, -1, 0
	v_mbcnt_hi_u32_b32 v10, -1, v10
	s_cbranch_scc1 .LBB0_1397
	s_lshl_b32 s11, s89, 10
	v_lshl_add_u32 v0, v10, 4, s11
	v_add_u32_e32 v1, 0x2000, v0
	v_ashrrev_i32_e32 v2, 31, v1
	v_lshrrev_b32_e32 v2, 22, v2
	v_add_u32_e32 v2, v1, v2
	v_ashrrev_i32_e32 v8, 10, v2
	v_mul_i32_i24_e32 v2, 0x400, v8
	v_sub_u32_e32 v1, v1, v2
	v_lshrrev_b32_e32 v2, 4, v1
	v_bitop3_b32 v1, v2, v1, 32 bitop3:0x6c
	v_ashrrev_i32_e32 v2, 31, v1
	v_lshrrev_b32_e32 v2, 26, v2
	v_add_u32_e32 v2, v1, v2
	v_ashrrev_i32_e32 v9, 6, v2
	v_lshlrev_b32_e32 v3, 3, v8
	v_and_b32_e32 v2, 0xffc0, v2
	v_and_b32_e32 v3, -16, v3
	v_sub_u32_e32 v1, v1, v2
	v_add_u32_e32 v3, v9, v3
	v_lshrrev_b16_e32 v2, 7, v1
	v_and_b32_e32 v4, 3, v9
	s_mov_b32 s0, 0xfffe0
	v_lshrrev_b32_e32 v5, 2, v3
	v_lshlrev_b32_e32 v6, 1, v3
	v_and_b32_e32 v2, 1, v2
	v_and_or_b32 v4, v3, s0, v4
	v_and_b32_e32 v5, 4, v5
	v_and_b32_e32 v6, 24, v6
	v_add_u16_e32 v1, v1, v2
	v_mov_b32_e32 v2, 1
	v_or3_b32 v4, v4, v5, v6
	v_lshlrev_b32_e32 v5, 5, v8
	v_ashrrev_i16_sdwa v1, v2, sext(v1) dst_sel:DWORD dst_unused:UNUSED_PAD src0_sel:DWORD src1_sel:BYTE_0
	v_and_b32_e32 v5, 32, v5
	v_bfe_i32 v11, v1, 0, 16
	v_add_lshl_u32 v1, v5, v11, 1
	v_lshl_add_u32 v128, v4, 12, v1
	v_lshl_add_u32 v130, v3, 12, v1
	v_ashrrev_i32_e32 v1, 31, v0
	v_lshrrev_b32_e32 v1, 22, v1
	v_add_u32_e32 v1, v0, v1
	v_ashrrev_i32_e32 v12, 10, v1
	v_mul_i32_i24_e32 v1, 0x400, v12
	v_sub_u32_e32 v0, v0, v1
	v_lshrrev_b32_e32 v1, 4, v0
	v_bitop3_b32 v0, v1, v0, 32 bitop3:0x6c
	v_ashrrev_i32_e32 v1, 31, v0
	v_lshrrev_b32_e32 v1, 26, v1
	v_add_u32_e32 v1, v0, v1
	v_lshlrev_b32_e32 v3, 3, v12
	v_ashrrev_i32_e32 v13, 6, v1
	v_and_b32_e32 v3, -16, v3
	v_add_u32_e32 v3, v13, v3
	v_and_b32_e32 v4, 3, v13
	s_ashr_i32 s33, s88, 31
	v_and_or_b32 v4, v3, s0, v4
	s_lshr_b32 s0, s33, 29
	s_add_i32 s0, s88, s0
	s_ashr_i32 s1, s0, 3
	s_and_b32 s0, s0, -8
	s_ashr_i32 s3, s89, 2
	s_sub_i32 s0, s88, s0
	s_cmp_lt_i32 s0, 0
	s_movk_i32 s35, 0x2c1
	s_cselect_b32 s2, s35, 0x2c0
	s_mul_i32 s0, s0, s2
	s_add_i32 s0, s0, s1
	s_mul_hi_i32 s1, s0, 0x2e8ba2e9
	s_lshr_b32 s2, s1, 31
	s_ashr_i32 s1, s1, 6
	s_add_i32 s1, s1, s2
	s_lshl_b32 s4, s1, 3
	s_mulk_i32 s1, 0x160
	s_sub_i32 s0, s0, s1
	s_sext_i32_i16 s1, s0
	s_bfe_u32 s1, s1, 0x3001c
	s_add_i32 s1, s0, s1
	s_sext_i32_i16 s2, s1
	s_and_b32 s1, s1, 0xfff8
	s_sub_i32 s0, s0, s1
	s_sext_i32_i16 s0, s0
	v_lshrrev_b32_e32 v5, 2, v3
	v_lshlrev_b32_e32 v6, 1, v3
	v_and_b32_e32 v1, 0xc0, v1
	s_lshr_b32 s2, s2, 3
	s_add_i32 s60, s4, s0
	v_and_b32_e32 v5, 4, v5
	v_and_b32_e32 v6, 24, v6
	v_sub_u32_e32 v0, v0, v1
	s_ashr_i32 s61, s60, 31
	s_bfe_i64 s[4:5], s[2:3], 0x100000
	v_or3_b32 v4, v4, v5, v6
	v_lshlrev_b32_e32 v5, 5, v12
	v_ashrrev_i16_sdwa v0, v2, sext(v0) dst_sel:DWORD dst_unused:UNUSED_PAD src0_sel:DWORD src1_sel:BYTE_0
	s_lshl_b64 s[0:1], s[60:61], 20
	s_lshl_b64 s[4:5], s[4:5], 20
	v_readlane_b32 s6, v255, 46
	v_and_b32_e32 v5, 32, v5
	v_bfe_i32 v14, v0, 0, 16
	v_readlane_b32 s7, v255, 47
	s_add_u32 s64, s6, s4
	v_add_lshl_u32 v0, v5, v14, 1
	s_addc_u32 s65, s7, s5
	s_add_i32 s48, s11, 0
	v_lshl_add_u32 v132, v4, 12, v0
	s_add_i32 m0, s48, 0x10000
	v_lshl_add_u32 v134, v3, 12, v0
	global_load_lds_dwordx4 v132, s[64:65]
	s_add_i32 m0, s48, 0x12000
	s_add_u32 s4, s64, 0x80000
	global_load_lds_dwordx4 v128, s[64:65]
	s_addc_u32 s5, s65, 0
	s_add_i32 m0, s48, 0x14000
	v_mov_b32_e32 v133, 0
	global_load_lds_dwordx4 v132, s[4:5]
	s_add_i32 m0, s48, 0x16000
	s_add_u32 s62, s46, s0
	s_addc_u32 s63, s47, s1
	s_add_i32 s49, s48, 0x2000
	global_load_lds_dwordx4 v128, s[4:5]
	s_mov_b32 m0, s48
	s_add_u32 s0, s62, 0x80000
	global_load_lds_dwordx4 v134, s[62:63]
	s_mov_b32 m0, s49
	s_addc_u32 s1, s63, 0
	s_add_i32 s50, s48, 0x4000
	global_load_lds_dwordx4 v130, s[62:63]
	s_mov_b32 m0, s50
	s_add_i32 s51, s48, 0x6000
	global_load_lds_dwordx4 v134, s[0:1]
	s_mov_b32 m0, s51
	v_mov_b32_e32 v129, v133
	global_load_lds_dwordx4 v130, s[0:1]
	v_mov_b32_e32 v135, v133
	v_mov_b32_e32 v131, v133
	s_cmp_eq_u32 s3, 1
	s_mov_b32 s61, 0
	v_lshl_add_u64 v[6:7], s[64:65], 0, v[132:133]
	v_lshl_add_u64 v[4:5], s[64:65], 0, v[128:129]
	v_lshl_add_u64 v[0:1], s[62:63], 0, v[134:135]
	s_cselect_b64 s[0:1], -1, 0
	s_cmp_lg_u32 s3, 1
	v_lshl_add_u64 v[2:3], s[62:63], 0, v[130:131]
	s_cbranch_scc1 .LBB0_1384
	s_barrier

; #define PG8_STAGE(bufoff, gbase, voff) do { _Pragma("unroll") for (int _i = 0; _i < 2; ++_i) \
;         __builtin_amdgcn_global_load_lds((const unsigned*)((const char*)(gbase) + (voff)[_i]), (PG8_LAS unsigned*)(lds + (bufoff) + ldsw + _i * 8192), 16, 0, 0); } while (0)
; #define PG8_LDA(dst, b, h) do { _Pragma("unroll") for (int m = 0; m < 4; ++m) _Pragma("unroll") for (int k = 0; k < 2; ++k) dst[m][k] = *(const PG8_LAS bf16x8*)(lds + PG8_SA(b, h) + aoff + m * 2048 + k * 1024); } while (0)
; #define PG8_LDB(dst, b, h) do { _Pragma("unroll") for (int n = 0; n < 2; ++n) _Pragma("unroll") for (int k = 0; k < 2; ++k) dst[n][k] = *(const PG8_LAS bf16x8*)(lds + PG8_SB(b, h) + boff + n * 2048 + k * 1024); } while (0)
; #define PG8_MMA(ai, bj, At, Bt) do { __builtin_amdgcn_s_setprio(1); _Pragma("unroll") for (int m = 0; m < 4; ++m) _Pragma("unroll") for (int n = 0; n < 2; ++n) _Pragma("unroll") for (int k = 0; k < 2; ++k) \
;         acc[ai][bj][m][n] = __builtin_amdgcn_mfma_f32_16x16x32_bf16(Bt[n][k], At[m][k], acc[ai][bj][m][n], 0, 0, 0); __builtin_amdgcn_s_setprio(0); } while (0)
; #define PG8_WAIT_V(n) asm volatile("s_waitcnt vmcnt(" #n ")" ::: "memory")
; #define PG8_WAIT_L(n) asm volatile("s_waitcnt lgkmcnt(" #n ")" ::: "memory")
; #define PG8_BAR __builtin_amdgcn_s_barrier()
; #define PG8_SCHED __builtin_amdgcn_sched_barrier(0)
; template <class Epi, class Sched, bool ALIGN_EPI = false, bool SP2 = false>
; __device__ __forceinline__ void gemm_phase(PG8_LAS unsigned char* lds, const Gemm g, const Sched& S, const Epi& E, const int wave_in) {
;     ...
;             PG8_LDB(B0, 0, 0); PG8_LDB(B1, 0, 1); PG8_SCHED; PG8_LDA(At, 0, 0); PG8_STAGE(PG8_SA(1, 1), a1 + hstepA, voffA);
;             PG8_WAIT_V(8); PG8_WAIT_L(0); PG8_BAR; PG8_MMA(0, 0, At, B0); PG8_MMA(0, 1, At, B1); PG8_BAR; PG8_SCHED;
;             PG8_LDA(At, 0, 1); PG8_STAGE(PG8_SB(0, 0), b2, voffB); PG8_STAGE(PG8_SB(0, 1), b2 + hstep, voffB); PG8_STAGE(PG8_SA(0, 0), a2, voffA);
.LBB0_1390:
	ds_read_b128 v[144:147], v151
	ds_read_b128 v[156:159], v151 offset:1024
	ds_read_b128 v[160:163], v151 offset:2048
	ds_read_b128 v[164:167], v151 offset:3072
	ds_read_b128 v[168:171], v152
	ds_read_b128 v[172:175], v152 offset:1024
	ds_read_b128 v[176:179], v152 offset:2048
	ds_read_b128 v[180:183], v152 offset:3072
	s_add_u32 s64, s62, 0xfff80080
	s_addc_u32 s65, s63, -1
	s_cmp_eq_u32 s78, 28
	s_cselect_b32 s67, s41, s65
	s_cselect_b32 s66, s74, s64
	s_cselect_b32 s65, s39, s77
	s_cselect_b32 s64, s75, s76
	v_lshl_add_u64 v[216:217], s[62:63], 0, v[136:137]
	s_add_i32 m0, s48, 0xc000
	ds_read_b128 v[184:187], v153
	ds_read_b128 v[188:191], v153 offset:1024
	ds_read_b128 v[192:195], v153 offset:2048
	ds_read_b128 v[196:199], v153 offset:3072
	ds_read_b128 v[200:203], v153 offset:4096
	ds_read_b128 v[204:207], v153 offset:5120
	ds_read_b128 v[208:211], v153 offset:6144
	ds_read_b128 v[212:215], v153 offset:7168
	global_load_lds_dwordx4 v[216:217], off
	v_lshl_add_u64 v[216:217], s[62:63], 0, v[138:139]
	s_add_i32 m0, s48, 0xe000
	s_nop 0
	global_load_lds_dwordx4 v[216:217], off
	s_waitcnt vmcnt(8)
	s_waitcnt lgkmcnt(0)
	s_barrier
	s_waitcnt lgkmcnt(0)
	v_mfma_f32_16x16x32_bf16 v[116:119], v[144:147], v[184:187], v[116:119]
	v_mfma_f32_16x16x32_bf16 v[112:115], v[160:163], v[184:187], v[112:115]
	v_mfma_f32_16x16x32_bf16 v[100:103], v[144:147], v[192:195], v[100:103]
	v_mfma_f32_16x16x32_bf16 v[96:99], v[160:163], v[192:195], v[96:99]
	v_mfma_f32_16x16x32_bf16 v[84:87], v[144:147], v[200:203], v[84:87]
	v_mfma_f32_16x16x32_bf16 v[80:83], v[160:163], v[200:203], v[80:83]
	v_mfma_f32_16x16x32_bf16 v[68:71], v[144:147], v[208:211], v[68:71]
	v_mfma_f32_16x16x32_bf16 v[64:67], v[160:163], v[208:211], v[64:67]
	v_mfma_f32_16x16x32_bf16 v[116:119], v[156:159], v[188:191], v[116:119]
	v_mfma_f32_16x16x32_bf16 v[112:115], v[164:167], v[188:191], v[112:115]
	v_mfma_f32_16x16x32_bf16 v[100:103], v[156:159], v[196:199], v[100:103]
	v_mfma_f32_16x16x32_bf16 v[96:99], v[164:167], v[196:199], v[96:99]
	v_mfma_f32_16x16x32_bf16 v[84:87], v[156:159], v[204:207], v[84:87]
	v_mfma_f32_16x16x32_bf16 v[80:83], v[164:167], v[204:207], v[80:83]
	v_mfma_f32_16x16x32_bf16 v[68:71], v[156:159], v[212:215], v[68:71]
	v_mfma_f32_16x16x32_bf16 v[64:67], v[164:167], v[212:215], v[64:67]
	v_mfma_f32_16x16x32_bf16 v[124:127], v[168:171], v[184:187], v[124:127]
	v_mfma_f32_16x16x32_bf16 v[120:123], v[176:179], v[184:187], v[120:123]
	v_mfma_f32_16x16x32_bf16 v[108:111], v[168:171], v[192:195], v[108:111]
	v_mfma_f32_16x16x32_bf16 v[104:107], v[176:179], v[192:195], v[104:107]
	v_mfma_f32_16x16x32_bf16 v[92:95], v[168:171], v[200:203], v[92:95]
	v_mfma_f32_16x16x32_bf16 v[88:91], v[176:179], v[200:203], v[88:91]
	v_mfma_f32_16x16x32_bf16 v[76:79], v[168:171], v[208:211], v[76:79]
	v_mfma_f32_16x16x32_bf16 v[72:75], v[176:179], v[208:211], v[72:75]
	v_mfma_f32_16x16x32_bf16 v[124:127], v[172:175], v[188:191], v[124:127]
	v_mfma_f32_16x16x32_bf16 v[120:123], v[180:183], v[188:191], v[120:123]
	v_mfma_f32_16x16x32_bf16 v[108:111], v[172:175], v[196:199], v[108:111]
	v_mfma_f32_16x16x32_bf16 v[104:107], v[180:183], v[196:199], v[104:107]
	v_mfma_f32_16x16x32_bf16 v[92:95], v[172:175], v[204:207], v[92:95]
	v_mfma_f32_16x16x32_bf16 v[88:91], v[180:183], v[204:207], v[88:91]
	v_mfma_f32_16x16x32_bf16 v[76:79], v[172:175], v[212:215], v[76:79]
	v_mfma_f32_16x16x32_bf16 v[72:75], v[180:183], v[212:215], v[72:75]
	s_barrier
	s_add_i32 s79, s70, s11
	v_lshl_add_u64 v[216:217], s[64:65], 0, v[132:133]
	s_mov_b32 m0, s79
	ds_read_b128 v[184:187], v153 offset:16384
	ds_read_b128 v[188:191], v153 offset:17408
	ds_read_b128 v[192:195], v153 offset:18432
	ds_read_b128 v[196:199], v153 offset:19456
	ds_read_b128 v[200:203], v153 offset:20480
	ds_read_b128 v[204:207], v153 offset:21504
	ds_read_b128 v[208:211], v153 offset:22528
	ds_read_b128 v[212:215], v153 offset:23552
	global_load_lds_dwordx4 v[216:217], off
	s_add_i32 m0, s79, 0x2000
	s_add_u32 s80, s64, 0x80000
	v_lshl_add_u64 v[218:219], s[64:65], 0, v[128:129]
	s_addc_u32 s81, s65, 0
	s_add_i32 s79, s71, s11
	global_load_lds_dwordx4 v[218:219], off
	v_lshl_add_u64 v[220:221], s[80:81], 0, v[132:133]
	s_mov_b32 m0, s79
	v_lshl_add_u64 v[222:223], s[66:67], 0, v[130:131]
	global_load_lds_dwordx4 v[220:221], off
	v_lshl_add_u64 v[220:221], s[80:81], 0, v[128:129]
	s_add_i32 m0, s79, 0x2000
	s_nop 0
	global_load_lds_dwordx4 v[220:221], off
	v_lshl_add_u64 v[220:221], s[66:67], 0, v[134:135]
	s_mov_b32 m0, s48
	s_nop 0
	global_load_lds_dwordx4 v[220:221], off
	s_mov_b32 m0, s49
	s_nop 0
	global_load_lds_dwordx4 v[222:223], off
	s_waitcnt vmcnt(8)
	s_waitcnt lgkmcnt(0)
	s_barrier
; #define PG8_STAGE(bufoff, gbase, voff) do { _Pragma("unroll") for (int _i = 0; _i < 2; ++_i) \
;         __builtin_amdgcn_global_load_lds((const unsigned*)((const char*)(gbase) + (voff)[_i]), (PG8_LAS unsigned*)(lds + (bufoff) + ldsw + _i * 8192), 16, 0, 0); } while (0)
; #define PG8_LDA(dst, b, h) do { _Pragma("unroll") for (int m = 0; m < 4; ++m) _Pragma("unroll") for (int k = 0; k < 2; ++k) dst[m][k] = *(const PG8_LAS bf16x8*)(lds + PG8_SA(b, h) + aoff + m * 2048 + k * 1024); } while (0)
; #define PG8_LDB(dst, b, h) do { _Pragma("unroll") for (int n = 0; n < 2; ++n) _Pragma("unroll") for (int k = 0; k < 2; ++k) dst[n][k] = *(const PG8_LAS bf16x8*)(lds + PG8_SB(b, h) + boff + n * 2048 + k * 1024); } while (0)
; #define PG8_MMA(ai, bj, At, Bt) do { __builtin_amdgcn_s_setprio(1); _Pragma("unroll") for (int m = 0; m < 4; ++m) _Pragma("unroll") for (int n = 0; n < 2; ++n) _Pragma("unroll") for (int k = 0; k < 2; ++k) \
;         acc[ai][bj][m][n] = __builtin_amdgcn_mfma_f32_16x16x32_bf16(Bt[n][k], At[m][k], acc[ai][bj][m][n], 0, 0, 0); __builtin_amdgcn_s_setprio(0); } while (0)
; #define PG8_WAIT_V(n) asm volatile("s_waitcnt vmcnt(" #n ")" ::: "memory")
; #define PG8_WAIT_L(n) asm volatile("s_waitcnt lgkmcnt(" #n ")" ::: "memory")
; #define PG8_BAR __builtin_amdgcn_s_barrier()
; #define PG8_SCHED __builtin_amdgcn_sched_barrier(0)
; template <class Epi, class Sched, bool ALIGN_EPI = false, bool SP2 = false>
; __device__ __forceinline__ void gemm_phase(PG8_LAS unsigned char* lds, const Gemm g, const Sched& S, const Epi& E, const int wave_in) {
;     ...
;             PG8_WAIT_V(8); PG8_WAIT_L(0); PG8_BAR; PG8_MMA(1, 0, At, B0); PG8_MMA(1, 1, At, B1); PG8_BAR; PG8_SCHED;
;             PG8_LDB(B0, 1, 0); PG8_LDB(B1, 1, 1); PG8_SCHED; PG8_LDA(At, 1, 0); PG8_STAGE(PG8_SA(0, 1), a2 + hstepA, voffA);
;             PG8_WAIT_V(8); PG8_WAIT_L(0); PG8_BAR; PG8_MMA(0, 0, At, B0); PG8_MMA(0, 1, At, B1); PG8_BAR; PG8_SCHED;
	s_waitcnt lgkmcnt(0)
	v_mfma_f32_16x16x32_bf16 v[52:55], v[144:147], v[184:187], v[52:55]
	v_mfma_f32_16x16x32_bf16 v[48:51], v[160:163], v[184:187], v[48:51]
	v_mfma_f32_16x16x32_bf16 v[36:39], v[144:147], v[192:195], v[36:39]
	v_mfma_f32_16x16x32_bf16 v[32:35], v[160:163], v[192:195], v[32:35]
	v_mfma_f32_16x16x32_bf16 v[20:23], v[144:147], v[200:203], v[20:23]
	v_mfma_f32_16x16x32_bf16 v[16:19], v[160:163], v[200:203], v[16:19]
	v_mfma_f32_16x16x32_bf16 v[4:7], v[144:147], v[208:211], v[4:7]
	v_mfma_f32_16x16x32_bf16 v[0:3], v[160:163], v[208:211], v[0:3]
	v_mfma_f32_16x16x32_bf16 v[52:55], v[156:159], v[188:191], v[52:55]
	v_mfma_f32_16x16x32_bf16 v[48:51], v[164:167], v[188:191], v[48:51]
	v_mfma_f32_16x16x32_bf16 v[36:39], v[156:159], v[196:199], v[36:39]
	v_mfma_f32_16x16x32_bf16 v[32:35], v[164:167], v[196:199], v[32:35]
	v_mfma_f32_16x16x32_bf16 v[20:23], v[156:159], v[204:207], v[20:23]
	v_mfma_f32_16x16x32_bf16 v[16:19], v[164:167], v[204:207], v[16:19]
	v_mfma_f32_16x16x32_bf16 v[4:7], v[156:159], v[212:215], v[4:7]
	v_mfma_f32_16x16x32_bf16 v[0:3], v[164:167], v[212:215], v[0:3]
	v_mfma_f32_16x16x32_bf16 v[60:63], v[168:171], v[184:187], v[60:63]
	v_mfma_f32_16x16x32_bf16 v[56:59], v[176:179], v[184:187], v[56:59]
	v_mfma_f32_16x16x32_bf16 v[44:47], v[168:171], v[192:195], v[44:47]
	v_mfma_f32_16x16x32_bf16 v[40:43], v[176:179], v[192:195], v[40:43]
	v_mfma_f32_16x16x32_bf16 v[28:31], v[168:171], v[200:203], v[28:31]
	v_mfma_f32_16x16x32_bf16 v[24:27], v[176:179], v[200:203], v[24:27]
	v_mfma_f32_16x16x32_bf16 v[12:15], v[168:171], v[208:211], v[12:15]
	v_mfma_f32_16x16x32_bf16 v[8:11], v[176:179], v[208:211], v[8:11]
	v_mfma_f32_16x16x32_bf16 v[60:63], v[172:175], v[188:191], v[60:63]
	v_mfma_f32_16x16x32_bf16 v[56:59], v[180:183], v[188:191], v[56:59]
	v_mfma_f32_16x16x32_bf16 v[44:47], v[172:175], v[196:199], v[44:47]
	v_mfma_f32_16x16x32_bf16 v[40:43], v[180:183], v[196:199], v[40:43]
	v_mfma_f32_16x16x32_bf16 v[28:31], v[172:175], v[204:207], v[28:31]
	v_mfma_f32_16x16x32_bf16 v[24:27], v[180:183], v[204:207], v[24:27]
	v_mfma_f32_16x16x32_bf16 v[12:15], v[172:175], v[212:215], v[12:15]
	v_mfma_f32_16x16x32_bf16 v[8:11], v[180:183], v[212:215], v[8:11]
	s_barrier
	s_add_i32 s79, 0, 0x18000
	v_add_u32_e32 v155, s79, v149
	s_add_i32 s80, 0, 0x1c000
	ds_read_b128 v[144:147], v155
	ds_read_b128 v[156:159], v155 offset:1024
	ds_read_b128 v[160:163], v155 offset:2048
	ds_read_b128 v[164:167], v155 offset:3072
	v_add_u32_e32 v155, s80, v149
	ds_read_b128 v[168:171], v155
	ds_read_b128 v[172:175], v155 offset:1024
	ds_read_b128 v[176:179], v155 offset:2048
	ds_read_b128 v[180:183], v155 offset:3072
	s_add_u32 s66, s66, 0x80000
	s_addc_u32 s67, s67, 0
	s_mov_b32 m0, s50
	v_lshl_add_u64 v[224:225], s[66:67], 0, v[134:135]
	ds_read_b128 v[184:187], v153 offset:32768
	ds_read_b128 v[188:191], v153 offset:33792
	ds_read_b128 v[192:195], v153 offset:34816
	ds_read_b128 v[196:199], v153 offset:35840
	ds_read_b128 v[200:203], v153 offset:36864
	ds_read_b128 v[204:207], v153 offset:37888
	ds_read_b128 v[208:211], v153 offset:38912
	ds_read_b128 v[212:215], v153 offset:39936
	global_load_lds_dwordx4 v[224:225], off
	v_lshl_add_u64 v[224:225], s[66:67], 0, v[130:131]
	s_mov_b32 m0, s51
	s_nop 0
	global_load_lds_dwordx4 v[224:225], off
	s_waitcnt vmcnt(8)
	s_waitcnt lgkmcnt(0)
	s_barrier
	s_waitcnt lgkmcnt(0)
	v_mfma_f32_16x16x32_bf16 v[116:119], v[144:147], v[184:187], v[116:119]
	v_mfma_f32_16x16x32_bf16 v[112:115], v[160:163], v[184:187], v[112:115]
	v_mfma_f32_16x16x32_bf16 v[100:103], v[144:147], v[192:195], v[100:103]
	v_mfma_f32_16x16x32_bf16 v[96:99], v[160:163], v[192:195], v[96:99]
	v_mfma_f32_16x16x32_bf16 v[84:87], v[144:147], v[200:203], v[84:87]
	v_mfma_f32_16x16x32_bf16 v[80:83], v[160:163], v[200:203], v[80:83]
	v_mfma_f32_16x16x32_bf16 v[68:71], v[144:147], v[208:211], v[68:71]
	v_mfma_f32_16x16x32_bf16 v[64:67], v[160:163], v[208:211], v[64:67]
	v_mfma_f32_16x16x32_bf16 v[116:119], v[156:159], v[188:191], v[116:119]
	v_mfma_f32_16x16x32_bf16 v[112:115], v[164:167], v[188:191], v[112:115]
	v_mfma_f32_16x16x32_bf16 v[100:103], v[156:159], v[196:199], v[100:103]
	v_mfma_f32_16x16x32_bf16 v[96:99], v[164:167], v[196:199], v[96:99]
	v_mfma_f32_16x16x32_bf16 v[84:87], v[156:159], v[204:207], v[84:87]
	v_mfma_f32_16x16x32_bf16 v[80:83], v[164:167], v[204:207], v[80:83]
	v_mfma_f32_16x16x32_bf16 v[68:71], v[156:159], v[212:215], v[68:71]
	v_mfma_f32_16x16x32_bf16 v[64:67], v[164:167], v[212:215], v[64:67]
	v_mfma_f32_16x16x32_bf16 v[124:127], v[168:171], v[184:187], v[124:127]
	v_mfma_f32_16x16x32_bf16 v[120:123], v[176:179], v[184:187], v[120:123]
	v_mfma_f32_16x16x32_bf16 v[108:111], v[168:171], v[192:195], v[108:111]
	v_mfma_f32_16x16x32_bf16 v[104:107], v[176:179], v[192:195], v[104:107]
	v_mfma_f32_16x16x32_bf16 v[92:95], v[168:171], v[200:203], v[92:95]
	v_mfma_f32_16x16x32_bf16 v[88:91], v[176:179], v[200:203], v[88:91]
	v_mfma_f32_16x16x32_bf16 v[76:79], v[168:171], v[208:211], v[76:79]
	v_mfma_f32_16x16x32_bf16 v[72:75], v[176:179], v[208:211], v[72:75]
	v_mfma_f32_16x16x32_bf16 v[124:127], v[172:175], v[188:191], v[124:127]
	v_mfma_f32_16x16x32_bf16 v[120:123], v[180:183], v[188:191], v[120:123]
	v_mfma_f32_16x16x32_bf16 v[108:111], v[172:175], v[196:199], v[108:111]
	v_mfma_f32_16x16x32_bf16 v[104:107], v[180:183], v[196:199], v[104:107]
	v_mfma_f32_16x16x32_bf16 v[92:95], v[172:175], v[204:207], v[92:95]
	v_mfma_f32_16x16x32_bf16 v[88:91], v[180:183], v[204:207], v[88:91]
	v_mfma_f32_16x16x32_bf16 v[76:79], v[172:175], v[212:215], v[76:79]
	v_mfma_f32_16x16x32_bf16 v[72:75], v[180:183], v[212:215], v[72:75]
	s_barrier
; #define PG8_STAGE(bufoff, gbase, voff) do { _Pragma("unroll") for (int _i = 0; _i < 2; ++_i) \
;         __builtin_amdgcn_global_load_lds((const unsigned*)((const char*)(gbase) + (voff)[_i]), (PG8_LAS unsigned*)(lds + (bufoff) + ldsw + _i * 8192), 16, 0, 0); } while (0)
; #define PG8_LDA(dst, b, h) do { _Pragma("unroll") for (int m = 0; m < 4; ++m) _Pragma("unroll") for (int k = 0; k < 2; ++k) dst[m][k] = *(const PG8_LAS bf16x8*)(lds + PG8_SA(b, h) + aoff + m * 2048 + k * 1024); } while (0)
; #define PG8_MMA(ai, bj, At, Bt) do { __builtin_amdgcn_s_setprio(1); _Pragma("unroll") for (int m = 0; m < 4; ++m) _Pragma("unroll") for (int n = 0; n < 2; ++n) _Pragma("unroll") for (int k = 0; k < 2; ++k) \
;         acc[ai][bj][m][n] = __builtin_amdgcn_mfma_f32_16x16x32_bf16(Bt[n][k], At[m][k], acc[ai][bj][m][n], 0, 0, 0); __builtin_amdgcn_s_setprio(0); } while (0)
; #define PG8_WAIT_V(n) asm volatile("s_waitcnt vmcnt(" #n ")" ::: "memory")
; #define PG8_WAIT_L(n) asm volatile("s_waitcnt lgkmcnt(" #n ")" ::: "memory")
; #define PG8_BAR __builtin_amdgcn_s_barrier()
; #define PG8_SCHED __builtin_amdgcn_sched_barrier(0)
; template <class Epi, class Sched, bool ALIGN_EPI = false, bool SP2 = false>
; __device__ __forceinline__ void gemm_phase(PG8_LAS unsigned char* lds, const Gemm g, const Sched& S, const Epi& E, const int wave_in) {
;     ...
;             PG8_LDA(At, 1, 1); PG8_STAGE(PG8_SB(1, 0), b3, voffB); PG8_STAGE(PG8_SB(1, 1), b3 + hstep, voffB); PG8_STAGE(PG8_SA(1, 0), a3, voffA);
;             PG8_WAIT_V(8); PG8_WAIT_L(0); PG8_BAR; PG8_MMA(1, 0, At, B0); PG8_MMA(1, 1, At, B1); PG8_BAR; PG8_SCHED;
	s_add_i32 s66, s79, s11
	v_lshl_add_u64 v[216:217], v[216:217], 0, s[6:7]
	s_mov_b32 m0, s66
	ds_read_b128 v[184:187], v153 offset:49152
	ds_read_b128 v[188:191], v153 offset:50176
	ds_read_b128 v[192:195], v153 offset:51200
	ds_read_b128 v[196:199], v153 offset:52224
	ds_read_b128 v[200:203], v153 offset:53248
	ds_read_b128 v[204:207], v153 offset:54272
	ds_read_b128 v[208:211], v153 offset:55296
	ds_read_b128 v[212:215], v153 offset:56320
	global_load_lds_dwordx4 v[216:217], off
	s_add_i32 m0, s66, 0x2000
	s_add_u32 s64, s64, 0x80080
	v_lshl_add_u64 v[216:217], v[218:219], 0, s[6:7]
	s_addc_u32 s65, s65, 0
	s_add_i32 s66, s80, s11
	global_load_lds_dwordx4 v[216:217], off
	v_lshl_add_u64 v[216:217], s[64:65], 0, v[132:133]
	s_mov_b32 m0, s66
	s_nop 0
	global_load_lds_dwordx4 v[216:217], off
	v_lshl_add_u64 v[216:217], s[64:65], 0, v[128:129]
	s_add_i32 m0, s66, 0x2000
	s_nop 0
	global_load_lds_dwordx4 v[216:217], off
	v_lshl_add_u64 v[216:217], v[220:221], 0, s[6:7]
	s_mov_b32 m0, s68
	s_nop 0
	global_load_lds_dwordx4 v[216:217], off
	v_lshl_add_u64 v[216:217], v[222:223], 0, s[6:7]
	s_mov_b32 m0, s69
	s_nop 0
	global_load_lds_dwordx4 v[216:217], off
	s_waitcnt vmcnt(8)
	s_waitcnt lgkmcnt(0)
	s_barrier
	s_waitcnt lgkmcnt(0)
	v_mfma_f32_16x16x32_bf16 v[52:55], v[144:147], v[184:187], v[52:55]
	v_mfma_f32_16x16x32_bf16 v[48:51], v[160:163], v[184:187], v[48:51]
	v_mfma_f32_16x16x32_bf16 v[36:39], v[144:147], v[192:195], v[36:39]
	v_mfma_f32_16x16x32_bf16 v[32:35], v[160:163], v[192:195], v[32:35]
	v_mfma_f32_16x16x32_bf16 v[20:23], v[144:147], v[200:203], v[20:23]
	v_mfma_f32_16x16x32_bf16 v[16:19], v[160:163], v[200:203], v[16:19]
	v_mfma_f32_16x16x32_bf16 v[4:7], v[144:147], v[208:211], v[4:7]
	v_mfma_f32_16x16x32_bf16 v[0:3], v[160:163], v[208:211], v[0:3]
	v_mfma_f32_16x16x32_bf16 v[52:55], v[156:159], v[188:191], v[52:55]
	v_mfma_f32_16x16x32_bf16 v[48:51], v[164:167], v[188:191], v[48:51]
	v_mfma_f32_16x16x32_bf16 v[36:39], v[156:159], v[196:199], v[36:39]
	v_mfma_f32_16x16x32_bf16 v[32:35], v[164:167], v[196:199], v[32:35]
	v_mfma_f32_16x16x32_bf16 v[20:23], v[156:159], v[204:207], v[20:23]
	v_mfma_f32_16x16x32_bf16 v[16:19], v[164:167], v[204:207], v[16:19]
	v_mfma_f32_16x16x32_bf16 v[4:7], v[156:159], v[212:215], v[4:7]
	v_mfma_f32_16x16x32_bf16 v[0:3], v[164:167], v[212:215], v[0:3]
	v_mfma_f32_16x16x32_bf16 v[60:63], v[168:171], v[184:187], v[60:63]
	v_mfma_f32_16x16x32_bf16 v[56:59], v[176:179], v[184:187], v[56:59]
	v_mfma_f32_16x16x32_bf16 v[44:47], v[168:171], v[192:195], v[44:47]
	v_mfma_f32_16x16x32_bf16 v[40:43], v[176:179], v[192:195], v[40:43]
	v_mfma_f32_16x16x32_bf16 v[28:31], v[168:171], v[200:203], v[28:31]
	v_mfma_f32_16x16x32_bf16 v[24:27], v[176:179], v[200:203], v[24:27]
	v_mfma_f32_16x16x32_bf16 v[12:15], v[168:171], v[208:211], v[12:15]
	v_mfma_f32_16x16x32_bf16 v[8:11], v[176:179], v[208:211], v[8:11]
	v_mfma_f32_16x16x32_bf16 v[60:63], v[172:175], v[188:191], v[60:63]
	v_mfma_f32_16x16x32_bf16 v[56:59], v[180:183], v[188:191], v[56:59]
	v_mfma_f32_16x16x32_bf16 v[44:47], v[172:175], v[196:199], v[44:47]
	v_mfma_f32_16x16x32_bf16 v[40:43], v[180:183], v[196:199], v[40:43]
	v_mfma_f32_16x16x32_bf16 v[28:31], v[172:175], v[204:207], v[28:31]
	v_mfma_f32_16x16x32_bf16 v[24:27], v[180:183], v[204:207], v[24:27]
	v_mfma_f32_16x16x32_bf16 v[12:15], v[172:175], v[212:215], v[12:15]
	v_mfma_f32_16x16x32_bf16 v[8:11], v[180:183], v[212:215], v[8:11]
	s_barrier
	s_add_i32 s78, s78, 2
	s_add_u32 s62, s62, 0x100
	s_addc_u32 s63, s63, 0
	s_add_u32 s76, s76, 0x100
	s_addc_u32 s77, s77, 0
	s_cmp_gt_u32 s78, 29
	s_cbranch_scc0 .LBB0_1390
	s_and_b64 vcc, exec, s[18:19]
	s_cbranch_vccz .LBB0_1393
	s_barrier

; #define GEMM_RESID(Aop, Kdim, WT, XIN, ssi, ALPHA) do { pg8::Gemm g_{Aop, WT, T, DM, Kdim, Kdim}; pg8::StaticOrder S_; S_.init(T, DM, G, bx); pg8::EpiResid E_{XIN, p.out, XB, SS + (size_t)(ssi) * T, ALPHA}; \
;         pg8::gemm_phase<pg8::EpiResid, pg8::StaticOrder, true, true>(ldsl, g_, S_, E_, wave); } while (0)
; __global__ void __launch_bounds__(512, 2) fwd_kernel(Params p) {
;     ...
;     if (IN(9)) GEMM_RESID(Hh, FF, W_DN1, p.out, 3, 0.5f);
.LBB0_1451:
	s_cmp_lt_i32 s92, 10
	s_cselect_b64 s[0:1], -1, 0
	s_cmp_gt_i32 s93, 9
	s_cselect_b64 s[2:3], -1, 0
	s_and_b64 s[0:1], s[0:1], s[2:3]
	s_andn2_b64 vcc, exec, s[0:1]
	s_waitcnt lgkmcnt(0)
	s_barrier
	s_cbranch_vccnz .LBB0_1498
	s_setprio 0
	s_cmp_lt_u32 s89, 4
	s_cbranch_scc1 .Lgprio_5
	s_setprio 1

; #define PG8_STAGE(bufoff, gbase, voff) do { _Pragma("unroll") for (int _i = 0; _i < 2; ++_i) \
;         __builtin_amdgcn_global_load_lds((const unsigned*)((const char*)(gbase) + (voff)[_i]), (PG8_LAS unsigned*)(lds + (bufoff) + ldsw + _i * 8192), 16, 0, 0); } while (0)
; #define PG8_LDA(dst, b, h) do { _Pragma("unroll") for (int m = 0; m < 4; ++m) _Pragma("unroll") for (int k = 0; k < 2; ++k) dst[m][k] = *(const PG8_LAS bf16x8*)(lds + PG8_SA(b, h) + aoff + m * 2048 + k * 1024); } while (0)
; #define PG8_LDB(dst, b, h) do { _Pragma("unroll") for (int n = 0; n < 2; ++n) _Pragma("unroll") for (int k = 0; k < 2; ++k) dst[n][k] = *(const PG8_LAS bf16x8*)(lds + PG8_SB(b, h) + boff + n * 2048 + k * 1024); } while (0)
; #define PG8_MMA(ai, bj, At, Bt) do { __builtin_amdgcn_s_setprio(1); _Pragma("unroll") for (int m = 0; m < 4; ++m) _Pragma("unroll") for (int n = 0; n < 2; ++n) _Pragma("unroll") for (int k = 0; k < 2; ++k) \
;         acc[ai][bj][m][n] = __builtin_amdgcn_mfma_f32_16x16x32_bf16(Bt[n][k], At[m][k], acc[ai][bj][m][n], 0, 0, 0); __builtin_amdgcn_s_setprio(0); } while (0)
; #define PG8_WAIT_V(n) asm volatile("s_waitcnt vmcnt(" #n ")" ::: "memory")
; #define PG8_WAIT_L(n) asm volatile("s_waitcnt lgkmcnt(" #n ")" ::: "memory")
; #define PG8_BAR __builtin_amdgcn_s_barrier()
; #define PG8_SCHED __builtin_amdgcn_sched_barrier(0)
; template <class Epi, class Sched, bool ALIGN_EPI = false, bool SP2 = false>
; __device__ __forceinline__ void gemm_phase(PG8_LAS unsigned char* lds, const Gemm g, const Sched& S, const Epi& E, const int wave_in) {
;     ...
;             PG8_LDB(B0, 0, 0); PG8_LDB(B1, 0, 1); PG8_SCHED; PG8_LDA(At, 0, 0); PG8_STAGE(PG8_SA(1, 1), a1 + hstepA, voffA);
;             PG8_WAIT_V(8); PG8_WAIT_L(0); PG8_BAR; PG8_MMA(0, 0, At, B0); PG8_MMA(0, 1, At, B1); PG8_BAR; PG8_SCHED;
;             PG8_LDA(At, 0, 1); PG8_STAGE(PG8_SB(0, 0), b2, voffB); PG8_STAGE(PG8_SB(0, 1), b2 + hstep, voffB); PG8_STAGE(PG8_SA(0, 0), a2, voffA);
.LBB0_1475:
	ds_read_b128 v[144:147], v151
	ds_read_b128 v[156:159], v151 offset:1024
	ds_read_b128 v[160:163], v151 offset:2048
	ds_read_b128 v[164:167], v151 offset:3072
	ds_read_b128 v[168:171], v152
	ds_read_b128 v[172:175], v152 offset:1024
	ds_read_b128 v[176:179], v152 offset:2048
	ds_read_b128 v[180:183], v152 offset:3072
	s_add_u32 s60, s58, 0x100
	s_addc_u32 s61, s59, 0
	s_cmpk_eq_i32 s76, 0x54
	s_cselect_b32 s65, s7, s61
	s_cselect_b32 s64, s6, s60
	s_cselect_b32 s63, s43, s75
	s_cselect_b32 s62, s42, s74
	v_lshl_add_u64 v[216:217], s[58:59], 0, v[136:137]
	s_add_i32 m0, s33, 0xc000
	ds_read_b128 v[184:187], v153
	ds_read_b128 v[188:191], v153 offset:1024
	ds_read_b128 v[192:195], v153 offset:2048
	ds_read_b128 v[196:199], v153 offset:3072
	ds_read_b128 v[200:203], v153 offset:4096
	ds_read_b128 v[204:207], v153 offset:5120
	ds_read_b128 v[208:211], v153 offset:6144
	ds_read_b128 v[212:215], v153 offset:7168
	global_load_lds_dwordx4 v[216:217], off
	v_lshl_add_u64 v[216:217], s[58:59], 0, v[138:139]
	s_add_i32 m0, s33, 0xe000
	s_nop 0
	global_load_lds_dwordx4 v[216:217], off
	s_waitcnt vmcnt(8)
	s_waitcnt lgkmcnt(0)
	s_barrier
	s_waitcnt lgkmcnt(0)
	v_mfma_f32_16x16x32_bf16 v[124:127], v[144:147], v[184:187], v[124:127]
	v_mfma_f32_16x16x32_bf16 v[120:123], v[160:163], v[184:187], v[120:123]
	v_mfma_f32_16x16x32_bf16 v[108:111], v[144:147], v[192:195], v[108:111]
	v_mfma_f32_16x16x32_bf16 v[104:107], v[160:163], v[192:195], v[104:107]
	v_mfma_f32_16x16x32_bf16 v[92:95], v[144:147], v[200:203], v[92:95]
	v_mfma_f32_16x16x32_bf16 v[88:91], v[160:163], v[200:203], v[88:91]
	v_mfma_f32_16x16x32_bf16 v[76:79], v[144:147], v[208:211], v[76:79]
	v_mfma_f32_16x16x32_bf16 v[72:75], v[160:163], v[208:211], v[72:75]
	v_mfma_f32_16x16x32_bf16 v[124:127], v[156:159], v[188:191], v[124:127]
	v_mfma_f32_16x16x32_bf16 v[120:123], v[164:167], v[188:191], v[120:123]
	v_mfma_f32_16x16x32_bf16 v[108:111], v[156:159], v[196:199], v[108:111]
	v_mfma_f32_16x16x32_bf16 v[104:107], v[164:167], v[196:199], v[104:107]
	v_mfma_f32_16x16x32_bf16 v[92:95], v[156:159], v[204:207], v[92:95]
	v_mfma_f32_16x16x32_bf16 v[88:91], v[164:167], v[204:207], v[88:91]
	v_mfma_f32_16x16x32_bf16 v[76:79], v[156:159], v[212:215], v[76:79]
	v_mfma_f32_16x16x32_bf16 v[72:75], v[164:167], v[212:215], v[72:75]
	v_mfma_f32_16x16x32_bf16 v[116:119], v[168:171], v[184:187], v[116:119]
	v_mfma_f32_16x16x32_bf16 v[112:115], v[176:179], v[184:187], v[112:115]
	v_mfma_f32_16x16x32_bf16 v[100:103], v[168:171], v[192:195], v[100:103]
	v_mfma_f32_16x16x32_bf16 v[96:99], v[176:179], v[192:195], v[96:99]
	v_mfma_f32_16x16x32_bf16 v[84:87], v[168:171], v[200:203], v[84:87]
	v_mfma_f32_16x16x32_bf16 v[80:83], v[176:179], v[200:203], v[80:83]
	v_mfma_f32_16x16x32_bf16 v[68:71], v[168:171], v[208:211], v[68:71]
	v_mfma_f32_16x16x32_bf16 v[64:67], v[176:179], v[208:211], v[64:67]
	v_mfma_f32_16x16x32_bf16 v[116:119], v[172:175], v[188:191], v[116:119]
	v_mfma_f32_16x16x32_bf16 v[112:115], v[180:183], v[188:191], v[112:115]
	v_mfma_f32_16x16x32_bf16 v[100:103], v[172:175], v[196:199], v[100:103]
	v_mfma_f32_16x16x32_bf16 v[96:99], v[180:183], v[196:199], v[96:99]
	v_mfma_f32_16x16x32_bf16 v[84:87], v[172:175], v[204:207], v[84:87]
	v_mfma_f32_16x16x32_bf16 v[80:83], v[180:183], v[204:207], v[80:83]
	v_mfma_f32_16x16x32_bf16 v[68:71], v[172:175], v[212:215], v[68:71]
	v_mfma_f32_16x16x32_bf16 v[64:67], v[180:183], v[212:215], v[64:67]
	s_barrier
	s_add_i32 s58, s70, s11
	v_lshl_add_u64 v[216:217], s[62:63], 0, v[130:131]
	s_mov_b32 m0, s58
	ds_read_b128 v[184:187], v153 offset:16384
	ds_read_b128 v[188:191], v153 offset:17408
	ds_read_b128 v[192:195], v153 offset:18432
	ds_read_b128 v[196:199], v153 offset:19456
	ds_read_b128 v[200:203], v153 offset:20480
	ds_read_b128 v[204:207], v153 offset:21504
	ds_read_b128 v[208:211], v153 offset:22528
	ds_read_b128 v[212:215], v153 offset:23552
	global_load_lds_dwordx4 v[216:217], off
	s_add_i32 m0, s58, 0x2000
	s_add_u32 s58, s62, 0x160000
	v_lshl_add_u64 v[218:219], s[62:63], 0, v[134:135]
	s_addc_u32 s59, s63, 0
	s_add_i32 s77, s71, s11
	global_load_lds_dwordx4 v[218:219], off
	v_lshl_add_u64 v[220:221], s[58:59], 0, v[130:131]
	s_mov_b32 m0, s77
	v_lshl_add_u64 v[222:223], s[64:65], 0, v[132:133]
	global_load_lds_dwordx4 v[220:221], off
	v_lshl_add_u64 v[220:221], s[58:59], 0, v[134:135]
	s_add_i32 m0, s77, 0x2000
	s_nop 0
	global_load_lds_dwordx4 v[220:221], off
	v_lshl_add_u64 v[220:221], s[64:65], 0, v[128:129]
	s_mov_b32 m0, s33
	s_nop 0
	global_load_lds_dwordx4 v[220:221], off
	s_mov_b32 m0, s35
	s_nop 0
	global_load_lds_dwordx4 v[222:223], off
	s_waitcnt vmcnt(8)
	s_waitcnt lgkmcnt(0)
	s_barrier
; #define PG8_STAGE(bufoff, gbase, voff) do { _Pragma("unroll") for (int _i = 0; _i < 2; ++_i) \
;         __builtin_amdgcn_global_load_lds((const unsigned*)((const char*)(gbase) + (voff)[_i]), (PG8_LAS unsigned*)(lds + (bufoff) + ldsw + _i * 8192), 16, 0, 0); } while (0)
; #define PG8_LDA(dst, b, h) do { _Pragma("unroll") for (int m = 0; m < 4; ++m) _Pragma("unroll") for (int k = 0; k < 2; ++k) dst[m][k] = *(const PG8_LAS bf16x8*)(lds + PG8_SA(b, h) + aoff + m * 2048 + k * 1024); } while (0)
; #define PG8_LDB(dst, b, h) do { _Pragma("unroll") for (int n = 0; n < 2; ++n) _Pragma("unroll") for (int k = 0; k < 2; ++k) dst[n][k] = *(const PG8_LAS bf16x8*)(lds + PG8_SB(b, h) + boff + n * 2048 + k * 1024); } while (0)
; #define PG8_MMA(ai, bj, At, Bt) do { __builtin_amdgcn_s_setprio(1); _Pragma("unroll") for (int m = 0; m < 4; ++m) _Pragma("unroll") for (int n = 0; n < 2; ++n) _Pragma("unroll") for (int k = 0; k < 2; ++k) \
;         acc[ai][bj][m][n] = __builtin_amdgcn_mfma_f32_16x16x32_bf16(Bt[n][k], At[m][k], acc[ai][bj][m][n], 0, 0, 0); __builtin_amdgcn_s_setprio(0); } while (0)
; #define PG8_WAIT_V(n) asm volatile("s_waitcnt vmcnt(" #n ")" ::: "memory")
; #define PG8_WAIT_L(n) asm volatile("s_waitcnt lgkmcnt(" #n ")" ::: "memory")
; #define PG8_BAR __builtin_amdgcn_s_barrier()
; #define PG8_SCHED __builtin_amdgcn_sched_barrier(0)
; template <class Epi, class Sched, bool ALIGN_EPI = false, bool SP2 = false>
; __device__ __forceinline__ void gemm_phase(PG8_LAS unsigned char* lds, const Gemm g, const Sched& S, const Epi& E, const int wave_in) {
;     ...
;             PG8_WAIT_V(8); PG8_WAIT_L(0); PG8_BAR; PG8_MMA(1, 0, At, B0); PG8_MMA(1, 1, At, B1); PG8_BAR; PG8_SCHED;
;             PG8_LDB(B0, 1, 0); PG8_LDB(B1, 1, 1); PG8_SCHED; PG8_LDA(At, 1, 0); PG8_STAGE(PG8_SA(0, 1), a2 + hstepA, voffA);
;             PG8_WAIT_V(8); PG8_WAIT_L(0); PG8_BAR; PG8_MMA(0, 0, At, B0); PG8_MMA(0, 1, At, B1); PG8_BAR; PG8_SCHED;
	s_waitcnt lgkmcnt(0)
	v_mfma_f32_16x16x32_bf16 v[60:63], v[144:147], v[184:187], v[60:63]
	v_mfma_f32_16x16x32_bf16 v[56:59], v[160:163], v[184:187], v[56:59]
	v_mfma_f32_16x16x32_bf16 v[44:47], v[144:147], v[192:195], v[44:47]
	v_mfma_f32_16x16x32_bf16 v[40:43], v[160:163], v[192:195], v[40:43]
	v_mfma_f32_16x16x32_bf16 v[28:31], v[144:147], v[200:203], v[28:31]
	v_mfma_f32_16x16x32_bf16 v[24:27], v[160:163], v[200:203], v[24:27]
	v_mfma_f32_16x16x32_bf16 v[12:15], v[144:147], v[208:211], v[12:15]
	v_mfma_f32_16x16x32_bf16 v[8:11], v[160:163], v[208:211], v[8:11]
	v_mfma_f32_16x16x32_bf16 v[60:63], v[156:159], v[188:191], v[60:63]
	v_mfma_f32_16x16x32_bf16 v[56:59], v[164:167], v[188:191], v[56:59]
	v_mfma_f32_16x16x32_bf16 v[44:47], v[156:159], v[196:199], v[44:47]
	v_mfma_f32_16x16x32_bf16 v[40:43], v[164:167], v[196:199], v[40:43]
	v_mfma_f32_16x16x32_bf16 v[28:31], v[156:159], v[204:207], v[28:31]
	v_mfma_f32_16x16x32_bf16 v[24:27], v[164:167], v[204:207], v[24:27]
	v_mfma_f32_16x16x32_bf16 v[12:15], v[156:159], v[212:215], v[12:15]
	v_mfma_f32_16x16x32_bf16 v[8:11], v[164:167], v[212:215], v[8:11]
	v_mfma_f32_16x16x32_bf16 v[52:55], v[168:171], v[184:187], v[52:55]
	v_mfma_f32_16x16x32_bf16 v[48:51], v[176:179], v[184:187], v[48:51]
	v_mfma_f32_16x16x32_bf16 v[36:39], v[168:171], v[192:195], v[36:39]
	v_mfma_f32_16x16x32_bf16 v[32:35], v[176:179], v[192:195], v[32:35]
	v_mfma_f32_16x16x32_bf16 v[20:23], v[168:171], v[200:203], v[20:23]
	v_mfma_f32_16x16x32_bf16 v[16:19], v[176:179], v[200:203], v[16:19]
	v_mfma_f32_16x16x32_bf16 v[4:7], v[168:171], v[208:211], v[4:7]
	v_mfma_f32_16x16x32_bf16 v[0:3], v[176:179], v[208:211], v[0:3]
	v_mfma_f32_16x16x32_bf16 v[52:55], v[172:175], v[188:191], v[52:55]
	v_mfma_f32_16x16x32_bf16 v[48:51], v[180:183], v[188:191], v[48:51]
	v_mfma_f32_16x16x32_bf16 v[36:39], v[172:175], v[196:199], v[36:39]
	v_mfma_f32_16x16x32_bf16 v[32:35], v[180:183], v[196:199], v[32:35]
	v_mfma_f32_16x16x32_bf16 v[20:23], v[172:175], v[204:207], v[20:23]
	v_mfma_f32_16x16x32_bf16 v[16:19], v[180:183], v[204:207], v[16:19]
	v_mfma_f32_16x16x32_bf16 v[4:7], v[172:175], v[212:215], v[4:7]
	v_mfma_f32_16x16x32_bf16 v[0:3], v[180:183], v[212:215], v[0:3]
	s_barrier
	s_add_i32 s77, 0, 0x18000
	v_add_u32_e32 v155, s77, v149
	s_add_i32 s78, 0, 0x1c000
	ds_read_b128 v[144:147], v155
	ds_read_b128 v[156:159], v155 offset:1024
	ds_read_b128 v[160:163], v155 offset:2048
	ds_read_b128 v[164:167], v155 offset:3072
	v_add_u32_e32 v155, s78, v149
	ds_read_b128 v[168:171], v155
	ds_read_b128 v[172:175], v155 offset:1024
	ds_read_b128 v[176:179], v155 offset:2048
	ds_read_b128 v[180:183], v155 offset:3072
	s_add_u32 s58, s64, 0x160000
	s_addc_u32 s59, s65, 0
	s_mov_b32 m0, s50
	v_lshl_add_u64 v[224:225], s[58:59], 0, v[128:129]
	ds_read_b128 v[184:187], v153 offset:32768
	ds_read_b128 v[188:191], v153 offset:33792
	ds_read_b128 v[192:195], v153 offset:34816
	ds_read_b128 v[196:199], v153 offset:35840
	ds_read_b128 v[200:203], v153 offset:36864
	ds_read_b128 v[204:207], v153 offset:37888
	ds_read_b128 v[208:211], v153 offset:38912
	ds_read_b128 v[212:215], v153 offset:39936
	global_load_lds_dwordx4 v[224:225], off
	v_lshl_add_u64 v[224:225], s[58:59], 0, v[132:133]
	s_mov_b32 m0, s51
	s_nop 0
	global_load_lds_dwordx4 v[224:225], off
	s_waitcnt vmcnt(8)
	s_waitcnt lgkmcnt(0)
	s_barrier
	s_waitcnt lgkmcnt(0)
	v_mfma_f32_16x16x32_bf16 v[124:127], v[144:147], v[184:187], v[124:127]
	v_mfma_f32_16x16x32_bf16 v[120:123], v[160:163], v[184:187], v[120:123]
	v_mfma_f32_16x16x32_bf16 v[108:111], v[144:147], v[192:195], v[108:111]
	v_mfma_f32_16x16x32_bf16 v[104:107], v[160:163], v[192:195], v[104:107]
	v_mfma_f32_16x16x32_bf16 v[92:95], v[144:147], v[200:203], v[92:95]
	v_mfma_f32_16x16x32_bf16 v[88:91], v[160:163], v[200:203], v[88:91]
	v_mfma_f32_16x16x32_bf16 v[76:79], v[144:147], v[208:211], v[76:79]
	v_mfma_f32_16x16x32_bf16 v[72:75], v[160:163], v[208:211], v[72:75]
	v_mfma_f32_16x16x32_bf16 v[124:127], v[156:159], v[188:191], v[124:127]
	v_mfma_f32_16x16x32_bf16 v[120:123], v[164:167], v[188:191], v[120:123]
	v_mfma_f32_16x16x32_bf16 v[108:111], v[156:159], v[196:199], v[108:111]
	v_mfma_f32_16x16x32_bf16 v[104:107], v[164:167], v[196:199], v[104:107]
	v_mfma_f32_16x16x32_bf16 v[92:95], v[156:159], v[204:207], v[92:95]
	v_mfma_f32_16x16x32_bf16 v[88:91], v[164:167], v[204:207], v[88:91]
	v_mfma_f32_16x16x32_bf16 v[76:79], v[156:159], v[212:215], v[76:79]
	v_mfma_f32_16x16x32_bf16 v[72:75], v[164:167], v[212:215], v[72:75]
	v_mfma_f32_16x16x32_bf16 v[116:119], v[168:171], v[184:187], v[116:119]
	v_mfma_f32_16x16x32_bf16 v[112:115], v[176:179], v[184:187], v[112:115]
	v_mfma_f32_16x16x32_bf16 v[100:103], v[168:171], v[192:195], v[100:103]
	v_mfma_f32_16x16x32_bf16 v[96:99], v[176:179], v[192:195], v[96:99]
	v_mfma_f32_16x16x32_bf16 v[84:87], v[168:171], v[200:203], v[84:87]
	v_mfma_f32_16x16x32_bf16 v[80:83], v[176:179], v[200:203], v[80:83]
	v_mfma_f32_16x16x32_bf16 v[68:71], v[168:171], v[208:211], v[68:71]
	v_mfma_f32_16x16x32_bf16 v[64:67], v[176:179], v[208:211], v[64:67]
	v_mfma_f32_16x16x32_bf16 v[116:119], v[172:175], v[188:191], v[116:119]
	v_mfma_f32_16x16x32_bf16 v[112:115], v[180:183], v[188:191], v[112:115]
	v_mfma_f32_16x16x32_bf16 v[100:103], v[172:175], v[196:199], v[100:103]
	v_mfma_f32_16x16x32_bf16 v[96:99], v[180:183], v[196:199], v[96:99]
	v_mfma_f32_16x16x32_bf16 v[84:87], v[172:175], v[204:207], v[84:87]
	v_mfma_f32_16x16x32_bf16 v[80:83], v[180:183], v[204:207], v[80:83]
	v_mfma_f32_16x16x32_bf16 v[68:71], v[172:175], v[212:215], v[68:71]
	v_mfma_f32_16x16x32_bf16 v[64:67], v[180:183], v[212:215], v[64:67]
	s_barrier
; #define PG8_STAGE(bufoff, gbase, voff) do { _Pragma("unroll") for (int _i = 0; _i < 2; ++_i) \
;         __builtin_amdgcn_global_load_lds((const unsigned*)((const char*)(gbase) + (voff)[_i]), (PG8_LAS unsigned*)(lds + (bufoff) + ldsw + _i * 8192), 16, 0, 0); } while (0)
; #define PG8_LDA(dst, b, h) do { _Pragma("unroll") for (int m = 0; m < 4; ++m) _Pragma("unroll") for (int k = 0; k < 2; ++k) dst[m][k] = *(const PG8_LAS bf16x8*)(lds + PG8_SA(b, h) + aoff + m * 2048 + k * 1024); } while (0)
; #define PG8_MMA(ai, bj, At, Bt) do { __builtin_amdgcn_s_setprio(1); _Pragma("unroll") for (int m = 0; m < 4; ++m) _Pragma("unroll") for (int n = 0; n < 2; ++n) _Pragma("unroll") for (int k = 0; k < 2; ++k) \
;         acc[ai][bj][m][n] = __builtin_amdgcn_mfma_f32_16x16x32_bf16(Bt[n][k], At[m][k], acc[ai][bj][m][n], 0, 0, 0); __builtin_amdgcn_s_setprio(0); } while (0)
; #define PG8_WAIT_V(n) asm volatile("s_waitcnt vmcnt(" #n ")" ::: "memory")
; #define PG8_WAIT_L(n) asm volatile("s_waitcnt lgkmcnt(" #n ")" ::: "memory")
; #define PG8_BAR __builtin_amdgcn_s_barrier()
; #define PG8_SCHED __builtin_amdgcn_sched_barrier(0)
; template <class Epi, class Sched, bool ALIGN_EPI = false, bool SP2 = false>
; __device__ __forceinline__ void gemm_phase(PG8_LAS unsigned char* lds, const Gemm g, const Sched& S, const Epi& E, const int wave_in) {
;     ...
;             PG8_LDA(At, 1, 1); PG8_STAGE(PG8_SB(1, 0), b3, voffB); PG8_STAGE(PG8_SB(1, 1), b3 + hstep, voffB); PG8_STAGE(PG8_SA(1, 0), a3, voffA);
;             PG8_WAIT_V(8); PG8_WAIT_L(0); PG8_BAR; PG8_MMA(1, 0, At, B0); PG8_MMA(1, 1, At, B1); PG8_BAR; PG8_SCHED;
	s_add_i32 s58, s77, s11
	v_lshl_add_u64 v[216:217], v[216:217], 0, s[38:39]
	s_mov_b32 m0, s58
	ds_read_b128 v[184:187], v153 offset:49152
	ds_read_b128 v[188:191], v153 offset:50176
	ds_read_b128 v[192:195], v153 offset:51200
	ds_read_b128 v[196:199], v153 offset:52224
	ds_read_b128 v[200:203], v153 offset:53248
	ds_read_b128 v[204:207], v153 offset:54272
	ds_read_b128 v[208:211], v153 offset:55296
	ds_read_b128 v[212:215], v153 offset:56320
	global_load_lds_dwordx4 v[216:217], off
	s_add_i32 m0, s58, 0x2000
	s_add_u32 s58, s62, 0x160080
	v_lshl_add_u64 v[216:217], v[218:219], 0, s[38:39]
	s_addc_u32 s59, s63, 0
	s_add_i32 s62, s78, s11
	global_load_lds_dwordx4 v[216:217], off
	v_lshl_add_u64 v[216:217], s[58:59], 0, v[130:131]
	s_mov_b32 m0, s62
	s_nop 0
	global_load_lds_dwordx4 v[216:217], off
	v_lshl_add_u64 v[216:217], s[58:59], 0, v[134:135]
	s_add_i32 m0, s62, 0x2000
	s_nop 0
	global_load_lds_dwordx4 v[216:217], off
	v_lshl_add_u64 v[216:217], v[220:221], 0, s[38:39]
	s_mov_b32 m0, s67
	s_nop 0
	global_load_lds_dwordx4 v[216:217], off
	v_lshl_add_u64 v[216:217], v[222:223], 0, s[38:39]
	s_mov_b32 m0, s68
	s_nop 0
	global_load_lds_dwordx4 v[216:217], off
	s_waitcnt vmcnt(8)
	s_waitcnt lgkmcnt(0)
	s_barrier
	s_waitcnt lgkmcnt(0)
	v_mfma_f32_16x16x32_bf16 v[60:63], v[144:147], v[184:187], v[60:63]
	v_mfma_f32_16x16x32_bf16 v[56:59], v[160:163], v[184:187], v[56:59]
	v_mfma_f32_16x16x32_bf16 v[44:47], v[144:147], v[192:195], v[44:47]
	v_mfma_f32_16x16x32_bf16 v[40:43], v[160:163], v[192:195], v[40:43]
	v_mfma_f32_16x16x32_bf16 v[28:31], v[144:147], v[200:203], v[28:31]
	v_mfma_f32_16x16x32_bf16 v[24:27], v[160:163], v[200:203], v[24:27]
	v_mfma_f32_16x16x32_bf16 v[12:15], v[144:147], v[208:211], v[12:15]
	v_mfma_f32_16x16x32_bf16 v[8:11], v[160:163], v[208:211], v[8:11]
	v_mfma_f32_16x16x32_bf16 v[60:63], v[156:159], v[188:191], v[60:63]
	v_mfma_f32_16x16x32_bf16 v[56:59], v[164:167], v[188:191], v[56:59]
	v_mfma_f32_16x16x32_bf16 v[44:47], v[156:159], v[196:199], v[44:47]
	v_mfma_f32_16x16x32_bf16 v[40:43], v[164:167], v[196:199], v[40:43]
	v_mfma_f32_16x16x32_bf16 v[28:31], v[156:159], v[204:207], v[28:31]
	v_mfma_f32_16x16x32_bf16 v[24:27], v[164:167], v[204:207], v[24:27]
	v_mfma_f32_16x16x32_bf16 v[12:15], v[156:159], v[212:215], v[12:15]
	v_mfma_f32_16x16x32_bf16 v[8:11], v[164:167], v[212:215], v[8:11]
	v_mfma_f32_16x16x32_bf16 v[52:55], v[168:171], v[184:187], v[52:55]
	v_mfma_f32_16x16x32_bf16 v[48:51], v[176:179], v[184:187], v[48:51]
	v_mfma_f32_16x16x32_bf16 v[36:39], v[168:171], v[192:195], v[36:39]
	v_mfma_f32_16x16x32_bf16 v[32:35], v[176:179], v[192:195], v[32:35]
	v_mfma_f32_16x16x32_bf16 v[20:23], v[168:171], v[200:203], v[20:23]
	v_mfma_f32_16x16x32_bf16 v[16:19], v[176:179], v[200:203], v[16:19]
	v_mfma_f32_16x16x32_bf16 v[4:7], v[168:171], v[208:211], v[4:7]
	v_mfma_f32_16x16x32_bf16 v[0:3], v[176:179], v[208:211], v[0:3]
	v_mfma_f32_16x16x32_bf16 v[52:55], v[172:175], v[188:191], v[52:55]
	v_mfma_f32_16x16x32_bf16 v[48:51], v[180:183], v[188:191], v[48:51]
	v_mfma_f32_16x16x32_bf16 v[36:39], v[172:175], v[196:199], v[36:39]
	v_mfma_f32_16x16x32_bf16 v[32:35], v[180:183], v[196:199], v[32:35]
	v_mfma_f32_16x16x32_bf16 v[20:23], v[172:175], v[204:207], v[20:23]
	v_mfma_f32_16x16x32_bf16 v[16:19], v[180:183], v[204:207], v[16:19]
	v_mfma_f32_16x16x32_bf16 v[4:7], v[172:175], v[212:215], v[4:7]
	v_mfma_f32_16x16x32_bf16 v[0:3], v[180:183], v[212:215], v[0:3]
	s_barrier
	s_add_i32 s76, s76, 2
	s_add_u32 s74, s74, 0x100
	s_addc_u32 s75, s75, 0
	s_cmpk_gt_u32 s76, 0x55
	s_mov_b64 s[58:59], s[60:61]
	s_cbranch_scc0 .LBB0_1475
	s_and_b64 vcc, exec, s[40:41]
	s_cbranch_vccz .LBB0_1478
	s_barrier

; __device__ __forceinline__ int mk_lane() { int l; asm volatile("v_mbcnt_lo_u32_b32 %0, -1, 0\n\tv_mbcnt_hi_u32_b32 %0, -1, %0" : "=v"(l)); return l; }
; #define PG8_STAGE(bufoff, gbase, voff) do { _Pragma("unroll") for (int _i = 0; _i < 2; ++_i) \
;         __builtin_amdgcn_global_load_lds((const unsigned*)((const char*)(gbase) + (voff)[_i]), (PG8_LAS unsigned*)(lds + (bufoff) + ldsw + _i * 8192), 16, 0, 0); } while (0)
; #define PG8_WAIT_V(n) asm volatile("s_waitcnt vmcnt(" #n ")" ::: "memory")
; #define lane mk_lane()
; template <class Epi, class Sched, bool ALIGN_EPI = false, bool SP2 = false>
; __device__ __forceinline__ void gemm_phase(PG8_LAS unsigned char* lds, const Gemm g, const Sched& S, const Epi& E, const int wave_in) {
;     const int wid = __builtin_amdgcn_readfirstlane(wave_in), lane = mk_lane(), tid = wid * 64 + lane, wr = wid >> 2, wc = wid & 3, fr = lane & 15, fq = lane >> 4;
;     const int K = g.K, nt = K / BK;
;     unsigned voffA[2], voffB[2];
; #pragma unroll
;     for (int i = 0; i < 2; ++i) { int R, C; stage_rc(tid * 16 + i * 8192, R, C); const int Rb = Epi::PERM ? ((R & ~31) + perm32(R & 31)) : R;
;         voffA[i] = (unsigned)(R * g.lda + C) * 2u; voffB[i] = (unsigned)(Rb * K + C) * 2u; }
;     const size_t kstep = (size_t)(BK * 2);
;     const size_t hstep = (size_t)HALF * K * 2, hstepA = (size_t)HALF * g.lda * 2;
;     const size_t tstep = 2 * hstep, tstepA = 2 * hstepA;
;     const unsigned ldsw = (unsigned)wid * 1024u;
;     const int aoff = lds_byte(wr * 64 + fr, fq * 8), boff = lds_byte(wc * 32 + fr, fq * 8);
;     ...
;     Unit cur, nxt; int ui = 0;
;     if (!S.next(0, cur)) return;
;     f32x4 acc[2][2][4][2];
; #pragma unroll
;     for (int a = 0; a < 2; ++a)
; #pragma unroll
;         for (int b = 0; b < 2; ++b)
; #pragma unroll
;             for (int m = 0; m < 4; ++m)
; #pragma unroll
;                 for (int n = 0; n < 2; ++n) acc[a][b][m][n] = (f32x4){0.f, 0.f, 0.f, 0.f};
;     bf16x8 At[4][2], B0[2][2], B1[2][2];
;     const char* cA = (const char*)g.A + (size_t)cur.pm * tstepA; const char* cB = (const char*)g.Bt + (size_t)cur.pn * tstep;
;     S.a_ready(cur);
;     if constexpr (SP2) {
;         PG8_STAGE(PG8_SB(0, 0), cB, voffB); PG8_STAGE(PG8_SB(0, 1), cB + hstep, voffB); PG8_STAGE(PG8_SA(0, 0), cA, voffA); PG8_STAGE(PG8_SA(0, 1), cA + hstepA, voffA);
;         if (wr == 1) PG8_BAR;
;         PG8_WAIT_V(2); PG8_BAR;
.LBB0_1552:
	s_cmp_lt_i32 s92, 11
	s_cselect_b64 s[0:1], -1, 0
	s_cmp_gt_i32 s93, 10
	s_cselect_b64 s[2:3], -1, 0
	s_and_b64 s[0:1], s[0:1], s[2:3]
	s_andn2_b64 vcc, exec, s[0:1]
	s_waitcnt lgkmcnt(0)
	s_barrier
	s_cbranch_vccnz .LBB0_1569
	s_setprio 0
	s_cmp_lt_u32 s89, 4
	s_cbranch_scc1 .Lgprio_6
	s_setprio 1
.Lgprio_6:
	s_cmpk_gt_i32 s88, 0x15ff
	s_waitcnt vmcnt(0)
	v_mbcnt_lo_u32_b32 v10, -1, 0
	v_mbcnt_hi_u32_b32 v10, -1, v10
	s_cbranch_scc1 .LBB0_1569
	s_lshl_b32 s11, s89, 10
	v_lshl_add_u32 v0, v10, 4, s11
	v_add_u32_e32 v1, 0x2000, v0
	v_ashrrev_i32_e32 v2, 31, v1
	v_lshrrev_b32_e32 v2, 22, v2
	v_add_u32_e32 v2, v1, v2
	v_ashrrev_i32_e32 v8, 10, v2
	v_mul_i32_i24_e32 v2, 0x400, v8
	v_sub_u32_e32 v1, v1, v2
	v_lshrrev_b32_e32 v2, 4, v1
	v_bitop3_b32 v1, v2, v1, 32 bitop3:0x6c
	v_ashrrev_i32_e32 v2, 31, v1
	v_lshrrev_b32_e32 v2, 26, v2
	v_add_u32_e32 v2, v1, v2
	v_ashrrev_i32_e32 v9, 6, v2
	v_lshlrev_b32_e32 v3, 3, v8
	v_and_b32_e32 v2, 0xffc0, v2
	v_and_b32_e32 v3, -16, v3
	v_sub_u32_e32 v1, v1, v2
	v_add_u32_e32 v3, v9, v3
	v_lshrrev_b16_e32 v2, 7, v1
	v_and_b32_e32 v4, 3, v9
	s_mov_b32 s0, 0xfffe0
	v_lshrrev_b32_e32 v5, 2, v3
	v_lshlrev_b32_e32 v6, 1, v3
	v_and_b32_e32 v2, 1, v2
	v_and_or_b32 v4, v3, s0, v4
	v_and_b32_e32 v5, 4, v5
	v_and_b32_e32 v6, 24, v6
	v_add_u16_e32 v1, v1, v2
	v_mov_b32_e32 v2, 1
	v_or3_b32 v4, v4, v5, v6
	v_lshlrev_b32_e32 v5, 5, v8
	v_ashrrev_i16_sdwa v1, v2, sext(v1) dst_sel:DWORD dst_unused:UNUSED_PAD src0_sel:DWORD src1_sel:BYTE_0
	v_and_b32_e32 v5, 32, v5
	v_bfe_i32 v11, v1, 0, 16
	v_add_lshl_u32 v1, v5, v11, 1
	v_lshl_add_u32 v128, v4, 12, v1
	v_lshl_add_u32 v130, v3, 12, v1
	v_ashrrev_i32_e32 v1, 31, v0
	v_lshrrev_b32_e32 v1, 22, v1
	v_add_u32_e32 v1, v0, v1
	v_ashrrev_i32_e32 v12, 10, v1
	v_mul_i32_i24_e32 v1, 0x400, v12
	v_sub_u32_e32 v0, v0, v1
	v_lshrrev_b32_e32 v1, 4, v0
	v_bitop3_b32 v0, v1, v0, 32 bitop3:0x6c
	v_ashrrev_i32_e32 v1, 31, v0
	v_lshrrev_b32_e32 v1, 26, v1
	v_add_u32_e32 v1, v0, v1
	v_lshlrev_b32_e32 v3, 3, v12
	v_ashrrev_i32_e32 v13, 6, v1
	v_and_b32_e32 v3, -16, v3
	v_add_u32_e32 v3, v13, v3
	v_and_b32_e32 v4, 3, v13
	s_ashr_i32 s33, s88, 31
	v_and_or_b32 v4, v3, s0, v4
	s_lshr_b32 s0, s33, 29
	s_add_i32 s0, s88, s0
	s_ashr_i32 s1, s0, 3
	s_and_b32 s0, s0, -8
	s_ashr_i32 s3, s89, 2
	s_sub_i32 s0, s88, s0
	s_cmp_lt_i32 s0, 0
	s_movk_i32 s35, 0x2c1
	s_cselect_b32 s2, s35, 0x2c0
	s_mul_i32 s0, s0, s2
	s_add_i32 s0, s0, s1
	s_mul_hi_i32 s1, s0, 0x2e8ba2e9
	s_lshr_b32 s2, s1, 31
	s_ashr_i32 s1, s1, 6
	s_add_i32 s1, s1, s2
	s_lshl_b32 s4, s1, 3
	s_mulk_i32 s1, 0x160
	s_sub_i32 s0, s0, s1
	s_sext_i32_i16 s1, s0
	s_bfe_u32 s1, s1, 0x3001c
	s_add_i32 s1, s0, s1
	s_sext_i32_i16 s2, s1
	s_and_b32 s1, s1, 0xfff8
	s_sub_i32 s0, s0, s1
	s_sext_i32_i16 s0, s0
	v_lshrrev_b32_e32 v5, 2, v3
	v_lshlrev_b32_e32 v6, 1, v3
	v_and_b32_e32 v1, 0xc0, v1
	s_lshr_b32 s2, s2, 3
	s_add_i32 s60, s4, s0
	v_and_b32_e32 v5, 4, v5
	v_and_b32_e32 v6, 24, v6
	v_sub_u32_e32 v0, v0, v1
	s_ashr_i32 s61, s60, 31
	s_bfe_i64 s[4:5], s[2:3], 0x100000
	v_or3_b32 v4, v4, v5, v6
	v_lshlrev_b32_e32 v5, 5, v12
	v_ashrrev_i16_sdwa v0, v2, sext(v0) dst_sel:DWORD dst_unused:UNUSED_PAD src0_sel:DWORD src1_sel:BYTE_0
	s_lshl_b64 s[0:1], s[60:61], 20
	s_lshl_b64 s[4:5], s[4:5], 20
	v_and_b32_e32 v5, 32, v5
	v_bfe_i32 v14, v0, 0, 16
	s_add_u32 s64, s56, s4
	v_add_lshl_u32 v0, v5, v14, 1
	s_addc_u32 s65, s57, s5
	s_add_i32 s48, s11, 0
	v_lshl_add_u32 v132, v4, 12, v0
	s_add_i32 m0, s48, 0x10000
	v_lshl_add_u32 v134, v3, 12, v0
	global_load_lds_dwordx4 v132, s[64:65]
	s_add_i32 m0, s48, 0x12000
	s_add_u32 s4, s64, 0x80000
	global_load_lds_dwordx4 v128, s[64:65]
	s_addc_u32 s5, s65, 0
	s_add_i32 m0, s48, 0x14000
	v_mov_b32_e32 v133, 0
	global_load_lds_dwordx4 v132, s[4:5]
	s_add_i32 m0, s48, 0x16000
	s_add_u32 s62, s46, s0
	s_addc_u32 s63, s47, s1
	s_add_i32 s49, s48, 0x2000
	global_load_lds_dwordx4 v128, s[4:5]
	s_mov_b32 m0, s48
	s_add_u32 s0, s62, 0x80000
	global_load_lds_dwordx4 v134, s[62:63]
	s_mov_b32 m0, s49
	s_addc_u32 s1, s63, 0
	s_add_i32 s50, s48, 0x4000
	global_load_lds_dwordx4 v130, s[62:63]
	s_mov_b32 m0, s50
	s_add_i32 s51, s48, 0x6000
	global_load_lds_dwordx4 v134, s[0:1]
	s_mov_b32 m0, s51
	v_mov_b32_e32 v129, v133
	global_load_lds_dwordx4 v130, s[0:1]
	v_mov_b32_e32 v135, v133
	v_mov_b32_e32 v131, v133
	s_cmp_eq_u32 s3, 1
	s_mov_b32 s61, 0
	v_lshl_add_u64 v[6:7], s[64:65], 0, v[132:133]
	v_lshl_add_u64 v[4:5], s[64:65], 0, v[128:129]
	v_lshl_add_u64 v[0:1], s[62:63], 0, v[134:135]
	s_cselect_b64 s[0:1], -1, 0
	s_cmp_lg_u32 s3, 1
	v_lshl_add_u64 v[2:3], s[62:63], 0, v[130:131]
	s_cbranch_scc1 .LBB0_1556
	s_barrier

; #define GEMM_RESID(Aop, Kdim, WT, XIN, ssi, ALPHA) do { pg8::Gemm g_{Aop, WT, T, DM, Kdim, Kdim}; pg8::StaticOrder S_; S_.init(T, DM, G, bx); pg8::EpiResid E_{XIN, p.out, XB, SS + (size_t)(ssi) * T, ALPHA}; \
;         pg8::gemm_phase<pg8::EpiResid, pg8::StaticOrder, true, true>(ldsl, g_, S_, E_, wave); } while (0)
; __global__ void __launch_bounds__(512, 2) fwd_kernel(Params p) {
;     ...
;     if (IN(11)) GEMM_RESID(Hh, FF, W_DN2, p.out, 4, 0.5f);
.LBB0_1623:
	s_cmp_lt_i32 s92, 12
	s_cselect_b64 s[0:1], -1, 0
	s_cmp_gt_i32 s93, 11
	s_cselect_b64 s[2:3], -1, 0
	s_and_b64 s[0:1], s[0:1], s[2:3]
	s_andn2_b64 vcc, exec, s[0:1]
	s_waitcnt lgkmcnt(0)
	s_barrier
	s_cbranch_vccnz .LBB0_1670
	s_setprio 0
	s_cmp_lt_u32 s89, 4
	s_cbranch_scc1 .Lgprio_7
	s_setprio 1

; #define PG8_STAGE(bufoff, gbase, voff) do { _Pragma("unroll") for (int _i = 0; _i < 2; ++_i) \
;         __builtin_amdgcn_global_load_lds((const unsigned*)((const char*)(gbase) + (voff)[_i]), (PG8_LAS unsigned*)(lds + (bufoff) + ldsw + _i * 8192), 16, 0, 0); } while (0)
; #define PG8_LDA(dst, b, h) do { _Pragma("unroll") for (int m = 0; m < 4; ++m) _Pragma("unroll") for (int k = 0; k < 2; ++k) dst[m][k] = *(const PG8_LAS bf16x8*)(lds + PG8_SA(b, h) + aoff + m * 2048 + k * 1024); } while (0)
; #define PG8_LDB(dst, b, h) do { _Pragma("unroll") for (int n = 0; n < 2; ++n) _Pragma("unroll") for (int k = 0; k < 2; ++k) dst[n][k] = *(const PG8_LAS bf16x8*)(lds + PG8_SB(b, h) + boff + n * 2048 + k * 1024); } while (0)
; #define PG8_MMA(ai, bj, At, Bt) do { __builtin_amdgcn_s_setprio(1); _Pragma("unroll") for (int m = 0; m < 4; ++m) _Pragma("unroll") for (int n = 0; n < 2; ++n) _Pragma("unroll") for (int k = 0; k < 2; ++k) \
;         acc[ai][bj][m][n] = __builtin_amdgcn_mfma_f32_16x16x32_bf16(Bt[n][k], At[m][k], acc[ai][bj][m][n], 0, 0, 0); __builtin_amdgcn_s_setprio(0); } while (0)
; #define PG8_WAIT_V(n) asm volatile("s_waitcnt vmcnt(" #n ")" ::: "memory")
; #define PG8_WAIT_L(n) asm volatile("s_waitcnt lgkmcnt(" #n ")" ::: "memory")
; #define PG8_BAR __builtin_amdgcn_s_barrier()
; #define PG8_SCHED __builtin_amdgcn_sched_barrier(0)
; template <class Epi, class Sched, bool ALIGN_EPI = false, bool SP2 = false>
; __device__ __forceinline__ void gemm_phase(PG8_LAS unsigned char* lds, const Gemm g, const Sched& S, const Epi& E, const int wave_in) {
;     ...
;             PG8_LDB(B0, 0, 0); PG8_LDB(B1, 0, 1); PG8_SCHED; PG8_LDA(At, 0, 0); PG8_STAGE(PG8_SA(1, 1), a1 + hstepA, voffA);
;             PG8_WAIT_V(8); PG8_WAIT_L(0); PG8_BAR; PG8_MMA(0, 0, At, B0); PG8_MMA(0, 1, At, B1); PG8_BAR; PG8_SCHED;
;             PG8_LDA(At, 0, 1); PG8_STAGE(PG8_SB(0, 0), b2, voffB); PG8_STAGE(PG8_SB(0, 1), b2 + hstep, voffB); PG8_STAGE(PG8_SA(0, 0), a2, voffA);
.LBB0_1647:
	ds_read_b128 v[144:147], v151
	ds_read_b128 v[156:159], v151 offset:1024
	ds_read_b128 v[160:163], v151 offset:2048
	ds_read_b128 v[164:167], v151 offset:3072
	ds_read_b128 v[168:171], v152
	ds_read_b128 v[172:175], v152 offset:1024
	ds_read_b128 v[176:179], v152 offset:2048
	ds_read_b128 v[180:183], v152 offset:3072
	s_add_u32 s58, s56, 0x100
	s_addc_u32 s59, s57, 0
	s_cmpk_eq_i32 s74, 0x54
	s_cselect_b32 s63, s7, s59
	s_cselect_b32 s62, s6, s58
	s_cselect_b32 s61, s43, s73
	s_cselect_b32 s60, s42, s72
	v_lshl_add_u64 v[216:217], s[56:57], 0, v[136:137]
	s_add_i32 m0, s33, 0xc000
	ds_read_b128 v[184:187], v153
	ds_read_b128 v[188:191], v153 offset:1024
	ds_read_b128 v[192:195], v153 offset:2048
	ds_read_b128 v[196:199], v153 offset:3072
	ds_read_b128 v[200:203], v153 offset:4096
	ds_read_b128 v[204:207], v153 offset:5120
	ds_read_b128 v[208:211], v153 offset:6144
	ds_read_b128 v[212:215], v153 offset:7168
	global_load_lds_dwordx4 v[216:217], off
	v_lshl_add_u64 v[216:217], s[56:57], 0, v[138:139]
	s_add_i32 m0, s33, 0xe000
	s_nop 0
	global_load_lds_dwordx4 v[216:217], off
	s_waitcnt vmcnt(8)
	s_waitcnt lgkmcnt(0)
	s_barrier
	s_waitcnt lgkmcnt(0)
	v_mfma_f32_16x16x32_bf16 v[124:127], v[144:147], v[184:187], v[124:127]
	v_mfma_f32_16x16x32_bf16 v[120:123], v[160:163], v[184:187], v[120:123]
	v_mfma_f32_16x16x32_bf16 v[108:111], v[144:147], v[192:195], v[108:111]
	v_mfma_f32_16x16x32_bf16 v[104:107], v[160:163], v[192:195], v[104:107]
	v_mfma_f32_16x16x32_bf16 v[92:95], v[144:147], v[200:203], v[92:95]
	v_mfma_f32_16x16x32_bf16 v[88:91], v[160:163], v[200:203], v[88:91]
	v_mfma_f32_16x16x32_bf16 v[76:79], v[144:147], v[208:211], v[76:79]
	v_mfma_f32_16x16x32_bf16 v[72:75], v[160:163], v[208:211], v[72:75]
	v_mfma_f32_16x16x32_bf16 v[124:127], v[156:159], v[188:191], v[124:127]
	v_mfma_f32_16x16x32_bf16 v[120:123], v[164:167], v[188:191], v[120:123]
	v_mfma_f32_16x16x32_bf16 v[108:111], v[156:159], v[196:199], v[108:111]
	v_mfma_f32_16x16x32_bf16 v[104:107], v[164:167], v[196:199], v[104:107]
	v_mfma_f32_16x16x32_bf16 v[92:95], v[156:159], v[204:207], v[92:95]
	v_mfma_f32_16x16x32_bf16 v[88:91], v[164:167], v[204:207], v[88:91]
	v_mfma_f32_16x16x32_bf16 v[76:79], v[156:159], v[212:215], v[76:79]
	v_mfma_f32_16x16x32_bf16 v[72:75], v[164:167], v[212:215], v[72:75]
	v_mfma_f32_16x16x32_bf16 v[116:119], v[168:171], v[184:187], v[116:119]
	v_mfma_f32_16x16x32_bf16 v[112:115], v[176:179], v[184:187], v[112:115]
	v_mfma_f32_16x16x32_bf16 v[100:103], v[168:171], v[192:195], v[100:103]
	v_mfma_f32_16x16x32_bf16 v[96:99], v[176:179], v[192:195], v[96:99]
	v_mfma_f32_16x16x32_bf16 v[84:87], v[168:171], v[200:203], v[84:87]
	v_mfma_f32_16x16x32_bf16 v[80:83], v[176:179], v[200:203], v[80:83]
	v_mfma_f32_16x16x32_bf16 v[68:71], v[168:171], v[208:211], v[68:71]
	v_mfma_f32_16x16x32_bf16 v[64:67], v[176:179], v[208:211], v[64:67]
	v_mfma_f32_16x16x32_bf16 v[116:119], v[172:175], v[188:191], v[116:119]
	v_mfma_f32_16x16x32_bf16 v[112:115], v[180:183], v[188:191], v[112:115]
	v_mfma_f32_16x16x32_bf16 v[100:103], v[172:175], v[196:199], v[100:103]
	v_mfma_f32_16x16x32_bf16 v[96:99], v[180:183], v[196:199], v[96:99]
	v_mfma_f32_16x16x32_bf16 v[84:87], v[172:175], v[204:207], v[84:87]
	v_mfma_f32_16x16x32_bf16 v[80:83], v[180:183], v[204:207], v[80:83]
	v_mfma_f32_16x16x32_bf16 v[68:71], v[172:175], v[212:215], v[68:71]
	v_mfma_f32_16x16x32_bf16 v[64:67], v[180:183], v[212:215], v[64:67]
	s_barrier
	s_add_i32 s56, s68, s11
	v_lshl_add_u64 v[216:217], s[60:61], 0, v[130:131]
	s_mov_b32 m0, s56
	ds_read_b128 v[184:187], v153 offset:16384
	ds_read_b128 v[188:191], v153 offset:17408
	ds_read_b128 v[192:195], v153 offset:18432
	ds_read_b128 v[196:199], v153 offset:19456
	ds_read_b128 v[200:203], v153 offset:20480
	ds_read_b128 v[204:207], v153 offset:21504
	ds_read_b128 v[208:211], v153 offset:22528
	ds_read_b128 v[212:215], v153 offset:23552
	global_load_lds_dwordx4 v[216:217], off
	s_add_i32 m0, s56, 0x2000
	s_add_u32 s56, s60, 0x160000
	v_lshl_add_u64 v[218:219], s[60:61], 0, v[134:135]
	s_addc_u32 s57, s61, 0
	s_add_i32 s75, s69, s11
	global_load_lds_dwordx4 v[218:219], off
	v_lshl_add_u64 v[220:221], s[56:57], 0, v[130:131]
	s_mov_b32 m0, s75
	v_lshl_add_u64 v[222:223], s[62:63], 0, v[132:133]
	global_load_lds_dwordx4 v[220:221], off
	v_lshl_add_u64 v[220:221], s[56:57], 0, v[134:135]
	s_add_i32 m0, s75, 0x2000
	s_nop 0
	global_load_lds_dwordx4 v[220:221], off
	v_lshl_add_u64 v[220:221], s[62:63], 0, v[128:129]
	s_mov_b32 m0, s33
	s_nop 0
	global_load_lds_dwordx4 v[220:221], off
	s_mov_b32 m0, s35
	s_nop 0
	global_load_lds_dwordx4 v[222:223], off
	s_waitcnt vmcnt(8)
	s_waitcnt lgkmcnt(0)
	s_barrier
; #define PG8_STAGE(bufoff, gbase, voff) do { _Pragma("unroll") for (int _i = 0; _i < 2; ++_i) \
;         __builtin_amdgcn_global_load_lds((const unsigned*)((const char*)(gbase) + (voff)[_i]), (PG8_LAS unsigned*)(lds + (bufoff) + ldsw + _i * 8192), 16, 0, 0); } while (0)
; #define PG8_LDA(dst, b, h) do { _Pragma("unroll") for (int m = 0; m < 4; ++m) _Pragma("unroll") for (int k = 0; k < 2; ++k) dst[m][k] = *(const PG8_LAS bf16x8*)(lds + PG8_SA(b, h) + aoff + m * 2048 + k * 1024); } while (0)
; #define PG8_LDB(dst, b, h) do { _Pragma("unroll") for (int n = 0; n < 2; ++n) _Pragma("unroll") for (int k = 0; k < 2; ++k) dst[n][k] = *(const PG8_LAS bf16x8*)(lds + PG8_SB(b, h) + boff + n * 2048 + k * 1024); } while (0)
; #define PG8_MMA(ai, bj, At, Bt) do { __builtin_amdgcn_s_setprio(1); _Pragma("unroll") for (int m = 0; m < 4; ++m) _Pragma("unroll") for (int n = 0; n < 2; ++n) _Pragma("unroll") for (int k = 0; k < 2; ++k) \
;         acc[ai][bj][m][n] = __builtin_amdgcn_mfma_f32_16x16x32_bf16(Bt[n][k], At[m][k], acc[ai][bj][m][n], 0, 0, 0); __builtin_amdgcn_s_setprio(0); } while (0)
; #define PG8_WAIT_V(n) asm volatile("s_waitcnt vmcnt(" #n ")" ::: "memory")
; #define PG8_WAIT_L(n) asm volatile("s_waitcnt lgkmcnt(" #n ")" ::: "memory")
; #define PG8_BAR __builtin_amdgcn_s_barrier()
; #define PG8_SCHED __builtin_amdgcn_sched_barrier(0)
; template <class Epi, class Sched, bool ALIGN_EPI = false, bool SP2 = false>
; __device__ __forceinline__ void gemm_phase(PG8_LAS unsigned char* lds, const Gemm g, const Sched& S, const Epi& E, const int wave_in) {
;     ...
;             PG8_WAIT_V(8); PG8_WAIT_L(0); PG8_BAR; PG8_MMA(1, 0, At, B0); PG8_MMA(1, 1, At, B1); PG8_BAR; PG8_SCHED;
;             PG8_LDB(B0, 1, 0); PG8_LDB(B1, 1, 1); PG8_SCHED; PG8_LDA(At, 1, 0); PG8_STAGE(PG8_SA(0, 1), a2 + hstepA, voffA);
;             PG8_WAIT_V(8); PG8_WAIT_L(0); PG8_BAR; PG8_MMA(0, 0, At, B0); PG8_MMA(0, 1, At, B1); PG8_BAR; PG8_SCHED;
	s_waitcnt lgkmcnt(0)
	v_mfma_f32_16x16x32_bf16 v[60:63], v[144:147], v[184:187], v[60:63]
	v_mfma_f32_16x16x32_bf16 v[56:59], v[160:163], v[184:187], v[56:59]
	v_mfma_f32_16x16x32_bf16 v[44:47], v[144:147], v[192:195], v[44:47]
	v_mfma_f32_16x16x32_bf16 v[40:43], v[160:163], v[192:195], v[40:43]
	v_mfma_f32_16x16x32_bf16 v[28:31], v[144:147], v[200:203], v[28:31]
	v_mfma_f32_16x16x32_bf16 v[24:27], v[160:163], v[200:203], v[24:27]
	v_mfma_f32_16x16x32_bf16 v[12:15], v[144:147], v[208:211], v[12:15]
	v_mfma_f32_16x16x32_bf16 v[8:11], v[160:163], v[208:211], v[8:11]
	v_mfma_f32_16x16x32_bf16 v[60:63], v[156:159], v[188:191], v[60:63]
	v_mfma_f32_16x16x32_bf16 v[56:59], v[164:167], v[188:191], v[56:59]
	v_mfma_f32_16x16x32_bf16 v[44:47], v[156:159], v[196:199], v[44:47]
	v_mfma_f32_16x16x32_bf16 v[40:43], v[164:167], v[196:199], v[40:43]
	v_mfma_f32_16x16x32_bf16 v[28:31], v[156:159], v[204:207], v[28:31]
	v_mfma_f32_16x16x32_bf16 v[24:27], v[164:167], v[204:207], v[24:27]
	v_mfma_f32_16x16x32_bf16 v[12:15], v[156:159], v[212:215], v[12:15]
	v_mfma_f32_16x16x32_bf16 v[8:11], v[164:167], v[212:215], v[8:11]
	v_mfma_f32_16x16x32_bf16 v[52:55], v[168:171], v[184:187], v[52:55]
	v_mfma_f32_16x16x32_bf16 v[48:51], v[176:179], v[184:187], v[48:51]
	v_mfma_f32_16x16x32_bf16 v[36:39], v[168:171], v[192:195], v[36:39]
	v_mfma_f32_16x16x32_bf16 v[32:35], v[176:179], v[192:195], v[32:35]
	v_mfma_f32_16x16x32_bf16 v[20:23], v[168:171], v[200:203], v[20:23]
	v_mfma_f32_16x16x32_bf16 v[16:19], v[176:179], v[200:203], v[16:19]
	v_mfma_f32_16x16x32_bf16 v[4:7], v[168:171], v[208:211], v[4:7]
	v_mfma_f32_16x16x32_bf16 v[0:3], v[176:179], v[208:211], v[0:3]
	v_mfma_f32_16x16x32_bf16 v[52:55], v[172:175], v[188:191], v[52:55]
	v_mfma_f32_16x16x32_bf16 v[48:51], v[180:183], v[188:191], v[48:51]
	v_mfma_f32_16x16x32_bf16 v[36:39], v[172:175], v[196:199], v[36:39]
	v_mfma_f32_16x16x32_bf16 v[32:35], v[180:183], v[196:199], v[32:35]
	v_mfma_f32_16x16x32_bf16 v[20:23], v[172:175], v[204:207], v[20:23]
	v_mfma_f32_16x16x32_bf16 v[16:19], v[180:183], v[204:207], v[16:19]
	v_mfma_f32_16x16x32_bf16 v[4:7], v[172:175], v[212:215], v[4:7]
	v_mfma_f32_16x16x32_bf16 v[0:3], v[180:183], v[212:215], v[0:3]
	s_barrier
	s_add_i32 s75, 0, 0x18000
	v_add_u32_e32 v155, s75, v149
	s_add_i32 s76, 0, 0x1c000
	ds_read_b128 v[144:147], v155
	ds_read_b128 v[156:159], v155 offset:1024
	ds_read_b128 v[160:163], v155 offset:2048
	ds_read_b128 v[164:167], v155 offset:3072
	v_add_u32_e32 v155, s76, v149
	ds_read_b128 v[168:171], v155
	ds_read_b128 v[172:175], v155 offset:1024
	ds_read_b128 v[176:179], v155 offset:2048
	ds_read_b128 v[180:183], v155 offset:3072
	s_add_u32 s56, s62, 0x160000
	s_addc_u32 s57, s63, 0
	s_mov_b32 m0, s50
	v_lshl_add_u64 v[224:225], s[56:57], 0, v[128:129]
	ds_read_b128 v[184:187], v153 offset:32768
	ds_read_b128 v[188:191], v153 offset:33792
	ds_read_b128 v[192:195], v153 offset:34816
	ds_read_b128 v[196:199], v153 offset:35840
	ds_read_b128 v[200:203], v153 offset:36864
	ds_read_b128 v[204:207], v153 offset:37888
	ds_read_b128 v[208:211], v153 offset:38912
	ds_read_b128 v[212:215], v153 offset:39936
	global_load_lds_dwordx4 v[224:225], off
	v_lshl_add_u64 v[224:225], s[56:57], 0, v[132:133]
	s_mov_b32 m0, s51
	s_nop 0
	global_load_lds_dwordx4 v[224:225], off
	s_waitcnt vmcnt(8)
	s_waitcnt lgkmcnt(0)
	s_barrier
	s_waitcnt lgkmcnt(0)
	v_mfma_f32_16x16x32_bf16 v[124:127], v[144:147], v[184:187], v[124:127]
	v_mfma_f32_16x16x32_bf16 v[120:123], v[160:163], v[184:187], v[120:123]
	v_mfma_f32_16x16x32_bf16 v[108:111], v[144:147], v[192:195], v[108:111]
	v_mfma_f32_16x16x32_bf16 v[104:107], v[160:163], v[192:195], v[104:107]
	v_mfma_f32_16x16x32_bf16 v[92:95], v[144:147], v[200:203], v[92:95]
	v_mfma_f32_16x16x32_bf16 v[88:91], v[160:163], v[200:203], v[88:91]
	v_mfma_f32_16x16x32_bf16 v[76:79], v[144:147], v[208:211], v[76:79]
	v_mfma_f32_16x16x32_bf16 v[72:75], v[160:163], v[208:211], v[72:75]
	v_mfma_f32_16x16x32_bf16 v[124:127], v[156:159], v[188:191], v[124:127]
	v_mfma_f32_16x16x32_bf16 v[120:123], v[164:167], v[188:191], v[120:123]
	v_mfma_f32_16x16x32_bf16 v[108:111], v[156:159], v[196:199], v[108:111]
	v_mfma_f32_16x16x32_bf16 v[104:107], v[164:167], v[196:199], v[104:107]
	v_mfma_f32_16x16x32_bf16 v[92:95], v[156:159], v[204:207], v[92:95]
	v_mfma_f32_16x16x32_bf16 v[88:91], v[164:167], v[204:207], v[88:91]
	v_mfma_f32_16x16x32_bf16 v[76:79], v[156:159], v[212:215], v[76:79]
	v_mfma_f32_16x16x32_bf16 v[72:75], v[164:167], v[212:215], v[72:75]
	v_mfma_f32_16x16x32_bf16 v[116:119], v[168:171], v[184:187], v[116:119]
	v_mfma_f32_16x16x32_bf16 v[112:115], v[176:179], v[184:187], v[112:115]
	v_mfma_f32_16x16x32_bf16 v[100:103], v[168:171], v[192:195], v[100:103]
	v_mfma_f32_16x16x32_bf16 v[96:99], v[176:179], v[192:195], v[96:99]
	v_mfma_f32_16x16x32_bf16 v[84:87], v[168:171], v[200:203], v[84:87]
	v_mfma_f32_16x16x32_bf16 v[80:83], v[176:179], v[200:203], v[80:83]
	v_mfma_f32_16x16x32_bf16 v[68:71], v[168:171], v[208:211], v[68:71]
	v_mfma_f32_16x16x32_bf16 v[64:67], v[176:179], v[208:211], v[64:67]
	v_mfma_f32_16x16x32_bf16 v[116:119], v[172:175], v[188:191], v[116:119]
	v_mfma_f32_16x16x32_bf16 v[112:115], v[180:183], v[188:191], v[112:115]
	v_mfma_f32_16x16x32_bf16 v[100:103], v[172:175], v[196:199], v[100:103]
	v_mfma_f32_16x16x32_bf16 v[96:99], v[180:183], v[196:199], v[96:99]
	v_mfma_f32_16x16x32_bf16 v[84:87], v[172:175], v[204:207], v[84:87]
	v_mfma_f32_16x16x32_bf16 v[80:83], v[180:183], v[204:207], v[80:83]
	v_mfma_f32_16x16x32_bf16 v[68:71], v[172:175], v[212:215], v[68:71]
	v_mfma_f32_16x16x32_bf16 v[64:67], v[180:183], v[212:215], v[64:67]
	s_barrier
; #define PG8_STAGE(bufoff, gbase, voff) do { _Pragma("unroll") for (int _i = 0; _i < 2; ++_i) \
;         __builtin_amdgcn_global_load_lds((const unsigned*)((const char*)(gbase) + (voff)[_i]), (PG8_LAS unsigned*)(lds + (bufoff) + ldsw + _i * 8192), 16, 0, 0); } while (0)
; #define PG8_LDA(dst, b, h) do { _Pragma("unroll") for (int m = 0; m < 4; ++m) _Pragma("unroll") for (int k = 0; k < 2; ++k) dst[m][k] = *(const PG8_LAS bf16x8*)(lds + PG8_SA(b, h) + aoff + m * 2048 + k * 1024); } while (0)
; #define PG8_MMA(ai, bj, At, Bt) do { __builtin_amdgcn_s_setprio(1); _Pragma("unroll") for (int m = 0; m < 4; ++m) _Pragma("unroll") for (int n = 0; n < 2; ++n) _Pragma("unroll") for (int k = 0; k < 2; ++k) \
;         acc[ai][bj][m][n] = __builtin_amdgcn_mfma_f32_16x16x32_bf16(Bt[n][k], At[m][k], acc[ai][bj][m][n], 0, 0, 0); __builtin_amdgcn_s_setprio(0); } while (0)
; #define PG8_WAIT_V(n) asm volatile("s_waitcnt vmcnt(" #n ")" ::: "memory")
; #define PG8_WAIT_L(n) asm volatile("s_waitcnt lgkmcnt(" #n ")" ::: "memory")
; #define PG8_BAR __builtin_amdgcn_s_barrier()
; #define PG8_SCHED __builtin_amdgcn_sched_barrier(0)
; template <class Epi, class Sched, bool ALIGN_EPI = false, bool SP2 = false>
; __device__ __forceinline__ void gemm_phase(PG8_LAS unsigned char* lds, const Gemm g, const Sched& S, const Epi& E, const int wave_in) {
;     ...
;             PG8_LDA(At, 1, 1); PG8_STAGE(PG8_SB(1, 0), b3, voffB); PG8_STAGE(PG8_SB(1, 1), b3 + hstep, voffB); PG8_STAGE(PG8_SA(1, 0), a3, voffA);
;             PG8_WAIT_V(8); PG8_WAIT_L(0); PG8_BAR; PG8_MMA(1, 0, At, B0); PG8_MMA(1, 1, At, B1); PG8_BAR; PG8_SCHED;
	s_add_i32 s56, s75, s11
	v_lshl_add_u64 v[216:217], v[216:217], 0, s[38:39]
	s_mov_b32 m0, s56
	ds_read_b128 v[184:187], v153 offset:49152
	ds_read_b128 v[188:191], v153 offset:50176
	ds_read_b128 v[192:195], v153 offset:51200
	ds_read_b128 v[196:199], v153 offset:52224
	ds_read_b128 v[200:203], v153 offset:53248
	ds_read_b128 v[204:207], v153 offset:54272
	ds_read_b128 v[208:211], v153 offset:55296
	ds_read_b128 v[212:215], v153 offset:56320
	global_load_lds_dwordx4 v[216:217], off
	s_add_i32 m0, s56, 0x2000
	s_add_u32 s56, s60, 0x160080
	v_lshl_add_u64 v[216:217], v[218:219], 0, s[38:39]
	s_addc_u32 s57, s61, 0
	s_add_i32 s60, s76, s11
	global_load_lds_dwordx4 v[216:217], off
	v_lshl_add_u64 v[216:217], s[56:57], 0, v[130:131]
	s_mov_b32 m0, s60
	s_nop 0
	global_load_lds_dwordx4 v[216:217], off
	v_lshl_add_u64 v[216:217], s[56:57], 0, v[134:135]
	s_add_i32 m0, s60, 0x2000
	s_nop 0
	global_load_lds_dwordx4 v[216:217], off
	v_lshl_add_u64 v[216:217], v[220:221], 0, s[38:39]
	s_mov_b32 m0, s65
	s_nop 0
	global_load_lds_dwordx4 v[216:217], off
	v_lshl_add_u64 v[216:217], v[222:223], 0, s[38:39]
	s_mov_b32 m0, s66
	s_nop 0
	global_load_lds_dwordx4 v[216:217], off
	s_waitcnt vmcnt(8)
	s_waitcnt lgkmcnt(0)
	s_barrier
	s_waitcnt lgkmcnt(0)
	v_mfma_f32_16x16x32_bf16 v[60:63], v[144:147], v[184:187], v[60:63]
	v_mfma_f32_16x16x32_bf16 v[56:59], v[160:163], v[184:187], v[56:59]
	v_mfma_f32_16x16x32_bf16 v[44:47], v[144:147], v[192:195], v[44:47]
	v_mfma_f32_16x16x32_bf16 v[40:43], v[160:163], v[192:195], v[40:43]
	v_mfma_f32_16x16x32_bf16 v[28:31], v[144:147], v[200:203], v[28:31]
	v_mfma_f32_16x16x32_bf16 v[24:27], v[160:163], v[200:203], v[24:27]
	v_mfma_f32_16x16x32_bf16 v[12:15], v[144:147], v[208:211], v[12:15]
	v_mfma_f32_16x16x32_bf16 v[8:11], v[160:163], v[208:211], v[8:11]
	v_mfma_f32_16x16x32_bf16 v[60:63], v[156:159], v[188:191], v[60:63]
	v_mfma_f32_16x16x32_bf16 v[56:59], v[164:167], v[188:191], v[56:59]
	v_mfma_f32_16x16x32_bf16 v[44:47], v[156:159], v[196:199], v[44:47]
	v_mfma_f32_16x16x32_bf16 v[40:43], v[164:167], v[196:199], v[40:43]
	v_mfma_f32_16x16x32_bf16 v[28:31], v[156:159], v[204:207], v[28:31]
	v_mfma_f32_16x16x32_bf16 v[24:27], v[164:167], v[204:207], v[24:27]
	v_mfma_f32_16x16x32_bf16 v[12:15], v[156:159], v[212:215], v[12:15]
	v_mfma_f32_16x16x32_bf16 v[8:11], v[164:167], v[212:215], v[8:11]
	v_mfma_f32_16x16x32_bf16 v[52:55], v[168:171], v[184:187], v[52:55]
	v_mfma_f32_16x16x32_bf16 v[48:51], v[176:179], v[184:187], v[48:51]
	v_mfma_f32_16x16x32_bf16 v[36:39], v[168:171], v[192:195], v[36:39]
	v_mfma_f32_16x16x32_bf16 v[32:35], v[176:179], v[192:195], v[32:35]
	v_mfma_f32_16x16x32_bf16 v[20:23], v[168:171], v[200:203], v[20:23]
	v_mfma_f32_16x16x32_bf16 v[16:19], v[176:179], v[200:203], v[16:19]
	v_mfma_f32_16x16x32_bf16 v[4:7], v[168:171], v[208:211], v[4:7]
	v_mfma_f32_16x16x32_bf16 v[0:3], v[176:179], v[208:211], v[0:3]
	v_mfma_f32_16x16x32_bf16 v[52:55], v[172:175], v[188:191], v[52:55]
	v_mfma_f32_16x16x32_bf16 v[48:51], v[180:183], v[188:191], v[48:51]
	v_mfma_f32_16x16x32_bf16 v[36:39], v[172:175], v[196:199], v[36:39]
	v_mfma_f32_16x16x32_bf16 v[32:35], v[180:183], v[196:199], v[32:35]
	v_mfma_f32_16x16x32_bf16 v[20:23], v[172:175], v[204:207], v[20:23]
	v_mfma_f32_16x16x32_bf16 v[16:19], v[180:183], v[204:207], v[16:19]
	v_mfma_f32_16x16x32_bf16 v[4:7], v[172:175], v[212:215], v[4:7]
	v_mfma_f32_16x16x32_bf16 v[0:3], v[180:183], v[212:215], v[0:3]
	s_barrier
	s_add_i32 s74, s74, 2
	s_add_u32 s72, s72, 0x100
	s_addc_u32 s73, s73, 0
	s_cmpk_gt_u32 s74, 0x55
	s_mov_b64 s[56:57], s[58:59]
	s_cbranch_scc0 .LBB0_1647
	s_and_b64 vcc, exec, s[40:41]
	s_cbranch_vccz .LBB0_1650
	s_barrier

; #define lane mk_lane()
; template <class Epi, class Sched, bool ALIGN_EPI = false, bool SP2 = false>
; __device__ __forceinline__ void gemm_phase(PG8_LAS unsigned char* lds, const Gemm g, const Sched& S, const Epi& E, const int wave_in) {
;     const int wid = __builtin_amdgcn_readfirstlane(wave_in), lane = mk_lane(), tid = wid * 64 + lane, wr = wid >> 2, wc = wid & 3, fr = lane & 15, fq = lane >> 4;
;     const int K = g.K, nt = K / BK;
;     unsigned voffA[2], voffB[2];
; #pragma unroll
;     for (int i = 0; i < 2; ++i) { int R, C; stage_rc(tid * 16 + i * 8192, R, C); const int Rb = Epi::PERM ? ((R & ~31) + perm32(R & 31)) : R;
;         voffA[i] = (unsigned)(R * g.lda + C) * 2u; voffB[i] = (unsigned)(Rb * K + C) * 2u; }
;     const size_t kstep = (size_t)(BK * 2);
;     const size_t hstep = (size_t)HALF * K * 2, hstepA = (size_t)HALF * g.lda * 2;
;     const size_t tstep = 2 * hstep, tstepA = 2 * hstepA;
;     const unsigned ldsw = (unsigned)wid * 1024u;
;     const int aoff = lds_byte(wr * 64 + fr, fq * 8), boff = lds_byte(wc * 32 + fr, fq * 8);
;     ...
;     Unit cur, nxt; int ui = 0;
;     if (!S.next(0, cur)) return;
;     f32x4 acc[2][2][4][2];
; #pragma unroll
;     for (int a = 0; a < 2; ++a)
; #pragma unroll
;         for (int b = 0; b < 2; ++b)
; #pragma unroll
;             for (int m = 0; m < 4; ++m)
; #pragma unroll
;                 for (int n = 0; n < 2; ++n) acc[a][b][m][n] = (f32x4){0.f, 0.f, 0.f, 0.f};
;     bf16x8 At[4][2], B0[2][2], B1[2][2];
;     const char* cA = (const char*)g.A + (size_t)cur.pm * tstepA; const char* cB = (const char*)g.Bt + (size_t)cur.pn * tstep;
;     S.a_ready(cur);
;     if constexpr (SP2) {
;         PG8_STAGE(PG8_SB(0, 0), cB, voffB); PG8_STAGE(PG8_SB(0, 1), cB + hstep, voffB); PG8_STAGE(PG8_SA(0, 0), cA, voffA); PG8_STAGE(PG8_SA(0, 1), cA + hstepA, voffA);
;         if (wr == 1) PG8_BAR;
;         PG8_WAIT_V(2); PG8_BAR;
;         PG8_STAGE(PG8_SB(1, 0), cB + kstep, voffB); PG8_STAGE(PG8_SA(1, 0), cA + kstep, voffA); PG8_STAGE(PG8_SB(1, 1), cB + hstep + kstep, voffB);
; __global__ void __launch_bounds__(512, 2) fwd_kernel(Params p) {
;     ...
;     if (IN(12)) { { pg8::Gemm g_{XB, W_IN1, T, 6144, DM, DM}; pg8::StaticOrder S_; S_.init(T, 6144, G, bx); pg8::EpiScaled E_{QKV1, 6144, SS + (size_t)4 * T, 1.0f / 2048.0f};
;           pg8::gemm_phase<pg8::EpiScaled, pg8::StaticOrder, true, true>(ldsl, g_, S_, E_, wave); }
.LBB0_1724:
	s_cmp_lt_i32 s92, 13
	s_cselect_b64 s[0:1], -1, 0
	s_cmp_gt_i32 s93, 12
	s_cselect_b64 s[2:3], -1, 0
	s_and_b64 s[0:1], s[0:1], s[2:3]
	s_andn2_b64 vcc, exec, s[0:1]
	s_waitcnt lgkmcnt(0)
	s_barrier
	s_cbranch_vccnz .LBB0_1848
	s_setprio 0
	s_cmp_lt_u32 s89, 4
	s_cbranch_scc1 .Lgprio_8
	s_setprio 1
.Lgprio_8:
	s_cmpk_gt_i32 s88, 0xbff
	s_waitcnt vmcnt(0)
	v_mbcnt_lo_u32_b32 v10, -1, 0
	v_mbcnt_hi_u32_b32 v10, -1, v10
	s_cbranch_scc1 .LBB0_1741
	s_lshl_b32 s11, s89, 10
	v_lshl_add_u32 v0, v10, 4, s11
	v_add_u32_e32 v1, 0x2000, v0
	v_ashrrev_i32_e32 v2, 31, v1
	v_lshrrev_b32_e32 v2, 22, v2
	v_add_u32_e32 v2, v1, v2
	v_ashrrev_i32_e32 v8, 10, v2
	v_mul_i32_i24_e32 v2, 0x400, v8
	v_sub_u32_e32 v1, v1, v2
	v_lshrrev_b32_e32 v2, 4, v1
	v_bitop3_b32 v1, v2, v1, 32 bitop3:0x6c
	v_ashrrev_i32_e32 v2, 31, v1
	v_lshrrev_b32_e32 v2, 26, v2
	v_add_u32_e32 v2, v1, v2
	v_ashrrev_i32_e32 v9, 6, v2
	v_lshlrev_b32_e32 v3, 3, v8
	v_and_b32_e32 v2, 0xffc0, v2
	v_and_b32_e32 v3, -16, v3
	v_sub_u32_e32 v1, v1, v2
	v_add_u32_e32 v3, v9, v3
	v_lshrrev_b16_e32 v2, 7, v1
	v_and_b32_e32 v4, 3, v9
	s_mov_b32 s0, 0xfffe0
	v_lshrrev_b32_e32 v5, 2, v3
	v_lshlrev_b32_e32 v6, 1, v3
	v_and_b32_e32 v2, 1, v2
	v_and_or_b32 v4, v3, s0, v4
	v_and_b32_e32 v5, 4, v5
	v_and_b32_e32 v6, 24, v6
	v_add_u16_e32 v1, v1, v2
	v_mov_b32_e32 v2, 1
	v_or3_b32 v4, v4, v5, v6
	v_lshlrev_b32_e32 v5, 5, v8
	v_ashrrev_i16_sdwa v1, v2, sext(v1) dst_sel:DWORD dst_unused:UNUSED_PAD src0_sel:DWORD src1_sel:BYTE_0
	v_and_b32_e32 v5, 32, v5
	v_bfe_i32 v11, v1, 0, 16
	v_add_lshl_u32 v1, v5, v11, 1
	v_lshl_add_u32 v128, v4, 12, v1
	v_lshl_add_u32 v130, v3, 12, v1
	v_ashrrev_i32_e32 v1, 31, v0
	v_lshrrev_b32_e32 v1, 22, v1
	v_add_u32_e32 v1, v0, v1
	v_ashrrev_i32_e32 v12, 10, v1
	v_mul_i32_i24_e32 v1, 0x400, v12
	v_sub_u32_e32 v0, v0, v1
	v_lshrrev_b32_e32 v1, 4, v0
	v_bitop3_b32 v0, v1, v0, 32 bitop3:0x6c
	v_ashrrev_i32_e32 v1, 31, v0
	v_lshrrev_b32_e32 v1, 26, v1
	v_add_u32_e32 v1, v0, v1
	v_lshlrev_b32_e32 v3, 3, v12
	v_ashrrev_i32_e32 v13, 6, v1
	v_and_b32_e32 v3, -16, v3
	v_add_u32_e32 v3, v13, v3
	v_and_b32_e32 v4, 3, v13
	s_ashr_i32 s33, s88, 31
	v_and_or_b32 v4, v3, s0, v4
	s_lshr_b32 s0, s33, 29
	s_add_i32 s0, s88, s0
	s_ashr_i32 s1, s0, 3
	s_and_b32 s0, s0, -8
	s_ashr_i32 s3, s89, 2
	s_sub_i32 s0, s88, s0
	s_cmp_lt_i32 s0, 0
	s_movk_i32 s35, 0x181
	s_cselect_b32 s2, s35, 0x180
	s_mul_i32 s0, s0, s2
	s_add_i32 s0, s0, s1
	s_mul_hi_i32 s1, s0, 0x2aaaaaab
	s_lshr_b32 s2, s1, 31
	s_ashr_i32 s1, s1, 5
	s_add_i32 s1, s1, s2
	s_lshl_b32 s4, s1, 3
	s_mulk_i32 s1, 0xc0
	s_sub_i32 s0, s0, s1
	s_sext_i32_i16 s1, s0
	s_bfe_u32 s1, s1, 0x3001c
	s_add_i32 s1, s0, s1
	s_sext_i32_i16 s2, s1
	s_and_b32 s1, s1, 0xfff8
	s_sub_i32 s0, s0, s1
	s_sext_i32_i16 s0, s0
	v_lshrrev_b32_e32 v5, 2, v3
	v_lshlrev_b32_e32 v6, 1, v3
	v_and_b32_e32 v1, 0xc0, v1
	s_lshr_b32 s2, s2, 3
	s_add_i32 s56, s4, s0
	v_and_b32_e32 v5, 4, v5
	v_and_b32_e32 v6, 24, v6
	v_sub_u32_e32 v0, v0, v1
	s_ashr_i32 s57, s56, 31
	s_bfe_i64 s[4:5], s[2:3], 0x100000
	v_or3_b32 v4, v4, v5, v6
	v_lshlrev_b32_e32 v5, 5, v12
	v_ashrrev_i16_sdwa v0, v2, sext(v0) dst_sel:DWORD dst_unused:UNUSED_PAD src0_sel:DWORD src1_sel:BYTE_0
	s_lshl_b64 s[0:1], s[56:57], 20
	s_lshl_b64 s[4:5], s[4:5], 20
	v_readlane_b32 s6, v255, 42
	v_and_b32_e32 v5, 32, v5
	v_bfe_i32 v14, v0, 0, 16
	v_readlane_b32 s7, v255, 43
	s_add_u32 s60, s6, s4
	v_add_lshl_u32 v0, v5, v14, 1
	s_addc_u32 s61, s7, s5
	s_add_i32 s48, s11, 0
	v_lshl_add_u32 v132, v4, 12, v0
	s_add_i32 m0, s48, 0x10000
	v_lshl_add_u32 v134, v3, 12, v0
	global_load_lds_dwordx4 v132, s[60:61]
	s_add_i32 m0, s48, 0x12000
	s_add_u32 s4, s60, 0x80000
	global_load_lds_dwordx4 v128, s[60:61]
	s_addc_u32 s5, s61, 0
	s_add_i32 m0, s48, 0x14000
	v_mov_b32_e32 v133, 0
	global_load_lds_dwordx4 v132, s[4:5]
	s_add_i32 m0, s48, 0x16000
	s_add_u32 s58, s46, s0
	s_addc_u32 s59, s47, s1
	s_add_i32 s49, s48, 0x2000
	global_load_lds_dwordx4 v128, s[4:5]
	s_mov_b32 m0, s48
	s_add_u32 s0, s58, 0x80000
	global_load_lds_dwordx4 v134, s[58:59]
	s_mov_b32 m0, s49
	s_addc_u32 s1, s59, 0
	s_add_i32 s50, s48, 0x4000
	global_load_lds_dwordx4 v130, s[58:59]
	s_mov_b32 m0, s50
	s_add_i32 s51, s48, 0x6000
	global_load_lds_dwordx4 v134, s[0:1]
	s_mov_b32 m0, s51
	v_mov_b32_e32 v129, v133
	global_load_lds_dwordx4 v130, s[0:1]
	v_mov_b32_e32 v135, v133
	v_mov_b32_e32 v131, v133
	s_cmp_eq_u32 s3, 1
	s_mov_b32 s57, 0
	v_lshl_add_u64 v[6:7], s[60:61], 0, v[132:133]
	v_lshl_add_u64 v[4:5], s[60:61], 0, v[128:129]
	v_lshl_add_u64 v[0:1], s[58:59], 0, v[134:135]
	s_cselect_b64 s[0:1], -1, 0
	s_cmp_lg_u32 s3, 1
	v_lshl_add_u64 v[2:3], s[58:59], 0, v[130:131]
	s_cbranch_scc1 .LBB0_1728
	s_barrier

; #define PG8_STAGE(bufoff, gbase, voff) do { _Pragma("unroll") for (int _i = 0; _i < 2; ++_i) \
;         __builtin_amdgcn_global_load_lds((const unsigned*)((const char*)(gbase) + (voff)[_i]), (PG8_LAS unsigned*)(lds + (bufoff) + ldsw + _i * 8192), 16, 0, 0); } while (0)
; #define PG8_LDA(dst, b, h) do { _Pragma("unroll") for (int m = 0; m < 4; ++m) _Pragma("unroll") for (int k = 0; k < 2; ++k) dst[m][k] = *(const PG8_LAS bf16x8*)(lds + PG8_SA(b, h) + aoff + m * 2048 + k * 1024); } while (0)
; #define PG8_LDB(dst, b, h) do { _Pragma("unroll") for (int n = 0; n < 2; ++n) _Pragma("unroll") for (int k = 0; k < 2; ++k) dst[n][k] = *(const PG8_LAS bf16x8*)(lds + PG8_SB(b, h) + boff + n * 2048 + k * 1024); } while (0)
; #define PG8_WAIT_V(n) asm volatile("s_waitcnt vmcnt(" #n ")" ::: "memory")
; #define PG8_WAIT_L(n) asm volatile("s_waitcnt lgkmcnt(" #n ")" ::: "memory")
; #define PG8_BAR __builtin_amdgcn_s_barrier()
; #define PG8_SCHED __builtin_amdgcn_sched_barrier(0)
; template <class Epi, class Sched, bool ALIGN_EPI = false, bool SP2 = false>
; __device__ __forceinline__ void gemm_phase(PG8_LAS unsigned char* lds, const Gemm g, const Sched& S, const Epi& E, const int wave_in) {
;     ...
;         const char* nA = has_next ? (const char*)g.A + (size_t)nxt.pm * tstepA : cA; const char* nB = has_next ? (const char*)g.Bt + (size_t)nxt.pn * tstep : cB;
;         for (int t = 0; t < nt; t += 2) {
;             const bool last = (t == nt - 2);
;             const char* a1 = cA + (size_t)(t + 1) * kstep;
;             const char* a2 = last ? nA : cA + (size_t)(t + 2) * kstep; const char* b2 = last ? nB : cB + (size_t)(t + 2) * kstep;
;             const char* a3 = a2 + kstep; const char* b3 = b2 + kstep;
;             if (last && has_next) S.a_ready(nxt);
;             if constexpr (SP2) {
;             PG8_LDB(B0, 0, 0); PG8_LDB(B1, 0, 1); PG8_SCHED; PG8_LDA(At, 0, 0); PG8_STAGE(PG8_SA(1, 1), a1 + hstepA, voffA);
;             PG8_WAIT_V(8); PG8_WAIT_L(0); PG8_BAR; PG8_MMA(0, 0, At, B0); PG8_MMA(0, 1, At, B1); PG8_BAR; PG8_SCHED;
;             PG8_LDA(At, 0, 1); PG8_STAGE(PG8_SB(0, 0), b2, voffB); PG8_STAGE(PG8_SB(0, 1), b2 + hstep, voffB); PG8_STAGE(PG8_SA(0, 0), a2, voffA);
;             PG8_WAIT_V(8); PG8_WAIT_L(0); PG8_BAR; PG8_MMA(1, 0, At, B0); PG8_MMA(1, 1, At, B1); PG8_BAR; PG8_SCHED;
.LBB0_1734:
	ds_read_b128 v[144:147], v155
	ds_read_b128 v[148:151], v155 offset:1024
	ds_read_b128 v[160:163], v155 offset:2048
	ds_read_b128 v[164:167], v155 offset:3072
	ds_read_b128 v[168:171], v156
	ds_read_b128 v[172:175], v156 offset:1024
	ds_read_b128 v[176:179], v156 offset:2048
	ds_read_b128 v[180:183], v156 offset:3072
	s_add_u32 s60, s58, 0xfff80080
	s_addc_u32 s61, s59, -1
	s_cmp_eq_u32 s74, 28
	s_cselect_b32 s63, s39, s61
	s_cselect_b32 s62, s70, s60
	s_cselect_b32 s61, s37, s73
	s_cselect_b32 s60, s71, s72
	v_lshl_add_u64 v[216:217], s[58:59], 0, v[136:137]
	s_add_i32 m0, s48, 0xc000
	ds_read_b128 v[184:187], v157
	ds_read_b128 v[188:191], v157 offset:1024
	ds_read_b128 v[192:195], v157 offset:2048
	ds_read_b128 v[196:199], v157 offset:3072
	ds_read_b128 v[200:203], v157 offset:4096
	ds_read_b128 v[204:207], v157 offset:5120
	ds_read_b128 v[208:211], v157 offset:6144
	ds_read_b128 v[212:215], v157 offset:7168
	global_load_lds_dwordx4 v[216:217], off
	v_lshl_add_u64 v[216:217], s[58:59], 0, v[138:139]
	s_add_i32 m0, s48, 0xe000
	s_nop 0
	global_load_lds_dwordx4 v[216:217], off
	s_waitcnt vmcnt(8)
	s_waitcnt lgkmcnt(0)
	s_barrier
	s_waitcnt lgkmcnt(0)
	v_mfma_f32_16x16x32_bf16 v[124:127], v[144:147], v[184:187], v[124:127]
	v_mfma_f32_16x16x32_bf16 v[120:123], v[160:163], v[184:187], v[120:123]
	v_mfma_f32_16x16x32_bf16 v[108:111], v[144:147], v[192:195], v[108:111]
	v_mfma_f32_16x16x32_bf16 v[104:107], v[160:163], v[192:195], v[104:107]
	v_mfma_f32_16x16x32_bf16 v[92:95], v[144:147], v[200:203], v[92:95]
	v_mfma_f32_16x16x32_bf16 v[88:91], v[160:163], v[200:203], v[88:91]
	v_mfma_f32_16x16x32_bf16 v[76:79], v[144:147], v[208:211], v[76:79]
	v_mfma_f32_16x16x32_bf16 v[72:75], v[160:163], v[208:211], v[72:75]
	v_mfma_f32_16x16x32_bf16 v[124:127], v[148:151], v[188:191], v[124:127]
	v_mfma_f32_16x16x32_bf16 v[120:123], v[164:167], v[188:191], v[120:123]
	v_mfma_f32_16x16x32_bf16 v[108:111], v[148:151], v[196:199], v[108:111]
	v_mfma_f32_16x16x32_bf16 v[104:107], v[164:167], v[196:199], v[104:107]
	v_mfma_f32_16x16x32_bf16 v[92:95], v[148:151], v[204:207], v[92:95]
	v_mfma_f32_16x16x32_bf16 v[88:91], v[164:167], v[204:207], v[88:91]
	v_mfma_f32_16x16x32_bf16 v[76:79], v[148:151], v[212:215], v[76:79]
	v_mfma_f32_16x16x32_bf16 v[72:75], v[164:167], v[212:215], v[72:75]
	v_mfma_f32_16x16x32_bf16 v[116:119], v[168:171], v[184:187], v[116:119]
	v_mfma_f32_16x16x32_bf16 v[112:115], v[176:179], v[184:187], v[112:115]
	v_mfma_f32_16x16x32_bf16 v[100:103], v[168:171], v[192:195], v[100:103]
	v_mfma_f32_16x16x32_bf16 v[96:99], v[176:179], v[192:195], v[96:99]
	v_mfma_f32_16x16x32_bf16 v[84:87], v[168:171], v[200:203], v[84:87]
	v_mfma_f32_16x16x32_bf16 v[80:83], v[176:179], v[200:203], v[80:83]
	v_mfma_f32_16x16x32_bf16 v[68:71], v[168:171], v[208:211], v[68:71]
	v_mfma_f32_16x16x32_bf16 v[64:67], v[176:179], v[208:211], v[64:67]
	v_mfma_f32_16x16x32_bf16 v[116:119], v[172:175], v[188:191], v[116:119]
	v_mfma_f32_16x16x32_bf16 v[112:115], v[180:183], v[188:191], v[112:115]
	v_mfma_f32_16x16x32_bf16 v[100:103], v[172:175], v[196:199], v[100:103]
	v_mfma_f32_16x16x32_bf16 v[96:99], v[180:183], v[196:199], v[96:99]
	v_mfma_f32_16x16x32_bf16 v[84:87], v[172:175], v[204:207], v[84:87]
	v_mfma_f32_16x16x32_bf16 v[80:83], v[180:183], v[204:207], v[80:83]
	v_mfma_f32_16x16x32_bf16 v[68:71], v[172:175], v[212:215], v[68:71]
	v_mfma_f32_16x16x32_bf16 v[64:67], v[180:183], v[212:215], v[64:67]
	s_barrier
	s_add_i32 s75, s66, s11
	v_lshl_add_u64 v[216:217], s[60:61], 0, v[132:133]
	s_mov_b32 m0, s75
	ds_read_b128 v[184:187], v157 offset:16384
	ds_read_b128 v[188:191], v157 offset:17408
	ds_read_b128 v[192:195], v157 offset:18432
	ds_read_b128 v[196:199], v157 offset:19456
	ds_read_b128 v[200:203], v157 offset:20480
	ds_read_b128 v[204:207], v157 offset:21504
	ds_read_b128 v[208:211], v157 offset:22528
	ds_read_b128 v[212:215], v157 offset:23552
	global_load_lds_dwordx4 v[216:217], off
	s_add_i32 m0, s75, 0x2000
	s_add_u32 s76, s60, 0x80000
	v_lshl_add_u64 v[218:219], s[60:61], 0, v[128:129]
	s_addc_u32 s77, s61, 0
	s_add_i32 s75, s67, s11
	global_load_lds_dwordx4 v[218:219], off
	v_lshl_add_u64 v[220:221], s[76:77], 0, v[132:133]
	s_mov_b32 m0, s75
	v_lshl_add_u64 v[222:223], s[62:63], 0, v[130:131]
	global_load_lds_dwordx4 v[220:221], off
	v_lshl_add_u64 v[220:221], s[76:77], 0, v[128:129]
	s_add_i32 m0, s75, 0x2000
	s_nop 0
	global_load_lds_dwordx4 v[220:221], off
	v_lshl_add_u64 v[220:221], s[62:63], 0, v[134:135]
	s_mov_b32 m0, s48
	s_nop 0
	global_load_lds_dwordx4 v[220:221], off
	s_mov_b32 m0, s49
	s_nop 0
	global_load_lds_dwordx4 v[222:223], off
	s_waitcnt vmcnt(8)
	s_waitcnt lgkmcnt(0)
	s_barrier
; #define PG8_STAGE(bufoff, gbase, voff) do { _Pragma("unroll") for (int _i = 0; _i < 2; ++_i) \
;         __builtin_amdgcn_global_load_lds((const unsigned*)((const char*)(gbase) + (voff)[_i]), (PG8_LAS unsigned*)(lds + (bufoff) + ldsw + _i * 8192), 16, 0, 0); } while (0)
; #define PG8_LDA(dst, b, h) do { _Pragma("unroll") for (int m = 0; m < 4; ++m) _Pragma("unroll") for (int k = 0; k < 2; ++k) dst[m][k] = *(const PG8_LAS bf16x8*)(lds + PG8_SA(b, h) + aoff + m * 2048 + k * 1024); } while (0)
; #define PG8_LDB(dst, b, h) do { _Pragma("unroll") for (int n = 0; n < 2; ++n) _Pragma("unroll") for (int k = 0; k < 2; ++k) dst[n][k] = *(const PG8_LAS bf16x8*)(lds + PG8_SB(b, h) + boff + n * 2048 + k * 1024); } while (0)
; #define PG8_MMA(ai, bj, At, Bt) do { __builtin_amdgcn_s_setprio(1); _Pragma("unroll") for (int m = 0; m < 4; ++m) _Pragma("unroll") for (int n = 0; n < 2; ++n) _Pragma("unroll") for (int k = 0; k < 2; ++k) \
;         acc[ai][bj][m][n] = __builtin_amdgcn_mfma_f32_16x16x32_bf16(Bt[n][k], At[m][k], acc[ai][bj][m][n], 0, 0, 0); __builtin_amdgcn_s_setprio(0); } while (0)
; #define PG8_WAIT_V(n) asm volatile("s_waitcnt vmcnt(" #n ")" ::: "memory")
; #define PG8_WAIT_L(n) asm volatile("s_waitcnt lgkmcnt(" #n ")" ::: "memory")
; #define PG8_BAR __builtin_amdgcn_s_barrier()
; #define PG8_SCHED __builtin_amdgcn_sched_barrier(0)
; template <class Epi, class Sched, bool ALIGN_EPI = false, bool SP2 = false>
; __device__ __forceinline__ void gemm_phase(PG8_LAS unsigned char* lds, const Gemm g, const Sched& S, const Epi& E, const int wave_in) {
;     ...
;             PG8_WAIT_V(8); PG8_WAIT_L(0); PG8_BAR; PG8_MMA(1, 0, At, B0); PG8_MMA(1, 1, At, B1); PG8_BAR; PG8_SCHED;
;             PG8_LDB(B0, 1, 0); PG8_LDB(B1, 1, 1); PG8_SCHED; PG8_LDA(At, 1, 0); PG8_STAGE(PG8_SA(0, 1), a2 + hstepA, voffA);
;             PG8_WAIT_V(8); PG8_WAIT_L(0); PG8_BAR; PG8_MMA(0, 0, At, B0); PG8_MMA(0, 1, At, B1); PG8_BAR; PG8_SCHED;
	s_waitcnt lgkmcnt(0)
	v_mfma_f32_16x16x32_bf16 v[60:63], v[144:147], v[184:187], v[60:63]
	v_mfma_f32_16x16x32_bf16 v[56:59], v[160:163], v[184:187], v[56:59]
	v_mfma_f32_16x16x32_bf16 v[44:47], v[144:147], v[192:195], v[44:47]
	v_mfma_f32_16x16x32_bf16 v[40:43], v[160:163], v[192:195], v[40:43]
	v_mfma_f32_16x16x32_bf16 v[28:31], v[144:147], v[200:203], v[28:31]
	v_mfma_f32_16x16x32_bf16 v[24:27], v[160:163], v[200:203], v[24:27]
	v_mfma_f32_16x16x32_bf16 v[12:15], v[144:147], v[208:211], v[12:15]
	v_mfma_f32_16x16x32_bf16 v[8:11], v[160:163], v[208:211], v[8:11]
	v_mfma_f32_16x16x32_bf16 v[60:63], v[148:151], v[188:191], v[60:63]
	v_mfma_f32_16x16x32_bf16 v[56:59], v[164:167], v[188:191], v[56:59]
	v_mfma_f32_16x16x32_bf16 v[44:47], v[148:151], v[196:199], v[44:47]
	v_mfma_f32_16x16x32_bf16 v[40:43], v[164:167], v[196:199], v[40:43]
	v_mfma_f32_16x16x32_bf16 v[28:31], v[148:151], v[204:207], v[28:31]
	v_mfma_f32_16x16x32_bf16 v[24:27], v[164:167], v[204:207], v[24:27]
	v_mfma_f32_16x16x32_bf16 v[12:15], v[148:151], v[212:215], v[12:15]
	v_mfma_f32_16x16x32_bf16 v[8:11], v[164:167], v[212:215], v[8:11]
	v_mfma_f32_16x16x32_bf16 v[52:55], v[168:171], v[184:187], v[52:55]
	v_mfma_f32_16x16x32_bf16 v[48:51], v[176:179], v[184:187], v[48:51]
	v_mfma_f32_16x16x32_bf16 v[36:39], v[168:171], v[192:195], v[36:39]
	v_mfma_f32_16x16x32_bf16 v[32:35], v[176:179], v[192:195], v[32:35]
	v_mfma_f32_16x16x32_bf16 v[20:23], v[168:171], v[200:203], v[20:23]
	v_mfma_f32_16x16x32_bf16 v[16:19], v[176:179], v[200:203], v[16:19]
	v_mfma_f32_16x16x32_bf16 v[4:7], v[168:171], v[208:211], v[4:7]
	v_mfma_f32_16x16x32_bf16 v[0:3], v[176:179], v[208:211], v[0:3]
	v_mfma_f32_16x16x32_bf16 v[52:55], v[172:175], v[188:191], v[52:55]
	v_mfma_f32_16x16x32_bf16 v[48:51], v[180:183], v[188:191], v[48:51]
	v_mfma_f32_16x16x32_bf16 v[36:39], v[172:175], v[196:199], v[36:39]
	v_mfma_f32_16x16x32_bf16 v[32:35], v[180:183], v[196:199], v[32:35]
	v_mfma_f32_16x16x32_bf16 v[20:23], v[172:175], v[204:207], v[20:23]
	v_mfma_f32_16x16x32_bf16 v[16:19], v[180:183], v[204:207], v[16:19]
	v_mfma_f32_16x16x32_bf16 v[4:7], v[172:175], v[212:215], v[4:7]
	v_mfma_f32_16x16x32_bf16 v[0:3], v[180:183], v[212:215], v[0:3]
	s_barrier
	s_add_i32 s75, 0, 0x18000
	v_add_u32_e32 v159, s75, v153
	s_add_i32 s76, 0, 0x1c000
	ds_read_b128 v[144:147], v159
	ds_read_b128 v[148:151], v159 offset:1024
	ds_read_b128 v[160:163], v159 offset:2048
	ds_read_b128 v[164:167], v159 offset:3072
	v_add_u32_e32 v159, s76, v153
	ds_read_b128 v[168:171], v159
	ds_read_b128 v[172:175], v159 offset:1024
	ds_read_b128 v[176:179], v159 offset:2048
	ds_read_b128 v[180:183], v159 offset:3072
	s_add_u32 s62, s62, 0x80000
	s_addc_u32 s63, s63, 0
	s_mov_b32 m0, s50
	v_lshl_add_u64 v[224:225], s[62:63], 0, v[134:135]
	ds_read_b128 v[184:187], v157 offset:32768
	ds_read_b128 v[188:191], v157 offset:33792
	ds_read_b128 v[192:195], v157 offset:34816
	ds_read_b128 v[196:199], v157 offset:35840
	ds_read_b128 v[200:203], v157 offset:36864
	ds_read_b128 v[204:207], v157 offset:37888
	ds_read_b128 v[208:211], v157 offset:38912
	ds_read_b128 v[212:215], v157 offset:39936
	global_load_lds_dwordx4 v[224:225], off
	v_lshl_add_u64 v[224:225], s[62:63], 0, v[130:131]
	s_mov_b32 m0, s51
	s_nop 0
	global_load_lds_dwordx4 v[224:225], off
	s_waitcnt vmcnt(8)
	s_waitcnt lgkmcnt(0)
	s_barrier
	s_waitcnt lgkmcnt(0)
	v_mfma_f32_16x16x32_bf16 v[124:127], v[144:147], v[184:187], v[124:127]
	v_mfma_f32_16x16x32_bf16 v[120:123], v[160:163], v[184:187], v[120:123]
	v_mfma_f32_16x16x32_bf16 v[108:111], v[144:147], v[192:195], v[108:111]
	v_mfma_f32_16x16x32_bf16 v[104:107], v[160:163], v[192:195], v[104:107]
	v_mfma_f32_16x16x32_bf16 v[92:95], v[144:147], v[200:203], v[92:95]
	v_mfma_f32_16x16x32_bf16 v[88:91], v[160:163], v[200:203], v[88:91]
	v_mfma_f32_16x16x32_bf16 v[76:79], v[144:147], v[208:211], v[76:79]
	v_mfma_f32_16x16x32_bf16 v[72:75], v[160:163], v[208:211], v[72:75]
	v_mfma_f32_16x16x32_bf16 v[124:127], v[148:151], v[188:191], v[124:127]
	v_mfma_f32_16x16x32_bf16 v[120:123], v[164:167], v[188:191], v[120:123]
	v_mfma_f32_16x16x32_bf16 v[108:111], v[148:151], v[196:199], v[108:111]
	v_mfma_f32_16x16x32_bf16 v[104:107], v[164:167], v[196:199], v[104:107]
	v_mfma_f32_16x16x32_bf16 v[92:95], v[148:151], v[204:207], v[92:95]
	v_mfma_f32_16x16x32_bf16 v[88:91], v[164:167], v[204:207], v[88:91]
	v_mfma_f32_16x16x32_bf16 v[76:79], v[148:151], v[212:215], v[76:79]
	v_mfma_f32_16x16x32_bf16 v[72:75], v[164:167], v[212:215], v[72:75]
	v_mfma_f32_16x16x32_bf16 v[116:119], v[168:171], v[184:187], v[116:119]
	v_mfma_f32_16x16x32_bf16 v[112:115], v[176:179], v[184:187], v[112:115]
	v_mfma_f32_16x16x32_bf16 v[100:103], v[168:171], v[192:195], v[100:103]
	v_mfma_f32_16x16x32_bf16 v[96:99], v[176:179], v[192:195], v[96:99]
	v_mfma_f32_16x16x32_bf16 v[84:87], v[168:171], v[200:203], v[84:87]
	v_mfma_f32_16x16x32_bf16 v[80:83], v[176:179], v[200:203], v[80:83]
	v_mfma_f32_16x16x32_bf16 v[68:71], v[168:171], v[208:211], v[68:71]
	v_mfma_f32_16x16x32_bf16 v[64:67], v[176:179], v[208:211], v[64:67]
	v_mfma_f32_16x16x32_bf16 v[116:119], v[172:175], v[188:191], v[116:119]
	v_mfma_f32_16x16x32_bf16 v[112:115], v[180:183], v[188:191], v[112:115]
	v_mfma_f32_16x16x32_bf16 v[100:103], v[172:175], v[196:199], v[100:103]
	v_mfma_f32_16x16x32_bf16 v[96:99], v[180:183], v[196:199], v[96:99]
	v_mfma_f32_16x16x32_bf16 v[84:87], v[172:175], v[204:207], v[84:87]
	v_mfma_f32_16x16x32_bf16 v[80:83], v[180:183], v[204:207], v[80:83]
	v_mfma_f32_16x16x32_bf16 v[68:71], v[172:175], v[212:215], v[68:71]
	v_mfma_f32_16x16x32_bf16 v[64:67], v[180:183], v[212:215], v[64:67]
	s_barrier
; #define PG8_STAGE(bufoff, gbase, voff) do { _Pragma("unroll") for (int _i = 0; _i < 2; ++_i) \
;         __builtin_amdgcn_global_load_lds((const unsigned*)((const char*)(gbase) + (voff)[_i]), (PG8_LAS unsigned*)(lds + (bufoff) + ldsw + _i * 8192), 16, 0, 0); } while (0)
; #define PG8_LDA(dst, b, h) do { _Pragma("unroll") for (int m = 0; m < 4; ++m) _Pragma("unroll") for (int k = 0; k < 2; ++k) dst[m][k] = *(const PG8_LAS bf16x8*)(lds + PG8_SA(b, h) + aoff + m * 2048 + k * 1024); } while (0)
; #define PG8_BAR __builtin_amdgcn_s_barrier()
; template <class Epi, class Sched, bool ALIGN_EPI = false, bool SP2 = false>
; __device__ __forceinline__ void gemm_phase(PG8_LAS unsigned char* lds, const Gemm g, const Sched& S, const Epi& E, const int wave_in) {
;     ...
;             PG8_LDA(At, 1, 1); PG8_STAGE(PG8_SB(1, 0), b3, voffB); PG8_STAGE(PG8_SB(1, 1), b3 + hstep, voffB); PG8_STAGE(PG8_SA(1, 0), a3, voffA);
;             PG8_WAIT_V(8); PG8_WAIT_L(0); PG8_BAR; PG8_MMA(1, 0, At, B0); PG8_MMA(1, 1, At, B1); PG8_BAR; PG8_SCHED;
;             } else {
;             PG8_LDB(B0, 0, 0); PG8_SCHED; PG8_LDA(At, 0, 0); PG8_STAGE(PG8_SA(1, 1), a1 + hstepA, voffA);
;             PG8_WAIT_L(8); PG8_BAR; PG8_WAIT_L(0); PG8_MMA(0, 0, At, B0); PG8_BAR; PG8_SCHED;
;             PG8_LDB(B1, 0, 1); PG8_STAGE(PG8_SB(0, 0), b2, voffB);
;             PG8_BAR; PG8_WAIT_L(0); PG8_MMA(0, 1, At, B1); PG8_BAR;
;             PG8_LDA(At, 0, 1); PG8_STAGE(PG8_SA(0, 0), a2, voffA);
;             PG8_BAR; PG8_WAIT_L(0); PG8_MMA(1, 0, At, B0); PG8_BAR; PG8_SCHED;
;             PG8_STAGE(PG8_SB(0, 1), b2 + hstep, voffB);
;             PG8_WAIT_V(6); PG8_BAR; PG8_MMA(1, 1, At, B1); PG8_BAR;
;             PG8_LDB(B0, 1, 0); PG8_SCHED; PG8_LDA(At, 1, 0); PG8_STAGE(PG8_SA(0, 1), a2 + hstepA, voffA);
;             PG8_WAIT_L(8); PG8_BAR; PG8_WAIT_L(0); PG8_MMA(0, 0, At, B0); PG8_BAR; PG8_SCHED;
;             PG8_LDB(B1, 1, 1); PG8_STAGE(PG8_SB(1, 0), b3, voffB);
;             PG8_BAR; PG8_WAIT_L(0); PG8_MMA(0, 1, At, B1); PG8_BAR;
;             PG8_LDA(At, 1, 1); PG8_STAGE(PG8_SA(1, 0), a3, voffA);
;             PG8_BAR; PG8_WAIT_L(0); PG8_MMA(1, 0, At, B0); PG8_BAR; PG8_SCHED;
;             PG8_STAGE(PG8_SB(1, 1), b3 + hstep, voffB);
;             PG8_WAIT_V(6); PG8_BAR; PG8_MMA(1, 1, At, B1); PG8_BAR;
;             }
;         }
;         if constexpr (ALIGN_EPI) { if (wr == 0) PG8_BAR; }
	s_add_i32 s62, s75, s11
	v_lshl_add_u64 v[216:217], v[216:217], 0, s[6:7]
	s_mov_b32 m0, s62
	ds_read_b128 v[184:187], v157 offset:49152
	ds_read_b128 v[188:191], v157 offset:50176
	ds_read_b128 v[192:195], v157 offset:51200
	ds_read_b128 v[196:199], v157 offset:52224
	ds_read_b128 v[200:203], v157 offset:53248
	ds_read_b128 v[204:207], v157 offset:54272
	ds_read_b128 v[208:211], v157 offset:55296
	ds_read_b128 v[212:215], v157 offset:56320
	global_load_lds_dwordx4 v[216:217], off
	s_add_i32 m0, s62, 0x2000
	s_add_u32 s60, s60, 0x80080
	v_lshl_add_u64 v[216:217], v[218:219], 0, s[6:7]
	s_addc_u32 s61, s61, 0
	s_add_i32 s62, s76, s11
	global_load_lds_dwordx4 v[216:217], off
	v_lshl_add_u64 v[216:217], s[60:61], 0, v[132:133]
	s_mov_b32 m0, s62
	s_nop 0
	global_load_lds_dwordx4 v[216:217], off
	v_lshl_add_u64 v[216:217], s[60:61], 0, v[128:129]
	s_add_i32 m0, s62, 0x2000
	s_nop 0
	global_load_lds_dwordx4 v[216:217], off
	v_lshl_add_u64 v[216:217], v[220:221], 0, s[6:7]
	s_mov_b32 m0, s64
	s_nop 0
	global_load_lds_dwordx4 v[216:217], off
	v_lshl_add_u64 v[216:217], v[222:223], 0, s[6:7]
	s_mov_b32 m0, s65
	s_nop 0
	global_load_lds_dwordx4 v[216:217], off
	s_waitcnt vmcnt(8)
	s_waitcnt lgkmcnt(0)
	s_barrier
	s_waitcnt lgkmcnt(0)
	v_mfma_f32_16x16x32_bf16 v[60:63], v[144:147], v[184:187], v[60:63]
	v_mfma_f32_16x16x32_bf16 v[56:59], v[160:163], v[184:187], v[56:59]
	v_mfma_f32_16x16x32_bf16 v[44:47], v[144:147], v[192:195], v[44:47]
	v_mfma_f32_16x16x32_bf16 v[40:43], v[160:163], v[192:195], v[40:43]
	v_mfma_f32_16x16x32_bf16 v[28:31], v[144:147], v[200:203], v[28:31]
	v_mfma_f32_16x16x32_bf16 v[24:27], v[160:163], v[200:203], v[24:27]
	v_mfma_f32_16x16x32_bf16 v[12:15], v[144:147], v[208:211], v[12:15]
	v_mfma_f32_16x16x32_bf16 v[8:11], v[160:163], v[208:211], v[8:11]
	v_mfma_f32_16x16x32_bf16 v[60:63], v[148:151], v[188:191], v[60:63]
	v_mfma_f32_16x16x32_bf16 v[56:59], v[164:167], v[188:191], v[56:59]
	v_mfma_f32_16x16x32_bf16 v[44:47], v[148:151], v[196:199], v[44:47]
	v_mfma_f32_16x16x32_bf16 v[40:43], v[164:167], v[196:199], v[40:43]
	v_mfma_f32_16x16x32_bf16 v[28:31], v[148:151], v[204:207], v[28:31]
	v_mfma_f32_16x16x32_bf16 v[24:27], v[164:167], v[204:207], v[24:27]
	v_mfma_f32_16x16x32_bf16 v[12:15], v[148:151], v[212:215], v[12:15]
	v_mfma_f32_16x16x32_bf16 v[8:11], v[164:167], v[212:215], v[8:11]
	v_mfma_f32_16x16x32_bf16 v[52:55], v[168:171], v[184:187], v[52:55]
	v_mfma_f32_16x16x32_bf16 v[48:51], v[176:179], v[184:187], v[48:51]
	v_mfma_f32_16x16x32_bf16 v[36:39], v[168:171], v[192:195], v[36:39]
	v_mfma_f32_16x16x32_bf16 v[32:35], v[176:179], v[192:195], v[32:35]
	v_mfma_f32_16x16x32_bf16 v[20:23], v[168:171], v[200:203], v[20:23]
	v_mfma_f32_16x16x32_bf16 v[16:19], v[176:179], v[200:203], v[16:19]
	v_mfma_f32_16x16x32_bf16 v[4:7], v[168:171], v[208:211], v[4:7]
	v_mfma_f32_16x16x32_bf16 v[0:3], v[176:179], v[208:211], v[0:3]
	v_mfma_f32_16x16x32_bf16 v[52:55], v[172:175], v[188:191], v[52:55]
	v_mfma_f32_16x16x32_bf16 v[48:51], v[180:183], v[188:191], v[48:51]
	v_mfma_f32_16x16x32_bf16 v[36:39], v[172:175], v[196:199], v[36:39]
	v_mfma_f32_16x16x32_bf16 v[32:35], v[180:183], v[196:199], v[32:35]
	v_mfma_f32_16x16x32_bf16 v[20:23], v[172:175], v[204:207], v[20:23]
	v_mfma_f32_16x16x32_bf16 v[16:19], v[180:183], v[204:207], v[16:19]
	v_mfma_f32_16x16x32_bf16 v[4:7], v[172:175], v[212:215], v[4:7]
	v_mfma_f32_16x16x32_bf16 v[0:3], v[180:183], v[212:215], v[0:3]
	s_barrier
	s_add_i32 s74, s74, 2
	s_add_u32 s58, s58, 0x100
	s_addc_u32 s59, s59, 0
	s_add_u32 s72, s72, 0x100
	s_addc_u32 s73, s73, 0
	s_cmp_gt_u32 s74, 29
	s_cbranch_scc0 .LBB0_1734
	s_and_b64 vcc, exec, s[18:19]
	s_cbranch_vccz .LBB0_1737
	s_barrier

; #define SEAM() do { xcd_barrier(xbar); } while (0)
; #define SEAM() do { } while (0)
; #define GEMM_RESID(Aop, Kdim, WT, XIN, ssi, ALPHA) do { pg8::Gemm g_{Aop, WT, T, DM, Kdim, Kdim}; pg8::StaticOrder S_; S_.init(T, DM, G, bx); pg8::EpiResid E_{XIN, p.out, XB, SS + (size_t)(ssi) * T, ALPHA}; \
;         pg8::gemm_phase<pg8::EpiResid, pg8::StaticOrder, true, true>(ldsl, g_, S_, E_, wave); } while (0)
; __global__ void __launch_bounds__(512, 2) fwd_kernel(Params p) {
;     ...
;     SEAM();
;     if (IN(15)) GEMM_RESID(COMB, DM, W_O1, p.out, 5, 1.0f);
.LBB0_2062:
	s_cmp_lt_i32 s92, 16
	s_cselect_b64 s[0:1], -1, 0
	s_cmp_gt_i32 s93, 15
	s_cselect_b64 s[2:3], -1, 0
	s_and_b64 s[0:1], s[0:1], s[2:3]
	s_andn2_b64 vcc, exec, s[0:1]
	s_waitcnt lgkmcnt(0)
	s_barrier
	s_cbranch_vccnz .LBB0_2105
	s_setprio 0
	s_cmp_lt_u32 s89, 4
	s_cbranch_scc1 .Lgprio_9
	s_setprio 1

; #define PG8_STAGE(bufoff, gbase, voff) do { _Pragma("unroll") for (int _i = 0; _i < 2; ++_i) \
;         __builtin_amdgcn_global_load_lds((const unsigned*)((const char*)(gbase) + (voff)[_i]), (PG8_LAS unsigned*)(lds + (bufoff) + ldsw + _i * 8192), 16, 0, 0); } while (0)
; #define PG8_LDA(dst, b, h) do { _Pragma("unroll") for (int m = 0; m < 4; ++m) _Pragma("unroll") for (int k = 0; k < 2; ++k) dst[m][k] = *(const PG8_LAS bf16x8*)(lds + PG8_SA(b, h) + aoff + m * 2048 + k * 1024); } while (0)
; #define PG8_LDB(dst, b, h) do { _Pragma("unroll") for (int n = 0; n < 2; ++n) _Pragma("unroll") for (int k = 0; k < 2; ++k) dst[n][k] = *(const PG8_LAS bf16x8*)(lds + PG8_SB(b, h) + boff + n * 2048 + k * 1024); } while (0)
; #define PG8_WAIT_V(n) asm volatile("s_waitcnt vmcnt(" #n ")" ::: "memory")
; #define PG8_WAIT_L(n) asm volatile("s_waitcnt lgkmcnt(" #n ")" ::: "memory")
; #define PG8_BAR __builtin_amdgcn_s_barrier()
; #define PG8_SCHED __builtin_amdgcn_sched_barrier(0)
; template <class Epi, class Sched, bool ALIGN_EPI = false, bool SP2 = false>
; __device__ __forceinline__ void gemm_phase(PG8_LAS unsigned char* lds, const Gemm g, const Sched& S, const Epi& E, const int wave_in) {
;     ...
;         const char* nA = has_next ? (const char*)g.A + (size_t)nxt.pm * tstepA : cA; const char* nB = has_next ? (const char*)g.Bt + (size_t)nxt.pn * tstep : cB;
;         for (int t = 0; t < nt; t += 2) {
;             const bool last = (t == nt - 2);
;             const char* a1 = cA + (size_t)(t + 1) * kstep;
;             const char* a2 = last ? nA : cA + (size_t)(t + 2) * kstep; const char* b2 = last ? nB : cB + (size_t)(t + 2) * kstep;
;             const char* a3 = a2 + kstep; const char* b3 = b2 + kstep;
;             if (last && has_next) S.a_ready(nxt);
;             if constexpr (SP2) {
;             PG8_LDB(B0, 0, 0); PG8_LDB(B1, 0, 1); PG8_SCHED; PG8_LDA(At, 0, 0); PG8_STAGE(PG8_SA(1, 1), a1 + hstepA, voffA);
;             PG8_WAIT_V(8); PG8_WAIT_L(0); PG8_BAR; PG8_MMA(0, 0, At, B0); PG8_MMA(0, 1, At, B1); PG8_BAR; PG8_SCHED;
;             PG8_LDA(At, 0, 1); PG8_STAGE(PG8_SB(0, 0), b2, voffB); PG8_STAGE(PG8_SB(0, 1), b2 + hstep, voffB); PG8_STAGE(PG8_SA(0, 0), a2, voffA);
;             PG8_WAIT_V(8); PG8_WAIT_L(0); PG8_BAR; PG8_MMA(1, 0, At, B0); PG8_MMA(1, 1, At, B1); PG8_BAR; PG8_SCHED;
.LBB0_2082:
	ds_read_b128 v[144:147], v151
	ds_read_b128 v[156:159], v151 offset:1024
	ds_read_b128 v[160:163], v151 offset:2048
	ds_read_b128 v[164:167], v151 offset:3072
	ds_read_b128 v[168:171], v152
	ds_read_b128 v[172:175], v152 offset:1024
	ds_read_b128 v[176:179], v152 offset:2048
	ds_read_b128 v[180:183], v152 offset:3072
	s_add_u32 s40, s38, 0xfff80080
	s_addc_u32 s41, s39, -1
	s_cmp_eq_u32 s58, 28
	s_cselect_b32 s43, s19, s41
	s_cselect_b32 s42, s25, s40
	s_cselect_b32 s41, s17, s57
	s_cselect_b32 s40, s55, s56
	v_lshl_add_u64 v[216:217], s[38:39], 0, v[136:137]
	s_add_i32 m0, s33, 0xc000
	ds_read_b128 v[184:187], v153
	ds_read_b128 v[188:191], v153 offset:1024
	ds_read_b128 v[192:195], v153 offset:2048
	ds_read_b128 v[196:199], v153 offset:3072
	ds_read_b128 v[200:203], v153 offset:4096
	ds_read_b128 v[204:207], v153 offset:5120
	ds_read_b128 v[208:211], v153 offset:6144
	ds_read_b128 v[212:215], v153 offset:7168
	global_load_lds_dwordx4 v[216:217], off
	v_lshl_add_u64 v[216:217], s[38:39], 0, v[138:139]
	s_add_i32 m0, s33, 0xe000
	s_nop 0
	global_load_lds_dwordx4 v[216:217], off
	s_waitcnt vmcnt(8)
	s_waitcnt lgkmcnt(0)
	s_barrier
	s_waitcnt lgkmcnt(0)
	v_mfma_f32_16x16x32_bf16 v[124:127], v[144:147], v[184:187], v[124:127]
	v_mfma_f32_16x16x32_bf16 v[120:123], v[160:163], v[184:187], v[120:123]
	v_mfma_f32_16x16x32_bf16 v[108:111], v[144:147], v[192:195], v[108:111]
	v_mfma_f32_16x16x32_bf16 v[104:107], v[160:163], v[192:195], v[104:107]
	v_mfma_f32_16x16x32_bf16 v[92:95], v[144:147], v[200:203], v[92:95]
	v_mfma_f32_16x16x32_bf16 v[88:91], v[160:163], v[200:203], v[88:91]
	v_mfma_f32_16x16x32_bf16 v[76:79], v[144:147], v[208:211], v[76:79]
	v_mfma_f32_16x16x32_bf16 v[72:75], v[160:163], v[208:211], v[72:75]
	v_mfma_f32_16x16x32_bf16 v[124:127], v[156:159], v[188:191], v[124:127]
	v_mfma_f32_16x16x32_bf16 v[120:123], v[164:167], v[188:191], v[120:123]
	v_mfma_f32_16x16x32_bf16 v[108:111], v[156:159], v[196:199], v[108:111]
	v_mfma_f32_16x16x32_bf16 v[104:107], v[164:167], v[196:199], v[104:107]
	v_mfma_f32_16x16x32_bf16 v[92:95], v[156:159], v[204:207], v[92:95]
	v_mfma_f32_16x16x32_bf16 v[88:91], v[164:167], v[204:207], v[88:91]
	v_mfma_f32_16x16x32_bf16 v[76:79], v[156:159], v[212:215], v[76:79]
	v_mfma_f32_16x16x32_bf16 v[72:75], v[164:167], v[212:215], v[72:75]
	v_mfma_f32_16x16x32_bf16 v[116:119], v[168:171], v[184:187], v[116:119]
	v_mfma_f32_16x16x32_bf16 v[112:115], v[176:179], v[184:187], v[112:115]
	v_mfma_f32_16x16x32_bf16 v[100:103], v[168:171], v[192:195], v[100:103]
	v_mfma_f32_16x16x32_bf16 v[96:99], v[176:179], v[192:195], v[96:99]
	v_mfma_f32_16x16x32_bf16 v[84:87], v[168:171], v[200:203], v[84:87]
	v_mfma_f32_16x16x32_bf16 v[80:83], v[176:179], v[200:203], v[80:83]
	v_mfma_f32_16x16x32_bf16 v[68:71], v[168:171], v[208:211], v[68:71]
	v_mfma_f32_16x16x32_bf16 v[64:67], v[176:179], v[208:211], v[64:67]
	v_mfma_f32_16x16x32_bf16 v[116:119], v[172:175], v[188:191], v[116:119]
	v_mfma_f32_16x16x32_bf16 v[112:115], v[180:183], v[188:191], v[112:115]
	v_mfma_f32_16x16x32_bf16 v[100:103], v[172:175], v[196:199], v[100:103]
	v_mfma_f32_16x16x32_bf16 v[96:99], v[180:183], v[196:199], v[96:99]
	v_mfma_f32_16x16x32_bf16 v[84:87], v[172:175], v[204:207], v[84:87]
	v_mfma_f32_16x16x32_bf16 v[80:83], v[180:183], v[204:207], v[80:83]
	v_mfma_f32_16x16x32_bf16 v[68:71], v[172:175], v[212:215], v[68:71]
	v_mfma_f32_16x16x32_bf16 v[64:67], v[180:183], v[212:215], v[64:67]
	s_barrier
	s_add_i32 s59, s53, s11
	v_lshl_add_u64 v[216:217], s[40:41], 0, v[130:131]
	s_mov_b32 m0, s59
	ds_read_b128 v[184:187], v153 offset:16384
	ds_read_b128 v[188:191], v153 offset:17408
	ds_read_b128 v[192:195], v153 offset:18432
	ds_read_b128 v[196:199], v153 offset:19456
	ds_read_b128 v[200:203], v153 offset:20480
	ds_read_b128 v[204:207], v153 offset:21504
	ds_read_b128 v[208:211], v153 offset:22528
	ds_read_b128 v[212:215], v153 offset:23552
	global_load_lds_dwordx4 v[216:217], off
	s_add_i32 m0, s59, 0x2000
	s_add_u32 s60, s40, 0x80000
	v_lshl_add_u64 v[218:219], s[40:41], 0, v[134:135]
	s_addc_u32 s61, s41, 0
	s_add_i32 s59, s54, s11
	global_load_lds_dwordx4 v[218:219], off
	v_lshl_add_u64 v[220:221], s[60:61], 0, v[130:131]
	s_mov_b32 m0, s59
	v_lshl_add_u64 v[222:223], s[42:43], 0, v[132:133]
	global_load_lds_dwordx4 v[220:221], off
	v_lshl_add_u64 v[220:221], s[60:61], 0, v[134:135]
	s_add_i32 m0, s59, 0x2000
	s_nop 0
	global_load_lds_dwordx4 v[220:221], off
	v_lshl_add_u64 v[220:221], s[42:43], 0, v[128:129]
	s_mov_b32 m0, s33
	s_nop 0
	global_load_lds_dwordx4 v[220:221], off
	s_mov_b32 m0, s35
	s_nop 0
	global_load_lds_dwordx4 v[222:223], off
	s_waitcnt vmcnt(8)
	s_waitcnt lgkmcnt(0)
	s_barrier
; #define PG8_STAGE(bufoff, gbase, voff) do { _Pragma("unroll") for (int _i = 0; _i < 2; ++_i) \
;         __builtin_amdgcn_global_load_lds((const unsigned*)((const char*)(gbase) + (voff)[_i]), (PG8_LAS unsigned*)(lds + (bufoff) + ldsw + _i * 8192), 16, 0, 0); } while (0)
; #define PG8_LDA(dst, b, h) do { _Pragma("unroll") for (int m = 0; m < 4; ++m) _Pragma("unroll") for (int k = 0; k < 2; ++k) dst[m][k] = *(const PG8_LAS bf16x8*)(lds + PG8_SA(b, h) + aoff + m * 2048 + k * 1024); } while (0)
; #define PG8_LDB(dst, b, h) do { _Pragma("unroll") for (int n = 0; n < 2; ++n) _Pragma("unroll") for (int k = 0; k < 2; ++k) dst[n][k] = *(const PG8_LAS bf16x8*)(lds + PG8_SB(b, h) + boff + n * 2048 + k * 1024); } while (0)
; #define PG8_MMA(ai, bj, At, Bt) do { __builtin_amdgcn_s_setprio(1); _Pragma("unroll") for (int m = 0; m < 4; ++m) _Pragma("unroll") for (int n = 0; n < 2; ++n) _Pragma("unroll") for (int k = 0; k < 2; ++k) \
;         acc[ai][bj][m][n] = __builtin_amdgcn_mfma_f32_16x16x32_bf16(Bt[n][k], At[m][k], acc[ai][bj][m][n], 0, 0, 0); __builtin_amdgcn_s_setprio(0); } while (0)
; #define PG8_WAIT_V(n) asm volatile("s_waitcnt vmcnt(" #n ")" ::: "memory")
; #define PG8_WAIT_L(n) asm volatile("s_waitcnt lgkmcnt(" #n ")" ::: "memory")
; #define PG8_BAR __builtin_amdgcn_s_barrier()
; #define PG8_SCHED __builtin_amdgcn_sched_barrier(0)
; template <class Epi, class Sched, bool ALIGN_EPI = false, bool SP2 = false>
; __device__ __forceinline__ void gemm_phase(PG8_LAS unsigned char* lds, const Gemm g, const Sched& S, const Epi& E, const int wave_in) {
;     ...
;             PG8_WAIT_V(8); PG8_WAIT_L(0); PG8_BAR; PG8_MMA(1, 0, At, B0); PG8_MMA(1, 1, At, B1); PG8_BAR; PG8_SCHED;
;             PG8_LDB(B0, 1, 0); PG8_LDB(B1, 1, 1); PG8_SCHED; PG8_LDA(At, 1, 0); PG8_STAGE(PG8_SA(0, 1), a2 + hstepA, voffA);
;             PG8_WAIT_V(8); PG8_WAIT_L(0); PG8_BAR; PG8_MMA(0, 0, At, B0); PG8_MMA(0, 1, At, B1); PG8_BAR; PG8_SCHED;
	s_waitcnt lgkmcnt(0)
	v_mfma_f32_16x16x32_bf16 v[60:63], v[144:147], v[184:187], v[60:63]
	v_mfma_f32_16x16x32_bf16 v[56:59], v[160:163], v[184:187], v[56:59]
	v_mfma_f32_16x16x32_bf16 v[44:47], v[144:147], v[192:195], v[44:47]
	v_mfma_f32_16x16x32_bf16 v[40:43], v[160:163], v[192:195], v[40:43]
	v_mfma_f32_16x16x32_bf16 v[28:31], v[144:147], v[200:203], v[28:31]
	v_mfma_f32_16x16x32_bf16 v[24:27], v[160:163], v[200:203], v[24:27]
	v_mfma_f32_16x16x32_bf16 v[12:15], v[144:147], v[208:211], v[12:15]
	v_mfma_f32_16x16x32_bf16 v[8:11], v[160:163], v[208:211], v[8:11]
	v_mfma_f32_16x16x32_bf16 v[60:63], v[156:159], v[188:191], v[60:63]
	v_mfma_f32_16x16x32_bf16 v[56:59], v[164:167], v[188:191], v[56:59]
	v_mfma_f32_16x16x32_bf16 v[44:47], v[156:159], v[196:199], v[44:47]
	v_mfma_f32_16x16x32_bf16 v[40:43], v[164:167], v[196:199], v[40:43]
	v_mfma_f32_16x16x32_bf16 v[28:31], v[156:159], v[204:207], v[28:31]
	v_mfma_f32_16x16x32_bf16 v[24:27], v[164:167], v[204:207], v[24:27]
	v_mfma_f32_16x16x32_bf16 v[12:15], v[156:159], v[212:215], v[12:15]
	v_mfma_f32_16x16x32_bf16 v[8:11], v[164:167], v[212:215], v[8:11]
	v_mfma_f32_16x16x32_bf16 v[52:55], v[168:171], v[184:187], v[52:55]
	v_mfma_f32_16x16x32_bf16 v[48:51], v[176:179], v[184:187], v[48:51]
	v_mfma_f32_16x16x32_bf16 v[36:39], v[168:171], v[192:195], v[36:39]
	v_mfma_f32_16x16x32_bf16 v[32:35], v[176:179], v[192:195], v[32:35]
	v_mfma_f32_16x16x32_bf16 v[20:23], v[168:171], v[200:203], v[20:23]
	v_mfma_f32_16x16x32_bf16 v[16:19], v[176:179], v[200:203], v[16:19]
	v_mfma_f32_16x16x32_bf16 v[4:7], v[168:171], v[208:211], v[4:7]
	v_mfma_f32_16x16x32_bf16 v[0:3], v[176:179], v[208:211], v[0:3]
	v_mfma_f32_16x16x32_bf16 v[52:55], v[172:175], v[188:191], v[52:55]
	v_mfma_f32_16x16x32_bf16 v[48:51], v[180:183], v[188:191], v[48:51]
	v_mfma_f32_16x16x32_bf16 v[36:39], v[172:175], v[196:199], v[36:39]
	v_mfma_f32_16x16x32_bf16 v[32:35], v[180:183], v[196:199], v[32:35]
	v_mfma_f32_16x16x32_bf16 v[20:23], v[172:175], v[204:207], v[20:23]
	v_mfma_f32_16x16x32_bf16 v[16:19], v[180:183], v[204:207], v[16:19]
	v_mfma_f32_16x16x32_bf16 v[4:7], v[172:175], v[212:215], v[4:7]
	v_mfma_f32_16x16x32_bf16 v[0:3], v[180:183], v[212:215], v[0:3]
	s_barrier
	s_add_i32 s59, 0, 0x18000
	v_add_u32_e32 v155, s59, v149
	s_add_i32 s60, 0, 0x1c000
	ds_read_b128 v[144:147], v155
	ds_read_b128 v[156:159], v155 offset:1024
	ds_read_b128 v[160:163], v155 offset:2048
	ds_read_b128 v[164:167], v155 offset:3072
	v_add_u32_e32 v155, s60, v149
	ds_read_b128 v[168:171], v155
	ds_read_b128 v[172:175], v155 offset:1024
	ds_read_b128 v[176:179], v155 offset:2048
	ds_read_b128 v[180:183], v155 offset:3072
	s_add_u32 s42, s42, 0x80000
	s_addc_u32 s43, s43, 0
	s_mov_b32 m0, s37
	v_lshl_add_u64 v[224:225], s[42:43], 0, v[128:129]
	ds_read_b128 v[184:187], v153 offset:32768
	ds_read_b128 v[188:191], v153 offset:33792
	ds_read_b128 v[192:195], v153 offset:34816
	ds_read_b128 v[196:199], v153 offset:35840
	ds_read_b128 v[200:203], v153 offset:36864
	ds_read_b128 v[204:207], v153 offset:37888
	ds_read_b128 v[208:211], v153 offset:38912
	ds_read_b128 v[212:215], v153 offset:39936
	global_load_lds_dwordx4 v[224:225], off
	v_lshl_add_u64 v[224:225], s[42:43], 0, v[132:133]
	s_mov_b32 m0, s48
	s_nop 0
	global_load_lds_dwordx4 v[224:225], off
	s_waitcnt vmcnt(8)
	s_waitcnt lgkmcnt(0)
	s_barrier
	s_waitcnt lgkmcnt(0)
	v_mfma_f32_16x16x32_bf16 v[124:127], v[144:147], v[184:187], v[124:127]
	v_mfma_f32_16x16x32_bf16 v[120:123], v[160:163], v[184:187], v[120:123]
	v_mfma_f32_16x16x32_bf16 v[108:111], v[144:147], v[192:195], v[108:111]
	v_mfma_f32_16x16x32_bf16 v[104:107], v[160:163], v[192:195], v[104:107]
	v_mfma_f32_16x16x32_bf16 v[92:95], v[144:147], v[200:203], v[92:95]
	v_mfma_f32_16x16x32_bf16 v[88:91], v[160:163], v[200:203], v[88:91]
	v_mfma_f32_16x16x32_bf16 v[76:79], v[144:147], v[208:211], v[76:79]
	v_mfma_f32_16x16x32_bf16 v[72:75], v[160:163], v[208:211], v[72:75]
	v_mfma_f32_16x16x32_bf16 v[124:127], v[156:159], v[188:191], v[124:127]
	v_mfma_f32_16x16x32_bf16 v[120:123], v[164:167], v[188:191], v[120:123]
	v_mfma_f32_16x16x32_bf16 v[108:111], v[156:159], v[196:199], v[108:111]
	v_mfma_f32_16x16x32_bf16 v[104:107], v[164:167], v[196:199], v[104:107]
	v_mfma_f32_16x16x32_bf16 v[92:95], v[156:159], v[204:207], v[92:95]
	v_mfma_f32_16x16x32_bf16 v[88:91], v[164:167], v[204:207], v[88:91]
	v_mfma_f32_16x16x32_bf16 v[76:79], v[156:159], v[212:215], v[76:79]
	v_mfma_f32_16x16x32_bf16 v[72:75], v[164:167], v[212:215], v[72:75]
	v_mfma_f32_16x16x32_bf16 v[116:119], v[168:171], v[184:187], v[116:119]
	v_mfma_f32_16x16x32_bf16 v[112:115], v[176:179], v[184:187], v[112:115]
	v_mfma_f32_16x16x32_bf16 v[100:103], v[168:171], v[192:195], v[100:103]
	v_mfma_f32_16x16x32_bf16 v[96:99], v[176:179], v[192:195], v[96:99]
	v_mfma_f32_16x16x32_bf16 v[84:87], v[168:171], v[200:203], v[84:87]
	v_mfma_f32_16x16x32_bf16 v[80:83], v[176:179], v[200:203], v[80:83]
	v_mfma_f32_16x16x32_bf16 v[68:71], v[168:171], v[208:211], v[68:71]
	v_mfma_f32_16x16x32_bf16 v[64:67], v[176:179], v[208:211], v[64:67]
	v_mfma_f32_16x16x32_bf16 v[116:119], v[172:175], v[188:191], v[116:119]
	v_mfma_f32_16x16x32_bf16 v[112:115], v[180:183], v[188:191], v[112:115]
	v_mfma_f32_16x16x32_bf16 v[100:103], v[172:175], v[196:199], v[100:103]
	v_mfma_f32_16x16x32_bf16 v[96:99], v[180:183], v[196:199], v[96:99]
	v_mfma_f32_16x16x32_bf16 v[84:87], v[172:175], v[204:207], v[84:87]
	v_mfma_f32_16x16x32_bf16 v[80:83], v[180:183], v[204:207], v[80:83]
	v_mfma_f32_16x16x32_bf16 v[68:71], v[172:175], v[212:215], v[68:71]
	v_mfma_f32_16x16x32_bf16 v[64:67], v[180:183], v[212:215], v[64:67]
	s_barrier
; #define PG8_STAGE(bufoff, gbase, voff) do { _Pragma("unroll") for (int _i = 0; _i < 2; ++_i) \
;         __builtin_amdgcn_global_load_lds((const unsigned*)((const char*)(gbase) + (voff)[_i]), (PG8_LAS unsigned*)(lds + (bufoff) + ldsw + _i * 8192), 16, 0, 0); } while (0)
; #define PG8_LDA(dst, b, h) do { _Pragma("unroll") for (int m = 0; m < 4; ++m) _Pragma("unroll") for (int k = 0; k < 2; ++k) dst[m][k] = *(const PG8_LAS bf16x8*)(lds + PG8_SA(b, h) + aoff + m * 2048 + k * 1024); } while (0)
; #define PG8_BAR __builtin_amdgcn_s_barrier()
; template <class Epi, class Sched, bool ALIGN_EPI = false, bool SP2 = false>
; __device__ __forceinline__ void gemm_phase(PG8_LAS unsigned char* lds, const Gemm g, const Sched& S, const Epi& E, const int wave_in) {
;     ...
;             PG8_LDA(At, 1, 1); PG8_STAGE(PG8_SB(1, 0), b3, voffB); PG8_STAGE(PG8_SB(1, 1), b3 + hstep, voffB); PG8_STAGE(PG8_SA(1, 0), a3, voffA);
;             PG8_WAIT_V(8); PG8_WAIT_L(0); PG8_BAR; PG8_MMA(1, 0, At, B0); PG8_MMA(1, 1, At, B1); PG8_BAR; PG8_SCHED;
;             } else {
;             PG8_LDB(B0, 0, 0); PG8_SCHED; PG8_LDA(At, 0, 0); PG8_STAGE(PG8_SA(1, 1), a1 + hstepA, voffA);
;             PG8_WAIT_L(8); PG8_BAR; PG8_WAIT_L(0); PG8_MMA(0, 0, At, B0); PG8_BAR; PG8_SCHED;
;             PG8_LDB(B1, 0, 1); PG8_STAGE(PG8_SB(0, 0), b2, voffB);
;             PG8_BAR; PG8_WAIT_L(0); PG8_MMA(0, 1, At, B1); PG8_BAR;
;             PG8_LDA(At, 0, 1); PG8_STAGE(PG8_SA(0, 0), a2, voffA);
;             PG8_BAR; PG8_WAIT_L(0); PG8_MMA(1, 0, At, B0); PG8_BAR; PG8_SCHED;
;             PG8_STAGE(PG8_SB(0, 1), b2 + hstep, voffB);
;             PG8_WAIT_V(6); PG8_BAR; PG8_MMA(1, 1, At, B1); PG8_BAR;
;             PG8_LDB(B0, 1, 0); PG8_SCHED; PG8_LDA(At, 1, 0); PG8_STAGE(PG8_SA(0, 1), a2 + hstepA, voffA);
;             PG8_WAIT_L(8); PG8_BAR; PG8_WAIT_L(0); PG8_MMA(0, 0, At, B0); PG8_BAR; PG8_SCHED;
;             PG8_LDB(B1, 1, 1); PG8_STAGE(PG8_SB(1, 0), b3, voffB);
;             PG8_BAR; PG8_WAIT_L(0); PG8_MMA(0, 1, At, B1); PG8_BAR;
;             PG8_LDA(At, 1, 1); PG8_STAGE(PG8_SA(1, 0), a3, voffA);
;             PG8_BAR; PG8_WAIT_L(0); PG8_MMA(1, 0, At, B0); PG8_BAR; PG8_SCHED;
;             PG8_STAGE(PG8_SB(1, 1), b3 + hstep, voffB);
;             PG8_WAIT_V(6); PG8_BAR; PG8_MMA(1, 1, At, B1); PG8_BAR;
;             }
;         }
;         if constexpr (ALIGN_EPI) { if (wr == 0) PG8_BAR; }
	s_add_i32 s42, s59, s11
	v_lshl_add_u64 v[216:217], v[216:217], 0, s[12:13]
	s_mov_b32 m0, s42
	ds_read_b128 v[184:187], v153 offset:49152
	ds_read_b128 v[188:191], v153 offset:50176
	ds_read_b128 v[192:195], v153 offset:51200
	ds_read_b128 v[196:199], v153 offset:52224
	ds_read_b128 v[200:203], v153 offset:53248
	ds_read_b128 v[204:207], v153 offset:54272
	ds_read_b128 v[208:211], v153 offset:55296
	ds_read_b128 v[212:215], v153 offset:56320
	global_load_lds_dwordx4 v[216:217], off
	s_add_i32 m0, s42, 0x2000
	s_add_u32 s40, s40, 0x80080
	v_lshl_add_u64 v[216:217], v[218:219], 0, s[12:13]
	s_addc_u32 s41, s41, 0
	s_add_i32 s42, s60, s11
	global_load_lds_dwordx4 v[216:217], off
	v_lshl_add_u64 v[216:217], s[40:41], 0, v[130:131]
	s_mov_b32 m0, s42
	s_nop 0
	global_load_lds_dwordx4 v[216:217], off
	v_lshl_add_u64 v[216:217], s[40:41], 0, v[134:135]
	s_add_i32 m0, s42, 0x2000
	s_nop 0
	global_load_lds_dwordx4 v[216:217], off
	v_lshl_add_u64 v[216:217], v[220:221], 0, s[12:13]
	s_mov_b32 m0, s50
	s_nop 0
	global_load_lds_dwordx4 v[216:217], off
	v_lshl_add_u64 v[216:217], v[222:223], 0, s[12:13]
	s_mov_b32 m0, s51
	s_nop 0
	global_load_lds_dwordx4 v[216:217], off
	s_waitcnt vmcnt(8)
	s_waitcnt lgkmcnt(0)
	s_barrier
	s_waitcnt lgkmcnt(0)
	v_mfma_f32_16x16x32_bf16 v[60:63], v[144:147], v[184:187], v[60:63]
	v_mfma_f32_16x16x32_bf16 v[56:59], v[160:163], v[184:187], v[56:59]
	v_mfma_f32_16x16x32_bf16 v[44:47], v[144:147], v[192:195], v[44:47]
	v_mfma_f32_16x16x32_bf16 v[40:43], v[160:163], v[192:195], v[40:43]
	v_mfma_f32_16x16x32_bf16 v[28:31], v[144:147], v[200:203], v[28:31]
	v_mfma_f32_16x16x32_bf16 v[24:27], v[160:163], v[200:203], v[24:27]
	v_mfma_f32_16x16x32_bf16 v[12:15], v[144:147], v[208:211], v[12:15]
	v_mfma_f32_16x16x32_bf16 v[8:11], v[160:163], v[208:211], v[8:11]
	v_mfma_f32_16x16x32_bf16 v[60:63], v[156:159], v[188:191], v[60:63]
	v_mfma_f32_16x16x32_bf16 v[56:59], v[164:167], v[188:191], v[56:59]
	v_mfma_f32_16x16x32_bf16 v[44:47], v[156:159], v[196:199], v[44:47]
	v_mfma_f32_16x16x32_bf16 v[40:43], v[164:167], v[196:199], v[40:43]
	v_mfma_f32_16x16x32_bf16 v[28:31], v[156:159], v[204:207], v[28:31]
	v_mfma_f32_16x16x32_bf16 v[24:27], v[164:167], v[204:207], v[24:27]
	v_mfma_f32_16x16x32_bf16 v[12:15], v[156:159], v[212:215], v[12:15]
	v_mfma_f32_16x16x32_bf16 v[8:11], v[164:167], v[212:215], v[8:11]
	v_mfma_f32_16x16x32_bf16 v[52:55], v[168:171], v[184:187], v[52:55]
	v_mfma_f32_16x16x32_bf16 v[48:51], v[176:179], v[184:187], v[48:51]
	v_mfma_f32_16x16x32_bf16 v[36:39], v[168:171], v[192:195], v[36:39]
	v_mfma_f32_16x16x32_bf16 v[32:35], v[176:179], v[192:195], v[32:35]
	v_mfma_f32_16x16x32_bf16 v[20:23], v[168:171], v[200:203], v[20:23]
	v_mfma_f32_16x16x32_bf16 v[16:19], v[176:179], v[200:203], v[16:19]
	v_mfma_f32_16x16x32_bf16 v[4:7], v[168:171], v[208:211], v[4:7]
	v_mfma_f32_16x16x32_bf16 v[0:3], v[176:179], v[208:211], v[0:3]
	v_mfma_f32_16x16x32_bf16 v[52:55], v[172:175], v[188:191], v[52:55]
	v_mfma_f32_16x16x32_bf16 v[48:51], v[180:183], v[188:191], v[48:51]
	v_mfma_f32_16x16x32_bf16 v[36:39], v[172:175], v[196:199], v[36:39]
	v_mfma_f32_16x16x32_bf16 v[32:35], v[180:183], v[196:199], v[32:35]
	v_mfma_f32_16x16x32_bf16 v[20:23], v[172:175], v[204:207], v[20:23]
	v_mfma_f32_16x16x32_bf16 v[16:19], v[180:183], v[204:207], v[16:19]
	v_mfma_f32_16x16x32_bf16 v[4:7], v[172:175], v[212:215], v[4:7]
	v_mfma_f32_16x16x32_bf16 v[0:3], v[180:183], v[212:215], v[0:3]
	s_barrier
	s_add_i32 s58, s58, 2
	s_add_u32 s38, s38, 0x100
	s_addc_u32 s39, s39, 0
	s_add_u32 s56, s56, 0x100
	s_addc_u32 s57, s57, 0
	s_cmp_gt_u32 s58, 29
	s_cbranch_scc0 .LBB0_2082
	s_and_b64 vcc, exec, s[14:15]
	s_cbranch_vccz .LBB0_2085
	s_barrier

; template <class Epi, class Sched, bool ALIGN_EPI = false, bool SP2 = false>
; __device__ __forceinline__ void gemm_phase(PG8_LAS unsigned char* lds, const Gemm g, const Sched& S, const Epi& E, const int wave_in) {
;     const int wid = __builtin_amdgcn_readfirstlane(wave_in), lane = mk_lane(), tid = wid * 64 + lane, wr = wid >> 2, wc = wid & 3, fr = lane & 15, fq = lane >> 4;
;     const int K = g.K, nt = K / BK;
;     unsigned voffA[2], voffB[2];
; #pragma unroll
;     for (int i = 0; i < 2; ++i) { int R, C; stage_rc(tid * 16 + i * 8192, R, C); const int Rb = Epi::PERM ? ((R & ~31) + perm32(R & 31)) : R;
;         voffA[i] = (unsigned)(R * g.lda + C) * 2u; voffB[i] = (unsigned)(Rb * K + C) * 2u; }
;     const size_t kstep = (size_t)(BK * 2);
;     const size_t hstep = (size_t)HALF * K * 2, hstepA = (size_t)HALF * g.lda * 2;
;     const size_t tstep = 2 * hstep, tstepA = 2 * hstepA;
;     const unsigned ldsw = (unsigned)wid * 1024u;
;     const int aoff = lds_byte(wr * 64 + fr, fq * 8), boff = lds_byte(wc * 32 + fr, fq * 8);
;     ...
;     Unit cur, nxt; int ui = 0;
;     if (!S.next(0, cur)) return;
;     f32x4 acc[2][2][4][2];
; #pragma unroll
;     for (int a = 0; a < 2; ++a)
; #pragma unroll
;         for (int b = 0; b < 2; ++b)
; #pragma unroll
;             for (int m = 0; m < 4; ++m)
; #pragma unroll
;                 for (int n = 0; n < 2; ++n) acc[a][b][m][n] = (f32x4){0.f, 0.f, 0.f, 0.f};
;     bf16x8 At[4][2], B0[2][2], B1[2][2];
;     const char* cA = (const char*)g.A + (size_t)cur.pm * tstepA; const char* cB = (const char*)g.Bt + (size_t)cur.pn * tstep;
;     S.a_ready(cur);
;     if constexpr (SP2) {
;         PG8_STAGE(PG8_SB(0, 0), cB, voffB); PG8_STAGE(PG8_SB(0, 1), cB + hstep, voffB); PG8_STAGE(PG8_SA(0, 0), cA, voffA); PG8_STAGE(PG8_SA(0, 1), cA + hstepA, voffA);
;         if (wr == 1) PG8_BAR;
;         PG8_WAIT_V(2); PG8_BAR;
;         PG8_STAGE(PG8_SB(1, 0), cB + kstep, voffB); PG8_STAGE(PG8_SA(1, 0), cA + kstep, voffA); PG8_STAGE(PG8_SB(1, 1), cB + hstep + kstep, voffB);
;         PG8_WAIT_V(6); PG8_BAR;
;     } else {
;         PG8_STAGE(PG8_SB(0, 0), cB, voffB); PG8_STAGE(PG8_SA(0, 0), cA, voffA); PG8_STAGE(PG8_SB(0, 1), cB + hstep, voffB); PG8_STAGE(PG8_SA(0, 1), cA + hstepA, voffA);
;         if (wr == 1) PG8_BAR;
; __global__ void __launch_bounds__(512, 2) fwd_kernel(Params p) {
;     ...
;     if (IN(16)) FFN_UP(W_GU1, 5);
.LBB0_2159:
	s_cmp_lt_i32 s92, 17
	s_cselect_b64 s[0:1], -1, 0
	s_cmp_gt_i32 s93, 16
	s_cselect_b64 s[2:3], -1, 0
	s_and_b64 s[0:1], s[0:1], s[2:3]
	s_andn2_b64 vcc, exec, s[0:1]
	s_waitcnt lgkmcnt(0)
	s_barrier
	s_cbranch_vccnz .LBB0_2176
	s_setprio 0
	s_cmp_lt_u32 s89, 4
	s_cbranch_scc1 .Lgprio_10
	s_setprio 1
.Lgprio_10:
	s_cmpk_gt_i32 s88, 0x15ff
	s_waitcnt vmcnt(0)
	v_mbcnt_lo_u32_b32 v10, -1, 0
	v_mbcnt_hi_u32_b32 v10, -1, v10
	s_cbranch_scc1 .LBB0_2176
	s_lshl_b32 s11, s89, 10
	v_lshl_add_u32 v0, v10, 4, s11
	v_add_u32_e32 v1, 0x2000, v0
	v_ashrrev_i32_e32 v2, 31, v1
	v_lshrrev_b32_e32 v2, 22, v2
	v_add_u32_e32 v2, v1, v2
	v_ashrrev_i32_e32 v8, 10, v2
	v_mul_i32_i24_e32 v2, 0x400, v8
	v_sub_u32_e32 v1, v1, v2
	v_lshrrev_b32_e32 v2, 4, v1
	v_bitop3_b32 v1, v2, v1, 32 bitop3:0x6c
	v_ashrrev_i32_e32 v2, 31, v1
	v_lshrrev_b32_e32 v2, 26, v2
	v_add_u32_e32 v2, v1, v2
	v_ashrrev_i32_e32 v9, 6, v2
	v_lshlrev_b32_e32 v3, 3, v8
	v_and_b32_e32 v2, 0xffc0, v2
	v_and_b32_e32 v3, -16, v3
	v_sub_u32_e32 v1, v1, v2
	v_add_u32_e32 v3, v9, v3
	v_lshrrev_b16_e32 v2, 7, v1
	v_and_b32_e32 v4, 3, v9
	s_mov_b32 s0, 0xfffe0
	v_lshrrev_b32_e32 v5, 2, v3
	v_lshlrev_b32_e32 v6, 1, v3
	v_and_b32_e32 v2, 1, v2
	v_and_or_b32 v4, v3, s0, v4
	v_and_b32_e32 v5, 4, v5
	v_and_b32_e32 v6, 24, v6
	v_add_u16_e32 v1, v1, v2
	v_mov_b32_e32 v2, 1
	v_or3_b32 v4, v4, v5, v6
	v_lshlrev_b32_e32 v5, 5, v8
	v_ashrrev_i16_sdwa v1, v2, sext(v1) dst_sel:DWORD dst_unused:UNUSED_PAD src0_sel:DWORD src1_sel:BYTE_0
	v_and_b32_e32 v5, 32, v5
	v_bfe_i32 v11, v1, 0, 16
	v_add_lshl_u32 v1, v5, v11, 1
	v_lshl_add_u32 v128, v4, 12, v1
	v_lshl_add_u32 v130, v3, 12, v1
	v_ashrrev_i32_e32 v1, 31, v0
	v_lshrrev_b32_e32 v1, 22, v1
	v_add_u32_e32 v1, v0, v1
	v_ashrrev_i32_e32 v12, 10, v1
	v_mul_i32_i24_e32 v1, 0x400, v12
	v_sub_u32_e32 v0, v0, v1
	v_lshrrev_b32_e32 v1, 4, v0
	v_bitop3_b32 v0, v1, v0, 32 bitop3:0x6c
	v_ashrrev_i32_e32 v1, 31, v0
	v_lshrrev_b32_e32 v1, 26, v1
	v_add_u32_e32 v1, v0, v1
	v_lshlrev_b32_e32 v3, 3, v12
	v_ashrrev_i32_e32 v13, 6, v1
	v_and_b32_e32 v3, -16, v3
	v_add_u32_e32 v3, v13, v3
	v_and_b32_e32 v4, 3, v13
	s_ashr_i32 s33, s88, 31
	v_and_or_b32 v4, v3, s0, v4
	s_lshr_b32 s0, s33, 29
	s_add_i32 s0, s88, s0
	s_ashr_i32 s1, s0, 3
	s_and_b32 s0, s0, -8
	s_ashr_i32 s3, s89, 2
	s_sub_i32 s0, s88, s0
	s_cmp_lt_i32 s0, 0
	s_movk_i32 s35, 0x2c1
	s_cselect_b32 s2, s35, 0x2c0
	s_mul_i32 s0, s0, s2
	s_add_i32 s0, s0, s1
	s_mul_hi_i32 s1, s0, 0x2e8ba2e9
	s_lshr_b32 s2, s1, 31
	s_ashr_i32 s1, s1, 6
	s_add_i32 s1, s1, s2
	s_lshl_b32 s4, s1, 3
	s_mulk_i32 s1, 0x160
	s_sub_i32 s0, s0, s1
	s_sext_i32_i16 s1, s0
	s_bfe_u32 s1, s1, 0x3001c
	s_add_i32 s1, s0, s1
	s_sext_i32_i16 s2, s1
	s_and_b32 s1, s1, 0xfff8
	s_sub_i32 s0, s0, s1
	s_sext_i32_i16 s0, s0
	v_lshrrev_b32_e32 v5, 2, v3
	v_lshlrev_b32_e32 v6, 1, v3
	v_and_b32_e32 v1, 0xc0, v1
	s_lshr_b32 s2, s2, 3
	s_add_i32 s22, s4, s0
	v_and_b32_e32 v5, 4, v5
	v_and_b32_e32 v6, 24, v6
	v_sub_u32_e32 v0, v0, v1
	s_ashr_i32 s23, s22, 31
	s_bfe_i64 s[4:5], s[2:3], 0x100000
	v_or3_b32 v4, v4, v5, v6
	v_lshlrev_b32_e32 v5, 5, v12
	v_ashrrev_i16_sdwa v0, v2, sext(v0) dst_sel:DWORD dst_unused:UNUSED_PAD src0_sel:DWORD src1_sel:BYTE_0
	s_lshl_b64 s[0:1], s[22:23], 20
	s_lshl_b64 s[4:5], s[4:5], 20
	v_readlane_b32 s6, v255, 46
	v_and_b32_e32 v5, 32, v5
	v_bfe_i32 v14, v0, 0, 16
	v_readlane_b32 s7, v255, 47
	s_add_u32 s36, s6, s4
	v_add_lshl_u32 v0, v5, v14, 1
	s_addc_u32 s37, s7, s5
	s_add_i32 s23, s11, 0
	v_lshl_add_u32 v132, v4, 12, v0
	s_add_i32 m0, s23, 0x10000
	v_lshl_add_u32 v134, v3, 12, v0
	global_load_lds_dwordx4 v132, s[36:37]
	s_add_i32 m0, s23, 0x12000
	s_add_u32 s4, s36, 0x80000
	global_load_lds_dwordx4 v128, s[36:37]
	s_addc_u32 s5, s37, 0
	s_add_i32 m0, s23, 0x14000
	v_mov_b32_e32 v133, 0
	global_load_lds_dwordx4 v132, s[4:5]
	s_add_i32 m0, s23, 0x16000
	s_add_u32 s24, s46, s0
	s_addc_u32 s25, s47, s1
	s_add_i32 s40, s23, 0x2000
	global_load_lds_dwordx4 v128, s[4:5]
	s_mov_b32 m0, s23
	s_add_u32 s0, s24, 0x80000
	global_load_lds_dwordx4 v134, s[24:25]
	s_mov_b32 m0, s40
	s_addc_u32 s1, s25, 0
	s_add_i32 s41, s23, 0x4000
	global_load_lds_dwordx4 v130, s[24:25]
	s_mov_b32 m0, s41
	s_add_i32 s42, s23, 0x6000
	global_load_lds_dwordx4 v134, s[0:1]
	s_mov_b32 m0, s42
	v_mov_b32_e32 v129, v133
	global_load_lds_dwordx4 v130, s[0:1]
	v_mov_b32_e32 v135, v133
	v_mov_b32_e32 v131, v133
	s_cmp_eq_u32 s3, 1
	s_mov_b32 s43, 0
	v_lshl_add_u64 v[6:7], s[36:37], 0, v[132:133]
	v_lshl_add_u64 v[4:5], s[36:37], 0, v[128:129]
	v_lshl_add_u64 v[0:1], s[24:25], 0, v[134:135]
	s_cselect_b64 s[0:1], -1, 0
	s_cmp_lg_u32 s3, 1
	v_lshl_add_u64 v[2:3], s[24:25], 0, v[130:131]
	s_cbranch_scc1 .LBB0_2163
	s_barrier

; #define PG8_STAGE(bufoff, gbase, voff) do { _Pragma("unroll") for (int _i = 0; _i < 2; ++_i) \
;         __builtin_amdgcn_global_load_lds((const unsigned*)((const char*)(gbase) + (voff)[_i]), (PG8_LAS unsigned*)(lds + (bufoff) + ldsw + _i * 8192), 16, 0, 0); } while (0)
; #define PG8_LDA(dst, b, h) do { _Pragma("unroll") for (int m = 0; m < 4; ++m) _Pragma("unroll") for (int k = 0; k < 2; ++k) dst[m][k] = *(const PG8_LAS bf16x8*)(lds + PG8_SA(b, h) + aoff + m * 2048 + k * 1024); } while (0)
; #define PG8_LDB(dst, b, h) do { _Pragma("unroll") for (int n = 0; n < 2; ++n) _Pragma("unroll") for (int k = 0; k < 2; ++k) dst[n][k] = *(const PG8_LAS bf16x8*)(lds + PG8_SB(b, h) + boff + n * 2048 + k * 1024); } while (0)
; #define PG8_WAIT_V(n) asm volatile("s_waitcnt vmcnt(" #n ")" ::: "memory")
; #define PG8_WAIT_L(n) asm volatile("s_waitcnt lgkmcnt(" #n ")" ::: "memory")
; #define PG8_BAR __builtin_amdgcn_s_barrier()
; #define PG8_SCHED __builtin_amdgcn_sched_barrier(0)
; template <class Epi, class Sched, bool ALIGN_EPI = false, bool SP2 = false>
; __device__ __forceinline__ void gemm_phase(PG8_LAS unsigned char* lds, const Gemm g, const Sched& S, const Epi& E, const int wave_in) {
;     ...
;         const char* nA = has_next ? (const char*)g.A + (size_t)nxt.pm * tstepA : cA; const char* nB = has_next ? (const char*)g.Bt + (size_t)nxt.pn * tstep : cB;
;         for (int t = 0; t < nt; t += 2) {
;             const bool last = (t == nt - 2);
;             const char* a1 = cA + (size_t)(t + 1) * kstep;
;             const char* a2 = last ? nA : cA + (size_t)(t + 2) * kstep; const char* b2 = last ? nB : cB + (size_t)(t + 2) * kstep;
;             const char* a3 = a2 + kstep; const char* b3 = b2 + kstep;
;             if (last && has_next) S.a_ready(nxt);
;             if constexpr (SP2) {
;             PG8_LDB(B0, 0, 0); PG8_LDB(B1, 0, 1); PG8_SCHED; PG8_LDA(At, 0, 0); PG8_STAGE(PG8_SA(1, 1), a1 + hstepA, voffA);
;             PG8_WAIT_V(8); PG8_WAIT_L(0); PG8_BAR; PG8_MMA(0, 0, At, B0); PG8_MMA(0, 1, At, B1); PG8_BAR; PG8_SCHED;
;             PG8_LDA(At, 0, 1); PG8_STAGE(PG8_SB(0, 0), b2, voffB); PG8_STAGE(PG8_SB(0, 1), b2 + hstep, voffB); PG8_STAGE(PG8_SA(0, 0), a2, voffA);
;             PG8_WAIT_V(8); PG8_WAIT_L(0); PG8_BAR; PG8_MMA(1, 0, At, B0); PG8_MMA(1, 1, At, B1); PG8_BAR; PG8_SCHED;
.LBB0_2169:
	ds_read_b128 v[144:147], v151
	ds_read_b128 v[156:159], v151 offset:1024
	ds_read_b128 v[160:163], v151 offset:2048
	ds_read_b128 v[164:167], v151 offset:3072
	ds_read_b128 v[168:171], v152
	ds_read_b128 v[172:175], v152 offset:1024
	ds_read_b128 v[176:179], v152 offset:2048
	ds_read_b128 v[180:183], v152 offset:3072
	s_add_u32 s36, s24, 0xfff80080
	s_addc_u32 s37, s25, -1
	s_cmp_eq_u32 s58, 28
	s_cselect_b32 s39, s17, s37
	s_cselect_b32 s38, s54, s36
	s_cselect_b32 s37, s15, s57
	s_cselect_b32 s36, s55, s56
	v_lshl_add_u64 v[216:217], s[24:25], 0, v[136:137]
	s_add_i32 m0, s23, 0xc000
	ds_read_b128 v[184:187], v153
	ds_read_b128 v[188:191], v153 offset:1024
	ds_read_b128 v[192:195], v153 offset:2048
	ds_read_b128 v[196:199], v153 offset:3072
	ds_read_b128 v[200:203], v153 offset:4096
	ds_read_b128 v[204:207], v153 offset:5120
	ds_read_b128 v[208:211], v153 offset:6144
	ds_read_b128 v[212:215], v153 offset:7168
	global_load_lds_dwordx4 v[216:217], off
	v_lshl_add_u64 v[216:217], s[24:25], 0, v[138:139]
	s_add_i32 m0, s23, 0xe000
	s_nop 0
	global_load_lds_dwordx4 v[216:217], off
	s_waitcnt vmcnt(8)
	s_waitcnt lgkmcnt(0)
	s_barrier
	s_waitcnt lgkmcnt(0)
	v_mfma_f32_16x16x32_bf16 v[116:119], v[144:147], v[184:187], v[116:119]
	v_mfma_f32_16x16x32_bf16 v[112:115], v[160:163], v[184:187], v[112:115]
	v_mfma_f32_16x16x32_bf16 v[100:103], v[144:147], v[192:195], v[100:103]
	v_mfma_f32_16x16x32_bf16 v[96:99], v[160:163], v[192:195], v[96:99]
	v_mfma_f32_16x16x32_bf16 v[84:87], v[144:147], v[200:203], v[84:87]
	v_mfma_f32_16x16x32_bf16 v[80:83], v[160:163], v[200:203], v[80:83]
	v_mfma_f32_16x16x32_bf16 v[68:71], v[144:147], v[208:211], v[68:71]
	v_mfma_f32_16x16x32_bf16 v[64:67], v[160:163], v[208:211], v[64:67]
	v_mfma_f32_16x16x32_bf16 v[116:119], v[156:159], v[188:191], v[116:119]
	v_mfma_f32_16x16x32_bf16 v[112:115], v[164:167], v[188:191], v[112:115]
	v_mfma_f32_16x16x32_bf16 v[100:103], v[156:159], v[196:199], v[100:103]
	v_mfma_f32_16x16x32_bf16 v[96:99], v[164:167], v[196:199], v[96:99]
	v_mfma_f32_16x16x32_bf16 v[84:87], v[156:159], v[204:207], v[84:87]
	v_mfma_f32_16x16x32_bf16 v[80:83], v[164:167], v[204:207], v[80:83]
	v_mfma_f32_16x16x32_bf16 v[68:71], v[156:159], v[212:215], v[68:71]
	v_mfma_f32_16x16x32_bf16 v[64:67], v[164:167], v[212:215], v[64:67]
	v_mfma_f32_16x16x32_bf16 v[124:127], v[168:171], v[184:187], v[124:127]
	v_mfma_f32_16x16x32_bf16 v[120:123], v[176:179], v[184:187], v[120:123]
	v_mfma_f32_16x16x32_bf16 v[108:111], v[168:171], v[192:195], v[108:111]
	v_mfma_f32_16x16x32_bf16 v[104:107], v[176:179], v[192:195], v[104:107]
	v_mfma_f32_16x16x32_bf16 v[92:95], v[168:171], v[200:203], v[92:95]
	v_mfma_f32_16x16x32_bf16 v[88:91], v[176:179], v[200:203], v[88:91]
	v_mfma_f32_16x16x32_bf16 v[76:79], v[168:171], v[208:211], v[76:79]
	v_mfma_f32_16x16x32_bf16 v[72:75], v[176:179], v[208:211], v[72:75]
	v_mfma_f32_16x16x32_bf16 v[124:127], v[172:175], v[188:191], v[124:127]
	v_mfma_f32_16x16x32_bf16 v[120:123], v[180:183], v[188:191], v[120:123]
	v_mfma_f32_16x16x32_bf16 v[108:111], v[172:175], v[196:199], v[108:111]
	v_mfma_f32_16x16x32_bf16 v[104:107], v[180:183], v[196:199], v[104:107]
	v_mfma_f32_16x16x32_bf16 v[92:95], v[172:175], v[204:207], v[92:95]
	v_mfma_f32_16x16x32_bf16 v[88:91], v[180:183], v[204:207], v[88:91]
	v_mfma_f32_16x16x32_bf16 v[76:79], v[172:175], v[212:215], v[76:79]
	v_mfma_f32_16x16x32_bf16 v[72:75], v[180:183], v[212:215], v[72:75]
	s_barrier
	s_add_i32 s59, s50, s11
	v_lshl_add_u64 v[216:217], s[36:37], 0, v[132:133]
	s_mov_b32 m0, s59
	ds_read_b128 v[184:187], v153 offset:16384
	ds_read_b128 v[188:191], v153 offset:17408
	ds_read_b128 v[192:195], v153 offset:18432
	ds_read_b128 v[196:199], v153 offset:19456
	ds_read_b128 v[200:203], v153 offset:20480
	ds_read_b128 v[204:207], v153 offset:21504
	ds_read_b128 v[208:211], v153 offset:22528
	ds_read_b128 v[212:215], v153 offset:23552
	global_load_lds_dwordx4 v[216:217], off
	s_add_i32 m0, s59, 0x2000
	s_add_u32 s60, s36, 0x80000
	v_lshl_add_u64 v[218:219], s[36:37], 0, v[128:129]
	s_addc_u32 s61, s37, 0
	s_add_i32 s59, s51, s11
	global_load_lds_dwordx4 v[218:219], off
	v_lshl_add_u64 v[220:221], s[60:61], 0, v[132:133]
	s_mov_b32 m0, s59
	v_lshl_add_u64 v[222:223], s[38:39], 0, v[130:131]
	global_load_lds_dwordx4 v[220:221], off
	v_lshl_add_u64 v[220:221], s[60:61], 0, v[128:129]
	s_add_i32 m0, s59, 0x2000
	s_nop 0
	global_load_lds_dwordx4 v[220:221], off
	v_lshl_add_u64 v[220:221], s[38:39], 0, v[134:135]
	s_mov_b32 m0, s23
	s_nop 0
	global_load_lds_dwordx4 v[220:221], off
	s_mov_b32 m0, s40
	s_nop 0
	global_load_lds_dwordx4 v[222:223], off
	s_waitcnt vmcnt(8)
	s_waitcnt lgkmcnt(0)
	s_barrier
; #define PG8_STAGE(bufoff, gbase, voff) do { _Pragma("unroll") for (int _i = 0; _i < 2; ++_i) \
;         __builtin_amdgcn_global_load_lds((const unsigned*)((const char*)(gbase) + (voff)[_i]), (PG8_LAS unsigned*)(lds + (bufoff) + ldsw + _i * 8192), 16, 0, 0); } while (0)
; #define PG8_LDA(dst, b, h) do { _Pragma("unroll") for (int m = 0; m < 4; ++m) _Pragma("unroll") for (int k = 0; k < 2; ++k) dst[m][k] = *(const PG8_LAS bf16x8*)(lds + PG8_SA(b, h) + aoff + m * 2048 + k * 1024); } while (0)
; #define PG8_LDB(dst, b, h) do { _Pragma("unroll") for (int n = 0; n < 2; ++n) _Pragma("unroll") for (int k = 0; k < 2; ++k) dst[n][k] = *(const PG8_LAS bf16x8*)(lds + PG8_SB(b, h) + boff + n * 2048 + k * 1024); } while (0)
; #define PG8_MMA(ai, bj, At, Bt) do { __builtin_amdgcn_s_setprio(1); _Pragma("unroll") for (int m = 0; m < 4; ++m) _Pragma("unroll") for (int n = 0; n < 2; ++n) _Pragma("unroll") for (int k = 0; k < 2; ++k) \
;         acc[ai][bj][m][n] = __builtin_amdgcn_mfma_f32_16x16x32_bf16(Bt[n][k], At[m][k], acc[ai][bj][m][n], 0, 0, 0); __builtin_amdgcn_s_setprio(0); } while (0)
; #define PG8_WAIT_V(n) asm volatile("s_waitcnt vmcnt(" #n ")" ::: "memory")
; #define PG8_WAIT_L(n) asm volatile("s_waitcnt lgkmcnt(" #n ")" ::: "memory")
; #define PG8_BAR __builtin_amdgcn_s_barrier()
; #define PG8_SCHED __builtin_amdgcn_sched_barrier(0)
; template <class Epi, class Sched, bool ALIGN_EPI = false, bool SP2 = false>
; __device__ __forceinline__ void gemm_phase(PG8_LAS unsigned char* lds, const Gemm g, const Sched& S, const Epi& E, const int wave_in) {
;     ...
;             PG8_WAIT_V(8); PG8_WAIT_L(0); PG8_BAR; PG8_MMA(1, 0, At, B0); PG8_MMA(1, 1, At, B1); PG8_BAR; PG8_SCHED;
;             PG8_LDB(B0, 1, 0); PG8_LDB(B1, 1, 1); PG8_SCHED; PG8_LDA(At, 1, 0); PG8_STAGE(PG8_SA(0, 1), a2 + hstepA, voffA);
;             PG8_WAIT_V(8); PG8_WAIT_L(0); PG8_BAR; PG8_MMA(0, 0, At, B0); PG8_MMA(0, 1, At, B1); PG8_BAR; PG8_SCHED;
	s_waitcnt lgkmcnt(0)
	v_mfma_f32_16x16x32_bf16 v[52:55], v[144:147], v[184:187], v[52:55]
	v_mfma_f32_16x16x32_bf16 v[48:51], v[160:163], v[184:187], v[48:51]
	v_mfma_f32_16x16x32_bf16 v[36:39], v[144:147], v[192:195], v[36:39]
	v_mfma_f32_16x16x32_bf16 v[32:35], v[160:163], v[192:195], v[32:35]
	v_mfma_f32_16x16x32_bf16 v[20:23], v[144:147], v[200:203], v[20:23]
	v_mfma_f32_16x16x32_bf16 v[16:19], v[160:163], v[200:203], v[16:19]
	v_mfma_f32_16x16x32_bf16 v[4:7], v[144:147], v[208:211], v[4:7]
	v_mfma_f32_16x16x32_bf16 v[0:3], v[160:163], v[208:211], v[0:3]
	v_mfma_f32_16x16x32_bf16 v[52:55], v[156:159], v[188:191], v[52:55]
	v_mfma_f32_16x16x32_bf16 v[48:51], v[164:167], v[188:191], v[48:51]
	v_mfma_f32_16x16x32_bf16 v[36:39], v[156:159], v[196:199], v[36:39]
	v_mfma_f32_16x16x32_bf16 v[32:35], v[164:167], v[196:199], v[32:35]
	v_mfma_f32_16x16x32_bf16 v[20:23], v[156:159], v[204:207], v[20:23]
	v_mfma_f32_16x16x32_bf16 v[16:19], v[164:167], v[204:207], v[16:19]
	v_mfma_f32_16x16x32_bf16 v[4:7], v[156:159], v[212:215], v[4:7]
	v_mfma_f32_16x16x32_bf16 v[0:3], v[164:167], v[212:215], v[0:3]
	v_mfma_f32_16x16x32_bf16 v[60:63], v[168:171], v[184:187], v[60:63]
	v_mfma_f32_16x16x32_bf16 v[56:59], v[176:179], v[184:187], v[56:59]
	v_mfma_f32_16x16x32_bf16 v[44:47], v[168:171], v[192:195], v[44:47]
	v_mfma_f32_16x16x32_bf16 v[40:43], v[176:179], v[192:195], v[40:43]
	v_mfma_f32_16x16x32_bf16 v[28:31], v[168:171], v[200:203], v[28:31]
	v_mfma_f32_16x16x32_bf16 v[24:27], v[176:179], v[200:203], v[24:27]
	v_mfma_f32_16x16x32_bf16 v[12:15], v[168:171], v[208:211], v[12:15]
	v_mfma_f32_16x16x32_bf16 v[8:11], v[176:179], v[208:211], v[8:11]
	v_mfma_f32_16x16x32_bf16 v[60:63], v[172:175], v[188:191], v[60:63]
	v_mfma_f32_16x16x32_bf16 v[56:59], v[180:183], v[188:191], v[56:59]
	v_mfma_f32_16x16x32_bf16 v[44:47], v[172:175], v[196:199], v[44:47]
	v_mfma_f32_16x16x32_bf16 v[40:43], v[180:183], v[196:199], v[40:43]
	v_mfma_f32_16x16x32_bf16 v[28:31], v[172:175], v[204:207], v[28:31]
	v_mfma_f32_16x16x32_bf16 v[24:27], v[180:183], v[204:207], v[24:27]
	v_mfma_f32_16x16x32_bf16 v[12:15], v[172:175], v[212:215], v[12:15]
	v_mfma_f32_16x16x32_bf16 v[8:11], v[180:183], v[212:215], v[8:11]
	s_barrier
	s_add_i32 s59, 0, 0x18000
	v_add_u32_e32 v155, s59, v149
	s_add_i32 s60, 0, 0x1c000
	ds_read_b128 v[144:147], v155
	ds_read_b128 v[156:159], v155 offset:1024
	ds_read_b128 v[160:163], v155 offset:2048
	ds_read_b128 v[164:167], v155 offset:3072
	v_add_u32_e32 v155, s60, v149
	ds_read_b128 v[168:171], v155
	ds_read_b128 v[172:175], v155 offset:1024
	ds_read_b128 v[176:179], v155 offset:2048
	ds_read_b128 v[180:183], v155 offset:3072
	s_add_u32 s38, s38, 0x80000
	s_addc_u32 s39, s39, 0
	s_mov_b32 m0, s41
	v_lshl_add_u64 v[224:225], s[38:39], 0, v[134:135]
	ds_read_b128 v[184:187], v153 offset:32768
	ds_read_b128 v[188:191], v153 offset:33792
	ds_read_b128 v[192:195], v153 offset:34816
	ds_read_b128 v[196:199], v153 offset:35840
	ds_read_b128 v[200:203], v153 offset:36864
	ds_read_b128 v[204:207], v153 offset:37888
	ds_read_b128 v[208:211], v153 offset:38912
	ds_read_b128 v[212:215], v153 offset:39936
	global_load_lds_dwordx4 v[224:225], off
	v_lshl_add_u64 v[224:225], s[38:39], 0, v[130:131]
	s_mov_b32 m0, s42
	s_nop 0
	global_load_lds_dwordx4 v[224:225], off
	s_waitcnt vmcnt(8)
	s_waitcnt lgkmcnt(0)
	s_barrier
	s_waitcnt lgkmcnt(0)
	v_mfma_f32_16x16x32_bf16 v[116:119], v[144:147], v[184:187], v[116:119]
	v_mfma_f32_16x16x32_bf16 v[112:115], v[160:163], v[184:187], v[112:115]
	v_mfma_f32_16x16x32_bf16 v[100:103], v[144:147], v[192:195], v[100:103]
	v_mfma_f32_16x16x32_bf16 v[96:99], v[160:163], v[192:195], v[96:99]
	v_mfma_f32_16x16x32_bf16 v[84:87], v[144:147], v[200:203], v[84:87]
	v_mfma_f32_16x16x32_bf16 v[80:83], v[160:163], v[200:203], v[80:83]
	v_mfma_f32_16x16x32_bf16 v[68:71], v[144:147], v[208:211], v[68:71]
	v_mfma_f32_16x16x32_bf16 v[64:67], v[160:163], v[208:211], v[64:67]
	v_mfma_f32_16x16x32_bf16 v[116:119], v[156:159], v[188:191], v[116:119]
	v_mfma_f32_16x16x32_bf16 v[112:115], v[164:167], v[188:191], v[112:115]
	v_mfma_f32_16x16x32_bf16 v[100:103], v[156:159], v[196:199], v[100:103]
	v_mfma_f32_16x16x32_bf16 v[96:99], v[164:167], v[196:199], v[96:99]
	v_mfma_f32_16x16x32_bf16 v[84:87], v[156:159], v[204:207], v[84:87]
	v_mfma_f32_16x16x32_bf16 v[80:83], v[164:167], v[204:207], v[80:83]
	v_mfma_f32_16x16x32_bf16 v[68:71], v[156:159], v[212:215], v[68:71]
	v_mfma_f32_16x16x32_bf16 v[64:67], v[164:167], v[212:215], v[64:67]
	v_mfma_f32_16x16x32_bf16 v[124:127], v[168:171], v[184:187], v[124:127]
	v_mfma_f32_16x16x32_bf16 v[120:123], v[176:179], v[184:187], v[120:123]
	v_mfma_f32_16x16x32_bf16 v[108:111], v[168:171], v[192:195], v[108:111]
	v_mfma_f32_16x16x32_bf16 v[104:107], v[176:179], v[192:195], v[104:107]
	v_mfma_f32_16x16x32_bf16 v[92:95], v[168:171], v[200:203], v[92:95]
	v_mfma_f32_16x16x32_bf16 v[88:91], v[176:179], v[200:203], v[88:91]
	v_mfma_f32_16x16x32_bf16 v[76:79], v[168:171], v[208:211], v[76:79]
	v_mfma_f32_16x16x32_bf16 v[72:75], v[176:179], v[208:211], v[72:75]
	v_mfma_f32_16x16x32_bf16 v[124:127], v[172:175], v[188:191], v[124:127]
	v_mfma_f32_16x16x32_bf16 v[120:123], v[180:183], v[188:191], v[120:123]
	v_mfma_f32_16x16x32_bf16 v[108:111], v[172:175], v[196:199], v[108:111]
	v_mfma_f32_16x16x32_bf16 v[104:107], v[180:183], v[196:199], v[104:107]
	v_mfma_f32_16x16x32_bf16 v[92:95], v[172:175], v[204:207], v[92:95]
	v_mfma_f32_16x16x32_bf16 v[88:91], v[180:183], v[204:207], v[88:91]
	v_mfma_f32_16x16x32_bf16 v[76:79], v[172:175], v[212:215], v[76:79]
	v_mfma_f32_16x16x32_bf16 v[72:75], v[180:183], v[212:215], v[72:75]
	s_barrier
; #define PG8_STAGE(bufoff, gbase, voff) do { _Pragma("unroll") for (int _i = 0; _i < 2; ++_i) \
;         __builtin_amdgcn_global_load_lds((const unsigned*)((const char*)(gbase) + (voff)[_i]), (PG8_LAS unsigned*)(lds + (bufoff) + ldsw + _i * 8192), 16, 0, 0); } while (0)
; #define PG8_LDA(dst, b, h) do { _Pragma("unroll") for (int m = 0; m < 4; ++m) _Pragma("unroll") for (int k = 0; k < 2; ++k) dst[m][k] = *(const PG8_LAS bf16x8*)(lds + PG8_SA(b, h) + aoff + m * 2048 + k * 1024); } while (0)
; #define PG8_BAR __builtin_amdgcn_s_barrier()
; template <class Epi, class Sched, bool ALIGN_EPI = false, bool SP2 = false>
; __device__ __forceinline__ void gemm_phase(PG8_LAS unsigned char* lds, const Gemm g, const Sched& S, const Epi& E, const int wave_in) {
;     ...
;             PG8_LDA(At, 1, 1); PG8_STAGE(PG8_SB(1, 0), b3, voffB); PG8_STAGE(PG8_SB(1, 1), b3 + hstep, voffB); PG8_STAGE(PG8_SA(1, 0), a3, voffA);
;             PG8_WAIT_V(8); PG8_WAIT_L(0); PG8_BAR; PG8_MMA(1, 0, At, B0); PG8_MMA(1, 1, At, B1); PG8_BAR; PG8_SCHED;
;             } else {
;             PG8_LDB(B0, 0, 0); PG8_SCHED; PG8_LDA(At, 0, 0); PG8_STAGE(PG8_SA(1, 1), a1 + hstepA, voffA);
;             PG8_WAIT_L(8); PG8_BAR; PG8_WAIT_L(0); PG8_MMA(0, 0, At, B0); PG8_BAR; PG8_SCHED;
;             PG8_LDB(B1, 0, 1); PG8_STAGE(PG8_SB(0, 0), b2, voffB);
;             PG8_BAR; PG8_WAIT_L(0); PG8_MMA(0, 1, At, B1); PG8_BAR;
;             PG8_LDA(At, 0, 1); PG8_STAGE(PG8_SA(0, 0), a2, voffA);
;             PG8_BAR; PG8_WAIT_L(0); PG8_MMA(1, 0, At, B0); PG8_BAR; PG8_SCHED;
;             PG8_STAGE(PG8_SB(0, 1), b2 + hstep, voffB);
;             PG8_WAIT_V(6); PG8_BAR; PG8_MMA(1, 1, At, B1); PG8_BAR;
;             PG8_LDB(B0, 1, 0); PG8_SCHED; PG8_LDA(At, 1, 0); PG8_STAGE(PG8_SA(0, 1), a2 + hstepA, voffA);
;             PG8_WAIT_L(8); PG8_BAR; PG8_WAIT_L(0); PG8_MMA(0, 0, At, B0); PG8_BAR; PG8_SCHED;
;             PG8_LDB(B1, 1, 1); PG8_STAGE(PG8_SB(1, 0), b3, voffB);
;             PG8_BAR; PG8_WAIT_L(0); PG8_MMA(0, 1, At, B1); PG8_BAR;
;             PG8_LDA(At, 1, 1); PG8_STAGE(PG8_SA(1, 0), a3, voffA);
;             PG8_BAR; PG8_WAIT_L(0); PG8_MMA(1, 0, At, B0); PG8_BAR; PG8_SCHED;
;             PG8_STAGE(PG8_SB(1, 1), b3 + hstep, voffB);
;             PG8_WAIT_V(6); PG8_BAR; PG8_MMA(1, 1, At, B1); PG8_BAR;
;             }
;         }
;         if constexpr (ALIGN_EPI) { if (wr == 0) PG8_BAR; }
	s_add_i32 s38, s59, s11
	v_lshl_add_u64 v[216:217], v[216:217], 0, s[6:7]
	s_mov_b32 m0, s38
	ds_read_b128 v[184:187], v153 offset:49152
	ds_read_b128 v[188:191], v153 offset:50176
	ds_read_b128 v[192:195], v153 offset:51200
	ds_read_b128 v[196:199], v153 offset:52224
	ds_read_b128 v[200:203], v153 offset:53248
	ds_read_b128 v[204:207], v153 offset:54272
	ds_read_b128 v[208:211], v153 offset:55296
	ds_read_b128 v[212:215], v153 offset:56320
	global_load_lds_dwordx4 v[216:217], off
	s_add_i32 m0, s38, 0x2000
	s_add_u32 s36, s36, 0x80080
	v_lshl_add_u64 v[216:217], v[218:219], 0, s[6:7]
	s_addc_u32 s37, s37, 0
	s_add_i32 s38, s60, s11
	global_load_lds_dwordx4 v[216:217], off
	v_lshl_add_u64 v[216:217], s[36:37], 0, v[132:133]
	s_mov_b32 m0, s38
	s_nop 0
	global_load_lds_dwordx4 v[216:217], off
	v_lshl_add_u64 v[216:217], s[36:37], 0, v[128:129]
	s_add_i32 m0, s38, 0x2000
	s_nop 0
	global_load_lds_dwordx4 v[216:217], off
	v_lshl_add_u64 v[216:217], v[220:221], 0, s[6:7]
	s_mov_b32 m0, s48
	s_nop 0
	global_load_lds_dwordx4 v[216:217], off
	v_lshl_add_u64 v[216:217], v[222:223], 0, s[6:7]
	s_mov_b32 m0, s49
	s_nop 0
	global_load_lds_dwordx4 v[216:217], off
	s_waitcnt vmcnt(8)
	s_waitcnt lgkmcnt(0)
	s_barrier
	s_waitcnt lgkmcnt(0)
	v_mfma_f32_16x16x32_bf16 v[52:55], v[144:147], v[184:187], v[52:55]
	v_mfma_f32_16x16x32_bf16 v[48:51], v[160:163], v[184:187], v[48:51]
	v_mfma_f32_16x16x32_bf16 v[36:39], v[144:147], v[192:195], v[36:39]
	v_mfma_f32_16x16x32_bf16 v[32:35], v[160:163], v[192:195], v[32:35]
	v_mfma_f32_16x16x32_bf16 v[20:23], v[144:147], v[200:203], v[20:23]
	v_mfma_f32_16x16x32_bf16 v[16:19], v[160:163], v[200:203], v[16:19]
	v_mfma_f32_16x16x32_bf16 v[4:7], v[144:147], v[208:211], v[4:7]
	v_mfma_f32_16x16x32_bf16 v[0:3], v[160:163], v[208:211], v[0:3]
	v_mfma_f32_16x16x32_bf16 v[52:55], v[156:159], v[188:191], v[52:55]
	v_mfma_f32_16x16x32_bf16 v[48:51], v[164:167], v[188:191], v[48:51]
	v_mfma_f32_16x16x32_bf16 v[36:39], v[156:159], v[196:199], v[36:39]
	v_mfma_f32_16x16x32_bf16 v[32:35], v[164:167], v[196:199], v[32:35]
	v_mfma_f32_16x16x32_bf16 v[20:23], v[156:159], v[204:207], v[20:23]
	v_mfma_f32_16x16x32_bf16 v[16:19], v[164:167], v[204:207], v[16:19]
	v_mfma_f32_16x16x32_bf16 v[4:7], v[156:159], v[212:215], v[4:7]
	v_mfma_f32_16x16x32_bf16 v[0:3], v[164:167], v[212:215], v[0:3]
	v_mfma_f32_16x16x32_bf16 v[60:63], v[168:171], v[184:187], v[60:63]
	v_mfma_f32_16x16x32_bf16 v[56:59], v[176:179], v[184:187], v[56:59]
	v_mfma_f32_16x16x32_bf16 v[44:47], v[168:171], v[192:195], v[44:47]
	v_mfma_f32_16x16x32_bf16 v[40:43], v[176:179], v[192:195], v[40:43]
	v_mfma_f32_16x16x32_bf16 v[28:31], v[168:171], v[200:203], v[28:31]
	v_mfma_f32_16x16x32_bf16 v[24:27], v[176:179], v[200:203], v[24:27]
	v_mfma_f32_16x16x32_bf16 v[12:15], v[168:171], v[208:211], v[12:15]
	v_mfma_f32_16x16x32_bf16 v[8:11], v[176:179], v[208:211], v[8:11]
	v_mfma_f32_16x16x32_bf16 v[60:63], v[172:175], v[188:191], v[60:63]
	v_mfma_f32_16x16x32_bf16 v[56:59], v[180:183], v[188:191], v[56:59]
	v_mfma_f32_16x16x32_bf16 v[44:47], v[172:175], v[196:199], v[44:47]
	v_mfma_f32_16x16x32_bf16 v[40:43], v[180:183], v[196:199], v[40:43]
	v_mfma_f32_16x16x32_bf16 v[28:31], v[172:175], v[204:207], v[28:31]
	v_mfma_f32_16x16x32_bf16 v[24:27], v[180:183], v[204:207], v[24:27]
	v_mfma_f32_16x16x32_bf16 v[12:15], v[172:175], v[212:215], v[12:15]
	v_mfma_f32_16x16x32_bf16 v[8:11], v[180:183], v[212:215], v[8:11]
	s_barrier
	s_add_i32 s58, s58, 2
	s_add_u32 s24, s24, 0x100
	s_addc_u32 s25, s25, 0
	s_add_u32 s56, s56, 0x100
	s_addc_u32 s57, s57, 0
	s_cmp_gt_u32 s58, 29
	s_cbranch_scc0 .LBB0_2169
	s_and_b64 vcc, exec, s[12:13]
	s_cbranch_vccz .LBB0_2172
	s_barrier

;     __host__ __device__ bool next(int i, Unit& u) const {
;         const long L = (long)i * G + c; if (L >= nwg) return false;
;         int wgid = (int)L; { const int q = nwg / NXCD, r = nwg % NXCD, xcd = wgid % NXCD, off = wgid / NXCD; wgid = (xcd < r ? xcd * (q + 1) : r * (q + 1) + (xcd - r) * q) + off; }
; __global__ void __launch_bounds__(512, 2) fwd_kernel(Params p) {
;     ...
;     if (IN(17)) { pg8::Gemm g_{Hh, W_DN1, T, DM, FF, FF}; pg8::StaticOrder S_; S_.init(T, DM, G, bx); pg8::EpiResidT<false> E_{p.out, p.out, XB, SS + (size_t)6 * T, 0.5f};
;         pg8::gemm_phase<pg8::EpiResidT<false>, pg8::StaticOrder, true, true>(ldsl, g_, S_, E_, wave); }
.LBB0_2230:
	s_cmp_lt_i32 s92, 18
	s_cselect_b64 s[0:1], -1, 0
	s_cmp_gt_i32 s93, 17
	s_cselect_b64 s[2:3], -1, 0
	s_and_b64 s[0:1], s[0:1], s[2:3]
	s_andn2_b64 vcc, exec, s[0:1]
	s_waitcnt lgkmcnt(0)
	s_barrier
	s_cbranch_vccnz .LBB0_2277
	s_setprio 0
	s_cmp_lt_u32 s89, 4
	s_cbranch_scc1 .Lgprio_11
	s_setprio 1
.Lgprio_11:
	s_cmpk_lt_i32 s88, 0x400
	s_cselect_b64 s[0:1], -1, 0
	s_cmpk_gt_i32 s88, 0x3ff
	s_waitcnt vmcnt(0)
	v_mbcnt_lo_u32_b32 v8, -1, 0
	v_mbcnt_hi_u32_b32 v8, -1, v8
	s_cbranch_scc1 .LBB0_2237
	s_ashr_i32 s2, s88, 31
	s_lshr_b32 s2, s2, 29
	s_add_i32 s6, s88, s2
	s_and_b32 s2, s6, -8
	s_sub_i32 s4, s88, s2
	s_cmp_gt_i32 s4, -1
	s_cbranch_scc0 .LBB0_2234
	s_lshl_b32 s5, s4, 7
	s_ashr_i32 s2, s6, 3
	s_cbranch_execz .LBB0_2235
	s_branch .LBB0_2236

; #define PG8_STAGE(bufoff, gbase, voff) do { _Pragma("unroll") for (int _i = 0; _i < 2; ++_i) \
;         __builtin_amdgcn_global_load_lds((const unsigned*)((const char*)(gbase) + (voff)[_i]), (PG8_LAS unsigned*)(lds + (bufoff) + ldsw + _i * 8192), 16, 0, 0); } while (0)
; #define PG8_LDA(dst, b, h) do { _Pragma("unroll") for (int m = 0; m < 4; ++m) _Pragma("unroll") for (int k = 0; k < 2; ++k) dst[m][k] = *(const PG8_LAS bf16x8*)(lds + PG8_SA(b, h) + aoff + m * 2048 + k * 1024); } while (0)
; #define PG8_LDB(dst, b, h) do { _Pragma("unroll") for (int n = 0; n < 2; ++n) _Pragma("unroll") for (int k = 0; k < 2; ++k) dst[n][k] = *(const PG8_LAS bf16x8*)(lds + PG8_SB(b, h) + boff + n * 2048 + k * 1024); } while (0)
; #define PG8_WAIT_V(n) asm volatile("s_waitcnt vmcnt(" #n ")" ::: "memory")
; #define PG8_WAIT_L(n) asm volatile("s_waitcnt lgkmcnt(" #n ")" ::: "memory")
; #define PG8_BAR __builtin_amdgcn_s_barrier()
; #define PG8_SCHED __builtin_amdgcn_sched_barrier(0)
; template <class Epi, class Sched, bool ALIGN_EPI = false, bool SP2 = false>
; __device__ __forceinline__ void gemm_phase(PG8_LAS unsigned char* lds, const Gemm g, const Sched& S, const Epi& E, const int wave_in) {
;     ...
;         const char* nA = has_next ? (const char*)g.A + (size_t)nxt.pm * tstepA : cA; const char* nB = has_next ? (const char*)g.Bt + (size_t)nxt.pn * tstep : cB;
;         for (int t = 0; t < nt; t += 2) {
;             const bool last = (t == nt - 2);
;             const char* a1 = cA + (size_t)(t + 1) * kstep;
;             const char* a2 = last ? nA : cA + (size_t)(t + 2) * kstep; const char* b2 = last ? nB : cB + (size_t)(t + 2) * kstep;
;             const char* a3 = a2 + kstep; const char* b3 = b2 + kstep;
;             if (last && has_next) S.a_ready(nxt);
;             if constexpr (SP2) {
;             PG8_LDB(B0, 0, 0); PG8_LDB(B1, 0, 1); PG8_SCHED; PG8_LDA(At, 0, 0); PG8_STAGE(PG8_SA(1, 1), a1 + hstepA, voffA);
;             PG8_WAIT_V(8); PG8_WAIT_L(0); PG8_BAR; PG8_MMA(0, 0, At, B0); PG8_MMA(0, 1, At, B1); PG8_BAR; PG8_SCHED;
;             PG8_LDA(At, 0, 1); PG8_STAGE(PG8_SB(0, 0), b2, voffB); PG8_STAGE(PG8_SB(0, 1), b2 + hstep, voffB); PG8_STAGE(PG8_SA(0, 0), a2, voffA);
;             PG8_WAIT_V(8); PG8_WAIT_L(0); PG8_BAR; PG8_MMA(1, 0, At, B0); PG8_MMA(1, 1, At, B1); PG8_BAR; PG8_SCHED;
.LBB0_2254:
	ds_read_b128 v[144:147], v151
	ds_read_b128 v[156:159], v151 offset:1024
	ds_read_b128 v[160:163], v151 offset:2048
	ds_read_b128 v[164:167], v151 offset:3072
	ds_read_b128 v[168:171], v152
	ds_read_b128 v[172:175], v152 offset:1024
	ds_read_b128 v[176:179], v152 offset:2048
	ds_read_b128 v[180:183], v152 offset:3072
	s_add_u32 s22, s20, 0x100
	s_addc_u32 s23, s21, 0
	s_cmpk_eq_i32 s53, 0x54
	s_cselect_b32 s37, s7, s23
	s_cselect_b32 s36, s6, s22
	s_cselect_b32 s25, s19, s52
	s_cselect_b32 s24, s18, s51
	v_lshl_add_u64 v[216:217], s[20:21], 0, v[136:137]
	s_add_i32 m0, s33, 0xc000
	ds_read_b128 v[184:187], v153
	ds_read_b128 v[188:191], v153 offset:1024
	ds_read_b128 v[192:195], v153 offset:2048
	ds_read_b128 v[196:199], v153 offset:3072
	ds_read_b128 v[200:203], v153 offset:4096
	ds_read_b128 v[204:207], v153 offset:5120
	ds_read_b128 v[208:211], v153 offset:6144
	ds_read_b128 v[212:215], v153 offset:7168
	global_load_lds_dwordx4 v[216:217], off
	v_lshl_add_u64 v[216:217], s[20:21], 0, v[138:139]
	s_add_i32 m0, s33, 0xe000
	s_nop 0
	global_load_lds_dwordx4 v[216:217], off
	s_waitcnt vmcnt(8)
	s_waitcnt lgkmcnt(0)
	s_barrier
	s_waitcnt lgkmcnt(0)
	v_mfma_f32_16x16x32_bf16 v[124:127], v[144:147], v[184:187], v[124:127]
	v_mfma_f32_16x16x32_bf16 v[120:123], v[160:163], v[184:187], v[120:123]
	v_mfma_f32_16x16x32_bf16 v[108:111], v[144:147], v[192:195], v[108:111]
	v_mfma_f32_16x16x32_bf16 v[104:107], v[160:163], v[192:195], v[104:107]
	v_mfma_f32_16x16x32_bf16 v[92:95], v[144:147], v[200:203], v[92:95]
	v_mfma_f32_16x16x32_bf16 v[88:91], v[160:163], v[200:203], v[88:91]
	v_mfma_f32_16x16x32_bf16 v[76:79], v[144:147], v[208:211], v[76:79]
	v_mfma_f32_16x16x32_bf16 v[72:75], v[160:163], v[208:211], v[72:75]
	v_mfma_f32_16x16x32_bf16 v[124:127], v[156:159], v[188:191], v[124:127]
	v_mfma_f32_16x16x32_bf16 v[120:123], v[164:167], v[188:191], v[120:123]
	v_mfma_f32_16x16x32_bf16 v[108:111], v[156:159], v[196:199], v[108:111]
	v_mfma_f32_16x16x32_bf16 v[104:107], v[164:167], v[196:199], v[104:107]
	v_mfma_f32_16x16x32_bf16 v[92:95], v[156:159], v[204:207], v[92:95]
	v_mfma_f32_16x16x32_bf16 v[88:91], v[164:167], v[204:207], v[88:91]
	v_mfma_f32_16x16x32_bf16 v[76:79], v[156:159], v[212:215], v[76:79]
	v_mfma_f32_16x16x32_bf16 v[72:75], v[164:167], v[212:215], v[72:75]
	v_mfma_f32_16x16x32_bf16 v[116:119], v[168:171], v[184:187], v[116:119]
	v_mfma_f32_16x16x32_bf16 v[112:115], v[176:179], v[184:187], v[112:115]
	v_mfma_f32_16x16x32_bf16 v[100:103], v[168:171], v[192:195], v[100:103]
	v_mfma_f32_16x16x32_bf16 v[96:99], v[176:179], v[192:195], v[96:99]
	v_mfma_f32_16x16x32_bf16 v[84:87], v[168:171], v[200:203], v[84:87]
	v_mfma_f32_16x16x32_bf16 v[80:83], v[176:179], v[200:203], v[80:83]
	v_mfma_f32_16x16x32_bf16 v[68:71], v[168:171], v[208:211], v[68:71]
	v_mfma_f32_16x16x32_bf16 v[64:67], v[176:179], v[208:211], v[64:67]
	v_mfma_f32_16x16x32_bf16 v[116:119], v[172:175], v[188:191], v[116:119]
	v_mfma_f32_16x16x32_bf16 v[112:115], v[180:183], v[188:191], v[112:115]
	v_mfma_f32_16x16x32_bf16 v[100:103], v[172:175], v[196:199], v[100:103]
	v_mfma_f32_16x16x32_bf16 v[96:99], v[180:183], v[196:199], v[96:99]
	v_mfma_f32_16x16x32_bf16 v[84:87], v[172:175], v[204:207], v[84:87]
	v_mfma_f32_16x16x32_bf16 v[80:83], v[180:183], v[204:207], v[80:83]
	v_mfma_f32_16x16x32_bf16 v[68:71], v[172:175], v[212:215], v[68:71]
	v_mfma_f32_16x16x32_bf16 v[64:67], v[180:183], v[212:215], v[64:67]
	s_barrier
	s_add_i32 s20, s43, s11
	v_lshl_add_u64 v[216:217], s[24:25], 0, v[130:131]
	s_mov_b32 m0, s20
	ds_read_b128 v[184:187], v153 offset:16384
	ds_read_b128 v[188:191], v153 offset:17408
	ds_read_b128 v[192:195], v153 offset:18432
	ds_read_b128 v[196:199], v153 offset:19456
	ds_read_b128 v[200:203], v153 offset:20480
	ds_read_b128 v[204:207], v153 offset:21504
	ds_read_b128 v[208:211], v153 offset:22528
	ds_read_b128 v[212:215], v153 offset:23552
	global_load_lds_dwordx4 v[216:217], off
	s_add_i32 m0, s20, 0x2000
	s_add_u32 s20, s24, 0x160000
	v_lshl_add_u64 v[218:219], s[24:25], 0, v[134:135]
	s_addc_u32 s21, s25, 0
	s_add_i32 s54, s46, s11
	global_load_lds_dwordx4 v[218:219], off
	v_lshl_add_u64 v[220:221], s[20:21], 0, v[130:131]
	s_mov_b32 m0, s54
	v_lshl_add_u64 v[222:223], s[36:37], 0, v[132:133]
	global_load_lds_dwordx4 v[220:221], off
	v_lshl_add_u64 v[220:221], s[20:21], 0, v[134:135]
	s_add_i32 m0, s54, 0x2000
	s_nop 0
	global_load_lds_dwordx4 v[220:221], off
	v_lshl_add_u64 v[220:221], s[36:37], 0, v[128:129]
	s_mov_b32 m0, s33
	s_nop 0
	global_load_lds_dwordx4 v[220:221], off
	s_mov_b32 m0, s35
	s_nop 0
	global_load_lds_dwordx4 v[222:223], off
	s_waitcnt vmcnt(8)
	s_waitcnt lgkmcnt(0)
	s_barrier
; #define PG8_STAGE(bufoff, gbase, voff) do { _Pragma("unroll") for (int _i = 0; _i < 2; ++_i) \
;         __builtin_amdgcn_global_load_lds((const unsigned*)((const char*)(gbase) + (voff)[_i]), (PG8_LAS unsigned*)(lds + (bufoff) + ldsw + _i * 8192), 16, 0, 0); } while (0)
; #define PG8_LDA(dst, b, h) do { _Pragma("unroll") for (int m = 0; m < 4; ++m) _Pragma("unroll") for (int k = 0; k < 2; ++k) dst[m][k] = *(const PG8_LAS bf16x8*)(lds + PG8_SA(b, h) + aoff + m * 2048 + k * 1024); } while (0)
; #define PG8_LDB(dst, b, h) do { _Pragma("unroll") for (int n = 0; n < 2; ++n) _Pragma("unroll") for (int k = 0; k < 2; ++k) dst[n][k] = *(const PG8_LAS bf16x8*)(lds + PG8_SB(b, h) + boff + n * 2048 + k * 1024); } while (0)
; #define PG8_MMA(ai, bj, At, Bt) do { __builtin_amdgcn_s_setprio(1); _Pragma("unroll") for (int m = 0; m < 4; ++m) _Pragma("unroll") for (int n = 0; n < 2; ++n) _Pragma("unroll") for (int k = 0; k < 2; ++k) \
;         acc[ai][bj][m][n] = __builtin_amdgcn_mfma_f32_16x16x32_bf16(Bt[n][k], At[m][k], acc[ai][bj][m][n], 0, 0, 0); __builtin_amdgcn_s_setprio(0); } while (0)
; #define PG8_WAIT_V(n) asm volatile("s_waitcnt vmcnt(" #n ")" ::: "memory")
; #define PG8_WAIT_L(n) asm volatile("s_waitcnt lgkmcnt(" #n ")" ::: "memory")
; #define PG8_BAR __builtin_amdgcn_s_barrier()
; #define PG8_SCHED __builtin_amdgcn_sched_barrier(0)
; template <class Epi, class Sched, bool ALIGN_EPI = false, bool SP2 = false>
; __device__ __forceinline__ void gemm_phase(PG8_LAS unsigned char* lds, const Gemm g, const Sched& S, const Epi& E, const int wave_in) {
;     ...
;             PG8_WAIT_V(8); PG8_WAIT_L(0); PG8_BAR; PG8_MMA(1, 0, At, B0); PG8_MMA(1, 1, At, B1); PG8_BAR; PG8_SCHED;
;             PG8_LDB(B0, 1, 0); PG8_LDB(B1, 1, 1); PG8_SCHED; PG8_LDA(At, 1, 0); PG8_STAGE(PG8_SA(0, 1), a2 + hstepA, voffA);
;             PG8_WAIT_V(8); PG8_WAIT_L(0); PG8_BAR; PG8_MMA(0, 0, At, B0); PG8_MMA(0, 1, At, B1); PG8_BAR; PG8_SCHED;
	s_waitcnt lgkmcnt(0)
	v_mfma_f32_16x16x32_bf16 v[60:63], v[144:147], v[184:187], v[60:63]
	v_mfma_f32_16x16x32_bf16 v[56:59], v[160:163], v[184:187], v[56:59]
	v_mfma_f32_16x16x32_bf16 v[44:47], v[144:147], v[192:195], v[44:47]
	v_mfma_f32_16x16x32_bf16 v[40:43], v[160:163], v[192:195], v[40:43]
	v_mfma_f32_16x16x32_bf16 v[28:31], v[144:147], v[200:203], v[28:31]
	v_mfma_f32_16x16x32_bf16 v[24:27], v[160:163], v[200:203], v[24:27]
	v_mfma_f32_16x16x32_bf16 v[12:15], v[144:147], v[208:211], v[12:15]
	v_mfma_f32_16x16x32_bf16 v[8:11], v[160:163], v[208:211], v[8:11]
	v_mfma_f32_16x16x32_bf16 v[60:63], v[156:159], v[188:191], v[60:63]
	v_mfma_f32_16x16x32_bf16 v[56:59], v[164:167], v[188:191], v[56:59]
	v_mfma_f32_16x16x32_bf16 v[44:47], v[156:159], v[196:199], v[44:47]
	v_mfma_f32_16x16x32_bf16 v[40:43], v[164:167], v[196:199], v[40:43]
	v_mfma_f32_16x16x32_bf16 v[28:31], v[156:159], v[204:207], v[28:31]
	v_mfma_f32_16x16x32_bf16 v[24:27], v[164:167], v[204:207], v[24:27]
	v_mfma_f32_16x16x32_bf16 v[12:15], v[156:159], v[212:215], v[12:15]
	v_mfma_f32_16x16x32_bf16 v[8:11], v[164:167], v[212:215], v[8:11]
	v_mfma_f32_16x16x32_bf16 v[52:55], v[168:171], v[184:187], v[52:55]
	v_mfma_f32_16x16x32_bf16 v[48:51], v[176:179], v[184:187], v[48:51]
	v_mfma_f32_16x16x32_bf16 v[36:39], v[168:171], v[192:195], v[36:39]
	v_mfma_f32_16x16x32_bf16 v[32:35], v[176:179], v[192:195], v[32:35]
	v_mfma_f32_16x16x32_bf16 v[20:23], v[168:171], v[200:203], v[20:23]
	v_mfma_f32_16x16x32_bf16 v[16:19], v[176:179], v[200:203], v[16:19]
	v_mfma_f32_16x16x32_bf16 v[4:7], v[168:171], v[208:211], v[4:7]
	v_mfma_f32_16x16x32_bf16 v[0:3], v[176:179], v[208:211], v[0:3]
	v_mfma_f32_16x16x32_bf16 v[52:55], v[172:175], v[188:191], v[52:55]
	v_mfma_f32_16x16x32_bf16 v[48:51], v[180:183], v[188:191], v[48:51]
	v_mfma_f32_16x16x32_bf16 v[36:39], v[172:175], v[196:199], v[36:39]
	v_mfma_f32_16x16x32_bf16 v[32:35], v[180:183], v[196:199], v[32:35]
	v_mfma_f32_16x16x32_bf16 v[20:23], v[172:175], v[204:207], v[20:23]
	v_mfma_f32_16x16x32_bf16 v[16:19], v[180:183], v[204:207], v[16:19]
	v_mfma_f32_16x16x32_bf16 v[4:7], v[172:175], v[212:215], v[4:7]
	v_mfma_f32_16x16x32_bf16 v[0:3], v[180:183], v[212:215], v[0:3]
	s_barrier
	s_add_i32 s54, 0, 0x18000
	v_add_u32_e32 v155, s54, v149
	s_add_i32 s55, 0, 0x1c000
	ds_read_b128 v[144:147], v155
	ds_read_b128 v[156:159], v155 offset:1024
	ds_read_b128 v[160:163], v155 offset:2048
	ds_read_b128 v[164:167], v155 offset:3072
	v_add_u32_e32 v155, s55, v149
	ds_read_b128 v[168:171], v155
	ds_read_b128 v[172:175], v155 offset:1024
	ds_read_b128 v[176:179], v155 offset:2048
	ds_read_b128 v[180:183], v155 offset:3072
	s_add_u32 s20, s36, 0x160000
	s_addc_u32 s21, s37, 0
	s_mov_b32 m0, s38
	v_lshl_add_u64 v[224:225], s[20:21], 0, v[128:129]
	ds_read_b128 v[184:187], v153 offset:32768
	ds_read_b128 v[188:191], v153 offset:33792
	ds_read_b128 v[192:195], v153 offset:34816
	ds_read_b128 v[196:199], v153 offset:35840
	ds_read_b128 v[200:203], v153 offset:36864
	ds_read_b128 v[204:207], v153 offset:37888
	ds_read_b128 v[208:211], v153 offset:38912
	ds_read_b128 v[212:215], v153 offset:39936
	global_load_lds_dwordx4 v[224:225], off
	v_lshl_add_u64 v[224:225], s[20:21], 0, v[132:133]
	s_mov_b32 m0, s39
	s_nop 0
	global_load_lds_dwordx4 v[224:225], off
	s_waitcnt vmcnt(8)
	s_waitcnt lgkmcnt(0)
	s_barrier
	s_waitcnt lgkmcnt(0)
	v_mfma_f32_16x16x32_bf16 v[124:127], v[144:147], v[184:187], v[124:127]
	v_mfma_f32_16x16x32_bf16 v[120:123], v[160:163], v[184:187], v[120:123]
	v_mfma_f32_16x16x32_bf16 v[108:111], v[144:147], v[192:195], v[108:111]
	v_mfma_f32_16x16x32_bf16 v[104:107], v[160:163], v[192:195], v[104:107]
	v_mfma_f32_16x16x32_bf16 v[92:95], v[144:147], v[200:203], v[92:95]
	v_mfma_f32_16x16x32_bf16 v[88:91], v[160:163], v[200:203], v[88:91]
	v_mfma_f32_16x16x32_bf16 v[76:79], v[144:147], v[208:211], v[76:79]
	v_mfma_f32_16x16x32_bf16 v[72:75], v[160:163], v[208:211], v[72:75]
	v_mfma_f32_16x16x32_bf16 v[124:127], v[156:159], v[188:191], v[124:127]
	v_mfma_f32_16x16x32_bf16 v[120:123], v[164:167], v[188:191], v[120:123]
	v_mfma_f32_16x16x32_bf16 v[108:111], v[156:159], v[196:199], v[108:111]
	v_mfma_f32_16x16x32_bf16 v[104:107], v[164:167], v[196:199], v[104:107]
	v_mfma_f32_16x16x32_bf16 v[92:95], v[156:159], v[204:207], v[92:95]
	v_mfma_f32_16x16x32_bf16 v[88:91], v[164:167], v[204:207], v[88:91]
	v_mfma_f32_16x16x32_bf16 v[76:79], v[156:159], v[212:215], v[76:79]
	v_mfma_f32_16x16x32_bf16 v[72:75], v[164:167], v[212:215], v[72:75]
	v_mfma_f32_16x16x32_bf16 v[116:119], v[168:171], v[184:187], v[116:119]
	v_mfma_f32_16x16x32_bf16 v[112:115], v[176:179], v[184:187], v[112:115]
	v_mfma_f32_16x16x32_bf16 v[100:103], v[168:171], v[192:195], v[100:103]
	v_mfma_f32_16x16x32_bf16 v[96:99], v[176:179], v[192:195], v[96:99]
	v_mfma_f32_16x16x32_bf16 v[84:87], v[168:171], v[200:203], v[84:87]
	v_mfma_f32_16x16x32_bf16 v[80:83], v[176:179], v[200:203], v[80:83]
	v_mfma_f32_16x16x32_bf16 v[68:71], v[168:171], v[208:211], v[68:71]
	v_mfma_f32_16x16x32_bf16 v[64:67], v[176:179], v[208:211], v[64:67]
	v_mfma_f32_16x16x32_bf16 v[116:119], v[172:175], v[188:191], v[116:119]
	v_mfma_f32_16x16x32_bf16 v[112:115], v[180:183], v[188:191], v[112:115]
	v_mfma_f32_16x16x32_bf16 v[100:103], v[172:175], v[196:199], v[100:103]
	v_mfma_f32_16x16x32_bf16 v[96:99], v[180:183], v[196:199], v[96:99]
	v_mfma_f32_16x16x32_bf16 v[84:87], v[172:175], v[204:207], v[84:87]
	v_mfma_f32_16x16x32_bf16 v[80:83], v[180:183], v[204:207], v[80:83]
	v_mfma_f32_16x16x32_bf16 v[68:71], v[172:175], v[212:215], v[68:71]
	v_mfma_f32_16x16x32_bf16 v[64:67], v[180:183], v[212:215], v[64:67]
	s_barrier
; #define PG8_STAGE(bufoff, gbase, voff) do { _Pragma("unroll") for (int _i = 0; _i < 2; ++_i) \
;         __builtin_amdgcn_global_load_lds((const unsigned*)((const char*)(gbase) + (voff)[_i]), (PG8_LAS unsigned*)(lds + (bufoff) + ldsw + _i * 8192), 16, 0, 0); } while (0)
; #define PG8_LDA(dst, b, h) do { _Pragma("unroll") for (int m = 0; m < 4; ++m) _Pragma("unroll") for (int k = 0; k < 2; ++k) dst[m][k] = *(const PG8_LAS bf16x8*)(lds + PG8_SA(b, h) + aoff + m * 2048 + k * 1024); } while (0)
; #define PG8_BAR __builtin_amdgcn_s_barrier()
; template <class Epi, class Sched, bool ALIGN_EPI = false, bool SP2 = false>
; __device__ __forceinline__ void gemm_phase(PG8_LAS unsigned char* lds, const Gemm g, const Sched& S, const Epi& E, const int wave_in) {
;     ...
;             PG8_LDA(At, 1, 1); PG8_STAGE(PG8_SB(1, 0), b3, voffB); PG8_STAGE(PG8_SB(1, 1), b3 + hstep, voffB); PG8_STAGE(PG8_SA(1, 0), a3, voffA);
;             PG8_WAIT_V(8); PG8_WAIT_L(0); PG8_BAR; PG8_MMA(1, 0, At, B0); PG8_MMA(1, 1, At, B1); PG8_BAR; PG8_SCHED;
;             } else {
;             PG8_LDB(B0, 0, 0); PG8_SCHED; PG8_LDA(At, 0, 0); PG8_STAGE(PG8_SA(1, 1), a1 + hstepA, voffA);
;             PG8_WAIT_L(8); PG8_BAR; PG8_WAIT_L(0); PG8_MMA(0, 0, At, B0); PG8_BAR; PG8_SCHED;
;             PG8_LDB(B1, 0, 1); PG8_STAGE(PG8_SB(0, 0), b2, voffB);
;             PG8_BAR; PG8_WAIT_L(0); PG8_MMA(0, 1, At, B1); PG8_BAR;
;             PG8_LDA(At, 0, 1); PG8_STAGE(PG8_SA(0, 0), a2, voffA);
;             PG8_BAR; PG8_WAIT_L(0); PG8_MMA(1, 0, At, B0); PG8_BAR; PG8_SCHED;
;             PG8_STAGE(PG8_SB(0, 1), b2 + hstep, voffB);
;             PG8_WAIT_V(6); PG8_BAR; PG8_MMA(1, 1, At, B1); PG8_BAR;
;             PG8_LDB(B0, 1, 0); PG8_SCHED; PG8_LDA(At, 1, 0); PG8_STAGE(PG8_SA(0, 1), a2 + hstepA, voffA);
;             PG8_WAIT_L(8); PG8_BAR; PG8_WAIT_L(0); PG8_MMA(0, 0, At, B0); PG8_BAR; PG8_SCHED;
;             PG8_LDB(B1, 1, 1); PG8_STAGE(PG8_SB(1, 0), b3, voffB);
;             PG8_BAR; PG8_WAIT_L(0); PG8_MMA(0, 1, At, B1); PG8_BAR;
;             PG8_LDA(At, 1, 1); PG8_STAGE(PG8_SA(1, 0), a3, voffA);
;             PG8_BAR; PG8_WAIT_L(0); PG8_MMA(1, 0, At, B0); PG8_BAR; PG8_SCHED;
;             PG8_STAGE(PG8_SB(1, 1), b3 + hstep, voffB);
;             PG8_WAIT_V(6); PG8_BAR; PG8_MMA(1, 1, At, B1); PG8_BAR;
;             }
;         }
;         if constexpr (ALIGN_EPI) { if (wr == 0) PG8_BAR; }
	s_add_i32 s20, s54, s11
	v_lshl_add_u64 v[216:217], v[216:217], 0, s[14:15]
	s_mov_b32 m0, s20
	ds_read_b128 v[184:187], v153 offset:49152
	ds_read_b128 v[188:191], v153 offset:50176
	ds_read_b128 v[192:195], v153 offset:51200
	ds_read_b128 v[196:199], v153 offset:52224
	ds_read_b128 v[200:203], v153 offset:53248
	ds_read_b128 v[204:207], v153 offset:54272
	ds_read_b128 v[208:211], v153 offset:55296
	ds_read_b128 v[212:215], v153 offset:56320
	global_load_lds_dwordx4 v[216:217], off
	s_add_i32 m0, s20, 0x2000
	s_add_u32 s20, s24, 0x160080
	v_lshl_add_u64 v[216:217], v[218:219], 0, s[14:15]
	s_addc_u32 s21, s25, 0
	s_add_i32 s24, s55, s11
	global_load_lds_dwordx4 v[216:217], off
	v_lshl_add_u64 v[216:217], s[20:21], 0, v[130:131]
	s_mov_b32 m0, s24
	s_nop 0
	global_load_lds_dwordx4 v[216:217], off
	v_lshl_add_u64 v[216:217], s[20:21], 0, v[134:135]
	s_add_i32 m0, s24, 0x2000
	s_nop 0
	global_load_lds_dwordx4 v[216:217], off
	v_lshl_add_u64 v[216:217], v[220:221], 0, s[14:15]
	s_mov_b32 m0, s41
	s_nop 0
	global_load_lds_dwordx4 v[216:217], off
	v_lshl_add_u64 v[216:217], v[222:223], 0, s[14:15]
	s_mov_b32 m0, s42
	s_nop 0
	global_load_lds_dwordx4 v[216:217], off
	s_waitcnt vmcnt(8)
	s_waitcnt lgkmcnt(0)
	s_barrier
	s_waitcnt lgkmcnt(0)
	v_mfma_f32_16x16x32_bf16 v[60:63], v[144:147], v[184:187], v[60:63]
	v_mfma_f32_16x16x32_bf16 v[56:59], v[160:163], v[184:187], v[56:59]
	v_mfma_f32_16x16x32_bf16 v[44:47], v[144:147], v[192:195], v[44:47]
	v_mfma_f32_16x16x32_bf16 v[40:43], v[160:163], v[192:195], v[40:43]
	v_mfma_f32_16x16x32_bf16 v[28:31], v[144:147], v[200:203], v[28:31]
	v_mfma_f32_16x16x32_bf16 v[24:27], v[160:163], v[200:203], v[24:27]
	v_mfma_f32_16x16x32_bf16 v[12:15], v[144:147], v[208:211], v[12:15]
	v_mfma_f32_16x16x32_bf16 v[8:11], v[160:163], v[208:211], v[8:11]
	v_mfma_f32_16x16x32_bf16 v[60:63], v[156:159], v[188:191], v[60:63]
	v_mfma_f32_16x16x32_bf16 v[56:59], v[164:167], v[188:191], v[56:59]
	v_mfma_f32_16x16x32_bf16 v[44:47], v[156:159], v[196:199], v[44:47]
	v_mfma_f32_16x16x32_bf16 v[40:43], v[164:167], v[196:199], v[40:43]
	v_mfma_f32_16x16x32_bf16 v[28:31], v[156:159], v[204:207], v[28:31]
	v_mfma_f32_16x16x32_bf16 v[24:27], v[164:167], v[204:207], v[24:27]
	v_mfma_f32_16x16x32_bf16 v[12:15], v[156:159], v[212:215], v[12:15]
	v_mfma_f32_16x16x32_bf16 v[8:11], v[164:167], v[212:215], v[8:11]
	v_mfma_f32_16x16x32_bf16 v[52:55], v[168:171], v[184:187], v[52:55]
	v_mfma_f32_16x16x32_bf16 v[48:51], v[176:179], v[184:187], v[48:51]
	v_mfma_f32_16x16x32_bf16 v[36:39], v[168:171], v[192:195], v[36:39]
	v_mfma_f32_16x16x32_bf16 v[32:35], v[176:179], v[192:195], v[32:35]
	v_mfma_f32_16x16x32_bf16 v[20:23], v[168:171], v[200:203], v[20:23]
	v_mfma_f32_16x16x32_bf16 v[16:19], v[176:179], v[200:203], v[16:19]
	v_mfma_f32_16x16x32_bf16 v[4:7], v[168:171], v[208:211], v[4:7]
	v_mfma_f32_16x16x32_bf16 v[0:3], v[176:179], v[208:211], v[0:3]
	v_mfma_f32_16x16x32_bf16 v[52:55], v[172:175], v[188:191], v[52:55]
	v_mfma_f32_16x16x32_bf16 v[48:51], v[180:183], v[188:191], v[48:51]
	v_mfma_f32_16x16x32_bf16 v[36:39], v[172:175], v[196:199], v[36:39]
	v_mfma_f32_16x16x32_bf16 v[32:35], v[180:183], v[196:199], v[32:35]
	v_mfma_f32_16x16x32_bf16 v[20:23], v[172:175], v[204:207], v[20:23]
	v_mfma_f32_16x16x32_bf16 v[16:19], v[180:183], v[204:207], v[16:19]
	v_mfma_f32_16x16x32_bf16 v[4:7], v[172:175], v[212:215], v[4:7]
	v_mfma_f32_16x16x32_bf16 v[0:3], v[180:183], v[212:215], v[0:3]
	s_barrier
	s_add_i32 s53, s53, 2
	s_add_u32 s51, s51, 0x100
	s_addc_u32 s52, s52, 0
	s_cmpk_gt_u32 s53, 0x55
	s_mov_b64 s[20:21], s[22:23]
	s_cbranch_scc0 .LBB0_2254
	s_and_b64 vcc, exec, s[16:17]
	s_cbranch_vccz .LBB0_2257
	s_barrier
